# t45 + each load segment's closing vmcnt(8) and lgkmcnt(0) merged into one s_waitcnt in front of the barrier (freed slot parked before it, same bytes)
# speedup vs baseline: 1.0018x; 1.0018x over previous
; #define PG8_STAGE(bufoff, gbase, voff) do { _Pragma("unroll") for (int _i = 0; _i < 2; ++_i) \
;         __builtin_amdgcn_global_load_lds((const unsigned*)((const char*)(gbase) + (voff)[_i]), (PG8_LAS unsigned*)(lds + (bufoff) + ldsw + _i * 8192), 16, 0, 0); } while (0)
; #define PG8_LDA(dst, b, h) do { _Pragma("unroll") for (int m = 0; m < 4; ++m) _Pragma("unroll") for (int k = 0; k < 2; ++k) dst[m][k] = *(const PG8_LAS bf16x8*)(lds + PG8_SA(b, h) + aoff + m * 2048 + k * 1024); } while (0)
; #define PG8_LDB(dst, b, h) do { _Pragma("unroll") for (int n = 0; n < 2; ++n) _Pragma("unroll") for (int k = 0; k < 2; ++k) dst[n][k] = *(const PG8_LAS bf16x8*)(lds + PG8_SB(b, h) + boff + n * 2048 + k * 1024); } while (0)
; #define PG8_MMA(ai, bj, At, Bt) do { __builtin_amdgcn_s_setprio(1); _Pragma("unroll") for (int m = 0; m < 4; ++m) _Pragma("unroll") for (int n = 0; n < 2; ++n) _Pragma("unroll") for (int k = 0; k < 2; ++k) \
;         acc[ai][bj][m][n] = __builtin_amdgcn_mfma_f32_16x16x32_bf16(Bt[n][k], At[m][k], acc[ai][bj][m][n], 0, 0, 0); __builtin_amdgcn_s_setprio(0); } while (0)
; #define PG8_WAIT_V(n) asm volatile("s_waitcnt vmcnt(" #n ")" ::: "memory")
; #define PG8_BAR __builtin_amdgcn_s_barrier()
; template <class Epi, class Sched, bool ALIGN_EPI = false, bool SP2 = false>
; __device__ __forceinline__ void gemm_phase(PG8_LAS unsigned char* lds, const Gemm g, const Sched& S, const Epi& E) {
;     ...
;         for (int t = 0; t < nt; t += 2) {
;             const bool last = (t == nt - 2);
;             const char* a1 = cA + (size_t)(t + 1) * kstep;
;             const char* a2 = last ? nA : cA + (size_t)(t + 2) * kstep; const char* b2 = last ? nB : cB + (size_t)(t + 2) * kstep;
;             const char* a3 = a2 + kstep; const char* b3 = b2 + kstep;
;             if (last && has_next) S.a_ready(nxt);
;             if constexpr (SP2) {
;             PG8_LDB(B0, 0, 0); PG8_LDB(B1, 0, 1); PG8_SCHED; PG8_LDA(At, 0, 0); PG8_STAGE(PG8_SA(1, 1), a1 + hstep, voffA);
;             PG8_WAIT_V(8); PG8_WAIT_L(0); PG8_BAR; PG8_MMA(0, 0, At, B0); PG8_MMA(0, 1, At, B1); PG8_BAR; PG8_SCHED;
;             PG8_LDA(At, 0, 1); PG8_STAGE(PG8_SB(0, 0), b2, voffB); PG8_STAGE(PG8_SB(0, 1), b2 + hstep, voffB); PG8_STAGE(PG8_SA(0, 0), a2, voffA);
;             PG8_WAIT_V(8); PG8_WAIT_L(0); PG8_BAR; PG8_MMA(1, 0, At, B0); PG8_MMA(1, 1, At, B1); PG8_BAR; PG8_SCHED;
.LBB0_239:
	s_add_u32 s48, s12, 0xfff80080
	s_addc_u32 s49, s13, -1
	s_cmp_eq_u32 s47, 28
	s_cselect_b32 s51, s1, s49
	s_cselect_b32 s50, s2, s48
	s_cselect_b32 s49, s3, s37
	s_cselect_b32 s48, s15, s35
	s_add_i32 s65, 0, 0x10000
	v_add_u32_e32 v0, s65, v185
	s_add_i32 s68, 0, 0x14000
	ds_read_b128 v[132:135], v0
	ds_read_b128 v[136:139], v0 offset:1024
	ds_read_b128 v[140:143], v0 offset:2048
	ds_read_b128 v[144:147], v0 offset:3072
	v_add_u32_e32 v0, s68, v185
	ds_read_b128 v[148:151], v0
	ds_read_b128 v[152:155], v0 offset:1024
	ds_read_b128 v[172:175], v0 offset:2048
	ds_read_b128 v[176:179], v0 offset:3072
	v_lshl_add_u64 v[228:229], s[12:13], 0, v[168:169]
	s_add_i32 m0, s53, 0xc000
	ds_read_b128 v[180:183], v190
	ds_read_b128 v[192:195], v190 offset:1024
	ds_read_b128 v[196:199], v190 offset:2048
	ds_read_b128 v[200:203], v190 offset:3072
	ds_read_b128 v[204:207], v190 offset:4096
	ds_read_b128 v[208:211], v190 offset:5120
	ds_read_b128 v[220:223], v190 offset:6144
	ds_read_b128 v[224:227], v190 offset:7168
	global_load_lds_dwordx4 v[228:229], off
	v_lshl_add_u64 v[228:229], s[12:13], 0, v[170:171]
	s_add_i32 m0, s53, 0xe000
	s_nop 0
	global_load_lds_dwordx4 v[228:229], off
	s_setprio 1
	s_nop 0
	s_waitcnt vmcnt(8) lgkmcnt(0)
	s_barrier
	v_mfma_f32_16x16x32_bf16 v[128:131], v[132:135], v[180:183], v[128:131]
	v_mfma_f32_16x16x32_bf16 v[124:127], v[140:143], v[180:183], v[124:127]
	v_mfma_f32_16x16x32_bf16 v[112:115], v[132:135], v[196:199], v[112:115]
	v_mfma_f32_16x16x32_bf16 v[108:111], v[140:143], v[196:199], v[108:111]
	v_mfma_f32_16x16x32_bf16 v[96:99], v[132:135], v[204:207], v[96:99]
	v_mfma_f32_16x16x32_bf16 v[92:95], v[140:143], v[204:207], v[92:95]
	v_mfma_f32_16x16x32_bf16 v[80:83], v[132:135], v[220:223], v[80:83]
	v_mfma_f32_16x16x32_bf16 v[76:79], v[140:143], v[220:223], v[76:79]
	v_mfma_f32_16x16x32_bf16 v[128:131], v[136:139], v[192:195], v[128:131]
	v_mfma_f32_16x16x32_bf16 v[124:127], v[144:147], v[192:195], v[124:127]
	v_mfma_f32_16x16x32_bf16 v[112:115], v[136:139], v[200:203], v[112:115]
	v_mfma_f32_16x16x32_bf16 v[108:111], v[144:147], v[200:203], v[108:111]
	v_mfma_f32_16x16x32_bf16 v[96:99], v[136:139], v[208:211], v[96:99]
	v_mfma_f32_16x16x32_bf16 v[92:95], v[144:147], v[208:211], v[92:95]
	v_mfma_f32_16x16x32_bf16 v[80:83], v[136:139], v[224:227], v[80:83]
	v_mfma_f32_16x16x32_bf16 v[76:79], v[144:147], v[224:227], v[76:79]
	v_mfma_f32_16x16x32_bf16 v[120:123], v[148:151], v[180:183], v[120:123]
	v_mfma_f32_16x16x32_bf16 v[116:119], v[172:175], v[180:183], v[116:119]
	v_mfma_f32_16x16x32_bf16 v[104:107], v[148:151], v[196:199], v[104:107]
	v_mfma_f32_16x16x32_bf16 v[100:103], v[172:175], v[196:199], v[100:103]
	v_mfma_f32_16x16x32_bf16 v[88:91], v[148:151], v[204:207], v[88:91]
	v_mfma_f32_16x16x32_bf16 v[84:87], v[172:175], v[204:207], v[84:87]
	v_mfma_f32_16x16x32_bf16 v[72:75], v[148:151], v[220:223], v[72:75]
	v_mfma_f32_16x16x32_bf16 v[68:71], v[172:175], v[220:223], v[68:71]
	v_mfma_f32_16x16x32_bf16 v[120:123], v[152:155], v[192:195], v[120:123]
	v_mfma_f32_16x16x32_bf16 v[116:119], v[176:179], v[192:195], v[116:119]
	v_mfma_f32_16x16x32_bf16 v[104:107], v[152:155], v[200:203], v[104:107]
	v_mfma_f32_16x16x32_bf16 v[100:103], v[176:179], v[200:203], v[100:103]
	v_mfma_f32_16x16x32_bf16 v[88:91], v[152:155], v[208:211], v[88:91]
	v_mfma_f32_16x16x32_bf16 v[84:87], v[176:179], v[208:211], v[84:87]
	v_mfma_f32_16x16x32_bf16 v[72:75], v[152:155], v[224:227], v[72:75]
	v_mfma_f32_16x16x32_bf16 v[68:71], v[176:179], v[224:227], v[68:71]
	s_barrier
	s_setprio 0
	s_setprio 1
	s_setprio 0
	s_waitcnt lgkmcnt(0)
	s_add_i32 s65, s65, s52
	v_lshl_add_u64 v[228:229], s[48:49], 0, v[158:159]
	s_mov_b32 m0, s65
	ds_read_b128 v[180:183], v190 offset:16384
	ds_read_b128 v[192:195], v190 offset:17408
	ds_read_b128 v[196:199], v190 offset:18432
	ds_read_b128 v[200:203], v190 offset:19456
	ds_read_b128 v[204:207], v190 offset:20480
	ds_read_b128 v[208:211], v190 offset:21504
	ds_read_b128 v[220:223], v190 offset:22528
	ds_read_b128 v[224:227], v190 offset:23552
	global_load_lds_dwordx4 v[228:229], off
	s_add_i32 m0, s65, 0x2000
	s_add_u32 s66, s48, 0x80000
	v_lshl_add_u64 v[230:231], s[48:49], 0, v[162:163]
	s_addc_u32 s67, s49, 0
	s_add_i32 s65, s68, s52
	global_load_lds_dwordx4 v[230:231], off
	v_lshl_add_u64 v[232:233], s[66:67], 0, v[158:159]
	s_mov_b32 m0, s65
	v_lshl_add_u64 v[234:235], s[50:51], 0, v[160:161]
	global_load_lds_dwordx4 v[232:233], off
	v_lshl_add_u64 v[232:233], s[66:67], 0, v[162:163]
	s_add_i32 m0, s65, 0x2000
	s_nop 0
	global_load_lds_dwordx4 v[232:233], off
	v_lshl_add_u64 v[232:233], s[50:51], 0, v[156:157]
	s_mov_b32 m0, s53
	s_nop 0
	global_load_lds_dwordx4 v[232:233], off
	s_mov_b32 m0, s54
	s_nop 0
	global_load_lds_dwordx4 v[234:235], off
	s_setprio 1
	s_nop 0
	s_waitcnt vmcnt(8) lgkmcnt(0)
	s_barrier
; #define PG8_STAGE(bufoff, gbase, voff) do { _Pragma("unroll") for (int _i = 0; _i < 2; ++_i) \
;         __builtin_amdgcn_global_load_lds((const unsigned*)((const char*)(gbase) + (voff)[_i]), (PG8_LAS unsigned*)(lds + (bufoff) + ldsw + _i * 8192), 16, 0, 0); } while (0)
; #define PG8_LDA(dst, b, h) do { _Pragma("unroll") for (int m = 0; m < 4; ++m) _Pragma("unroll") for (int k = 0; k < 2; ++k) dst[m][k] = *(const PG8_LAS bf16x8*)(lds + PG8_SA(b, h) + aoff + m * 2048 + k * 1024); } while (0)
; #define PG8_LDB(dst, b, h) do { _Pragma("unroll") for (int n = 0; n < 2; ++n) _Pragma("unroll") for (int k = 0; k < 2; ++k) dst[n][k] = *(const PG8_LAS bf16x8*)(lds + PG8_SB(b, h) + boff + n * 2048 + k * 1024); } while (0)
; #define PG8_MMA(ai, bj, At, Bt) do { __builtin_amdgcn_s_setprio(1); _Pragma("unroll") for (int m = 0; m < 4; ++m) _Pragma("unroll") for (int n = 0; n < 2; ++n) _Pragma("unroll") for (int k = 0; k < 2; ++k) \
;         acc[ai][bj][m][n] = __builtin_amdgcn_mfma_f32_16x16x32_bf16(Bt[n][k], At[m][k], acc[ai][bj][m][n], 0, 0, 0); __builtin_amdgcn_s_setprio(0); } while (0)
; #define PG8_WAIT_V(n) asm volatile("s_waitcnt vmcnt(" #n ")" ::: "memory")
; #define PG8_WAIT_L(n) asm volatile("s_waitcnt lgkmcnt(" #n ")" ::: "memory")
; #define PG8_BAR __builtin_amdgcn_s_barrier()
; #define PG8_SCHED __builtin_amdgcn_sched_barrier(0)
; template <class Epi, class Sched, bool ALIGN_EPI = false, bool SP2 = false>
; __device__ __forceinline__ void gemm_phase(PG8_LAS unsigned char* lds, const Gemm g, const Sched& S, const Epi& E) {
;     ...
;             PG8_WAIT_V(8); PG8_WAIT_L(0); PG8_BAR; PG8_MMA(1, 0, At, B0); PG8_MMA(1, 1, At, B1); PG8_BAR; PG8_SCHED;
;             PG8_LDB(B0, 1, 0); PG8_LDB(B1, 1, 1); PG8_SCHED; PG8_LDA(At, 1, 0); PG8_STAGE(PG8_SA(0, 1), a2 + hstep, voffA);
;             PG8_WAIT_V(8); PG8_WAIT_L(0); PG8_BAR; PG8_MMA(0, 0, At, B0); PG8_MMA(0, 1, At, B1); PG8_BAR; PG8_SCHED;
;             PG8_LDA(At, 1, 1); PG8_STAGE(PG8_SB(1, 0), b3, voffB); PG8_STAGE(PG8_SB(1, 1), b3 + hstep, voffB); PG8_STAGE(PG8_SA(1, 0), a3, voffA);
	v_mfma_f32_16x16x32_bf16 v[62:65], v[132:135], v[180:183], v[62:65]
	v_mfma_f32_16x16x32_bf16 v[58:61], v[140:143], v[180:183], v[58:61]
	v_mfma_f32_16x16x32_bf16 v[46:49], v[132:135], v[196:199], v[46:49]
	v_mfma_f32_16x16x32_bf16 v[42:45], v[140:143], v[196:199], v[42:45]
	v_mfma_f32_16x16x32_bf16 v[30:33], v[132:135], v[204:207], v[30:33]
	v_mfma_f32_16x16x32_bf16 v[26:29], v[140:143], v[204:207], v[26:29]
	v_mfma_f32_16x16x32_bf16 v[14:17], v[132:135], v[220:223], v[14:17]
	v_mfma_f32_16x16x32_bf16 v[10:13], v[140:143], v[220:223], v[10:13]
	v_mfma_f32_16x16x32_bf16 v[62:65], v[136:139], v[192:195], v[62:65]
	v_mfma_f32_16x16x32_bf16 v[58:61], v[144:147], v[192:195], v[58:61]
	v_mfma_f32_16x16x32_bf16 v[46:49], v[136:139], v[200:203], v[46:49]
	v_mfma_f32_16x16x32_bf16 v[42:45], v[144:147], v[200:203], v[42:45]
	v_mfma_f32_16x16x32_bf16 v[30:33], v[136:139], v[208:211], v[30:33]
	v_mfma_f32_16x16x32_bf16 v[26:29], v[144:147], v[208:211], v[26:29]
	v_mfma_f32_16x16x32_bf16 v[14:17], v[136:139], v[224:227], v[14:17]
	v_mfma_f32_16x16x32_bf16 v[10:13], v[144:147], v[224:227], v[10:13]
	v_mfma_f32_16x16x32_bf16 v[54:57], v[148:151], v[180:183], v[54:57]
	v_mfma_f32_16x16x32_bf16 v[50:53], v[172:175], v[180:183], v[50:53]
	v_mfma_f32_16x16x32_bf16 v[38:41], v[148:151], v[196:199], v[38:41]
	v_mfma_f32_16x16x32_bf16 v[34:37], v[172:175], v[196:199], v[34:37]
	v_mfma_f32_16x16x32_bf16 v[22:25], v[148:151], v[204:207], v[22:25]
	v_mfma_f32_16x16x32_bf16 v[18:21], v[172:175], v[204:207], v[18:21]
	v_mfma_f32_16x16x32_bf16 v[6:9], v[148:151], v[220:223], v[6:9]
	v_mfma_f32_16x16x32_bf16 v[2:5], v[172:175], v[220:223], v[2:5]
	v_mfma_f32_16x16x32_bf16 v[54:57], v[152:155], v[192:195], v[54:57]
	v_mfma_f32_16x16x32_bf16 v[50:53], v[176:179], v[192:195], v[50:53]
	v_mfma_f32_16x16x32_bf16 v[38:41], v[152:155], v[200:203], v[38:41]
	v_mfma_f32_16x16x32_bf16 v[34:37], v[176:179], v[200:203], v[34:37]
	v_mfma_f32_16x16x32_bf16 v[22:25], v[152:155], v[208:211], v[22:25]
	v_mfma_f32_16x16x32_bf16 v[18:21], v[176:179], v[208:211], v[18:21]
	v_mfma_f32_16x16x32_bf16 v[6:9], v[152:155], v[224:227], v[6:9]
	v_mfma_f32_16x16x32_bf16 v[2:5], v[176:179], v[224:227], v[2:5]
	s_barrier
	s_setprio 0
	s_setprio 1
	s_setprio 0
	s_waitcnt lgkmcnt(0)
	s_add_i32 s65, 0, 0x18000
	v_add_u32_e32 v0, s65, v185
	s_add_i32 s66, 0, 0x1c000
	ds_read_b128 v[132:135], v0
	ds_read_b128 v[136:139], v0 offset:1024
	ds_read_b128 v[140:143], v0 offset:2048
	ds_read_b128 v[144:147], v0 offset:3072
	v_add_u32_e32 v0, s66, v185
	ds_read_b128 v[148:151], v0
	ds_read_b128 v[152:155], v0 offset:1024
	ds_read_b128 v[172:175], v0 offset:2048
	ds_read_b128 v[176:179], v0 offset:3072
	s_add_u32 s50, s50, 0x80000
	s_addc_u32 s51, s51, 0
	s_mov_b32 m0, s55
	v_lshl_add_u64 v[246:247], s[50:51], 0, v[156:157]
	ds_read_b128 v[180:183], v190 offset:32768
	ds_read_b128 v[192:195], v190 offset:33792
	ds_read_b128 v[196:199], v190 offset:34816
	ds_read_b128 v[200:203], v190 offset:35840
	ds_read_b128 v[204:207], v190 offset:36864
	ds_read_b128 v[208:211], v190 offset:37888
	ds_read_b128 v[220:223], v190 offset:38912
	ds_read_b128 v[224:227], v190 offset:39936
	global_load_lds_dwordx4 v[246:247], off
	v_lshl_add_u64 v[246:247], s[50:51], 0, v[160:161]
	s_mov_b32 m0, s56
	s_nop 0
	global_load_lds_dwordx4 v[246:247], off
	s_setprio 1
	s_nop 0
	s_waitcnt vmcnt(8) lgkmcnt(0)
	s_barrier
	v_mfma_f32_16x16x32_bf16 v[128:131], v[132:135], v[180:183], v[128:131]
	v_mfma_f32_16x16x32_bf16 v[124:127], v[140:143], v[180:183], v[124:127]
	v_mfma_f32_16x16x32_bf16 v[112:115], v[132:135], v[196:199], v[112:115]
	v_mfma_f32_16x16x32_bf16 v[108:111], v[140:143], v[196:199], v[108:111]
	v_mfma_f32_16x16x32_bf16 v[96:99], v[132:135], v[204:207], v[96:99]
	v_mfma_f32_16x16x32_bf16 v[92:95], v[140:143], v[204:207], v[92:95]
	v_mfma_f32_16x16x32_bf16 v[80:83], v[132:135], v[220:223], v[80:83]
	v_mfma_f32_16x16x32_bf16 v[76:79], v[140:143], v[220:223], v[76:79]
	v_mfma_f32_16x16x32_bf16 v[128:131], v[136:139], v[192:195], v[128:131]
	v_mfma_f32_16x16x32_bf16 v[124:127], v[144:147], v[192:195], v[124:127]
	v_mfma_f32_16x16x32_bf16 v[112:115], v[136:139], v[200:203], v[112:115]
	v_mfma_f32_16x16x32_bf16 v[108:111], v[144:147], v[200:203], v[108:111]
	v_mfma_f32_16x16x32_bf16 v[96:99], v[136:139], v[208:211], v[96:99]
	v_mfma_f32_16x16x32_bf16 v[92:95], v[144:147], v[208:211], v[92:95]
	v_mfma_f32_16x16x32_bf16 v[80:83], v[136:139], v[224:227], v[80:83]
	v_mfma_f32_16x16x32_bf16 v[76:79], v[144:147], v[224:227], v[76:79]
	v_mfma_f32_16x16x32_bf16 v[120:123], v[148:151], v[180:183], v[120:123]
	v_mfma_f32_16x16x32_bf16 v[116:119], v[172:175], v[180:183], v[116:119]
	v_mfma_f32_16x16x32_bf16 v[104:107], v[148:151], v[196:199], v[104:107]
	v_mfma_f32_16x16x32_bf16 v[100:103], v[172:175], v[196:199], v[100:103]
	v_mfma_f32_16x16x32_bf16 v[88:91], v[148:151], v[204:207], v[88:91]
	v_mfma_f32_16x16x32_bf16 v[84:87], v[172:175], v[204:207], v[84:87]
	v_mfma_f32_16x16x32_bf16 v[72:75], v[148:151], v[220:223], v[72:75]
	v_mfma_f32_16x16x32_bf16 v[68:71], v[172:175], v[220:223], v[68:71]
	v_mfma_f32_16x16x32_bf16 v[120:123], v[152:155], v[192:195], v[120:123]
	v_mfma_f32_16x16x32_bf16 v[116:119], v[176:179], v[192:195], v[116:119]
	v_mfma_f32_16x16x32_bf16 v[104:107], v[152:155], v[200:203], v[104:107]
	v_mfma_f32_16x16x32_bf16 v[100:103], v[176:179], v[200:203], v[100:103]
	v_mfma_f32_16x16x32_bf16 v[88:91], v[152:155], v[208:211], v[88:91]
	v_mfma_f32_16x16x32_bf16 v[84:87], v[176:179], v[208:211], v[84:87]
	v_mfma_f32_16x16x32_bf16 v[72:75], v[152:155], v[224:227], v[72:75]
	v_mfma_f32_16x16x32_bf16 v[68:71], v[176:179], v[224:227], v[68:71]
	s_barrier
; #define PG8_STAGE(bufoff, gbase, voff) do { _Pragma("unroll") for (int _i = 0; _i < 2; ++_i) \
;         __builtin_amdgcn_global_load_lds((const unsigned*)((const char*)(gbase) + (voff)[_i]), (PG8_LAS unsigned*)(lds + (bufoff) + ldsw + _i * 8192), 16, 0, 0); } while (0)
; #define PG8_LDA(dst, b, h) do { _Pragma("unroll") for (int m = 0; m < 4; ++m) _Pragma("unroll") for (int k = 0; k < 2; ++k) dst[m][k] = *(const PG8_LAS bf16x8*)(lds + PG8_SA(b, h) + aoff + m * 2048 + k * 1024); } while (0)
; #define PG8_MMA(ai, bj, At, Bt) do { __builtin_amdgcn_s_setprio(1); _Pragma("unroll") for (int m = 0; m < 4; ++m) _Pragma("unroll") for (int n = 0; n < 2; ++n) _Pragma("unroll") for (int k = 0; k < 2; ++k) \
;         acc[ai][bj][m][n] = __builtin_amdgcn_mfma_f32_16x16x32_bf16(Bt[n][k], At[m][k], acc[ai][bj][m][n], 0, 0, 0); __builtin_amdgcn_s_setprio(0); } while (0)
; #define PG8_WAIT_V(n) asm volatile("s_waitcnt vmcnt(" #n ")" ::: "memory")
; #define PG8_WAIT_L(n) asm volatile("s_waitcnt lgkmcnt(" #n ")" ::: "memory")
; #define PG8_BAR __builtin_amdgcn_s_barrier()
; #define PG8_SCHED __builtin_amdgcn_sched_barrier(0)
; template <class Epi, class Sched, bool ALIGN_EPI = false, bool SP2 = false>
; __device__ __forceinline__ void gemm_phase(PG8_LAS unsigned char* lds, const Gemm g, const Sched& S, const Epi& E) {
;     ...
;             PG8_LDA(At, 1, 1); PG8_STAGE(PG8_SB(1, 0), b3, voffB); PG8_STAGE(PG8_SB(1, 1), b3 + hstep, voffB); PG8_STAGE(PG8_SA(1, 0), a3, voffA);
;             PG8_WAIT_V(8); PG8_WAIT_L(0); PG8_BAR; PG8_MMA(1, 0, At, B0); PG8_MMA(1, 1, At, B1); PG8_BAR; PG8_SCHED;
;     ...
;         if constexpr (ALIGN_EPI) { if (wr == 0) PG8_BAR; }
	s_setprio 0
	s_setprio 1
	s_setprio 0
	s_waitcnt lgkmcnt(0)
	s_add_i32 s50, s65, s52
	v_lshl_add_u64 v[228:229], v[228:229], 0, s[88:89]
	s_mov_b32 m0, s50
	ds_read_b128 v[180:183], v190 offset:49152
	ds_read_b128 v[192:195], v190 offset:50176
	ds_read_b128 v[196:199], v190 offset:51200
	ds_read_b128 v[200:203], v190 offset:52224
	ds_read_b128 v[204:207], v190 offset:53248
	ds_read_b128 v[208:211], v190 offset:54272
	ds_read_b128 v[220:223], v190 offset:55296
	ds_read_b128 v[224:227], v190 offset:56320
	global_load_lds_dwordx4 v[228:229], off
	s_add_i32 m0, s50, 0x2000
	s_add_u32 s48, s48, 0x80080
	v_lshl_add_u64 v[228:229], v[230:231], 0, s[88:89]
	s_addc_u32 s49, s49, 0
	s_add_i32 s50, s66, s52
	global_load_lds_dwordx4 v[228:229], off
	v_lshl_add_u64 v[228:229], s[48:49], 0, v[158:159]
	s_mov_b32 m0, s50
	s_nop 0
	global_load_lds_dwordx4 v[228:229], off
	v_lshl_add_u64 v[228:229], s[48:49], 0, v[162:163]
	s_add_i32 m0, s50, 0x2000
	s_nop 0
	global_load_lds_dwordx4 v[228:229], off
	v_lshl_add_u64 v[228:229], v[232:233], 0, s[88:89]
	s_mov_b32 m0, s58
	s_nop 0
	global_load_lds_dwordx4 v[228:229], off
	v_lshl_add_u64 v[228:229], v[234:235], 0, s[88:89]
	s_mov_b32 m0, s59
	s_nop 0
	global_load_lds_dwordx4 v[228:229], off
	s_setprio 1
	s_nop 0
	s_waitcnt vmcnt(8) lgkmcnt(0)
	s_barrier
	v_mfma_f32_16x16x32_bf16 v[62:65], v[132:135], v[180:183], v[62:65]
	v_mfma_f32_16x16x32_bf16 v[58:61], v[140:143], v[180:183], v[58:61]
	v_mfma_f32_16x16x32_bf16 v[46:49], v[132:135], v[196:199], v[46:49]
	v_mfma_f32_16x16x32_bf16 v[42:45], v[140:143], v[196:199], v[42:45]
	v_mfma_f32_16x16x32_bf16 v[30:33], v[132:135], v[204:207], v[30:33]
	v_mfma_f32_16x16x32_bf16 v[26:29], v[140:143], v[204:207], v[26:29]
	v_mfma_f32_16x16x32_bf16 v[14:17], v[132:135], v[220:223], v[14:17]
	v_mfma_f32_16x16x32_bf16 v[10:13], v[140:143], v[220:223], v[10:13]
	v_mfma_f32_16x16x32_bf16 v[62:65], v[136:139], v[192:195], v[62:65]
	v_mfma_f32_16x16x32_bf16 v[58:61], v[144:147], v[192:195], v[58:61]
	v_mfma_f32_16x16x32_bf16 v[46:49], v[136:139], v[200:203], v[46:49]
	v_mfma_f32_16x16x32_bf16 v[42:45], v[144:147], v[200:203], v[42:45]
	v_mfma_f32_16x16x32_bf16 v[30:33], v[136:139], v[208:211], v[30:33]
	v_mfma_f32_16x16x32_bf16 v[26:29], v[144:147], v[208:211], v[26:29]
	v_mfma_f32_16x16x32_bf16 v[14:17], v[136:139], v[224:227], v[14:17]
	v_mfma_f32_16x16x32_bf16 v[10:13], v[144:147], v[224:227], v[10:13]
	v_mfma_f32_16x16x32_bf16 v[54:57], v[148:151], v[180:183], v[54:57]
	v_mfma_f32_16x16x32_bf16 v[50:53], v[172:175], v[180:183], v[50:53]
	v_mfma_f32_16x16x32_bf16 v[38:41], v[148:151], v[196:199], v[38:41]
	v_mfma_f32_16x16x32_bf16 v[34:37], v[172:175], v[196:199], v[34:37]
	v_mfma_f32_16x16x32_bf16 v[22:25], v[148:151], v[204:207], v[22:25]
	v_mfma_f32_16x16x32_bf16 v[18:21], v[172:175], v[204:207], v[18:21]
	v_mfma_f32_16x16x32_bf16 v[6:9], v[148:151], v[220:223], v[6:9]
	v_mfma_f32_16x16x32_bf16 v[2:5], v[172:175], v[220:223], v[2:5]
	v_mfma_f32_16x16x32_bf16 v[54:57], v[152:155], v[192:195], v[54:57]
	v_mfma_f32_16x16x32_bf16 v[50:53], v[176:179], v[192:195], v[50:53]
	v_mfma_f32_16x16x32_bf16 v[38:41], v[152:155], v[200:203], v[38:41]
	v_mfma_f32_16x16x32_bf16 v[34:37], v[176:179], v[200:203], v[34:37]
	v_mfma_f32_16x16x32_bf16 v[22:25], v[152:155], v[208:211], v[22:25]
	v_mfma_f32_16x16x32_bf16 v[18:21], v[176:179], v[208:211], v[18:21]
	v_mfma_f32_16x16x32_bf16 v[6:9], v[152:155], v[224:227], v[6:9]
	v_mfma_f32_16x16x32_bf16 v[2:5], v[176:179], v[224:227], v[2:5]
	s_barrier
	s_setprio 0
	s_setprio 1
	s_setprio 0
	s_waitcnt lgkmcnt(0)
	s_add_i32 s47, s47, 2
	s_add_u32 s12, s12, 0x100
	s_addc_u32 s13, s13, 0
	s_add_u32 s35, s35, 0x100
	s_addc_u32 s37, s37, 0
	s_cmp_gt_u32 s47, 29
	s_cbranch_scc0 .LBB0_239
	s_and_b64 vcc, exec, s[30:31]
	s_cbranch_vccz .LBB0_242
	s_barrier

; #define PG8_STAGE(bufoff, gbase, voff) do { _Pragma("unroll") for (int _i = 0; _i < 2; ++_i) \
;         __builtin_amdgcn_global_load_lds((const unsigned*)((const char*)(gbase) + (voff)[_i]), (PG8_LAS unsigned*)(lds + (bufoff) + ldsw + _i * 8192), 16, 0, 0); } while (0)
; #define PG8_LDA(dst, b, h) do { _Pragma("unroll") for (int m = 0; m < 4; ++m) _Pragma("unroll") for (int k = 0; k < 2; ++k) dst[m][k] = *(const PG8_LAS bf16x8*)(lds + PG8_SA(b, h) + aoff + m * 2048 + k * 1024); } while (0)
; #define PG8_LDB(dst, b, h) do { _Pragma("unroll") for (int n = 0; n < 2; ++n) _Pragma("unroll") for (int k = 0; k < 2; ++k) dst[n][k] = *(const PG8_LAS bf16x8*)(lds + PG8_SB(b, h) + boff + n * 2048 + k * 1024); } while (0)
; #define PG8_MMA(ai, bj, At, Bt) do { __builtin_amdgcn_s_setprio(1); _Pragma("unroll") for (int m = 0; m < 4; ++m) _Pragma("unroll") for (int n = 0; n < 2; ++n) _Pragma("unroll") for (int k = 0; k < 2; ++k) \
;         acc[ai][bj][m][n] = __builtin_amdgcn_mfma_f32_16x16x32_bf16(Bt[n][k], At[m][k], acc[ai][bj][m][n], 0, 0, 0); __builtin_amdgcn_s_setprio(0); } while (0)
; #define PG8_WAIT_V(n) asm volatile("s_waitcnt vmcnt(" #n ")" ::: "memory")
; #define PG8_BAR __builtin_amdgcn_s_barrier()
; template <class Epi, class Sched, bool ALIGN_EPI = false, bool SP2 = false>
; __device__ __forceinline__ void gemm_phase(PG8_LAS unsigned char* lds, const Gemm g, const Sched& S, const Epi& E) {
;     ...
;         for (int t = 0; t < nt; t += 2) {
;             const bool last = (t == nt - 2);
;             const char* a1 = cA + (size_t)(t + 1) * kstep;
;             const char* a2 = last ? nA : cA + (size_t)(t + 2) * kstep; const char* b2 = last ? nB : cB + (size_t)(t + 2) * kstep;
;             const char* a3 = a2 + kstep; const char* b3 = b2 + kstep;
;             if (last && has_next) S.a_ready(nxt);
;             if constexpr (SP2) {
;             PG8_LDB(B0, 0, 0); PG8_LDB(B1, 0, 1); PG8_SCHED; PG8_LDA(At, 0, 0); PG8_STAGE(PG8_SA(1, 1), a1 + hstep, voffA);
;             PG8_WAIT_V(8); PG8_WAIT_L(0); PG8_BAR; PG8_MMA(0, 0, At, B0); PG8_MMA(0, 1, At, B1); PG8_BAR; PG8_SCHED;
;             PG8_LDA(At, 0, 1); PG8_STAGE(PG8_SB(0, 0), b2, voffB); PG8_STAGE(PG8_SB(0, 1), b2 + hstep, voffB); PG8_STAGE(PG8_SA(0, 0), a2, voffA);
;             PG8_WAIT_V(8); PG8_WAIT_L(0); PG8_BAR; PG8_MMA(1, 0, At, B0); PG8_MMA(1, 1, At, B1); PG8_BAR; PG8_SCHED;
.LBB0_398:
	s_lshl_b32 s54, s43, 7
	s_add_u32 s55, s30, s54
	s_addc_u32 s56, s31, 0
	s_add_u32 s57, s55, 0x100
	s_addc_u32 s58, s56, 0
	s_and_b64 s[52:53], s[12:13], exec
	s_cselect_b32 s53, s58, s1
	s_cselect_b32 s52, s57, s2
	s_add_u32 s54, s34, s54
	s_addc_u32 s57, s35, 0
	s_add_u32 s54, s54, 0x100
	s_addc_u32 s57, s57, 0
	s_and_b64 s[12:13], s[12:13], exec
	s_cselect_b32 s13, s57, s3
	s_cselect_b32 s12, s54, s41
	s_add_i32 s57, 0, 0x10000
	v_add_u32_e32 v0, s57, v181
	s_add_i32 s58, 0, 0x14000
	ds_read_b128 v[132:135], v0
	ds_read_b128 v[136:139], v0 offset:1024
	ds_read_b128 v[140:143], v0 offset:2048
	ds_read_b128 v[144:147], v0 offset:3072
	v_add_u32_e32 v0, s58, v181
	ds_read_b128 v[148:151], v0
	ds_read_b128 v[152:155], v0 offset:1024
	ds_read_b128 v[168:171], v0 offset:2048
	ds_read_b128 v[172:175], v0 offset:3072
	s_add_u32 s54, s55, 0x80080
	s_addc_u32 s55, s56, 0
	v_lshl_add_u64 v[224:225], s[54:55], 0, v[156:157]
	s_add_i32 m0, s29, 0xc000
	ds_read_b128 v[176:179], v187
	ds_read_b128 v[188:191], v187 offset:1024
	ds_read_b128 v[192:195], v187 offset:2048
	ds_read_b128 v[196:199], v187 offset:3072
	ds_read_b128 v[200:203], v187 offset:4096
	ds_read_b128 v[204:207], v187 offset:5120
	ds_read_b128 v[208:211], v187 offset:6144
	ds_read_b128 v[220:223], v187 offset:7168
	global_load_lds_dwordx4 v[224:225], off
	v_lshl_add_u64 v[224:225], s[54:55], 0, v[160:161]
	s_add_i32 m0, s29, 0xe000
	s_nop 0
	global_load_lds_dwordx4 v[224:225], off
	s_setprio 1
	s_nop 0
	s_waitcnt vmcnt(8) lgkmcnt(0)
	s_barrier
	v_mfma_f32_16x16x32_bf16 v[128:131], v[132:135], v[176:179], v[128:131]
	v_mfma_f32_16x16x32_bf16 v[124:127], v[140:143], v[176:179], v[124:127]
	v_mfma_f32_16x16x32_bf16 v[120:123], v[132:135], v[192:195], v[120:123]
	v_mfma_f32_16x16x32_bf16 v[116:119], v[140:143], v[192:195], v[116:119]
	v_mfma_f32_16x16x32_bf16 v[112:115], v[132:135], v[200:203], v[112:115]
	v_mfma_f32_16x16x32_bf16 v[108:111], v[140:143], v[200:203], v[108:111]
	v_mfma_f32_16x16x32_bf16 v[104:107], v[132:135], v[208:211], v[104:107]
	v_mfma_f32_16x16x32_bf16 v[100:103], v[140:143], v[208:211], v[100:103]
	v_mfma_f32_16x16x32_bf16 v[128:131], v[136:139], v[188:191], v[128:131]
	v_mfma_f32_16x16x32_bf16 v[124:127], v[144:147], v[188:191], v[124:127]
	v_mfma_f32_16x16x32_bf16 v[120:123], v[136:139], v[196:199], v[120:123]
	v_mfma_f32_16x16x32_bf16 v[116:119], v[144:147], v[196:199], v[116:119]
	v_mfma_f32_16x16x32_bf16 v[112:115], v[136:139], v[204:207], v[112:115]
	v_mfma_f32_16x16x32_bf16 v[108:111], v[144:147], v[204:207], v[108:111]
	v_mfma_f32_16x16x32_bf16 v[104:107], v[136:139], v[220:223], v[104:107]
	v_mfma_f32_16x16x32_bf16 v[100:103], v[144:147], v[220:223], v[100:103]
	v_mfma_f32_16x16x32_bf16 v[96:99], v[148:151], v[176:179], v[96:99]
	v_mfma_f32_16x16x32_bf16 v[92:95], v[168:171], v[176:179], v[92:95]
	v_mfma_f32_16x16x32_bf16 v[88:91], v[148:151], v[192:195], v[88:91]
	v_mfma_f32_16x16x32_bf16 v[84:87], v[168:171], v[192:195], v[84:87]
	v_mfma_f32_16x16x32_bf16 v[80:83], v[148:151], v[200:203], v[80:83]
	v_mfma_f32_16x16x32_bf16 v[76:79], v[168:171], v[200:203], v[76:79]
	v_mfma_f32_16x16x32_bf16 v[72:75], v[148:151], v[208:211], v[72:75]
	v_mfma_f32_16x16x32_bf16 v[68:71], v[168:171], v[208:211], v[68:71]
	v_mfma_f32_16x16x32_bf16 v[96:99], v[152:155], v[188:191], v[96:99]
	v_mfma_f32_16x16x32_bf16 v[92:95], v[172:175], v[188:191], v[92:95]
	v_mfma_f32_16x16x32_bf16 v[88:91], v[152:155], v[196:199], v[88:91]
	v_mfma_f32_16x16x32_bf16 v[84:87], v[172:175], v[196:199], v[84:87]
	v_mfma_f32_16x16x32_bf16 v[80:83], v[152:155], v[204:207], v[80:83]
	v_mfma_f32_16x16x32_bf16 v[76:79], v[172:175], v[204:207], v[76:79]
	v_mfma_f32_16x16x32_bf16 v[72:75], v[152:155], v[220:223], v[72:75]
	v_mfma_f32_16x16x32_bf16 v[68:71], v[172:175], v[220:223], v[68:71]
	s_barrier
	s_setprio 0
	s_setprio 1
	s_setprio 0
	s_waitcnt lgkmcnt(0)
	s_add_i32 s54, s57, s15
	v_lshl_add_u64 v[224:225], s[12:13], 0, v[158:159]
	s_mov_b32 m0, s54
	ds_read_b128 v[176:179], v187 offset:16384
	ds_read_b128 v[188:191], v187 offset:17408
	ds_read_b128 v[192:195], v187 offset:18432
	ds_read_b128 v[196:199], v187 offset:19456
	ds_read_b128 v[200:203], v187 offset:20480
	ds_read_b128 v[204:207], v187 offset:21504
	ds_read_b128 v[208:211], v187 offset:22528
	ds_read_b128 v[220:223], v187 offset:23552
	global_load_lds_dwordx4 v[224:225], off
	s_add_i32 m0, s54, 0x2000
	s_add_u32 s54, s12, 0x80000
	v_lshl_add_u64 v[226:227], s[12:13], 0, v[162:163]
	s_addc_u32 s55, s13, 0
	s_add_i32 s56, s58, s15
	global_load_lds_dwordx4 v[226:227], off
	v_lshl_add_u64 v[228:229], s[54:55], 0, v[158:159]
	s_mov_b32 m0, s56
	v_lshl_add_u64 v[230:231], s[52:53], 0, v[160:161]
	global_load_lds_dwordx4 v[228:229], off
	v_lshl_add_u64 v[228:229], s[54:55], 0, v[162:163]
	s_add_i32 m0, s56, 0x2000
	s_nop 0
	global_load_lds_dwordx4 v[228:229], off
	v_lshl_add_u64 v[228:229], s[52:53], 0, v[156:157]
	s_mov_b32 m0, s29
	s_nop 0
	global_load_lds_dwordx4 v[228:229], off
	s_mov_b32 m0, s65
	s_nop 0
	global_load_lds_dwordx4 v[230:231], off
	s_setprio 1
	s_nop 0
	s_waitcnt vmcnt(8) lgkmcnt(0)
	s_barrier
; #define PG8_STAGE(bufoff, gbase, voff) do { _Pragma("unroll") for (int _i = 0; _i < 2; ++_i) \
;         __builtin_amdgcn_global_load_lds((const unsigned*)((const char*)(gbase) + (voff)[_i]), (PG8_LAS unsigned*)(lds + (bufoff) + ldsw + _i * 8192), 16, 0, 0); } while (0)
; #define PG8_LDA(dst, b, h) do { _Pragma("unroll") for (int m = 0; m < 4; ++m) _Pragma("unroll") for (int k = 0; k < 2; ++k) dst[m][k] = *(const PG8_LAS bf16x8*)(lds + PG8_SA(b, h) + aoff + m * 2048 + k * 1024); } while (0)
; #define PG8_LDB(dst, b, h) do { _Pragma("unroll") for (int n = 0; n < 2; ++n) _Pragma("unroll") for (int k = 0; k < 2; ++k) dst[n][k] = *(const PG8_LAS bf16x8*)(lds + PG8_SB(b, h) + boff + n * 2048 + k * 1024); } while (0)
; #define PG8_MMA(ai, bj, At, Bt) do { __builtin_amdgcn_s_setprio(1); _Pragma("unroll") for (int m = 0; m < 4; ++m) _Pragma("unroll") for (int n = 0; n < 2; ++n) _Pragma("unroll") for (int k = 0; k < 2; ++k) \
;         acc[ai][bj][m][n] = __builtin_amdgcn_mfma_f32_16x16x32_bf16(Bt[n][k], At[m][k], acc[ai][bj][m][n], 0, 0, 0); __builtin_amdgcn_s_setprio(0); } while (0)
; #define PG8_WAIT_V(n) asm volatile("s_waitcnt vmcnt(" #n ")" ::: "memory")
; #define PG8_WAIT_L(n) asm volatile("s_waitcnt lgkmcnt(" #n ")" ::: "memory")
; #define PG8_BAR __builtin_amdgcn_s_barrier()
; #define PG8_SCHED __builtin_amdgcn_sched_barrier(0)
; template <class Epi, class Sched, bool ALIGN_EPI = false, bool SP2 = false>
; __device__ __forceinline__ void gemm_phase(PG8_LAS unsigned char* lds, const Gemm g, const Sched& S, const Epi& E) {
;     ...
;             PG8_WAIT_V(8); PG8_WAIT_L(0); PG8_BAR; PG8_MMA(1, 0, At, B0); PG8_MMA(1, 1, At, B1); PG8_BAR; PG8_SCHED;
;             PG8_LDB(B0, 1, 0); PG8_LDB(B1, 1, 1); PG8_SCHED; PG8_LDA(At, 1, 0); PG8_STAGE(PG8_SA(0, 1), a2 + hstep, voffA);
;             PG8_WAIT_V(8); PG8_WAIT_L(0); PG8_BAR; PG8_MMA(0, 0, At, B0); PG8_MMA(0, 1, At, B1); PG8_BAR; PG8_SCHED;
;             PG8_LDA(At, 1, 1); PG8_STAGE(PG8_SB(1, 0), b3, voffB); PG8_STAGE(PG8_SB(1, 1), b3 + hstep, voffB); PG8_STAGE(PG8_SA(1, 0), a3, voffA);
	v_mfma_f32_16x16x32_bf16 v[62:65], v[132:135], v[176:179], v[62:65]
	v_mfma_f32_16x16x32_bf16 v[58:61], v[140:143], v[176:179], v[58:61]
	v_mfma_f32_16x16x32_bf16 v[54:57], v[132:135], v[192:195], v[54:57]
	v_mfma_f32_16x16x32_bf16 v[50:53], v[140:143], v[192:195], v[50:53]
	v_mfma_f32_16x16x32_bf16 v[46:49], v[132:135], v[200:203], v[46:49]
	v_mfma_f32_16x16x32_bf16 v[42:45], v[140:143], v[200:203], v[42:45]
	v_mfma_f32_16x16x32_bf16 v[38:41], v[132:135], v[208:211], v[38:41]
	v_mfma_f32_16x16x32_bf16 v[34:37], v[140:143], v[208:211], v[34:37]
	v_mfma_f32_16x16x32_bf16 v[62:65], v[136:139], v[188:191], v[62:65]
	v_mfma_f32_16x16x32_bf16 v[58:61], v[144:147], v[188:191], v[58:61]
	v_mfma_f32_16x16x32_bf16 v[54:57], v[136:139], v[196:199], v[54:57]
	v_mfma_f32_16x16x32_bf16 v[50:53], v[144:147], v[196:199], v[50:53]
	v_mfma_f32_16x16x32_bf16 v[46:49], v[136:139], v[204:207], v[46:49]
	v_mfma_f32_16x16x32_bf16 v[42:45], v[144:147], v[204:207], v[42:45]
	v_mfma_f32_16x16x32_bf16 v[38:41], v[136:139], v[220:223], v[38:41]
	v_mfma_f32_16x16x32_bf16 v[34:37], v[144:147], v[220:223], v[34:37]
	v_mfma_f32_16x16x32_bf16 v[30:33], v[148:151], v[176:179], v[30:33]
	v_mfma_f32_16x16x32_bf16 v[26:29], v[168:171], v[176:179], v[26:29]
	v_mfma_f32_16x16x32_bf16 v[22:25], v[148:151], v[192:195], v[22:25]
	v_mfma_f32_16x16x32_bf16 v[18:21], v[168:171], v[192:195], v[18:21]
	v_mfma_f32_16x16x32_bf16 v[14:17], v[148:151], v[200:203], v[14:17]
	v_mfma_f32_16x16x32_bf16 v[10:13], v[168:171], v[200:203], v[10:13]
	v_mfma_f32_16x16x32_bf16 v[6:9], v[148:151], v[208:211], v[6:9]
	v_mfma_f32_16x16x32_bf16 v[2:5], v[168:171], v[208:211], v[2:5]
	v_mfma_f32_16x16x32_bf16 v[30:33], v[152:155], v[188:191], v[30:33]
	v_mfma_f32_16x16x32_bf16 v[26:29], v[172:175], v[188:191], v[26:29]
	v_mfma_f32_16x16x32_bf16 v[22:25], v[152:155], v[196:199], v[22:25]
	v_mfma_f32_16x16x32_bf16 v[18:21], v[172:175], v[196:199], v[18:21]
	v_mfma_f32_16x16x32_bf16 v[14:17], v[152:155], v[204:207], v[14:17]
	v_mfma_f32_16x16x32_bf16 v[10:13], v[172:175], v[204:207], v[10:13]
	v_mfma_f32_16x16x32_bf16 v[6:9], v[152:155], v[220:223], v[6:9]
	v_mfma_f32_16x16x32_bf16 v[2:5], v[172:175], v[220:223], v[2:5]
	s_barrier
	s_setprio 0
	s_setprio 1
	s_setprio 0
	s_waitcnt lgkmcnt(0)
	s_add_i32 s54, 0, 0x18000
	v_add_u32_e32 v0, s54, v181
	s_add_i32 s55, 0, 0x1c000
	ds_read_b128 v[132:135], v0
	ds_read_b128 v[136:139], v0 offset:1024
	ds_read_b128 v[140:143], v0 offset:2048
	ds_read_b128 v[144:147], v0 offset:3072
	v_add_u32_e32 v0, s55, v181
	ds_read_b128 v[148:151], v0
	ds_read_b128 v[152:155], v0 offset:1024
	ds_read_b128 v[168:171], v0 offset:2048
	ds_read_b128 v[172:175], v0 offset:3072
	s_add_u32 s52, s52, 0x80000
	s_addc_u32 s53, s53, 0
	s_mov_b32 m0, s66
	v_lshl_add_u64 v[232:233], s[52:53], 0, v[156:157]
	ds_read_b128 v[176:179], v187 offset:32768
	ds_read_b128 v[188:191], v187 offset:33792
	ds_read_b128 v[192:195], v187 offset:34816
	ds_read_b128 v[196:199], v187 offset:35840
	ds_read_b128 v[200:203], v187 offset:36864
	ds_read_b128 v[204:207], v187 offset:37888
	ds_read_b128 v[208:211], v187 offset:38912
	ds_read_b128 v[220:223], v187 offset:39936
	global_load_lds_dwordx4 v[232:233], off
	v_lshl_add_u64 v[232:233], s[52:53], 0, v[160:161]
	s_mov_b32 m0, s67
	s_nop 0
	global_load_lds_dwordx4 v[232:233], off
	s_setprio 1
	s_nop 0
	s_waitcnt vmcnt(8) lgkmcnt(0)
	s_barrier
	v_mfma_f32_16x16x32_bf16 v[128:131], v[132:135], v[176:179], v[128:131]
	v_mfma_f32_16x16x32_bf16 v[124:127], v[140:143], v[176:179], v[124:127]
	v_mfma_f32_16x16x32_bf16 v[120:123], v[132:135], v[192:195], v[120:123]
	v_mfma_f32_16x16x32_bf16 v[116:119], v[140:143], v[192:195], v[116:119]
	v_mfma_f32_16x16x32_bf16 v[112:115], v[132:135], v[200:203], v[112:115]
	v_mfma_f32_16x16x32_bf16 v[108:111], v[140:143], v[200:203], v[108:111]
	v_mfma_f32_16x16x32_bf16 v[104:107], v[132:135], v[208:211], v[104:107]
	v_mfma_f32_16x16x32_bf16 v[100:103], v[140:143], v[208:211], v[100:103]
	v_mfma_f32_16x16x32_bf16 v[128:131], v[136:139], v[188:191], v[128:131]
	v_mfma_f32_16x16x32_bf16 v[124:127], v[144:147], v[188:191], v[124:127]
	v_mfma_f32_16x16x32_bf16 v[120:123], v[136:139], v[196:199], v[120:123]
	v_mfma_f32_16x16x32_bf16 v[116:119], v[144:147], v[196:199], v[116:119]
	v_mfma_f32_16x16x32_bf16 v[112:115], v[136:139], v[204:207], v[112:115]
	v_mfma_f32_16x16x32_bf16 v[108:111], v[144:147], v[204:207], v[108:111]
	v_mfma_f32_16x16x32_bf16 v[104:107], v[136:139], v[220:223], v[104:107]
	v_mfma_f32_16x16x32_bf16 v[100:103], v[144:147], v[220:223], v[100:103]
	v_mfma_f32_16x16x32_bf16 v[96:99], v[148:151], v[176:179], v[96:99]
	v_mfma_f32_16x16x32_bf16 v[92:95], v[168:171], v[176:179], v[92:95]
	v_mfma_f32_16x16x32_bf16 v[88:91], v[148:151], v[192:195], v[88:91]
	v_mfma_f32_16x16x32_bf16 v[84:87], v[168:171], v[192:195], v[84:87]
	v_mfma_f32_16x16x32_bf16 v[80:83], v[148:151], v[200:203], v[80:83]
	v_mfma_f32_16x16x32_bf16 v[76:79], v[168:171], v[200:203], v[76:79]
	v_mfma_f32_16x16x32_bf16 v[72:75], v[148:151], v[208:211], v[72:75]
	v_mfma_f32_16x16x32_bf16 v[68:71], v[168:171], v[208:211], v[68:71]
	v_mfma_f32_16x16x32_bf16 v[96:99], v[152:155], v[188:191], v[96:99]
	v_mfma_f32_16x16x32_bf16 v[92:95], v[172:175], v[188:191], v[92:95]
	v_mfma_f32_16x16x32_bf16 v[88:91], v[152:155], v[196:199], v[88:91]
	v_mfma_f32_16x16x32_bf16 v[84:87], v[172:175], v[196:199], v[84:87]
	v_mfma_f32_16x16x32_bf16 v[80:83], v[152:155], v[204:207], v[80:83]
	v_mfma_f32_16x16x32_bf16 v[76:79], v[172:175], v[204:207], v[76:79]
	v_mfma_f32_16x16x32_bf16 v[72:75], v[152:155], v[220:223], v[72:75]
	v_mfma_f32_16x16x32_bf16 v[68:71], v[172:175], v[220:223], v[68:71]
	s_barrier
; #define PG8_STAGE(bufoff, gbase, voff) do { _Pragma("unroll") for (int _i = 0; _i < 2; ++_i) \
;         __builtin_amdgcn_global_load_lds((const unsigned*)((const char*)(gbase) + (voff)[_i]), (PG8_LAS unsigned*)(lds + (bufoff) + ldsw + _i * 8192), 16, 0, 0); } while (0)
; #define PG8_LDA(dst, b, h) do { _Pragma("unroll") for (int m = 0; m < 4; ++m) _Pragma("unroll") for (int k = 0; k < 2; ++k) dst[m][k] = *(const PG8_LAS bf16x8*)(lds + PG8_SA(b, h) + aoff + m * 2048 + k * 1024); } while (0)
; #define PG8_MMA(ai, bj, At, Bt) do { __builtin_amdgcn_s_setprio(1); _Pragma("unroll") for (int m = 0; m < 4; ++m) _Pragma("unroll") for (int n = 0; n < 2; ++n) _Pragma("unroll") for (int k = 0; k < 2; ++k) \
;         acc[ai][bj][m][n] = __builtin_amdgcn_mfma_f32_16x16x32_bf16(Bt[n][k], At[m][k], acc[ai][bj][m][n], 0, 0, 0); __builtin_amdgcn_s_setprio(0); } while (0)
; #define PG8_WAIT_V(n) asm volatile("s_waitcnt vmcnt(" #n ")" ::: "memory")
; #define PG8_WAIT_L(n) asm volatile("s_waitcnt lgkmcnt(" #n ")" ::: "memory")
; #define PG8_BAR __builtin_amdgcn_s_barrier()
; #define PG8_SCHED __builtin_amdgcn_sched_barrier(0)
; template <class Epi, class Sched, bool ALIGN_EPI = false, bool SP2 = false>
; __device__ __forceinline__ void gemm_phase(PG8_LAS unsigned char* lds, const Gemm g, const Sched& S, const Epi& E) {
;     ...
;             PG8_LDA(At, 1, 1); PG8_STAGE(PG8_SB(1, 0), b3, voffB); PG8_STAGE(PG8_SB(1, 1), b3 + hstep, voffB); PG8_STAGE(PG8_SA(1, 0), a3, voffA);
;             PG8_WAIT_V(8); PG8_WAIT_L(0); PG8_BAR; PG8_MMA(1, 0, At, B0); PG8_MMA(1, 1, At, B1); PG8_BAR; PG8_SCHED;
	s_setprio 0
	s_setprio 1
	s_setprio 0
	s_waitcnt lgkmcnt(0)
	s_add_i32 s52, s54, s15
	v_lshl_add_u64 v[224:225], v[224:225], 0, s[88:89]
	s_mov_b32 m0, s52
	ds_read_b128 v[176:179], v187 offset:49152
	ds_read_b128 v[188:191], v187 offset:50176
	ds_read_b128 v[192:195], v187 offset:51200
	ds_read_b128 v[196:199], v187 offset:52224
	ds_read_b128 v[200:203], v187 offset:53248
	ds_read_b128 v[204:207], v187 offset:54272
	ds_read_b128 v[208:211], v187 offset:55296
	ds_read_b128 v[220:223], v187 offset:56320
	global_load_lds_dwordx4 v[224:225], off
	s_add_i32 m0, s52, 0x2000
	s_add_u32 s12, s12, 0x80080
	v_lshl_add_u64 v[224:225], v[226:227], 0, s[88:89]
	s_addc_u32 s13, s13, 0
	s_add_i32 s52, s55, s15
	global_load_lds_dwordx4 v[224:225], off
	v_lshl_add_u64 v[224:225], s[12:13], 0, v[158:159]
	s_mov_b32 m0, s52
	s_nop 0
	global_load_lds_dwordx4 v[224:225], off
	v_lshl_add_u64 v[224:225], s[12:13], 0, v[162:163]
	s_add_i32 m0, s52, 0x2000
	s_nop 0
	global_load_lds_dwordx4 v[224:225], off
	v_lshl_add_u64 v[224:225], v[228:229], 0, s[88:89]
	s_mov_b32 m0, s69
	s_nop 0
	global_load_lds_dwordx4 v[224:225], off
	v_lshl_add_u64 v[224:225], v[230:231], 0, s[88:89]
	s_mov_b32 m0, s70
	s_nop 0
	global_load_lds_dwordx4 v[224:225], off
	s_setprio 1
	s_nop 0
	s_waitcnt vmcnt(8) lgkmcnt(0)
	s_barrier
	v_mfma_f32_16x16x32_bf16 v[62:65], v[132:135], v[176:179], v[62:65]
	v_mfma_f32_16x16x32_bf16 v[58:61], v[140:143], v[176:179], v[58:61]
	v_mfma_f32_16x16x32_bf16 v[54:57], v[132:135], v[192:195], v[54:57]
	v_mfma_f32_16x16x32_bf16 v[50:53], v[140:143], v[192:195], v[50:53]
	v_mfma_f32_16x16x32_bf16 v[46:49], v[132:135], v[200:203], v[46:49]
	v_mfma_f32_16x16x32_bf16 v[42:45], v[140:143], v[200:203], v[42:45]
	v_mfma_f32_16x16x32_bf16 v[38:41], v[132:135], v[208:211], v[38:41]
	v_mfma_f32_16x16x32_bf16 v[34:37], v[140:143], v[208:211], v[34:37]
	v_mfma_f32_16x16x32_bf16 v[62:65], v[136:139], v[188:191], v[62:65]
	v_mfma_f32_16x16x32_bf16 v[58:61], v[144:147], v[188:191], v[58:61]
	v_mfma_f32_16x16x32_bf16 v[54:57], v[136:139], v[196:199], v[54:57]
	v_mfma_f32_16x16x32_bf16 v[50:53], v[144:147], v[196:199], v[50:53]
	v_mfma_f32_16x16x32_bf16 v[46:49], v[136:139], v[204:207], v[46:49]
	v_mfma_f32_16x16x32_bf16 v[42:45], v[144:147], v[204:207], v[42:45]
	v_mfma_f32_16x16x32_bf16 v[38:41], v[136:139], v[220:223], v[38:41]
	v_mfma_f32_16x16x32_bf16 v[34:37], v[144:147], v[220:223], v[34:37]
	v_mfma_f32_16x16x32_bf16 v[30:33], v[148:151], v[176:179], v[30:33]
	v_mfma_f32_16x16x32_bf16 v[26:29], v[168:171], v[176:179], v[26:29]
	v_mfma_f32_16x16x32_bf16 v[22:25], v[148:151], v[192:195], v[22:25]
	v_mfma_f32_16x16x32_bf16 v[18:21], v[168:171], v[192:195], v[18:21]
	v_mfma_f32_16x16x32_bf16 v[14:17], v[148:151], v[200:203], v[14:17]
	v_mfma_f32_16x16x32_bf16 v[10:13], v[168:171], v[200:203], v[10:13]
	v_mfma_f32_16x16x32_bf16 v[6:9], v[148:151], v[208:211], v[6:9]
	v_mfma_f32_16x16x32_bf16 v[2:5], v[168:171], v[208:211], v[2:5]
	v_mfma_f32_16x16x32_bf16 v[30:33], v[152:155], v[188:191], v[30:33]
	v_mfma_f32_16x16x32_bf16 v[26:29], v[172:175], v[188:191], v[26:29]
	v_mfma_f32_16x16x32_bf16 v[22:25], v[152:155], v[196:199], v[22:25]
	v_mfma_f32_16x16x32_bf16 v[18:21], v[172:175], v[196:199], v[18:21]
	v_mfma_f32_16x16x32_bf16 v[14:17], v[152:155], v[204:207], v[14:17]
	v_mfma_f32_16x16x32_bf16 v[10:13], v[172:175], v[204:207], v[10:13]
	v_mfma_f32_16x16x32_bf16 v[6:9], v[152:155], v[220:223], v[6:9]
	v_mfma_f32_16x16x32_bf16 v[2:5], v[172:175], v[220:223], v[2:5]
	s_barrier
	s_setprio 0
	s_setprio 1
	s_setprio 0
	s_waitcnt lgkmcnt(0)
	s_add_i32 s12, s43, 2
	s_cmp_gt_u32 s43, 29
	s_cbranch_scc1 .LBB0_400
	s_mov_b32 s43, s12
	s_branch .LBB0_384

; #define PG8_STAGE(bufoff, gbase, voff) do { _Pragma("unroll") for (int _i = 0; _i < 2; ++_i) \
;         __builtin_amdgcn_global_load_lds((const unsigned*)((const char*)(gbase) + (voff)[_i]), (PG8_LAS unsigned*)(lds + (bufoff) + ldsw + _i * 8192), 16, 0, 0); } while (0)
; #define PG8_LDA(dst, b, h) do { _Pragma("unroll") for (int m = 0; m < 4; ++m) _Pragma("unroll") for (int k = 0; k < 2; ++k) dst[m][k] = *(const PG8_LAS bf16x8*)(lds + PG8_SA(b, h) + aoff + m * 2048 + k * 1024); } while (0)
; #define PG8_LDB(dst, b, h) do { _Pragma("unroll") for (int n = 0; n < 2; ++n) _Pragma("unroll") for (int k = 0; k < 2; ++k) dst[n][k] = *(const PG8_LAS bf16x8*)(lds + PG8_SB(b, h) + boff + n * 2048 + k * 1024); } while (0)
; #define PG8_MMA(ai, bj, At, Bt) do { __builtin_amdgcn_s_setprio(1); _Pragma("unroll") for (int m = 0; m < 4; ++m) _Pragma("unroll") for (int n = 0; n < 2; ++n) _Pragma("unroll") for (int k = 0; k < 2; ++k) \
;         acc[ai][bj][m][n] = __builtin_amdgcn_mfma_f32_16x16x32_bf16(Bt[n][k], At[m][k], acc[ai][bj][m][n], 0, 0, 0); __builtin_amdgcn_s_setprio(0); } while (0)
; #define PG8_WAIT_V(n) asm volatile("s_waitcnt vmcnt(" #n ")" ::: "memory")
; #define PG8_BAR __builtin_amdgcn_s_barrier()
; template <class Epi, class Sched, bool ALIGN_EPI = false, bool SP2 = false>
; __device__ __forceinline__ void gemm_phase(PG8_LAS unsigned char* lds, const Gemm g, const Sched& S, const Epi& E) {
;     ...
;         for (int t = 0; t < nt; t += 2) {
;             const bool last = (t == nt - 2);
;             const char* a1 = cA + (size_t)(t + 1) * kstep;
;             const char* a2 = last ? nA : cA + (size_t)(t + 2) * kstep; const char* b2 = last ? nB : cB + (size_t)(t + 2) * kstep;
;             const char* a3 = a2 + kstep; const char* b3 = b2 + kstep;
;             if (last && has_next) S.a_ready(nxt);
;             if constexpr (SP2) {
;             PG8_LDB(B0, 0, 0); PG8_LDB(B1, 0, 1); PG8_SCHED; PG8_LDA(At, 0, 0); PG8_STAGE(PG8_SA(1, 1), a1 + hstep, voffA);
;             PG8_WAIT_V(8); PG8_WAIT_L(0); PG8_BAR; PG8_MMA(0, 0, At, B0); PG8_MMA(0, 1, At, B1); PG8_BAR; PG8_SCHED;
;             PG8_LDA(At, 0, 1); PG8_STAGE(PG8_SB(0, 0), b2, voffB); PG8_STAGE(PG8_SB(0, 1), b2 + hstep, voffB); PG8_STAGE(PG8_SA(0, 0), a2, voffA);
;             PG8_WAIT_V(8); PG8_WAIT_L(0); PG8_BAR; PG8_MMA(1, 0, At, B0); PG8_MMA(1, 1, At, B1); PG8_BAR; PG8_SCHED;
.LBB0_702:
	s_add_u32 s14, s26, s12
	s_addc_u32 s15, s27, s13
	s_add_u32 s14, s14, 0x5800100
	s_addc_u32 s15, s15, 0
	s_add_u32 s31, s28, s12
	s_addc_u32 s34, s29, s13
	s_add_i32 s35, 0, 0x10000
	s_cmpk_eq_i32 s12, 0xf00
	s_cselect_b32 s17, s9, s15
	s_cselect_b32 s16, s8, s14
	v_add_u32_e32 v89, s35, v87
	s_cselect_b32 s15, s7, s34
	s_cselect_b32 s14, s6, s31
	s_add_i32 s31, 0, 0x14000
	ds_read_b128 v[148:151], v89
	ds_read_b128 v[152:155], v89 offset:1024
	ds_read_b128 v[156:159], v89 offset:2048
	ds_read_b128 v[160:163], v89 offset:3072
	v_add_u32_e32 v89, s31, v87
	ds_read_b128 v[166:169], v89
	ds_read_b128 v[170:173], v89 offset:1024
	ds_read_b128 v[174:177], v89 offset:2048
	ds_read_b128 v[178:181], v89 offset:3072
	v_lshl_add_u64 v[90:91], v[74:75], 0, s[12:13]
	s_add_i32 m0, s20, 0xc000
	ds_read_b128 v[182:185], v88
	ds_read_b128 v[186:189], v88 offset:1024
	ds_read_b128 v[190:193], v88 offset:2048
	ds_read_b128 v[194:197], v88 offset:3072
	ds_read_b128 v[200:203], v88 offset:4096
	ds_read_b128 v[204:207], v88 offset:5120
	ds_read_b128 v[208:211], v88 offset:6144
	ds_read_b128 v[220:223], v88 offset:7168
	global_load_lds_dwordx4 v[90:91], off
	v_lshl_add_u64 v[90:91], v[84:85], 0, s[12:13]
	s_add_i32 m0, s20, 0xe000
	s_nop 0
	global_load_lds_dwordx4 v[90:91], off
	s_setprio 1
	s_nop 0
	s_waitcnt vmcnt(8) lgkmcnt(0)
	s_barrier
	v_mfma_f32_16x16x32_bf16 v[144:147], v[148:151], v[182:185], v[144:147]
	v_mfma_f32_16x16x32_bf16 v[140:143], v[156:159], v[182:185], v[140:143]
	v_mfma_f32_16x16x32_bf16 v[128:131], v[148:151], v[190:193], v[128:131]
	v_mfma_f32_16x16x32_bf16 v[124:127], v[156:159], v[190:193], v[124:127]
	v_mfma_f32_16x16x32_bf16 v[112:115], v[148:151], v[200:203], v[112:115]
	v_mfma_f32_16x16x32_bf16 v[108:111], v[156:159], v[200:203], v[108:111]
	v_mfma_f32_16x16x32_bf16 v[96:99], v[148:151], v[208:211], v[96:99]
	v_mfma_f32_16x16x32_bf16 v[90:93], v[156:159], v[208:211], v[92:95]
	v_mfma_f32_16x16x32_bf16 v[144:147], v[152:155], v[186:189], v[144:147]
	v_mfma_f32_16x16x32_bf16 v[140:143], v[160:163], v[186:189], v[140:143]
	v_mfma_f32_16x16x32_bf16 v[128:131], v[152:155], v[194:197], v[128:131]
	v_mfma_f32_16x16x32_bf16 v[124:127], v[160:163], v[194:197], v[124:127]
	v_mfma_f32_16x16x32_bf16 v[112:115], v[152:155], v[204:207], v[112:115]
	v_mfma_f32_16x16x32_bf16 v[108:111], v[160:163], v[204:207], v[108:111]
	v_mfma_f32_16x16x32_bf16 v[96:99], v[152:155], v[220:223], v[96:99]
	v_mfma_f32_16x16x32_bf16 v[90:93], v[160:163], v[220:223], v[90:93]
	v_mfma_f32_16x16x32_bf16 v[136:139], v[166:169], v[182:185], v[136:139]
	v_mfma_f32_16x16x32_bf16 v[132:135], v[174:177], v[182:185], v[132:135]
	v_mfma_f32_16x16x32_bf16 v[120:123], v[166:169], v[190:193], v[120:123]
	v_mfma_f32_16x16x32_bf16 v[116:119], v[174:177], v[190:193], v[116:119]
	v_mfma_f32_16x16x32_bf16 v[104:107], v[166:169], v[200:203], v[104:107]
	v_mfma_f32_16x16x32_bf16 v[100:103], v[174:177], v[200:203], v[100:103]
	v_mfma_f32_16x16x32_bf16 v[80:83], v[166:169], v[208:211], v[80:83]
	v_mfma_f32_16x16x32_bf16 v[76:79], v[174:177], v[208:211], v[76:79]
	v_mfma_f32_16x16x32_bf16 v[136:139], v[170:173], v[186:189], v[136:139]
	v_mfma_f32_16x16x32_bf16 v[132:135], v[178:181], v[186:189], v[132:135]
	v_mfma_f32_16x16x32_bf16 v[120:123], v[170:173], v[194:197], v[120:123]
	v_mfma_f32_16x16x32_bf16 v[116:119], v[178:181], v[194:197], v[116:119]
	v_mfma_f32_16x16x32_bf16 v[104:107], v[170:173], v[204:207], v[104:107]
	v_mfma_f32_16x16x32_bf16 v[100:103], v[178:181], v[204:207], v[100:103]
	v_mfma_f32_16x16x32_bf16 v[80:83], v[170:173], v[220:223], v[80:83]
	v_mfma_f32_16x16x32_bf16 v[76:79], v[178:181], v[220:223], v[76:79]
	s_barrier
	s_setprio 0
	s_setprio 1
	s_setprio 0
	s_waitcnt lgkmcnt(0)
	s_add_i32 s34, s35, s18
	v_lshl_add_u64 v[224:225], s[14:15], 0, v[66:67]
	s_mov_b32 m0, s34
	ds_read_b128 v[182:185], v88 offset:16384
	ds_read_b128 v[186:189], v88 offset:17408
	ds_read_b128 v[190:193], v88 offset:18432
	ds_read_b128 v[194:197], v88 offset:19456
	ds_read_b128 v[200:203], v88 offset:20480
	ds_read_b128 v[204:207], v88 offset:21504
	ds_read_b128 v[208:211], v88 offset:22528
	ds_read_b128 v[220:223], v88 offset:23552
	global_load_lds_dwordx4 v[224:225], off
	s_add_i32 m0, s34, 0x2000
	s_add_u32 s34, s14, 0x80000
	v_lshl_add_u64 v[226:227], s[14:15], 0, v[72:73]
	s_addc_u32 s35, s15, 0
	s_add_i32 s31, s31, s18
	global_load_lds_dwordx4 v[226:227], off
	v_lshl_add_u64 v[94:95], s[34:35], 0, v[66:67]
	s_mov_b32 m0, s31
	v_lshl_add_u64 v[228:229], s[16:17], 0, v[68:69]
	global_load_lds_dwordx4 v[94:95], off
	v_lshl_add_u64 v[94:95], s[34:35], 0, v[72:73]
	s_add_i32 m0, s31, 0x2000
	v_lshl_add_u64 v[230:231], s[16:17], 0, v[70:71]
	global_load_lds_dwordx4 v[94:95], off
	s_mov_b32 m0, s20
	s_nop 0
	global_load_lds_dwordx4 v[228:229], off
	s_mov_b32 m0, s3
	s_nop 0
	global_load_lds_dwordx4 v[230:231], off
	s_setprio 1
	s_nop 0
	s_waitcnt vmcnt(8) lgkmcnt(0)
	s_barrier
; #define PG8_STAGE(bufoff, gbase, voff) do { _Pragma("unroll") for (int _i = 0; _i < 2; ++_i) \
;         __builtin_amdgcn_global_load_lds((const unsigned*)((const char*)(gbase) + (voff)[_i]), (PG8_LAS unsigned*)(lds + (bufoff) + ldsw + _i * 8192), 16, 0, 0); } while (0)
; #define PG8_LDA(dst, b, h) do { _Pragma("unroll") for (int m = 0; m < 4; ++m) _Pragma("unroll") for (int k = 0; k < 2; ++k) dst[m][k] = *(const PG8_LAS bf16x8*)(lds + PG8_SA(b, h) + aoff + m * 2048 + k * 1024); } while (0)
; #define PG8_LDB(dst, b, h) do { _Pragma("unroll") for (int n = 0; n < 2; ++n) _Pragma("unroll") for (int k = 0; k < 2; ++k) dst[n][k] = *(const PG8_LAS bf16x8*)(lds + PG8_SB(b, h) + boff + n * 2048 + k * 1024); } while (0)
; #define PG8_MMA(ai, bj, At, Bt) do { __builtin_amdgcn_s_setprio(1); _Pragma("unroll") for (int m = 0; m < 4; ++m) _Pragma("unroll") for (int n = 0; n < 2; ++n) _Pragma("unroll") for (int k = 0; k < 2; ++k) \
;         acc[ai][bj][m][n] = __builtin_amdgcn_mfma_f32_16x16x32_bf16(Bt[n][k], At[m][k], acc[ai][bj][m][n], 0, 0, 0); __builtin_amdgcn_s_setprio(0); } while (0)
; #define PG8_WAIT_V(n) asm volatile("s_waitcnt vmcnt(" #n ")" ::: "memory")
; template <class Epi, class Sched, bool ALIGN_EPI = false, bool SP2 = false>
; __device__ __forceinline__ void gemm_phase(PG8_LAS unsigned char* lds, const Gemm g, const Sched& S, const Epi& E) {
;     ...
;             PG8_LDB(B0, 0, 0); PG8_LDB(B1, 0, 1); PG8_SCHED; PG8_LDA(At, 0, 0); PG8_STAGE(PG8_SA(1, 1), a1 + hstep, voffA);
;             PG8_WAIT_V(8); PG8_WAIT_L(0); PG8_BAR; PG8_MMA(0, 0, At, B0); PG8_MMA(0, 1, At, B1); PG8_BAR; PG8_SCHED;
;             PG8_LDA(At, 0, 1); PG8_STAGE(PG8_SB(0, 0), b2, voffB); PG8_STAGE(PG8_SB(0, 1), b2 + hstep, voffB); PG8_STAGE(PG8_SA(0, 0), a2, voffA);
;             PG8_WAIT_V(8); PG8_WAIT_L(0); PG8_BAR; PG8_MMA(1, 0, At, B0); PG8_MMA(1, 1, At, B1); PG8_BAR; PG8_SCHED;
;             PG8_LDB(B0, 1, 0); PG8_LDB(B1, 1, 1); PG8_SCHED; PG8_LDA(At, 1, 0); PG8_STAGE(PG8_SA(0, 1), a2 + hstep, voffA);
;             PG8_WAIT_V(8); PG8_WAIT_L(0); PG8_BAR; PG8_MMA(0, 0, At, B0); PG8_MMA(0, 1, At, B1); PG8_BAR; PG8_SCHED;
;             PG8_LDA(At, 1, 1); PG8_STAGE(PG8_SB(1, 0), b3, voffB); PG8_STAGE(PG8_SB(1, 1), b3 + hstep, voffB); PG8_STAGE(PG8_SA(1, 0), a3, voffA);
;             PG8_WAIT_V(8); PG8_WAIT_L(0); PG8_BAR; PG8_MMA(1, 0, At, B0); PG8_MMA(1, 1, At, B1); PG8_BAR; PG8_SCHED;
	v_mfma_f32_16x16x32_bf16 v[62:65], v[148:151], v[182:185], v[62:65]
	v_mfma_f32_16x16x32_bf16 v[58:61], v[156:159], v[182:185], v[58:61]
	v_mfma_f32_16x16x32_bf16 v[46:49], v[148:151], v[190:193], v[46:49]
	v_mfma_f32_16x16x32_bf16 v[42:45], v[156:159], v[190:193], v[42:45]
	v_mfma_f32_16x16x32_bf16 v[30:33], v[148:151], v[200:203], v[30:33]
	v_mfma_f32_16x16x32_bf16 v[26:29], v[156:159], v[200:203], v[26:29]
	v_mfma_f32_16x16x32_bf16 v[14:17], v[148:151], v[208:211], v[14:17]
	v_mfma_f32_16x16x32_bf16 v[10:13], v[156:159], v[208:211], v[10:13]
	v_mfma_f32_16x16x32_bf16 v[62:65], v[152:155], v[186:189], v[62:65]
	v_mfma_f32_16x16x32_bf16 v[58:61], v[160:163], v[186:189], v[58:61]
	v_mfma_f32_16x16x32_bf16 v[46:49], v[152:155], v[194:197], v[46:49]
	v_mfma_f32_16x16x32_bf16 v[42:45], v[160:163], v[194:197], v[42:45]
	v_mfma_f32_16x16x32_bf16 v[30:33], v[152:155], v[204:207], v[30:33]
	v_mfma_f32_16x16x32_bf16 v[26:29], v[160:163], v[204:207], v[26:29]
	v_mfma_f32_16x16x32_bf16 v[14:17], v[152:155], v[220:223], v[14:17]
	v_mfma_f32_16x16x32_bf16 v[10:13], v[160:163], v[220:223], v[10:13]
	v_mfma_f32_16x16x32_bf16 v[54:57], v[166:169], v[182:185], v[54:57]
	v_mfma_f32_16x16x32_bf16 v[50:53], v[174:177], v[182:185], v[50:53]
	v_mfma_f32_16x16x32_bf16 v[38:41], v[166:169], v[190:193], v[38:41]
	v_mfma_f32_16x16x32_bf16 v[34:37], v[174:177], v[190:193], v[34:37]
	v_mfma_f32_16x16x32_bf16 v[22:25], v[166:169], v[200:203], v[22:25]
	v_mfma_f32_16x16x32_bf16 v[18:21], v[174:177], v[200:203], v[18:21]
	v_mfma_f32_16x16x32_bf16 v[6:9], v[166:169], v[208:211], v[6:9]
	v_mfma_f32_16x16x32_bf16 v[2:5], v[174:177], v[208:211], v[2:5]
	v_mfma_f32_16x16x32_bf16 v[54:57], v[170:173], v[186:189], v[54:57]
	v_mfma_f32_16x16x32_bf16 v[50:53], v[178:181], v[186:189], v[50:53]
	v_mfma_f32_16x16x32_bf16 v[38:41], v[170:173], v[194:197], v[38:41]
	v_mfma_f32_16x16x32_bf16 v[34:37], v[178:181], v[194:197], v[34:37]
	v_mfma_f32_16x16x32_bf16 v[22:25], v[170:173], v[204:207], v[22:25]
	v_mfma_f32_16x16x32_bf16 v[18:21], v[178:181], v[204:207], v[18:21]
	v_mfma_f32_16x16x32_bf16 v[6:9], v[170:173], v[220:223], v[6:9]
	v_mfma_f32_16x16x32_bf16 v[2:5], v[178:181], v[220:223], v[2:5]
	s_barrier
	s_setprio 0
	s_setprio 1
	s_setprio 0
	s_waitcnt lgkmcnt(0)
	s_add_i32 s31, 0, 0x18000
	v_add_u32_e32 v89, s31, v87
	s_add_i32 s34, 0, 0x1c000
	ds_read_b128 v[148:151], v89
	ds_read_b128 v[152:155], v89 offset:1024
	ds_read_b128 v[156:159], v89 offset:2048
	ds_read_b128 v[160:163], v89 offset:3072
	v_add_u32_e32 v89, s34, v87
	ds_read_b128 v[166:169], v89
	ds_read_b128 v[170:173], v89 offset:1024
	ds_read_b128 v[174:177], v89 offset:2048
	ds_read_b128 v[178:181], v89 offset:3072
	s_add_u32 s16, s16, 0x80000
	s_addc_u32 s17, s17, 0
	s_mov_b32 m0, s21
	v_lshl_add_u64 v[94:95], s[16:17], 0, v[68:69]
	ds_read_b128 v[182:185], v88 offset:32768
	ds_read_b128 v[186:189], v88 offset:33792
	ds_read_b128 v[190:193], v88 offset:34816
	ds_read_b128 v[194:197], v88 offset:35840
	ds_read_b128 v[200:203], v88 offset:36864
	ds_read_b128 v[204:207], v88 offset:37888
	ds_read_b128 v[208:211], v88 offset:38912
	ds_read_b128 v[220:223], v88 offset:39936
	global_load_lds_dwordx4 v[94:95], off
	v_lshl_add_u64 v[94:95], s[16:17], 0, v[70:71]
	s_mov_b32 m0, s22
	s_nop 0
	global_load_lds_dwordx4 v[94:95], off
	s_setprio 1
	s_nop 0
	s_waitcnt vmcnt(8) lgkmcnt(0)
	s_barrier
	v_mfma_f32_16x16x32_bf16 v[144:147], v[148:151], v[182:185], v[144:147]
	v_mfma_f32_16x16x32_bf16 v[140:143], v[156:159], v[182:185], v[140:143]
	v_mfma_f32_16x16x32_bf16 v[128:131], v[148:151], v[190:193], v[128:131]
	v_mfma_f32_16x16x32_bf16 v[124:127], v[156:159], v[190:193], v[124:127]
	v_mfma_f32_16x16x32_bf16 v[112:115], v[148:151], v[200:203], v[112:115]
	v_mfma_f32_16x16x32_bf16 v[108:111], v[156:159], v[200:203], v[108:111]
	v_mfma_f32_16x16x32_bf16 v[94:97], v[148:151], v[208:211], v[96:99]
	v_mfma_f32_16x16x32_bf16 v[90:93], v[156:159], v[208:211], v[90:93]
	v_mfma_f32_16x16x32_bf16 v[144:147], v[152:155], v[186:189], v[144:147]
	v_mfma_f32_16x16x32_bf16 v[140:143], v[160:163], v[186:189], v[140:143]
	v_mfma_f32_16x16x32_bf16 v[128:131], v[152:155], v[194:197], v[128:131]
	v_mfma_f32_16x16x32_bf16 v[124:127], v[160:163], v[194:197], v[124:127]
	v_mfma_f32_16x16x32_bf16 v[112:115], v[152:155], v[204:207], v[112:115]
	v_mfma_f32_16x16x32_bf16 v[108:111], v[160:163], v[204:207], v[108:111]
	v_mfma_f32_16x16x32_bf16 v[96:99], v[152:155], v[220:223], v[94:97]
	v_mfma_f32_16x16x32_bf16 v[92:95], v[160:163], v[220:223], v[90:93]
	v_mfma_f32_16x16x32_bf16 v[136:139], v[166:169], v[182:185], v[136:139]
	v_mfma_f32_16x16x32_bf16 v[132:135], v[174:177], v[182:185], v[132:135]
	v_mfma_f32_16x16x32_bf16 v[120:123], v[166:169], v[190:193], v[120:123]
	v_mfma_f32_16x16x32_bf16 v[116:119], v[174:177], v[190:193], v[116:119]
	v_mfma_f32_16x16x32_bf16 v[104:107], v[166:169], v[200:203], v[104:107]
	v_mfma_f32_16x16x32_bf16 v[100:103], v[174:177], v[200:203], v[100:103]
	v_mfma_f32_16x16x32_bf16 v[80:83], v[166:169], v[208:211], v[80:83]
	v_mfma_f32_16x16x32_bf16 v[76:79], v[174:177], v[208:211], v[76:79]
	v_mfma_f32_16x16x32_bf16 v[136:139], v[170:173], v[186:189], v[136:139]
	v_mfma_f32_16x16x32_bf16 v[132:135], v[178:181], v[186:189], v[132:135]
	v_mfma_f32_16x16x32_bf16 v[120:123], v[170:173], v[194:197], v[120:123]
	v_mfma_f32_16x16x32_bf16 v[116:119], v[178:181], v[194:197], v[116:119]
	v_mfma_f32_16x16x32_bf16 v[104:107], v[170:173], v[204:207], v[104:107]
	v_mfma_f32_16x16x32_bf16 v[100:103], v[178:181], v[204:207], v[100:103]
	v_mfma_f32_16x16x32_bf16 v[80:83], v[170:173], v[220:223], v[80:83]
	v_mfma_f32_16x16x32_bf16 v[76:79], v[178:181], v[220:223], v[76:79]
	s_barrier
; #define PG8_STAGE(bufoff, gbase, voff) do { _Pragma("unroll") for (int _i = 0; _i < 2; ++_i) \
;         __builtin_amdgcn_global_load_lds((const unsigned*)((const char*)(gbase) + (voff)[_i]), (PG8_LAS unsigned*)(lds + (bufoff) + ldsw + _i * 8192), 16, 0, 0); } while (0)
; #define PG8_LDA(dst, b, h) do { _Pragma("unroll") for (int m = 0; m < 4; ++m) _Pragma("unroll") for (int k = 0; k < 2; ++k) dst[m][k] = *(const PG8_LAS bf16x8*)(lds + PG8_SA(b, h) + aoff + m * 2048 + k * 1024); } while (0)
; #define PG8_MMA(ai, bj, At, Bt) do { __builtin_amdgcn_s_setprio(1); _Pragma("unroll") for (int m = 0; m < 4; ++m) _Pragma("unroll") for (int n = 0; n < 2; ++n) _Pragma("unroll") for (int k = 0; k < 2; ++k) \
;         acc[ai][bj][m][n] = __builtin_amdgcn_mfma_f32_16x16x32_bf16(Bt[n][k], At[m][k], acc[ai][bj][m][n], 0, 0, 0); __builtin_amdgcn_s_setprio(0); } while (0)
; #define PG8_WAIT_V(n) asm volatile("s_waitcnt vmcnt(" #n ")" ::: "memory")
; #define PG8_WAIT_L(n) asm volatile("s_waitcnt lgkmcnt(" #n ")" ::: "memory")
; #define PG8_BAR __builtin_amdgcn_s_barrier()
; #define PG8_SCHED __builtin_amdgcn_sched_barrier(0)
; template <class Epi, class Sched, bool ALIGN_EPI = false, bool SP2 = false>
; __device__ __forceinline__ void gemm_phase(PG8_LAS unsigned char* lds, const Gemm g, const Sched& S, const Epi& E) {
;     ...
;             PG8_LDA(At, 1, 1); PG8_STAGE(PG8_SB(1, 0), b3, voffB); PG8_STAGE(PG8_SB(1, 1), b3 + hstep, voffB); PG8_STAGE(PG8_SA(1, 0), a3, voffA);
;             PG8_WAIT_V(8); PG8_WAIT_L(0); PG8_BAR; PG8_MMA(1, 0, At, B0); PG8_MMA(1, 1, At, B1); PG8_BAR; PG8_SCHED;
;     ...
;         }
;         if constexpr (ALIGN_EPI) { if (wr == 0) PG8_BAR; }
	s_setprio 0
	s_setprio 1
	s_setprio 0
	s_waitcnt lgkmcnt(0)
	s_add_i32 s16, s31, s18
	v_lshl_add_u64 v[90:91], v[224:225], 0, s[88:89]
	s_mov_b32 m0, s16
	ds_read_b128 v[182:185], v88 offset:49152
	ds_read_b128 v[186:189], v88 offset:50176
	ds_read_b128 v[190:193], v88 offset:51200
	ds_read_b128 v[194:197], v88 offset:52224
	ds_read_b128 v[200:203], v88 offset:53248
	ds_read_b128 v[204:207], v88 offset:54272
	ds_read_b128 v[208:211], v88 offset:55296
	ds_read_b128 v[220:223], v88 offset:56320
	global_load_lds_dwordx4 v[90:91], off
	s_add_i32 m0, s16, 0x2000
	s_add_u32 s14, s14, 0x80080
	v_lshl_add_u64 v[90:91], v[226:227], 0, s[88:89]
	s_addc_u32 s15, s15, 0
	s_add_i32 s16, s34, s18
	global_load_lds_dwordx4 v[90:91], off
	v_lshl_add_u64 v[90:91], s[14:15], 0, v[66:67]
	s_mov_b32 m0, s16
	s_nop 0
	global_load_lds_dwordx4 v[90:91], off
	v_lshl_add_u64 v[90:91], s[14:15], 0, v[72:73]
	s_add_i32 m0, s16, 0x2000
	s_nop 0
	global_load_lds_dwordx4 v[90:91], off
	v_lshl_add_u64 v[90:91], v[228:229], 0, s[88:89]
	s_mov_b32 m0, s24
	s_nop 0
	global_load_lds_dwordx4 v[90:91], off
	v_lshl_add_u64 v[90:91], v[230:231], 0, s[88:89]
	s_mov_b32 m0, s25
	s_nop 0
	global_load_lds_dwordx4 v[90:91], off
	s_setprio 1
	s_nop 0
	s_waitcnt vmcnt(8) lgkmcnt(0)
	s_barrier
	v_mfma_f32_16x16x32_bf16 v[62:65], v[148:151], v[182:185], v[62:65]
	v_mfma_f32_16x16x32_bf16 v[58:61], v[156:159], v[182:185], v[58:61]
	v_mfma_f32_16x16x32_bf16 v[46:49], v[148:151], v[190:193], v[46:49]
	v_mfma_f32_16x16x32_bf16 v[42:45], v[156:159], v[190:193], v[42:45]
	v_mfma_f32_16x16x32_bf16 v[30:33], v[148:151], v[200:203], v[30:33]
	v_mfma_f32_16x16x32_bf16 v[26:29], v[156:159], v[200:203], v[26:29]
	v_mfma_f32_16x16x32_bf16 v[14:17], v[148:151], v[208:211], v[14:17]
	v_mfma_f32_16x16x32_bf16 v[10:13], v[156:159], v[208:211], v[10:13]
	v_mfma_f32_16x16x32_bf16 v[62:65], v[152:155], v[186:189], v[62:65]
	v_mfma_f32_16x16x32_bf16 v[58:61], v[160:163], v[186:189], v[58:61]
	v_mfma_f32_16x16x32_bf16 v[46:49], v[152:155], v[194:197], v[46:49]
	v_mfma_f32_16x16x32_bf16 v[42:45], v[160:163], v[194:197], v[42:45]
	v_mfma_f32_16x16x32_bf16 v[30:33], v[152:155], v[204:207], v[30:33]
	v_mfma_f32_16x16x32_bf16 v[26:29], v[160:163], v[204:207], v[26:29]
	v_mfma_f32_16x16x32_bf16 v[14:17], v[152:155], v[220:223], v[14:17]
	v_mfma_f32_16x16x32_bf16 v[10:13], v[160:163], v[220:223], v[10:13]
	v_mfma_f32_16x16x32_bf16 v[54:57], v[166:169], v[182:185], v[54:57]
	v_mfma_f32_16x16x32_bf16 v[50:53], v[174:177], v[182:185], v[50:53]
	v_mfma_f32_16x16x32_bf16 v[38:41], v[166:169], v[190:193], v[38:41]
	v_mfma_f32_16x16x32_bf16 v[34:37], v[174:177], v[190:193], v[34:37]
	v_mfma_f32_16x16x32_bf16 v[22:25], v[166:169], v[200:203], v[22:25]
	v_mfma_f32_16x16x32_bf16 v[18:21], v[174:177], v[200:203], v[18:21]
	v_mfma_f32_16x16x32_bf16 v[6:9], v[166:169], v[208:211], v[6:9]
	v_mfma_f32_16x16x32_bf16 v[2:5], v[174:177], v[208:211], v[2:5]
	v_mfma_f32_16x16x32_bf16 v[54:57], v[170:173], v[186:189], v[54:57]
	v_mfma_f32_16x16x32_bf16 v[50:53], v[178:181], v[186:189], v[50:53]
	v_mfma_f32_16x16x32_bf16 v[38:41], v[170:173], v[194:197], v[38:41]
	v_mfma_f32_16x16x32_bf16 v[34:37], v[178:181], v[194:197], v[34:37]
	v_mfma_f32_16x16x32_bf16 v[22:25], v[170:173], v[204:207], v[22:25]
	v_mfma_f32_16x16x32_bf16 v[18:21], v[178:181], v[204:207], v[18:21]
	v_mfma_f32_16x16x32_bf16 v[6:9], v[170:173], v[220:223], v[6:9]
	v_mfma_f32_16x16x32_bf16 v[2:5], v[178:181], v[220:223], v[2:5]
	s_barrier
	s_setprio 0
	s_setprio 1
	s_setprio 0
	s_waitcnt lgkmcnt(0)
	s_add_i32 s30, s30, 2
	s_add_u32 s12, s12, 0x100
	s_addc_u32 s13, s13, 0
	s_cmp_gt_u32 s30, 29
	s_cbranch_scc0 .LBB0_702
	s_cmpk_lt_u32 s1, 0x100
	s_cbranch_scc0 .LBB0_705
	s_barrier

; #define PG8_STAGE(bufoff, gbase, voff) do { _Pragma("unroll") for (int _i = 0; _i < 2; ++_i) \
;         __builtin_amdgcn_global_load_lds((const unsigned*)((const char*)(gbase) + (voff)[_i]), (PG8_LAS unsigned*)(lds + (bufoff) + ldsw + _i * 8192), 16, 0, 0); } while (0)
; #define PG8_LDA(dst, b, h) do { _Pragma("unroll") for (int m = 0; m < 4; ++m) _Pragma("unroll") for (int k = 0; k < 2; ++k) dst[m][k] = *(const PG8_LAS bf16x8*)(lds + PG8_SA(b, h) + aoff + m * 2048 + k * 1024); } while (0)
; #define PG8_LDB(dst, b, h) do { _Pragma("unroll") for (int n = 0; n < 2; ++n) _Pragma("unroll") for (int k = 0; k < 2; ++k) dst[n][k] = *(const PG8_LAS bf16x8*)(lds + PG8_SB(b, h) + boff + n * 2048 + k * 1024); } while (0)
; #define PG8_MMA(ai, bj, At, Bt) do { __builtin_amdgcn_s_setprio(1); _Pragma("unroll") for (int m = 0; m < 4; ++m) _Pragma("unroll") for (int n = 0; n < 2; ++n) _Pragma("unroll") for (int k = 0; k < 2; ++k) \
;         acc[ai][bj][m][n] = __builtin_amdgcn_mfma_f32_16x16x32_bf16(Bt[n][k], At[m][k], acc[ai][bj][m][n], 0, 0, 0); __builtin_amdgcn_s_setprio(0); } while (0)
; #define PG8_WAIT_V(n) asm volatile("s_waitcnt vmcnt(" #n ")" ::: "memory")
; template <class Epi, class Sched, bool ALIGN_EPI = false, bool SP2 = false>
; __device__ __forceinline__ void gemm_phase(PG8_LAS unsigned char* lds, const Gemm g, const Sched& S, const Epi& E) {
;     ...
;             PG8_LDB(B0, 0, 0); PG8_LDB(B1, 0, 1); PG8_SCHED; PG8_LDA(At, 0, 0); PG8_STAGE(PG8_SA(1, 1), a1 + hstep, voffA);
;             PG8_WAIT_V(8); PG8_WAIT_L(0); PG8_BAR; PG8_MMA(0, 0, At, B0); PG8_MMA(0, 1, At, B1); PG8_BAR; PG8_SCHED;
;             PG8_LDA(At, 0, 1); PG8_STAGE(PG8_SB(0, 0), b2, voffB); PG8_STAGE(PG8_SB(0, 1), b2 + hstep, voffB); PG8_STAGE(PG8_SA(0, 0), a2, voffA);
;             PG8_WAIT_V(8); PG8_WAIT_L(0); PG8_BAR; PG8_MMA(1, 0, At, B0); PG8_MMA(1, 1, At, B1); PG8_BAR; PG8_SCHED;
;             PG8_LDB(B0, 1, 0); PG8_LDB(B1, 1, 1); PG8_SCHED; PG8_LDA(At, 1, 0); PG8_STAGE(PG8_SA(0, 1), a2 + hstep, voffA);
;             PG8_WAIT_V(8); PG8_WAIT_L(0); PG8_BAR; PG8_MMA(0, 0, At, B0); PG8_MMA(0, 1, At, B1); PG8_BAR; PG8_SCHED;
;             PG8_LDA(At, 1, 1); PG8_STAGE(PG8_SB(1, 0), b3, voffB); PG8_STAGE(PG8_SB(1, 1), b3 + hstep, voffB); PG8_STAGE(PG8_SA(1, 0), a3, voffA);
;             PG8_WAIT_V(8); PG8_WAIT_L(0); PG8_BAR; PG8_MMA(1, 0, At, B0); PG8_MMA(1, 1, At, B1); PG8_BAR; PG8_SCHED;
.LBB0_782:
	s_add_u32 s1, s26, 0xfff80080
	s_addc_u32 s2, s27, -1
	s_add_i32 s3, 0, 0x10000
	s_cmpk_eq_i32 s28, 0x1e00
	s_cselect_b32 s35, s21, s2
	s_cselect_b32 s34, s50, s1
	v_add_u32_e32 v66, s3, v206
	s_cselect_b32 s31, s19, s53
	s_cselect_b32 s30, s51, s52
	s_add_i32 s1, 0, 0x14000
	ds_read_b128 v[152:155], v66
	ds_read_b128 v[156:159], v66 offset:1024
	ds_read_b128 v[160:163], v66 offset:2048
	ds_read_b128 v[164:167], v66 offset:3072
	v_add_u32_e32 v66, s1, v206
	ds_read_b128 v[168:171], v66
	ds_read_b128 v[172:175], v66 offset:1024
	ds_read_b128 v[176:179], v66 offset:2048
	ds_read_b128 v[180:183], v66 offset:3072
	v_lshl_add_u64 v[68:69], s[26:27], 0, v[142:143]
	s_add_i32 m0, s43, 0xc000
	ds_read_b128 v[184:187], v208
	ds_read_b128 v[188:191], v208 offset:1024
	ds_read_b128 v[192:195], v208 offset:2048
	ds_read_b128 v[196:199], v208 offset:3072
	ds_read_b128 v[200:203], v208 offset:4096
	ds_read_b128 v[220:223], v208 offset:5120
	ds_read_b128 v[224:227], v208 offset:6144
	ds_read_b128 v[228:231], v208 offset:7168
	global_load_lds_dwordx4 v[68:69], off
	v_lshl_add_u64 v[68:69], s[26:27], 0, v[144:145]
	s_add_i32 m0, s43, 0xe000
	s_nop 0
	global_load_lds_dwordx4 v[68:69], off
	s_setprio 1
	s_nop 0
	s_waitcnt vmcnt(8) lgkmcnt(0)
	s_barrier
	v_mfma_f32_16x16x32_bf16 v[130:133], v[152:155], v[184:187], v[130:133]
	v_mfma_f32_16x16x32_bf16 v[126:129], v[160:163], v[184:187], v[126:129]
	v_mfma_f32_16x16x32_bf16 v[114:117], v[152:155], v[192:195], v[114:117]
	v_mfma_f32_16x16x32_bf16 v[110:113], v[160:163], v[192:195], v[110:113]
	v_mfma_f32_16x16x32_bf16 v[98:101], v[152:155], v[200:203], v[98:101]
	v_mfma_f32_16x16x32_bf16 v[94:97], v[160:163], v[200:203], v[94:97]
	v_mfma_f32_16x16x32_bf16 v[82:85], v[152:155], v[224:227], v[82:85]
	v_mfma_f32_16x16x32_bf16 v[78:81], v[160:163], v[224:227], v[78:81]
	v_mfma_f32_16x16x32_bf16 v[130:133], v[156:159], v[188:191], v[130:133]
	v_mfma_f32_16x16x32_bf16 v[126:129], v[164:167], v[188:191], v[126:129]
	v_mfma_f32_16x16x32_bf16 v[114:117], v[156:159], v[196:199], v[114:117]
	v_mfma_f32_16x16x32_bf16 v[110:113], v[164:167], v[196:199], v[110:113]
	v_mfma_f32_16x16x32_bf16 v[98:101], v[156:159], v[220:223], v[98:101]
	v_mfma_f32_16x16x32_bf16 v[94:97], v[164:167], v[220:223], v[94:97]
	v_mfma_f32_16x16x32_bf16 v[82:85], v[156:159], v[228:231], v[82:85]
	v_mfma_f32_16x16x32_bf16 v[78:81], v[164:167], v[228:231], v[78:81]
	v_mfma_f32_16x16x32_bf16 v[122:125], v[168:171], v[184:187], v[122:125]
	v_mfma_f32_16x16x32_bf16 v[118:121], v[176:179], v[184:187], v[118:121]
	v_mfma_f32_16x16x32_bf16 v[106:109], v[168:171], v[192:195], v[106:109]
	v_mfma_f32_16x16x32_bf16 v[102:105], v[176:179], v[192:195], v[102:105]
	v_mfma_f32_16x16x32_bf16 v[90:93], v[168:171], v[200:203], v[90:93]
	v_mfma_f32_16x16x32_bf16 v[86:89], v[176:179], v[200:203], v[86:89]
	v_mfma_f32_16x16x32_bf16 v[74:77], v[168:171], v[224:227], v[74:77]
	v_mfma_f32_16x16x32_bf16 v[68:71], v[176:179], v[224:227], v[70:73]
	v_mfma_f32_16x16x32_bf16 v[122:125], v[172:175], v[188:191], v[122:125]
	v_mfma_f32_16x16x32_bf16 v[118:121], v[180:183], v[188:191], v[118:121]
	v_mfma_f32_16x16x32_bf16 v[106:109], v[172:175], v[196:199], v[106:109]
	v_mfma_f32_16x16x32_bf16 v[102:105], v[180:183], v[196:199], v[102:105]
	v_mfma_f32_16x16x32_bf16 v[90:93], v[172:175], v[220:223], v[90:93]
	v_mfma_f32_16x16x32_bf16 v[86:89], v[180:183], v[220:223], v[86:89]
	v_mfma_f32_16x16x32_bf16 v[74:77], v[172:175], v[228:231], v[74:77]
	v_mfma_f32_16x16x32_bf16 v[68:71], v[180:183], v[228:231], v[68:71]
	s_barrier
	s_setprio 0
	s_setprio 1
	s_setprio 0
	s_waitcnt lgkmcnt(0)
	s_add_i32 s2, s3, s42
	v_lshl_add_u64 v[204:205], s[30:31], 0, v[138:139]
	s_mov_b32 m0, s2
	ds_read_b128 v[184:187], v208 offset:16384
	ds_read_b128 v[188:191], v208 offset:17408
	ds_read_b128 v[192:195], v208 offset:18432
	ds_read_b128 v[196:199], v208 offset:19456
	ds_read_b128 v[200:203], v208 offset:20480
	ds_read_b128 v[220:223], v208 offset:21504
	ds_read_b128 v[224:227], v208 offset:22528
	ds_read_b128 v[228:231], v208 offset:23552
	global_load_lds_dwordx4 v[204:205], off
	s_add_i32 m0, s2, 0x2000
	s_add_u32 s2, s30, 0x80000
	v_lshl_add_u64 v[210:211], s[30:31], 0, v[134:135]
	s_addc_u32 s3, s31, 0
	s_add_i32 s1, s1, s42
	global_load_lds_dwordx4 v[210:211], off
	v_lshl_add_u64 v[72:73], s[2:3], 0, v[138:139]
	s_mov_b32 m0, s1
	v_lshl_add_u64 v[232:233], s[34:35], 0, v[140:141]
	global_load_lds_dwordx4 v[72:73], off
	v_lshl_add_u64 v[72:73], s[2:3], 0, v[134:135]
	s_add_i32 m0, s1, 0x2000
	v_lshl_add_u64 v[234:235], s[34:35], 0, v[136:137]
	global_load_lds_dwordx4 v[72:73], off
	s_mov_b32 m0, s43
	s_nop 0
	global_load_lds_dwordx4 v[232:233], off
	s_mov_b32 m0, s44
	s_nop 0
	global_load_lds_dwordx4 v[234:235], off
	s_setprio 1
	s_nop 0
	s_waitcnt vmcnt(8) lgkmcnt(0)
	s_barrier
; #define PG8_STAGE(bufoff, gbase, voff) do { _Pragma("unroll") for (int _i = 0; _i < 2; ++_i) \
;         __builtin_amdgcn_global_load_lds((const unsigned*)((const char*)(gbase) + (voff)[_i]), (PG8_LAS unsigned*)(lds + (bufoff) + ldsw + _i * 8192), 16, 0, 0); } while (0)
; #define PG8_LDA(dst, b, h) do { _Pragma("unroll") for (int m = 0; m < 4; ++m) _Pragma("unroll") for (int k = 0; k < 2; ++k) dst[m][k] = *(const PG8_LAS bf16x8*)(lds + PG8_SA(b, h) + aoff + m * 2048 + k * 1024); } while (0)
; #define PG8_LDB(dst, b, h) do { _Pragma("unroll") for (int n = 0; n < 2; ++n) _Pragma("unroll") for (int k = 0; k < 2; ++k) dst[n][k] = *(const PG8_LAS bf16x8*)(lds + PG8_SB(b, h) + boff + n * 2048 + k * 1024); } while (0)
; #define PG8_MMA(ai, bj, At, Bt) do { __builtin_amdgcn_s_setprio(1); _Pragma("unroll") for (int m = 0; m < 4; ++m) _Pragma("unroll") for (int n = 0; n < 2; ++n) _Pragma("unroll") for (int k = 0; k < 2; ++k) \
;         acc[ai][bj][m][n] = __builtin_amdgcn_mfma_f32_16x16x32_bf16(Bt[n][k], At[m][k], acc[ai][bj][m][n], 0, 0, 0); __builtin_amdgcn_s_setprio(0); } while (0)
; #define PG8_WAIT_V(n) asm volatile("s_waitcnt vmcnt(" #n ")" ::: "memory")
; template <class Epi, class Sched, bool ALIGN_EPI = false, bool SP2 = false>
; __device__ __forceinline__ void gemm_phase(PG8_LAS unsigned char* lds, const Gemm g, const Sched& S, const Epi& E) {
;     ...
;             PG8_LDB(B0, 0, 0); PG8_LDB(B1, 0, 1); PG8_SCHED; PG8_LDA(At, 0, 0); PG8_STAGE(PG8_SA(1, 1), a1 + hstep, voffA);
;             PG8_WAIT_V(8); PG8_WAIT_L(0); PG8_BAR; PG8_MMA(0, 0, At, B0); PG8_MMA(0, 1, At, B1); PG8_BAR; PG8_SCHED;
;             PG8_LDA(At, 0, 1); PG8_STAGE(PG8_SB(0, 0), b2, voffB); PG8_STAGE(PG8_SB(0, 1), b2 + hstep, voffB); PG8_STAGE(PG8_SA(0, 0), a2, voffA);
;             PG8_WAIT_V(8); PG8_WAIT_L(0); PG8_BAR; PG8_MMA(1, 0, At, B0); PG8_MMA(1, 1, At, B1); PG8_BAR; PG8_SCHED;
;             PG8_LDB(B0, 1, 0); PG8_LDB(B1, 1, 1); PG8_SCHED; PG8_LDA(At, 1, 0); PG8_STAGE(PG8_SA(0, 1), a2 + hstep, voffA);
;             PG8_WAIT_V(8); PG8_WAIT_L(0); PG8_BAR; PG8_MMA(0, 0, At, B0); PG8_MMA(0, 1, At, B1); PG8_BAR; PG8_SCHED;
;             PG8_LDA(At, 1, 1); PG8_STAGE(PG8_SB(1, 0), b3, voffB); PG8_STAGE(PG8_SB(1, 1), b3 + hstep, voffB); PG8_STAGE(PG8_SA(1, 0), a3, voffA);
;             PG8_WAIT_V(8); PG8_WAIT_L(0); PG8_BAR; PG8_MMA(1, 0, At, B0); PG8_MMA(1, 1, At, B1); PG8_BAR; PG8_SCHED;
	v_mfma_f32_16x16x32_bf16 v[62:65], v[152:155], v[184:187], v[62:65]
	v_mfma_f32_16x16x32_bf16 v[58:61], v[160:163], v[184:187], v[58:61]
	v_mfma_f32_16x16x32_bf16 v[46:49], v[152:155], v[192:195], v[46:49]
	v_mfma_f32_16x16x32_bf16 v[42:45], v[160:163], v[192:195], v[42:45]
	v_mfma_f32_16x16x32_bf16 v[30:33], v[152:155], v[200:203], v[30:33]
	v_mfma_f32_16x16x32_bf16 v[26:29], v[160:163], v[200:203], v[26:29]
	v_mfma_f32_16x16x32_bf16 v[14:17], v[152:155], v[224:227], v[14:17]
	v_mfma_f32_16x16x32_bf16 v[10:13], v[160:163], v[224:227], v[10:13]
	v_mfma_f32_16x16x32_bf16 v[62:65], v[156:159], v[188:191], v[62:65]
	v_mfma_f32_16x16x32_bf16 v[58:61], v[164:167], v[188:191], v[58:61]
	v_mfma_f32_16x16x32_bf16 v[46:49], v[156:159], v[196:199], v[46:49]
	v_mfma_f32_16x16x32_bf16 v[42:45], v[164:167], v[196:199], v[42:45]
	v_mfma_f32_16x16x32_bf16 v[30:33], v[156:159], v[220:223], v[30:33]
	v_mfma_f32_16x16x32_bf16 v[26:29], v[164:167], v[220:223], v[26:29]
	v_mfma_f32_16x16x32_bf16 v[14:17], v[156:159], v[228:231], v[14:17]
	v_mfma_f32_16x16x32_bf16 v[10:13], v[164:167], v[228:231], v[10:13]
	v_mfma_f32_16x16x32_bf16 v[54:57], v[168:171], v[184:187], v[54:57]
	v_mfma_f32_16x16x32_bf16 v[50:53], v[176:179], v[184:187], v[50:53]
	v_mfma_f32_16x16x32_bf16 v[38:41], v[168:171], v[192:195], v[38:41]
	v_mfma_f32_16x16x32_bf16 v[34:37], v[176:179], v[192:195], v[34:37]
	v_mfma_f32_16x16x32_bf16 v[22:25], v[168:171], v[200:203], v[22:25]
	v_mfma_f32_16x16x32_bf16 v[18:21], v[176:179], v[200:203], v[18:21]
	v_mfma_f32_16x16x32_bf16 v[6:9], v[168:171], v[224:227], v[6:9]
	v_mfma_f32_16x16x32_bf16 v[2:5], v[176:179], v[224:227], v[2:5]
	v_mfma_f32_16x16x32_bf16 v[54:57], v[172:175], v[188:191], v[54:57]
	v_mfma_f32_16x16x32_bf16 v[50:53], v[180:183], v[188:191], v[50:53]
	v_mfma_f32_16x16x32_bf16 v[38:41], v[172:175], v[196:199], v[38:41]
	v_mfma_f32_16x16x32_bf16 v[34:37], v[180:183], v[196:199], v[34:37]
	v_mfma_f32_16x16x32_bf16 v[22:25], v[172:175], v[220:223], v[22:25]
	v_mfma_f32_16x16x32_bf16 v[18:21], v[180:183], v[220:223], v[18:21]
	v_mfma_f32_16x16x32_bf16 v[6:9], v[172:175], v[228:231], v[6:9]
	v_mfma_f32_16x16x32_bf16 v[2:5], v[180:183], v[228:231], v[2:5]
	s_barrier
	s_setprio 0
	s_setprio 1
	s_setprio 0
	s_waitcnt lgkmcnt(0)
	s_add_i32 s1, 0, 0x18000
	v_add_u32_e32 v66, s1, v206
	s_add_i32 s55, 0, 0x1c000
	ds_read_b128 v[152:155], v66
	ds_read_b128 v[156:159], v66 offset:1024
	ds_read_b128 v[160:163], v66 offset:2048
	ds_read_b128 v[164:167], v66 offset:3072
	v_add_u32_e32 v66, s55, v206
	ds_read_b128 v[168:171], v66
	ds_read_b128 v[172:175], v66 offset:1024
	ds_read_b128 v[176:179], v66 offset:2048
	ds_read_b128 v[180:183], v66 offset:3072
	s_add_u32 s2, s34, 0x80000
	s_addc_u32 s3, s35, 0
	s_mov_b32 m0, s45
	v_lshl_add_u64 v[72:73], s[2:3], 0, v[140:141]
	ds_read_b128 v[184:187], v208 offset:32768
	ds_read_b128 v[188:191], v208 offset:33792
	ds_read_b128 v[192:195], v208 offset:34816
	ds_read_b128 v[196:199], v208 offset:35840
	ds_read_b128 v[200:203], v208 offset:36864
	ds_read_b128 v[220:223], v208 offset:37888
	ds_read_b128 v[224:227], v208 offset:38912
	ds_read_b128 v[228:231], v208 offset:39936
	global_load_lds_dwordx4 v[72:73], off
	v_lshl_add_u64 v[72:73], s[2:3], 0, v[136:137]
	s_mov_b32 m0, s46
	s_nop 0
	global_load_lds_dwordx4 v[72:73], off
	s_setprio 1
	s_nop 0
	s_waitcnt vmcnt(8) lgkmcnt(0)
	s_barrier
	v_mfma_f32_16x16x32_bf16 v[130:133], v[152:155], v[184:187], v[130:133]
	v_mfma_f32_16x16x32_bf16 v[126:129], v[160:163], v[184:187], v[126:129]
	v_mfma_f32_16x16x32_bf16 v[114:117], v[152:155], v[192:195], v[114:117]
	v_mfma_f32_16x16x32_bf16 v[110:113], v[160:163], v[192:195], v[110:113]
	v_mfma_f32_16x16x32_bf16 v[98:101], v[152:155], v[200:203], v[98:101]
	v_mfma_f32_16x16x32_bf16 v[94:97], v[160:163], v[200:203], v[94:97]
	v_mfma_f32_16x16x32_bf16 v[82:85], v[152:155], v[224:227], v[82:85]
	v_mfma_f32_16x16x32_bf16 v[78:81], v[160:163], v[224:227], v[78:81]
	v_mfma_f32_16x16x32_bf16 v[130:133], v[156:159], v[188:191], v[130:133]
	v_mfma_f32_16x16x32_bf16 v[126:129], v[164:167], v[188:191], v[126:129]
	v_mfma_f32_16x16x32_bf16 v[114:117], v[156:159], v[196:199], v[114:117]
	v_mfma_f32_16x16x32_bf16 v[110:113], v[164:167], v[196:199], v[110:113]
	v_mfma_f32_16x16x32_bf16 v[98:101], v[156:159], v[220:223], v[98:101]
	v_mfma_f32_16x16x32_bf16 v[94:97], v[164:167], v[220:223], v[94:97]
	v_mfma_f32_16x16x32_bf16 v[82:85], v[156:159], v[228:231], v[82:85]
	v_mfma_f32_16x16x32_bf16 v[78:81], v[164:167], v[228:231], v[78:81]
	v_mfma_f32_16x16x32_bf16 v[122:125], v[168:171], v[184:187], v[122:125]
	v_mfma_f32_16x16x32_bf16 v[118:121], v[176:179], v[184:187], v[118:121]
	v_mfma_f32_16x16x32_bf16 v[106:109], v[168:171], v[192:195], v[106:109]
	v_mfma_f32_16x16x32_bf16 v[102:105], v[176:179], v[192:195], v[102:105]
	v_mfma_f32_16x16x32_bf16 v[90:93], v[168:171], v[200:203], v[90:93]
	v_mfma_f32_16x16x32_bf16 v[86:89], v[176:179], v[200:203], v[86:89]
	v_mfma_f32_16x16x32_bf16 v[72:75], v[168:171], v[224:227], v[74:77]
	v_mfma_f32_16x16x32_bf16 v[68:71], v[176:179], v[224:227], v[68:71]
	v_mfma_f32_16x16x32_bf16 v[122:125], v[172:175], v[188:191], v[122:125]
	v_mfma_f32_16x16x32_bf16 v[118:121], v[180:183], v[188:191], v[118:121]
	v_mfma_f32_16x16x32_bf16 v[106:109], v[172:175], v[196:199], v[106:109]
	v_mfma_f32_16x16x32_bf16 v[102:105], v[180:183], v[196:199], v[102:105]
	v_mfma_f32_16x16x32_bf16 v[90:93], v[172:175], v[220:223], v[90:93]
	v_mfma_f32_16x16x32_bf16 v[86:89], v[180:183], v[220:223], v[86:89]
	v_mfma_f32_16x16x32_bf16 v[74:77], v[172:175], v[228:231], v[72:75]
	v_mfma_f32_16x16x32_bf16 v[70:73], v[180:183], v[228:231], v[68:71]
	s_barrier
; #define PG8_STAGE(bufoff, gbase, voff) do { _Pragma("unroll") for (int _i = 0; _i < 2; ++_i) \
;         __builtin_amdgcn_global_load_lds((const unsigned*)((const char*)(gbase) + (voff)[_i]), (PG8_LAS unsigned*)(lds + (bufoff) + ldsw + _i * 8192), 16, 0, 0); } while (0)
; #define PG8_LDA(dst, b, h) do { _Pragma("unroll") for (int m = 0; m < 4; ++m) _Pragma("unroll") for (int k = 0; k < 2; ++k) dst[m][k] = *(const PG8_LAS bf16x8*)(lds + PG8_SA(b, h) + aoff + m * 2048 + k * 1024); } while (0)
; #define PG8_MMA(ai, bj, At, Bt) do { __builtin_amdgcn_s_setprio(1); _Pragma("unroll") for (int m = 0; m < 4; ++m) _Pragma("unroll") for (int n = 0; n < 2; ++n) _Pragma("unroll") for (int k = 0; k < 2; ++k) \
;         acc[ai][bj][m][n] = __builtin_amdgcn_mfma_f32_16x16x32_bf16(Bt[n][k], At[m][k], acc[ai][bj][m][n], 0, 0, 0); __builtin_amdgcn_s_setprio(0); } while (0)
; #define PG8_WAIT_V(n) asm volatile("s_waitcnt vmcnt(" #n ")" ::: "memory")
; #define PG8_BAR __builtin_amdgcn_s_barrier()
;     __device__ __forceinline__ void mid(f32x4 (&acc)[2][2][4][2], const Unit& u, int seg, int wr, int wc, int fr, int fq) const {
;         typedef unsigned u32x2v __attribute__((ext_vector_type(2)));
;         int row0 = u.pm * BM + wr * 64 + fr; asm volatile("" : "+v"(row0));
;         const int col0 = u.pn * BM + wc * 32 + 8 * fq;
;         u32x2v ga[2][4][2], gb[2][4][2];
; #pragma unroll
;         for (int ai = 0; ai < 2; ++ai)
; #pragma unroll
;             for (int m = 0; m < 4; ++m) { const unsigned char* rowp = G + (size_t)(row0 + ai * HALF + m * 16) * 8192 + col0 + seg * 2048;
; #pragma unroll
;                 for (int bj = 0; bj < 2; ++bj) { ga[ai][m][bj] = *(const u32x2v*)(rowp + bj * HALF); gb[ai][m][bj] = *(const u32x2v*)(rowp + 2048 + bj * HALF); } }
; template <class Epi, class Sched, bool ALIGN_EPI = false, bool SP2 = false>
; __device__ __forceinline__ void gemm_phase(PG8_LAS unsigned char* lds, const Gemm g, const Sched& S, const Epi& E) {
;     ...
;             PG8_LDA(At, 1, 1); PG8_STAGE(PG8_SB(1, 0), b3, voffB); PG8_STAGE(PG8_SB(1, 1), b3 + hstep, voffB); PG8_STAGE(PG8_SA(1, 0), a3, voffA);
;             PG8_WAIT_V(8); PG8_WAIT_L(0); PG8_BAR; PG8_MMA(1, 0, At, B0); PG8_MMA(1, 1, At, B1); PG8_BAR; PG8_SCHED;
;     ...
;             if constexpr (Epi::HAS_MID) { if ((((t + 2) & 7) == 0) && ((t + 2) < nt)) E.mid(acc, cur, ((t + 2) >> 3) - 1, wr, wc, fr, fq); }
	s_setprio 0
	s_setprio 1
	s_setprio 0
	s_waitcnt lgkmcnt(0)
	s_add_i32 s1, s1, s42
	v_lshl_add_u64 v[68:69], v[204:205], 0, s[88:89]
	s_mov_b32 m0, s1
	ds_read_b128 v[184:187], v208 offset:49152
	ds_read_b128 v[188:191], v208 offset:50176
	ds_read_b128 v[192:195], v208 offset:51200
	ds_read_b128 v[196:199], v208 offset:52224
	ds_read_b128 v[200:203], v208 offset:53248
	ds_read_b128 v[220:223], v208 offset:54272
	ds_read_b128 v[224:227], v208 offset:55296
	ds_read_b128 v[228:231], v208 offset:56320
	global_load_lds_dwordx4 v[68:69], off
	s_add_i32 m0, s1, 0x2000
	s_add_u32 s2, s30, 0x80080
	v_lshl_add_u64 v[68:69], v[210:211], 0, s[88:89]
	s_addc_u32 s3, s31, 0
	s_add_i32 s1, s55, s42
	global_load_lds_dwordx4 v[68:69], off
	v_lshl_add_u64 v[68:69], s[2:3], 0, v[138:139]
	s_mov_b32 m0, s1
	s_nop 0
	global_load_lds_dwordx4 v[68:69], off
	v_lshl_add_u64 v[68:69], s[2:3], 0, v[134:135]
	s_add_i32 m0, s1, 0x2000
	s_nop 0
	global_load_lds_dwordx4 v[68:69], off
	v_lshl_add_u64 v[68:69], v[232:233], 0, s[88:89]
	s_mov_b32 m0, s47
	s_nop 0
	global_load_lds_dwordx4 v[68:69], off
	v_lshl_add_u64 v[68:69], v[234:235], 0, s[88:89]
	s_mov_b32 m0, s48
	s_nop 0
	global_load_lds_dwordx4 v[68:69], off
	s_setprio 1
	s_nop 0
	s_waitcnt vmcnt(8) lgkmcnt(0)
	s_barrier
	v_mfma_f32_16x16x32_bf16 v[62:65], v[152:155], v[184:187], v[62:65]
	v_mfma_f32_16x16x32_bf16 v[58:61], v[160:163], v[184:187], v[58:61]
	v_mfma_f32_16x16x32_bf16 v[46:49], v[152:155], v[192:195], v[46:49]
	v_mfma_f32_16x16x32_bf16 v[42:45], v[160:163], v[192:195], v[42:45]
	v_mfma_f32_16x16x32_bf16 v[30:33], v[152:155], v[200:203], v[30:33]
	v_mfma_f32_16x16x32_bf16 v[26:29], v[160:163], v[200:203], v[26:29]
	v_mfma_f32_16x16x32_bf16 v[14:17], v[152:155], v[224:227], v[14:17]
	v_mfma_f32_16x16x32_bf16 v[10:13], v[160:163], v[224:227], v[10:13]
	v_mfma_f32_16x16x32_bf16 v[62:65], v[156:159], v[188:191], v[62:65]
	v_mfma_f32_16x16x32_bf16 v[58:61], v[164:167], v[188:191], v[58:61]
	v_mfma_f32_16x16x32_bf16 v[46:49], v[156:159], v[196:199], v[46:49]
	v_mfma_f32_16x16x32_bf16 v[42:45], v[164:167], v[196:199], v[42:45]
	v_mfma_f32_16x16x32_bf16 v[30:33], v[156:159], v[220:223], v[30:33]
	v_mfma_f32_16x16x32_bf16 v[26:29], v[164:167], v[220:223], v[26:29]
	v_mfma_f32_16x16x32_bf16 v[14:17], v[156:159], v[228:231], v[14:17]
	v_mfma_f32_16x16x32_bf16 v[10:13], v[164:167], v[228:231], v[10:13]
	v_mfma_f32_16x16x32_bf16 v[54:57], v[168:171], v[184:187], v[54:57]
	v_mfma_f32_16x16x32_bf16 v[50:53], v[176:179], v[184:187], v[50:53]
	v_mfma_f32_16x16x32_bf16 v[38:41], v[168:171], v[192:195], v[38:41]
	v_mfma_f32_16x16x32_bf16 v[34:37], v[176:179], v[192:195], v[34:37]
	v_mfma_f32_16x16x32_bf16 v[22:25], v[168:171], v[200:203], v[22:25]
	v_mfma_f32_16x16x32_bf16 v[18:21], v[176:179], v[200:203], v[18:21]
	v_mfma_f32_16x16x32_bf16 v[6:9], v[168:171], v[224:227], v[6:9]
	v_mfma_f32_16x16x32_bf16 v[2:5], v[176:179], v[224:227], v[2:5]
	v_mfma_f32_16x16x32_bf16 v[54:57], v[172:175], v[188:191], v[54:57]
	v_mfma_f32_16x16x32_bf16 v[50:53], v[180:183], v[188:191], v[50:53]
	v_mfma_f32_16x16x32_bf16 v[38:41], v[172:175], v[196:199], v[38:41]
	v_mfma_f32_16x16x32_bf16 v[34:37], v[180:183], v[196:199], v[34:37]
	v_mfma_f32_16x16x32_bf16 v[22:25], v[172:175], v[220:223], v[22:25]
	v_mfma_f32_16x16x32_bf16 v[18:21], v[180:183], v[220:223], v[18:21]
	v_mfma_f32_16x16x32_bf16 v[6:9], v[172:175], v[228:231], v[6:9]
	v_mfma_f32_16x16x32_bf16 v[2:5], v[180:183], v[228:231], v[2:5]
	s_barrier
	s_setprio 0
	s_setprio 1
	s_setprio 0
	s_waitcnt lgkmcnt(0)
	s_mov_b32 s1, s54
	s_add_i32 s54, s54, 2
	s_and_b32 s2, s54, 6
	s_cmp_eq_u32 s2, 0
	s_cselect_b64 s[2:3], -1, 0
	s_cmp_gt_u32 s1, 29
	s_cselect_b64 s[30:31], -1, 0
	s_cmp_lt_u32 s1, 30
	s_cselect_b64 s[34:35], -1, 0
	s_and_b64 s[2:3], s[2:3], s[34:35]
	s_andn2_b64 vcc, exec, s[2:3]
	s_cbranch_vccnz .LBB0_781
	v_mov_b32_e32 v68, v148
	s_nop 0
	v_ashrrev_i32_e32 v69, 31, v68
	v_lshlrev_b64 v[68:69], 13, v[68:69]
	v_lshl_add_u64 v[68:69], s[28:29], 0, v[68:69]
	v_lshl_add_u64 v[68:69], v[150:151], 0, v[68:69]
	v_add_co_u32_e32 v152, vcc, 0xcbff000, v68
	s_nop 1
	v_addc_co_u32_e32 v153, vcc, 0, v69, vcc
	v_add_co_u32_e32 v154, vcc, 0xcc00000, v68
	s_nop 1
	v_addc_co_u32_e32 v155, vcc, 0, v69, vcc
	global_load_dwordx2 v[210:211], v[152:153], off offset:2560
	global_load_dwordx2 v[220:221], v[154:155], off offset:512
	global_load_dwordx2 v[222:223], v[154:155], off offset:640
	global_load_dwordx2 v[224:225], v[152:153], off offset:2688
	v_add_co_u32_e32 v152, vcc, 0xcc1f000, v68
	s_nop 1
	v_addc_co_u32_e32 v153, vcc, 0, v69, vcc
	v_add_co_u32_e32 v154, vcc, 0xcc20000, v68
	s_nop 0
	s_nop 0
	v_addc_co_u32_e32 v155, vcc, 0, v69, vcc
	global_load_dwordx2 v[202:203], v[152:153], off offset:2560
	global_load_dwordx2 v[204:205], v[154:155], off offset:512
	global_load_dwordx2 v[200:201], v[154:155], off offset:640
	global_load_dwordx2 v[198:199], v[152:153], off offset:2688
	v_add_co_u32_e32 v152, vcc, 0xcc3f000, v68
	s_nop 0
	s_nop 0
	v_addc_co_u32_e32 v153, vcc, 0, v69, vcc
	v_add_co_u32_e32 v154, vcc, 0xcc40000, v68
	s_nop 0
	s_nop 0
	v_addc_co_u32_e32 v155, vcc, 0, v69, vcc
	global_load_dwordx2 v[194:195], v[152:153], off offset:2560
	global_load_dwordx2 v[196:197], v[154:155], off offset:512
	global_load_dwordx2 v[192:193], v[154:155], off offset:640
	global_load_dwordx2 v[190:191], v[152:153], off offset:2688
	v_add_co_u32_e32 v152, vcc, 0xcc5f000, v68
	s_nop 0
	s_nop 0
	v_addc_co_u32_e32 v153, vcc, 0, v69, vcc
	v_add_co_u32_e32 v154, vcc, 0xcc60000, v68
	s_nop 1
	v_addc_co_u32_e32 v155, vcc, 0, v69, vcc
	global_load_dwordx2 v[186:187], v[152:153], off offset:2560
; __device__ __forceinline__ float gate_v(unsigned q) { return (float)q; }
;     __device__ __forceinline__ void mid(f32x4 (&acc)[2][2][4][2], const Unit& u, int seg, int wr, int wc, int fr, int fq) const {
;     ...
;             for (int m = 0; m < 4; ++m) { const unsigned char* rowp = G + (size_t)(row0 + ai * HALF + m * 16) * 8192 + col0 + seg * 2048;
; #pragma unroll
;                 for (int bj = 0; bj < 2; ++bj) { ga[ai][m][bj] = *(const u32x2v*)(rowp + bj * HALF); gb[ai][m][bj] = *(const u32x2v*)(rowp + 2048 + bj * HALF); } }
; #pragma unroll
;         for (int ai = 0; ai < 2; ++ai)
; #pragma unroll
;             for (int m = 0; m < 4; ++m)
; #pragma unroll
;                 for (int bj = 0; bj < 2; ++bj)
; #pragma unroll
;                     for (int e = 0; e < 8; ++e) { const unsigned a = (ga[ai][m][bj][e >> 2] >> (8 * (e & 3))) & 255u, b = (gb[ai][m][bj][e >> 2] >> (8 * (e & 3))) & 255u;
;                         acc[ai][bj][m][e >> 2][e & 3] *= gate_v(a) * __builtin_amdgcn_rcpf(gate_v(b)); }
	global_load_dwordx2 v[188:189], v[154:155], off offset:512
	global_load_dwordx2 v[184:185], v[154:155], off offset:640
	global_load_dwordx2 v[182:183], v[152:153], off offset:2688
	v_add_co_u32_e32 v152, vcc, 0xccff000, v68
	s_nop 1
	v_addc_co_u32_e32 v153, vcc, 0, v69, vcc
	v_add_co_u32_e32 v154, vcc, 0xcd00000, v68
	s_nop 1
	v_addc_co_u32_e32 v155, vcc, 0, v69, vcc
	global_load_dwordx2 v[178:179], v[152:153], off offset:2560
	global_load_dwordx2 v[180:181], v[154:155], off offset:512
	global_load_dwordx2 v[176:177], v[154:155], off offset:640
	global_load_dwordx2 v[174:175], v[152:153], off offset:2688
	v_add_co_u32_e32 v152, vcc, 0xcd1f000, v68
	s_nop 1
	v_addc_co_u32_e32 v153, vcc, 0, v69, vcc
	v_add_co_u32_e32 v154, vcc, 0xcd20000, v68
	s_nop 1
	v_addc_co_u32_e32 v155, vcc, 0, v69, vcc
	global_load_dwordx2 v[170:171], v[152:153], off offset:2560
	global_load_dwordx2 v[172:173], v[154:155], off offset:512
	global_load_dwordx2 v[168:169], v[154:155], off offset:640
	global_load_dwordx2 v[166:167], v[152:153], off offset:2688
	v_add_co_u32_e32 v152, vcc, 0xcd3f000, v68
	s_nop 1
	v_addc_co_u32_e32 v153, vcc, 0, v69, vcc
	v_add_co_u32_e32 v154, vcc, 0xcd40000, v68
	s_nop 1
	v_addc_co_u32_e32 v155, vcc, 0, v69, vcc
	v_add_co_u32_e32 v226, vcc, 0xcd5f000, v68
	global_load_dwordx2 v[162:163], v[152:153], off offset:2560
	global_load_dwordx2 v[164:165], v[154:155], off offset:512
	global_load_dwordx2 v[160:161], v[154:155], off offset:640
	global_load_dwordx2 v[158:159], v[152:153], off offset:2688
	v_addc_co_u32_e32 v227, vcc, 0, v69, vcc
	v_add_co_u32_e32 v68, vcc, 0xcd60000, v68
	s_nop 1
	v_addc_co_u32_e32 v69, vcc, 0, v69, vcc
	global_load_dwordx2 v[154:155], v[226:227], off offset:2560
	global_load_dwordx2 v[156:157], v[68:69], off offset:512
	global_load_dwordx2 v[152:153], v[68:69], off offset:640
	s_nop 0
	global_load_dwordx2 v[68:69], v[226:227], off offset:2688
	s_waitcnt vmcnt(28)
	v_cvt_f32_ubyte1_e32 v233, v210
	v_cvt_f32_ubyte0_e32 v66, v220
	v_cvt_f32_ubyte0_e32 v232, v210
	v_cvt_f32_ubyte3_e32 v231, v210
	v_cvt_f32_ubyte2_e32 v230, v210
	v_rcp_iflag_f32_e32 v226, v66
	v_cvt_f32_ubyte1_e32 v66, v220
	v_rcp_iflag_f32_e32 v227, v66
	v_cvt_f32_ubyte2_e32 v66, v220
	v_rcp_iflag_f32_e32 v228, v66
	v_cvt_f32_ubyte3_e32 v66, v220
	v_rcp_iflag_f32_e32 v229, v66
	v_pk_mul_f32 v[226:227], v[226:227], v[232:233]
	v_cvt_f32_ubyte0_e32 v66, v221
	v_pk_mul_f32 v[130:131], v[130:131], v[226:227]
	v_rcp_iflag_f32_e32 v226, v66
	v_cvt_f32_ubyte1_e32 v66, v221
	v_rcp_iflag_f32_e32 v227, v66
	v_cvt_f32_ubyte2_e32 v66, v221
	v_pk_mul_f32 v[228:229], v[228:229], v[230:231]
	v_rcp_iflag_f32_e32 v220, v66
	v_cvt_f32_ubyte3_e32 v66, v221
	v_cvt_f32_ubyte1_e32 v231, v211
	v_cvt_f32_ubyte0_e32 v230, v211
	v_pk_mul_f32 v[132:133], v[132:133], v[228:229]
	v_rcp_iflag_f32_e32 v221, v66
	v_cvt_f32_ubyte3_e32 v229, v211
	v_cvt_f32_ubyte2_e32 v228, v211
	v_pk_mul_f32 v[210:211], v[226:227], v[230:231]
	v_cvt_f32_ubyte0_e32 v66, v222
	v_pk_mul_f32 v[126:127], v[126:127], v[210:211]
	v_rcp_iflag_f32_e32 v210, v66
	v_cvt_f32_ubyte1_e32 v66, v222
	v_rcp_iflag_f32_e32 v211, v66
	v_pk_mul_f32 v[220:221], v[220:221], v[228:229]
	v_cvt_f32_ubyte2_e32 v66, v222
	v_pk_mul_f32 v[128:129], v[128:129], v[220:221]
	v_rcp_iflag_f32_e32 v220, v66
	v_cvt_f32_ubyte3_e32 v66, v222
	v_cvt_f32_ubyte1_e32 v229, v224
	v_cvt_f32_ubyte0_e32 v228, v224
	v_rcp_iflag_f32_e32 v221, v66
	v_pk_mul_f32 v[210:211], v[210:211], v[228:229]
	v_cvt_f32_ubyte0_e32 v66, v223
	v_pk_mul_f32 v[122:123], v[122:123], v[210:211]
	v_rcp_iflag_f32_e32 v210, v66
	v_cvt_f32_ubyte1_e32 v66, v223
	v_rcp_iflag_f32_e32 v211, v66
	v_cvt_f32_ubyte3_e32 v227, v224
	v_cvt_f32_ubyte2_e32 v226, v224
	v_pk_mul_f32 v[220:221], v[220:221], v[226:227]
	v_cvt_f32_ubyte2_e32 v66, v223
	v_pk_mul_f32 v[124:125], v[124:125], v[220:221]
	v_rcp_iflag_f32_e32 v220, v66
	v_cvt_f32_ubyte3_e32 v66, v223
	v_cvt_f32_ubyte1_e32 v227, v225
	v_cvt_f32_ubyte0_e32 v226, v225
	v_rcp_iflag_f32_e32 v221, v66
	v_pk_mul_f32 v[210:211], v[210:211], v[226:227]
	s_waitcnt vmcnt(26)
	v_cvt_f32_ubyte0_e32 v66, v204
	v_pk_mul_f32 v[118:119], v[118:119], v[210:211]
	v_rcp_iflag_f32_e32 v210, v66
	v_cvt_f32_ubyte1_e32 v66, v204
	v_rcp_iflag_f32_e32 v211, v66
	v_cvt_f32_ubyte3_e32 v223, v225
	v_cvt_f32_ubyte2_e32 v222, v225
	v_pk_mul_f32 v[220:221], v[220:221], v[222:223]
	v_cvt_f32_ubyte2_e32 v66, v204
	v_pk_mul_f32 v[120:121], v[120:121], v[220:221]
	v_rcp_iflag_f32_e32 v220, v66
	v_cvt_f32_ubyte3_e32 v66, v204
	v_cvt_f32_ubyte1_e32 v225, v202
	v_cvt_f32_ubyte0_e32 v224, v202
	v_rcp_iflag_f32_e32 v221, v66
	v_pk_mul_f32 v[210:211], v[210:211], v[224:225]
	v_cvt_f32_ubyte0_e32 v66, v205
	v_pk_mul_f32 v[114:115], v[114:115], v[210:211]
	v_rcp_iflag_f32_e32 v210, v66
	v_cvt_f32_ubyte1_e32 v66, v205
	v_rcp_iflag_f32_e32 v211, v66
	v_cvt_f32_ubyte3_e32 v223, v202
	v_cvt_f32_ubyte2_e32 v222, v202
	v_cvt_f32_ubyte2_e32 v66, v205
	v_pk_mul_f32 v[220:221], v[220:221], v[222:223]
	v_rcp_iflag_f32_e32 v204, v66
	v_cvt_f32_ubyte3_e32 v66, v205
	v_cvt_f32_ubyte1_e32 v223, v203
	v_cvt_f32_ubyte0_e32 v222, v203
	v_pk_mul_f32 v[116:117], v[116:117], v[220:221]
	v_rcp_iflag_f32_e32 v205, v66
	v_cvt_f32_ubyte3_e32 v221, v203
	v_cvt_f32_ubyte2_e32 v220, v203
	v_pk_mul_f32 v[202:203], v[210:211], v[222:223]
	s_waitcnt vmcnt(25)
	v_cvt_f32_ubyte0_e32 v66, v200
	v_pk_mul_f32 v[110:111], v[110:111], v[202:203]
	v_rcp_iflag_f32_e32 v202, v66
	v_cvt_f32_ubyte1_e32 v66, v200
	v_rcp_iflag_f32_e32 v203, v66
	v_pk_mul_f32 v[204:205], v[204:205], v[220:221]
	v_cvt_f32_ubyte2_e32 v66, v200
	v_pk_mul_f32 v[112:113], v[112:113], v[204:205]
	v_rcp_iflag_f32_e32 v204, v66
	v_cvt_f32_ubyte3_e32 v66, v200
	s_waitcnt vmcnt(24)
; __device__ __forceinline__ float gate_v(unsigned q) { return (float)q; }
;     __device__ __forceinline__ void mid(f32x4 (&acc)[2][2][4][2], const Unit& u, int seg, int wr, int wc, int fr, int fq) const {
;     ...
;         for (int ai = 0; ai < 2; ++ai)
; #pragma unroll
;             for (int m = 0; m < 4; ++m)
; #pragma unroll
;                 for (int bj = 0; bj < 2; ++bj)
; #pragma unroll
;                     for (int e = 0; e < 8; ++e) { const unsigned a = (ga[ai][m][bj][e >> 2] >> (8 * (e & 3))) & 255u, b = (gb[ai][m][bj][e >> 2] >> (8 * (e & 3))) & 255u;
;                         acc[ai][bj][m][e >> 2][e & 3] *= gate_v(a) * __builtin_amdgcn_rcpf(gate_v(b)); }
	v_cvt_f32_ubyte1_e32 v221, v198
	v_cvt_f32_ubyte0_e32 v220, v198
	v_rcp_iflag_f32_e32 v205, v66
	v_pk_mul_f32 v[202:203], v[202:203], v[220:221]
	v_cvt_f32_ubyte0_e32 v66, v201
	v_pk_mul_f32 v[106:107], v[106:107], v[202:203]
	v_rcp_iflag_f32_e32 v202, v66
	v_cvt_f32_ubyte1_e32 v66, v201
	v_rcp_iflag_f32_e32 v203, v66
	v_cvt_f32_ubyte3_e32 v211, v198
	v_cvt_f32_ubyte2_e32 v210, v198
	v_cvt_f32_ubyte2_e32 v66, v201
	v_pk_mul_f32 v[204:205], v[204:205], v[210:211]
	v_rcp_iflag_f32_e32 v200, v66
	v_cvt_f32_ubyte3_e32 v66, v201
	v_cvt_f32_ubyte1_e32 v211, v199
	v_cvt_f32_ubyte0_e32 v210, v199
	v_pk_mul_f32 v[108:109], v[108:109], v[204:205]
	v_rcp_iflag_f32_e32 v201, v66
	v_cvt_f32_ubyte3_e32 v205, v199
	v_cvt_f32_ubyte2_e32 v204, v199
	v_pk_mul_f32 v[198:199], v[202:203], v[210:211]
	s_waitcnt vmcnt(22)
	v_cvt_f32_ubyte0_e32 v66, v196
	v_pk_mul_f32 v[102:103], v[102:103], v[198:199]
	v_rcp_iflag_f32_e32 v198, v66
	v_cvt_f32_ubyte1_e32 v66, v196
	v_rcp_iflag_f32_e32 v199, v66
	v_pk_mul_f32 v[200:201], v[200:201], v[204:205]
	v_cvt_f32_ubyte2_e32 v66, v196
	v_pk_mul_f32 v[104:105], v[104:105], v[200:201]
	v_rcp_iflag_f32_e32 v200, v66
	v_cvt_f32_ubyte3_e32 v66, v196
	v_cvt_f32_ubyte1_e32 v205, v194
	v_cvt_f32_ubyte0_e32 v204, v194
	v_rcp_iflag_f32_e32 v201, v66
	v_pk_mul_f32 v[198:199], v[198:199], v[204:205]
	v_cvt_f32_ubyte0_e32 v66, v197
	v_pk_mul_f32 v[98:99], v[98:99], v[198:199]
	v_rcp_iflag_f32_e32 v198, v66
	v_cvt_f32_ubyte1_e32 v66, v197
	v_rcp_iflag_f32_e32 v199, v66
	v_cvt_f32_ubyte3_e32 v203, v194
	v_cvt_f32_ubyte2_e32 v202, v194
	v_cvt_f32_ubyte2_e32 v66, v197
	v_pk_mul_f32 v[200:201], v[200:201], v[202:203]
	v_rcp_iflag_f32_e32 v196, v66
	v_cvt_f32_ubyte3_e32 v66, v197
	v_cvt_f32_ubyte1_e32 v203, v195
	v_cvt_f32_ubyte0_e32 v202, v195
	v_pk_mul_f32 v[100:101], v[100:101], v[200:201]
	v_rcp_iflag_f32_e32 v197, v66
	v_cvt_f32_ubyte3_e32 v201, v195
	v_cvt_f32_ubyte2_e32 v200, v195
	v_pk_mul_f32 v[194:195], v[198:199], v[202:203]
	s_waitcnt vmcnt(21)
	v_cvt_f32_ubyte0_e32 v66, v192
	v_pk_mul_f32 v[94:95], v[94:95], v[194:195]
	v_rcp_iflag_f32_e32 v194, v66
	v_cvt_f32_ubyte1_e32 v66, v192
	v_rcp_iflag_f32_e32 v195, v66
	v_pk_mul_f32 v[196:197], v[196:197], v[200:201]
	v_cvt_f32_ubyte2_e32 v66, v192
	v_pk_mul_f32 v[96:97], v[96:97], v[196:197]
	v_rcp_iflag_f32_e32 v196, v66
	v_cvt_f32_ubyte3_e32 v66, v192
	s_waitcnt vmcnt(20)
	v_cvt_f32_ubyte1_e32 v201, v190
	v_cvt_f32_ubyte0_e32 v200, v190
	v_rcp_iflag_f32_e32 v197, v66
	v_pk_mul_f32 v[194:195], v[194:195], v[200:201]
	v_cvt_f32_ubyte0_e32 v66, v193
	v_pk_mul_f32 v[90:91], v[90:91], v[194:195]
	v_rcp_iflag_f32_e32 v194, v66
	v_cvt_f32_ubyte1_e32 v66, v193
	v_rcp_iflag_f32_e32 v195, v66
	v_cvt_f32_ubyte3_e32 v199, v190
	v_cvt_f32_ubyte2_e32 v198, v190
	v_cvt_f32_ubyte2_e32 v66, v193
	v_pk_mul_f32 v[196:197], v[196:197], v[198:199]
	v_rcp_iflag_f32_e32 v192, v66
	v_cvt_f32_ubyte3_e32 v66, v193
	v_cvt_f32_ubyte1_e32 v199, v191
	v_cvt_f32_ubyte0_e32 v198, v191
	v_pk_mul_f32 v[92:93], v[92:93], v[196:197]
	v_rcp_iflag_f32_e32 v193, v66
	v_cvt_f32_ubyte3_e32 v197, v191
	v_cvt_f32_ubyte2_e32 v196, v191
	v_pk_mul_f32 v[190:191], v[194:195], v[198:199]
	s_waitcnt vmcnt(18)
	v_cvt_f32_ubyte0_e32 v66, v188
	v_pk_mul_f32 v[86:87], v[86:87], v[190:191]
	v_rcp_iflag_f32_e32 v190, v66
	v_cvt_f32_ubyte1_e32 v66, v188
	v_rcp_iflag_f32_e32 v191, v66
	v_pk_mul_f32 v[192:193], v[192:193], v[196:197]
	v_cvt_f32_ubyte2_e32 v66, v188
	v_pk_mul_f32 v[88:89], v[88:89], v[192:193]
	v_rcp_iflag_f32_e32 v192, v66
	v_cvt_f32_ubyte3_e32 v66, v188
	v_cvt_f32_ubyte1_e32 v197, v186
	v_cvt_f32_ubyte0_e32 v196, v186
	v_rcp_iflag_f32_e32 v193, v66
	v_pk_mul_f32 v[190:191], v[190:191], v[196:197]
	v_cvt_f32_ubyte0_e32 v66, v189
	v_pk_mul_f32 v[82:83], v[82:83], v[190:191]
	v_rcp_iflag_f32_e32 v190, v66
	v_cvt_f32_ubyte1_e32 v66, v189
	v_rcp_iflag_f32_e32 v191, v66
	v_cvt_f32_ubyte3_e32 v195, v186
	v_cvt_f32_ubyte2_e32 v194, v186
	v_cvt_f32_ubyte2_e32 v66, v189
	v_pk_mul_f32 v[192:193], v[192:193], v[194:195]
	v_rcp_iflag_f32_e32 v188, v66
	v_cvt_f32_ubyte3_e32 v66, v189
	v_cvt_f32_ubyte1_e32 v195, v187
	v_cvt_f32_ubyte0_e32 v194, v187
	v_pk_mul_f32 v[84:85], v[84:85], v[192:193]
	v_rcp_iflag_f32_e32 v189, v66
	v_cvt_f32_ubyte3_e32 v193, v187
	v_cvt_f32_ubyte2_e32 v192, v187
	v_pk_mul_f32 v[186:187], v[190:191], v[194:195]
	s_waitcnt vmcnt(17)
	v_cvt_f32_ubyte0_e32 v66, v184
	v_pk_mul_f32 v[78:79], v[78:79], v[186:187]
	v_rcp_iflag_f32_e32 v186, v66
	v_cvt_f32_ubyte1_e32 v66, v184
	v_rcp_iflag_f32_e32 v187, v66
	v_pk_mul_f32 v[188:189], v[188:189], v[192:193]
	v_cvt_f32_ubyte2_e32 v66, v184
	v_pk_mul_f32 v[80:81], v[80:81], v[188:189]
	v_rcp_iflag_f32_e32 v188, v66
	v_cvt_f32_ubyte3_e32 v66, v184
	s_waitcnt vmcnt(16)
	v_cvt_f32_ubyte1_e32 v193, v182
	v_cvt_f32_ubyte0_e32 v192, v182
	v_rcp_iflag_f32_e32 v189, v66
	v_pk_mul_f32 v[186:187], v[186:187], v[192:193]
	v_cvt_f32_ubyte0_e32 v66, v185
	v_pk_mul_f32 v[74:75], v[74:75], v[186:187]
	v_rcp_iflag_f32_e32 v186, v66
	v_cvt_f32_ubyte1_e32 v66, v185
	v_rcp_iflag_f32_e32 v187, v66
	v_cvt_f32_ubyte3_e32 v191, v182
	v_cvt_f32_ubyte2_e32 v190, v182
	v_cvt_f32_ubyte2_e32 v66, v185
	v_pk_mul_f32 v[188:189], v[188:189], v[190:191]
	v_rcp_iflag_f32_e32 v184, v66
	v_cvt_f32_ubyte3_e32 v66, v185
	v_cvt_f32_ubyte1_e32 v191, v183
	v_cvt_f32_ubyte0_e32 v190, v183
	v_pk_mul_f32 v[76:77], v[76:77], v[188:189]
	v_rcp_iflag_f32_e32 v185, v66
	v_cvt_f32_ubyte3_e32 v189, v183
	v_cvt_f32_ubyte2_e32 v188, v183
	v_pk_mul_f32 v[182:183], v[186:187], v[190:191]
	s_waitcnt vmcnt(14)
; __device__ __forceinline__ float gate_v(unsigned q) { return (float)q; }
;     __device__ __forceinline__ void mid(f32x4 (&acc)[2][2][4][2], const Unit& u, int seg, int wr, int wc, int fr, int fq) const {
;     ...
;         for (int ai = 0; ai < 2; ++ai)
; #pragma unroll
;             for (int m = 0; m < 4; ++m)
; #pragma unroll
;                 for (int bj = 0; bj < 2; ++bj)
; #pragma unroll
;                     for (int e = 0; e < 8; ++e) { const unsigned a = (ga[ai][m][bj][e >> 2] >> (8 * (e & 3))) & 255u, b = (gb[ai][m][bj][e >> 2] >> (8 * (e & 3))) & 255u;
;                         acc[ai][bj][m][e >> 2][e & 3] *= gate_v(a) * __builtin_amdgcn_rcpf(gate_v(b)); }
	v_cvt_f32_ubyte0_e32 v66, v180
	v_pk_mul_f32 v[70:71], v[70:71], v[182:183]
	v_rcp_iflag_f32_e32 v182, v66
	v_cvt_f32_ubyte1_e32 v66, v180
	v_rcp_iflag_f32_e32 v183, v66
	v_pk_mul_f32 v[184:185], v[184:185], v[188:189]
	v_cvt_f32_ubyte2_e32 v66, v180
	v_pk_mul_f32 v[72:73], v[72:73], v[184:185]
	v_rcp_iflag_f32_e32 v184, v66
	v_cvt_f32_ubyte3_e32 v66, v180
	v_cvt_f32_ubyte1_e32 v189, v178
	v_cvt_f32_ubyte0_e32 v188, v178
	v_rcp_iflag_f32_e32 v185, v66
	v_pk_mul_f32 v[182:183], v[182:183], v[188:189]
	v_cvt_f32_ubyte0_e32 v66, v181
	v_pk_mul_f32 v[62:63], v[62:63], v[182:183]
	v_rcp_iflag_f32_e32 v182, v66
	v_cvt_f32_ubyte1_e32 v66, v181
	v_rcp_iflag_f32_e32 v183, v66
	v_cvt_f32_ubyte3_e32 v187, v178
	v_cvt_f32_ubyte2_e32 v186, v178
	v_cvt_f32_ubyte2_e32 v66, v181
	v_pk_mul_f32 v[184:185], v[184:185], v[186:187]
	v_rcp_iflag_f32_e32 v180, v66
	v_cvt_f32_ubyte3_e32 v66, v181
	v_cvt_f32_ubyte1_e32 v187, v179
	v_cvt_f32_ubyte0_e32 v186, v179
	v_pk_mul_f32 v[64:65], v[64:65], v[184:185]
	v_rcp_iflag_f32_e32 v181, v66
	v_cvt_f32_ubyte3_e32 v185, v179
	v_cvt_f32_ubyte2_e32 v184, v179
	v_pk_mul_f32 v[178:179], v[182:183], v[186:187]
	s_waitcnt vmcnt(13)
	v_cvt_f32_ubyte0_e32 v66, v176
	v_pk_mul_f32 v[58:59], v[58:59], v[178:179]
	v_rcp_iflag_f32_e32 v178, v66
	v_cvt_f32_ubyte1_e32 v66, v176
	v_rcp_iflag_f32_e32 v179, v66
	v_pk_mul_f32 v[180:181], v[180:181], v[184:185]
	v_cvt_f32_ubyte2_e32 v66, v176
	v_pk_mul_f32 v[60:61], v[60:61], v[180:181]
	v_rcp_iflag_f32_e32 v180, v66
	v_cvt_f32_ubyte3_e32 v66, v176
	s_waitcnt vmcnt(12)
	v_cvt_f32_ubyte1_e32 v185, v174
	v_cvt_f32_ubyte0_e32 v184, v174
	v_rcp_iflag_f32_e32 v181, v66
	v_pk_mul_f32 v[178:179], v[178:179], v[184:185]
	v_cvt_f32_ubyte0_e32 v66, v177
	v_pk_mul_f32 v[54:55], v[54:55], v[178:179]
	v_rcp_iflag_f32_e32 v178, v66
	v_cvt_f32_ubyte1_e32 v66, v177
	v_rcp_iflag_f32_e32 v179, v66
	v_cvt_f32_ubyte3_e32 v183, v174
	v_cvt_f32_ubyte2_e32 v182, v174
	v_cvt_f32_ubyte2_e32 v66, v177
	v_pk_mul_f32 v[180:181], v[180:181], v[182:183]
	v_rcp_iflag_f32_e32 v176, v66
	v_cvt_f32_ubyte3_e32 v66, v177
	v_cvt_f32_ubyte1_e32 v183, v175
	v_cvt_f32_ubyte0_e32 v182, v175
	v_pk_mul_f32 v[56:57], v[56:57], v[180:181]
	v_rcp_iflag_f32_e32 v177, v66
	v_cvt_f32_ubyte3_e32 v181, v175
	v_cvt_f32_ubyte2_e32 v180, v175
	v_pk_mul_f32 v[174:175], v[178:179], v[182:183]
	s_waitcnt vmcnt(10)
	v_cvt_f32_ubyte0_e32 v66, v172
	v_pk_mul_f32 v[50:51], v[50:51], v[174:175]
	v_rcp_iflag_f32_e32 v174, v66
	v_cvt_f32_ubyte1_e32 v66, v172
	v_rcp_iflag_f32_e32 v175, v66
	v_pk_mul_f32 v[176:177], v[176:177], v[180:181]
	v_cvt_f32_ubyte2_e32 v66, v172
	v_pk_mul_f32 v[52:53], v[52:53], v[176:177]
	v_rcp_iflag_f32_e32 v176, v66
	v_cvt_f32_ubyte3_e32 v66, v172
	v_cvt_f32_ubyte1_e32 v181, v170
	v_cvt_f32_ubyte0_e32 v180, v170
	v_rcp_iflag_f32_e32 v177, v66
	v_pk_mul_f32 v[174:175], v[174:175], v[180:181]
	v_cvt_f32_ubyte0_e32 v66, v173
	v_pk_mul_f32 v[46:47], v[46:47], v[174:175]
	v_rcp_iflag_f32_e32 v174, v66
	v_cvt_f32_ubyte1_e32 v66, v173
	v_rcp_iflag_f32_e32 v175, v66
	v_cvt_f32_ubyte3_e32 v179, v170
	v_cvt_f32_ubyte2_e32 v178, v170
	v_cvt_f32_ubyte2_e32 v66, v173
	v_pk_mul_f32 v[176:177], v[176:177], v[178:179]
	v_rcp_iflag_f32_e32 v172, v66
	v_cvt_f32_ubyte3_e32 v66, v173
	v_cvt_f32_ubyte1_e32 v179, v171
	v_cvt_f32_ubyte0_e32 v178, v171
	v_pk_mul_f32 v[48:49], v[48:49], v[176:177]
	v_rcp_iflag_f32_e32 v173, v66
	v_cvt_f32_ubyte3_e32 v177, v171
	v_cvt_f32_ubyte2_e32 v176, v171
	v_pk_mul_f32 v[170:171], v[174:175], v[178:179]
	s_waitcnt vmcnt(9)
	v_cvt_f32_ubyte0_e32 v66, v168
	v_pk_mul_f32 v[42:43], v[42:43], v[170:171]
	v_rcp_iflag_f32_e32 v170, v66
	v_cvt_f32_ubyte1_e32 v66, v168
	v_rcp_iflag_f32_e32 v171, v66
	v_pk_mul_f32 v[172:173], v[172:173], v[176:177]
	v_cvt_f32_ubyte2_e32 v66, v168
	v_pk_mul_f32 v[44:45], v[44:45], v[172:173]
	v_rcp_iflag_f32_e32 v172, v66
	v_cvt_f32_ubyte3_e32 v66, v168
	s_waitcnt vmcnt(8)
	v_cvt_f32_ubyte1_e32 v177, v166
	v_cvt_f32_ubyte0_e32 v176, v166
	v_rcp_iflag_f32_e32 v173, v66
	v_pk_mul_f32 v[170:171], v[170:171], v[176:177]
	v_cvt_f32_ubyte0_e32 v66, v169
	v_pk_mul_f32 v[38:39], v[38:39], v[170:171]
	v_rcp_iflag_f32_e32 v170, v66
	v_cvt_f32_ubyte1_e32 v66, v169
	v_rcp_iflag_f32_e32 v171, v66
	v_cvt_f32_ubyte3_e32 v175, v166
	v_cvt_f32_ubyte2_e32 v174, v166
	v_cvt_f32_ubyte2_e32 v66, v169
	v_pk_mul_f32 v[172:173], v[172:173], v[174:175]
	v_rcp_iflag_f32_e32 v168, v66
	v_cvt_f32_ubyte3_e32 v66, v169
	v_cvt_f32_ubyte1_e32 v175, v167
	v_cvt_f32_ubyte0_e32 v174, v167
	v_pk_mul_f32 v[40:41], v[40:41], v[172:173]
	v_rcp_iflag_f32_e32 v169, v66
	v_cvt_f32_ubyte3_e32 v173, v167
	v_cvt_f32_ubyte2_e32 v172, v167
	v_pk_mul_f32 v[166:167], v[170:171], v[174:175]
	s_waitcnt vmcnt(6)
; __device__ __forceinline__ float gate_v(unsigned q) { return (float)q; }
;     __device__ __forceinline__ void mid(f32x4 (&acc)[2][2][4][2], const Unit& u, int seg, int wr, int wc, int fr, int fq) const {
;     ...
;         for (int ai = 0; ai < 2; ++ai)
; #pragma unroll
;             for (int m = 0; m < 4; ++m)
; #pragma unroll
;                 for (int bj = 0; bj < 2; ++bj)
; #pragma unroll
;                     for (int e = 0; e < 8; ++e) { const unsigned a = (ga[ai][m][bj][e >> 2] >> (8 * (e & 3))) & 255u, b = (gb[ai][m][bj][e >> 2] >> (8 * (e & 3))) & 255u;
;                         acc[ai][bj][m][e >> 2][e & 3] *= gate_v(a) * __builtin_amdgcn_rcpf(gate_v(b)); }
;         asm volatile("" ::: "memory");
	v_cvt_f32_ubyte0_e32 v66, v164
	v_pk_mul_f32 v[34:35], v[34:35], v[166:167]
	v_rcp_iflag_f32_e32 v166, v66
	v_cvt_f32_ubyte1_e32 v66, v164
	v_rcp_iflag_f32_e32 v167, v66
	v_pk_mul_f32 v[168:169], v[168:169], v[172:173]
	v_cvt_f32_ubyte2_e32 v66, v164
	v_pk_mul_f32 v[36:37], v[36:37], v[168:169]
	v_rcp_iflag_f32_e32 v168, v66
	v_cvt_f32_ubyte3_e32 v66, v164
	v_cvt_f32_ubyte1_e32 v173, v162
	v_cvt_f32_ubyte0_e32 v172, v162
	v_rcp_iflag_f32_e32 v169, v66
	v_pk_mul_f32 v[166:167], v[166:167], v[172:173]
	v_cvt_f32_ubyte0_e32 v66, v165
	v_pk_mul_f32 v[30:31], v[30:31], v[166:167]
	v_rcp_iflag_f32_e32 v166, v66
	v_cvt_f32_ubyte1_e32 v66, v165
	v_rcp_iflag_f32_e32 v167, v66
	v_cvt_f32_ubyte3_e32 v171, v162
	v_cvt_f32_ubyte2_e32 v170, v162
	v_cvt_f32_ubyte2_e32 v66, v165
	v_pk_mul_f32 v[168:169], v[168:169], v[170:171]
	v_rcp_iflag_f32_e32 v164, v66
	v_cvt_f32_ubyte3_e32 v66, v165
	v_cvt_f32_ubyte1_e32 v171, v163
	v_cvt_f32_ubyte0_e32 v170, v163
	v_pk_mul_f32 v[32:33], v[32:33], v[168:169]
	v_rcp_iflag_f32_e32 v165, v66
	v_cvt_f32_ubyte3_e32 v169, v163
	v_cvt_f32_ubyte2_e32 v168, v163
	v_pk_mul_f32 v[162:163], v[166:167], v[170:171]
	s_waitcnt vmcnt(5)
	v_cvt_f32_ubyte0_e32 v66, v160
	v_pk_mul_f32 v[26:27], v[26:27], v[162:163]
	v_rcp_iflag_f32_e32 v162, v66
	v_cvt_f32_ubyte1_e32 v66, v160
	v_rcp_iflag_f32_e32 v163, v66
	v_pk_mul_f32 v[164:165], v[164:165], v[168:169]
	v_cvt_f32_ubyte2_e32 v66, v160
	v_pk_mul_f32 v[28:29], v[28:29], v[164:165]
	v_rcp_iflag_f32_e32 v164, v66
	v_cvt_f32_ubyte3_e32 v66, v160
	s_waitcnt vmcnt(4)
	v_cvt_f32_ubyte1_e32 v169, v158
	v_cvt_f32_ubyte0_e32 v168, v158
	v_rcp_iflag_f32_e32 v165, v66
	v_pk_mul_f32 v[162:163], v[162:163], v[168:169]
	v_cvt_f32_ubyte0_e32 v66, v161
	v_pk_mul_f32 v[22:23], v[22:23], v[162:163]
	v_rcp_iflag_f32_e32 v162, v66
	v_cvt_f32_ubyte1_e32 v66, v161
	v_rcp_iflag_f32_e32 v163, v66
	v_cvt_f32_ubyte3_e32 v167, v158
	v_cvt_f32_ubyte2_e32 v166, v158
	v_cvt_f32_ubyte2_e32 v66, v161
	v_pk_mul_f32 v[164:165], v[164:165], v[166:167]
	v_rcp_iflag_f32_e32 v160, v66
	v_cvt_f32_ubyte3_e32 v66, v161
	v_cvt_f32_ubyte1_e32 v167, v159
	v_cvt_f32_ubyte0_e32 v166, v159
	v_pk_mul_f32 v[24:25], v[24:25], v[164:165]
	v_rcp_iflag_f32_e32 v161, v66
	v_cvt_f32_ubyte3_e32 v165, v159
	v_cvt_f32_ubyte2_e32 v164, v159
	v_pk_mul_f32 v[158:159], v[162:163], v[166:167]
	s_waitcnt vmcnt(2)
	v_cvt_f32_ubyte0_e32 v66, v156
	v_pk_mul_f32 v[18:19], v[18:19], v[158:159]
	v_rcp_iflag_f32_e32 v158, v66
	v_cvt_f32_ubyte1_e32 v66, v156
	v_rcp_iflag_f32_e32 v159, v66
	v_pk_mul_f32 v[160:161], v[160:161], v[164:165]
	v_cvt_f32_ubyte2_e32 v66, v156
	v_pk_mul_f32 v[20:21], v[20:21], v[160:161]
	v_rcp_iflag_f32_e32 v160, v66
	v_cvt_f32_ubyte3_e32 v66, v156
	v_cvt_f32_ubyte1_e32 v165, v154
	v_cvt_f32_ubyte0_e32 v164, v154
	v_rcp_iflag_f32_e32 v161, v66
	v_pk_mul_f32 v[158:159], v[158:159], v[164:165]
	v_cvt_f32_ubyte0_e32 v66, v157
	v_pk_mul_f32 v[14:15], v[14:15], v[158:159]
	v_rcp_iflag_f32_e32 v158, v66
	v_cvt_f32_ubyte1_e32 v66, v157
	v_rcp_iflag_f32_e32 v159, v66
	v_cvt_f32_ubyte3_e32 v163, v154
	v_cvt_f32_ubyte2_e32 v162, v154
	v_cvt_f32_ubyte2_e32 v66, v157
	v_pk_mul_f32 v[160:161], v[160:161], v[162:163]
	v_rcp_iflag_f32_e32 v156, v66
	v_cvt_f32_ubyte3_e32 v66, v157
	v_cvt_f32_ubyte1_e32 v163, v155
	v_cvt_f32_ubyte0_e32 v162, v155
	v_pk_mul_f32 v[16:17], v[16:17], v[160:161]
	v_rcp_iflag_f32_e32 v157, v66
	v_cvt_f32_ubyte3_e32 v161, v155
	v_cvt_f32_ubyte2_e32 v160, v155
	v_pk_mul_f32 v[154:155], v[158:159], v[162:163]
	s_waitcnt vmcnt(1)
	v_cvt_f32_ubyte0_e32 v66, v152
	v_pk_mul_f32 v[10:11], v[10:11], v[154:155]
	v_rcp_iflag_f32_e32 v154, v66
	v_cvt_f32_ubyte1_e32 v66, v152
	v_rcp_iflag_f32_e32 v155, v66
	v_pk_mul_f32 v[156:157], v[156:157], v[160:161]
	v_cvt_f32_ubyte2_e32 v66, v152
	v_pk_mul_f32 v[12:13], v[12:13], v[156:157]
	v_rcp_iflag_f32_e32 v156, v66
	v_cvt_f32_ubyte3_e32 v66, v152
	s_waitcnt vmcnt(0)
	v_cvt_f32_ubyte1_e32 v161, v68
	v_cvt_f32_ubyte0_e32 v160, v68
	v_rcp_iflag_f32_e32 v157, v66
	v_pk_mul_f32 v[154:155], v[154:155], v[160:161]
	v_cvt_f32_ubyte0_e32 v66, v153
	v_pk_mul_f32 v[6:7], v[6:7], v[154:155]
	v_rcp_iflag_f32_e32 v154, v66
	v_cvt_f32_ubyte1_e32 v66, v153
	v_rcp_iflag_f32_e32 v155, v66
	v_cvt_f32_ubyte2_e32 v66, v153
	v_rcp_iflag_f32_e32 v152, v66
	v_cvt_f32_ubyte3_e32 v66, v153
	v_rcp_iflag_f32_e32 v153, v66
	v_cvt_f32_ubyte3_e32 v159, v68
	v_cvt_f32_ubyte2_e32 v158, v68
	v_pk_mul_f32 v[156:157], v[156:157], v[158:159]
	v_cvt_f32_ubyte1_e32 v159, v69
	v_pk_mul_f32 v[8:9], v[8:9], v[156:157]
	v_cvt_f32_ubyte3_e32 v157, v69
	v_cvt_f32_ubyte2_e32 v156, v69
	v_cvt_f32_ubyte0_e32 v158, v69
	v_pk_mul_f32 v[68:69], v[154:155], v[158:159]
	v_pk_mul_f32 v[152:153], v[152:153], v[156:157]
	v_pk_mul_f32 v[2:3], v[2:3], v[68:69]
	v_pk_mul_f32 v[4:5], v[4:5], v[152:153]
	s_branch .LBB0_781

; #define PG8_STAGE(bufoff, gbase, voff) do { _Pragma("unroll") for (int _i = 0; _i < 2; ++_i) \
;         __builtin_amdgcn_global_load_lds((const unsigned*)((const char*)(gbase) + (voff)[_i]), (PG8_LAS unsigned*)(lds + (bufoff) + ldsw + _i * 8192), 16, 0, 0); } while (0)
; #define PG8_LDA(dst, b, h) do { _Pragma("unroll") for (int m = 0; m < 4; ++m) _Pragma("unroll") for (int k = 0; k < 2; ++k) dst[m][k] = *(const PG8_LAS bf16x8*)(lds + PG8_SA(b, h) + aoff + m * 2048 + k * 1024); } while (0)
; #define PG8_LDB(dst, b, h) do { _Pragma("unroll") for (int n = 0; n < 2; ++n) _Pragma("unroll") for (int k = 0; k < 2; ++k) dst[n][k] = *(const PG8_LAS bf16x8*)(lds + PG8_SB(b, h) + boff + n * 2048 + k * 1024); } while (0)
; #define PG8_MMA(ai, bj, At, Bt) do { __builtin_amdgcn_s_setprio(1); _Pragma("unroll") for (int m = 0; m < 4; ++m) _Pragma("unroll") for (int n = 0; n < 2; ++n) _Pragma("unroll") for (int k = 0; k < 2; ++k) \
;         acc[ai][bj][m][n] = __builtin_amdgcn_mfma_f32_16x16x32_bf16(Bt[n][k], At[m][k], acc[ai][bj][m][n], 0, 0, 0); __builtin_amdgcn_s_setprio(0); } while (0)
; #define PG8_WAIT_V(n) asm volatile("s_waitcnt vmcnt(" #n ")" ::: "memory")
; template <class Epi, class Sched, bool ALIGN_EPI = false, bool SP2 = false>
; __device__ __forceinline__ void gemm_phase(PG8_LAS unsigned char* lds, const Gemm g, const Sched& S, const Epi& E) {
;     ...
;             PG8_LDB(B0, 0, 0); PG8_LDB(B1, 0, 1); PG8_SCHED; PG8_LDA(At, 0, 0); PG8_STAGE(PG8_SA(1, 1), a1 + hstep, voffA);
;             PG8_WAIT_V(8); PG8_WAIT_L(0); PG8_BAR; PG8_MMA(0, 0, At, B0); PG8_MMA(0, 1, At, B1); PG8_BAR; PG8_SCHED;
;             PG8_LDA(At, 0, 1); PG8_STAGE(PG8_SB(0, 0), b2, voffB); PG8_STAGE(PG8_SB(0, 1), b2 + hstep, voffB); PG8_STAGE(PG8_SA(0, 0), a2, voffA);
;             PG8_WAIT_V(8); PG8_WAIT_L(0); PG8_BAR; PG8_MMA(1, 0, At, B0); PG8_MMA(1, 1, At, B1); PG8_BAR; PG8_SCHED;
;             PG8_LDB(B0, 1, 0); PG8_LDB(B1, 1, 1); PG8_SCHED; PG8_LDA(At, 1, 0); PG8_STAGE(PG8_SA(0, 1), a2 + hstep, voffA);
;             PG8_WAIT_V(8); PG8_WAIT_L(0); PG8_BAR; PG8_MMA(0, 0, At, B0); PG8_MMA(0, 1, At, B1); PG8_BAR; PG8_SCHED;
;             PG8_LDA(At, 1, 1); PG8_STAGE(PG8_SB(1, 0), b3, voffB); PG8_STAGE(PG8_SB(1, 1), b3 + hstep, voffB); PG8_STAGE(PG8_SA(1, 0), a3, voffA);
;             PG8_WAIT_V(8); PG8_WAIT_L(0); PG8_BAR; PG8_MMA(1, 0, At, B0); PG8_MMA(1, 1, At, B1); PG8_BAR; PG8_SCHED;
.LBB0_802:
	s_add_u32 s22, s20, 0x100
	s_addc_u32 s23, s21, 0
	s_cmp_eq_u32 s43, 4
	s_cselect_b32 s27, s19, s23
	s_cselect_b32 s26, s18, s22
	s_cselect_b32 s25, s17, s15
	s_cselect_b32 s24, s16, s13
	s_add_i32 s44, 0, 0x10000
	s_add_i32 s45, 0, 0x14000
	v_add_u32_e32 v168, s44, v0
	v_add_u32_e32 v184, s45, v0
	ds_read_b128 v[156:159], v168
	ds_read_b128 v[160:163], v168 offset:1024
	ds_read_b128 v[164:167], v168 offset:2048
	ds_read_b128 v[168:171], v168 offset:3072
	ds_read_b128 v[172:175], v184
	ds_read_b128 v[176:179], v184 offset:1024
	ds_read_b128 v[180:183], v184 offset:2048
	ds_read_b128 v[184:187], v184 offset:3072
	v_lshl_add_u64 v[228:229], s[20:21], 0, v[150:151]
	s_add_i32 m0, s30, 0xc000
	ds_read_b128 v[188:191], v155
	ds_read_b128 v[192:195], v155 offset:1024
	ds_read_b128 v[196:199], v155 offset:2048
	ds_read_b128 v[200:203], v155 offset:3072
	ds_read_b128 v[204:207], v155 offset:4096
	ds_read_b128 v[208:211], v155 offset:5120
	ds_read_b128 v[220:223], v155 offset:6144
	ds_read_b128 v[224:227], v155 offset:7168
	global_load_lds_dwordx4 v[228:229], off
	v_lshl_add_u64 v[228:229], s[20:21], 0, v[152:153]
	s_add_i32 m0, s30, 0xe000
	s_nop 0
	global_load_lds_dwordx4 v[228:229], off
	s_setprio 1
	s_nop 0
	s_waitcnt vmcnt(8) lgkmcnt(0)
	s_barrier
	v_mfma_f32_16x16x32_bf16 v[128:131], v[156:159], v[188:191], v[128:131]
	v_mfma_f32_16x16x32_bf16 v[124:127], v[164:167], v[188:191], v[124:127]
	v_mfma_f32_16x16x32_bf16 v[120:123], v[156:159], v[196:199], v[120:123]
	v_mfma_f32_16x16x32_bf16 v[116:119], v[164:167], v[196:199], v[116:119]
	v_mfma_f32_16x16x32_bf16 v[112:115], v[156:159], v[204:207], v[112:115]
	v_mfma_f32_16x16x32_bf16 v[108:111], v[164:167], v[204:207], v[108:111]
	v_mfma_f32_16x16x32_bf16 v[100:103], v[156:159], v[220:223], v[100:103]
	v_mfma_f32_16x16x32_bf16 v[92:95], v[164:167], v[220:223], v[92:95]
	v_mfma_f32_16x16x32_bf16 v[128:131], v[160:163], v[192:195], v[128:131]
	v_mfma_f32_16x16x32_bf16 v[124:127], v[168:171], v[192:195], v[124:127]
	v_mfma_f32_16x16x32_bf16 v[120:123], v[160:163], v[200:203], v[120:123]
	v_mfma_f32_16x16x32_bf16 v[116:119], v[168:171], v[200:203], v[116:119]
	v_mfma_f32_16x16x32_bf16 v[112:115], v[160:163], v[208:211], v[112:115]
	v_mfma_f32_16x16x32_bf16 v[108:111], v[168:171], v[208:211], v[108:111]
	v_mfma_f32_16x16x32_bf16 v[100:103], v[160:163], v[224:227], v[100:103]
	v_mfma_f32_16x16x32_bf16 v[92:95], v[168:171], v[224:227], v[92:95]
	v_mfma_f32_16x16x32_bf16 v[104:107], v[172:175], v[188:191], v[104:107]
	v_mfma_f32_16x16x32_bf16 v[96:99], v[180:183], v[188:191], v[96:99]
	v_mfma_f32_16x16x32_bf16 v[88:91], v[172:175], v[196:199], v[88:91]
	v_mfma_f32_16x16x32_bf16 v[84:87], v[180:183], v[196:199], v[84:87]
	v_mfma_f32_16x16x32_bf16 v[80:83], v[172:175], v[204:207], v[80:83]
	v_mfma_f32_16x16x32_bf16 v[76:79], v[180:183], v[204:207], v[76:79]
	v_mfma_f32_16x16x32_bf16 v[72:75], v[172:175], v[220:223], v[72:75]
	v_mfma_f32_16x16x32_bf16 v[68:71], v[180:183], v[220:223], v[68:71]
	v_mfma_f32_16x16x32_bf16 v[104:107], v[176:179], v[192:195], v[104:107]
	v_mfma_f32_16x16x32_bf16 v[96:99], v[184:187], v[192:195], v[96:99]
	v_mfma_f32_16x16x32_bf16 v[88:91], v[176:179], v[200:203], v[88:91]
	v_mfma_f32_16x16x32_bf16 v[84:87], v[184:187], v[200:203], v[84:87]
	v_mfma_f32_16x16x32_bf16 v[80:83], v[176:179], v[208:211], v[80:83]
	v_mfma_f32_16x16x32_bf16 v[76:79], v[184:187], v[208:211], v[76:79]
	v_mfma_f32_16x16x32_bf16 v[72:75], v[176:179], v[224:227], v[72:75]
	v_mfma_f32_16x16x32_bf16 v[68:71], v[184:187], v[224:227], v[68:71]
	s_barrier
	s_setprio 0
	s_setprio 1
	s_setprio 0
	s_waitcnt lgkmcnt(0)
	s_add_i32 s20, s44, s1
	v_lshl_add_u64 v[228:229], s[24:25], 0, v[66:67]
	s_mov_b32 m0, s20
	ds_read_b128 v[188:191], v155 offset:16384
	ds_read_b128 v[192:195], v155 offset:17408
	ds_read_b128 v[196:199], v155 offset:18432
	ds_read_b128 v[200:203], v155 offset:19456
	ds_read_b128 v[204:207], v155 offset:20480
	ds_read_b128 v[208:211], v155 offset:21504
	ds_read_b128 v[220:223], v155 offset:22528
	ds_read_b128 v[224:227], v155 offset:23552
	global_load_lds_dwordx4 v[228:229], off
	s_add_i32 m0, s20, 0x2000
	s_add_u32 s20, s24, 0x80000
	v_lshl_add_u64 v[230:231], s[24:25], 0, v[132:133]
	s_addc_u32 s21, s25, 0
	s_add_i32 s44, s45, s1
	global_load_lds_dwordx4 v[230:231], off
	v_lshl_add_u64 v[232:233], s[20:21], 0, v[66:67]
	s_mov_b32 m0, s44
	v_lshl_add_u64 v[234:235], s[26:27], 0, v[132:133]
	global_load_lds_dwordx4 v[232:233], off
	v_lshl_add_u64 v[232:233], s[20:21], 0, v[132:133]
	s_add_i32 m0, s44, 0x2000
	s_nop 0
	global_load_lds_dwordx4 v[232:233], off
	v_lshl_add_u64 v[232:233], s[26:27], 0, v[66:67]
	s_mov_b32 m0, s30
	s_nop 0
	global_load_lds_dwordx4 v[232:233], off
	s_mov_b32 m0, s31
	s_nop 0
	global_load_lds_dwordx4 v[234:235], off
	s_setprio 1
	s_nop 0
	s_waitcnt vmcnt(8) lgkmcnt(0)
	s_barrier
; #define PG8_STAGE(bufoff, gbase, voff) do { _Pragma("unroll") for (int _i = 0; _i < 2; ++_i) \
;         __builtin_amdgcn_global_load_lds((const unsigned*)((const char*)(gbase) + (voff)[_i]), (PG8_LAS unsigned*)(lds + (bufoff) + ldsw + _i * 8192), 16, 0, 0); } while (0)
; #define PG8_LDA(dst, b, h) do { _Pragma("unroll") for (int m = 0; m < 4; ++m) _Pragma("unroll") for (int k = 0; k < 2; ++k) dst[m][k] = *(const PG8_LAS bf16x8*)(lds + PG8_SA(b, h) + aoff + m * 2048 + k * 1024); } while (0)
; #define PG8_LDB(dst, b, h) do { _Pragma("unroll") for (int n = 0; n < 2; ++n) _Pragma("unroll") for (int k = 0; k < 2; ++k) dst[n][k] = *(const PG8_LAS bf16x8*)(lds + PG8_SB(b, h) + boff + n * 2048 + k * 1024); } while (0)
; #define PG8_MMA(ai, bj, At, Bt) do { __builtin_amdgcn_s_setprio(1); _Pragma("unroll") for (int m = 0; m < 4; ++m) _Pragma("unroll") for (int n = 0; n < 2; ++n) _Pragma("unroll") for (int k = 0; k < 2; ++k) \
;         acc[ai][bj][m][n] = __builtin_amdgcn_mfma_f32_16x16x32_bf16(Bt[n][k], At[m][k], acc[ai][bj][m][n], 0, 0, 0); __builtin_amdgcn_s_setprio(0); } while (0)
; #define PG8_WAIT_V(n) asm volatile("s_waitcnt vmcnt(" #n ")" ::: "memory")
; template <class Epi, class Sched, bool ALIGN_EPI = false, bool SP2 = false>
; __device__ __forceinline__ void gemm_phase(PG8_LAS unsigned char* lds, const Gemm g, const Sched& S, const Epi& E) {
;     ...
;             PG8_LDB(B0, 0, 0); PG8_LDB(B1, 0, 1); PG8_SCHED; PG8_LDA(At, 0, 0); PG8_STAGE(PG8_SA(1, 1), a1 + hstep, voffA);
;             PG8_WAIT_V(8); PG8_WAIT_L(0); PG8_BAR; PG8_MMA(0, 0, At, B0); PG8_MMA(0, 1, At, B1); PG8_BAR; PG8_SCHED;
;             PG8_LDA(At, 0, 1); PG8_STAGE(PG8_SB(0, 0), b2, voffB); PG8_STAGE(PG8_SB(0, 1), b2 + hstep, voffB); PG8_STAGE(PG8_SA(0, 0), a2, voffA);
;             PG8_WAIT_V(8); PG8_WAIT_L(0); PG8_BAR; PG8_MMA(1, 0, At, B0); PG8_MMA(1, 1, At, B1); PG8_BAR; PG8_SCHED;
;             PG8_LDB(B0, 1, 0); PG8_LDB(B1, 1, 1); PG8_SCHED; PG8_LDA(At, 1, 0); PG8_STAGE(PG8_SA(0, 1), a2 + hstep, voffA);
;             PG8_WAIT_V(8); PG8_WAIT_L(0); PG8_BAR; PG8_MMA(0, 0, At, B0); PG8_MMA(0, 1, At, B1); PG8_BAR; PG8_SCHED;
;             PG8_LDA(At, 1, 1); PG8_STAGE(PG8_SB(1, 0), b3, voffB); PG8_STAGE(PG8_SB(1, 1), b3 + hstep, voffB); PG8_STAGE(PG8_SA(1, 0), a3, voffA);
;             PG8_WAIT_V(8); PG8_WAIT_L(0); PG8_BAR; PG8_MMA(1, 0, At, B0); PG8_MMA(1, 1, At, B1); PG8_BAR; PG8_SCHED;
	v_mfma_f32_16x16x32_bf16 v[62:65], v[156:159], v[188:191], v[62:65]
	v_mfma_f32_16x16x32_bf16 v[58:61], v[164:167], v[188:191], v[58:61]
	v_mfma_f32_16x16x32_bf16 v[54:57], v[156:159], v[196:199], v[54:57]
	v_mfma_f32_16x16x32_bf16 v[50:53], v[164:167], v[196:199], v[50:53]
	v_mfma_f32_16x16x32_bf16 v[46:49], v[156:159], v[204:207], v[46:49]
	v_mfma_f32_16x16x32_bf16 v[42:45], v[164:167], v[204:207], v[42:45]
	v_mfma_f32_16x16x32_bf16 v[34:37], v[156:159], v[220:223], v[34:37]
	v_mfma_f32_16x16x32_bf16 v[26:29], v[164:167], v[220:223], v[26:29]
	v_mfma_f32_16x16x32_bf16 v[62:65], v[160:163], v[192:195], v[62:65]
	v_mfma_f32_16x16x32_bf16 v[58:61], v[168:171], v[192:195], v[58:61]
	v_mfma_f32_16x16x32_bf16 v[54:57], v[160:163], v[200:203], v[54:57]
	v_mfma_f32_16x16x32_bf16 v[50:53], v[168:171], v[200:203], v[50:53]
	v_mfma_f32_16x16x32_bf16 v[46:49], v[160:163], v[208:211], v[46:49]
	v_mfma_f32_16x16x32_bf16 v[42:45], v[168:171], v[208:211], v[42:45]
	v_mfma_f32_16x16x32_bf16 v[34:37], v[160:163], v[224:227], v[34:37]
	v_mfma_f32_16x16x32_bf16 v[26:29], v[168:171], v[224:227], v[26:29]
	v_mfma_f32_16x16x32_bf16 v[38:41], v[172:175], v[188:191], v[38:41]
	v_mfma_f32_16x16x32_bf16 v[30:33], v[180:183], v[188:191], v[30:33]
	v_mfma_f32_16x16x32_bf16 v[22:25], v[172:175], v[196:199], v[22:25]
	v_mfma_f32_16x16x32_bf16 v[18:21], v[180:183], v[196:199], v[18:21]
	v_mfma_f32_16x16x32_bf16 v[14:17], v[172:175], v[204:207], v[14:17]
	v_mfma_f32_16x16x32_bf16 v[10:13], v[180:183], v[204:207], v[10:13]
	v_mfma_f32_16x16x32_bf16 v[6:9], v[172:175], v[220:223], v[6:9]
	v_mfma_f32_16x16x32_bf16 v[2:5], v[180:183], v[220:223], v[2:5]
	v_mfma_f32_16x16x32_bf16 v[38:41], v[176:179], v[192:195], v[38:41]
	v_mfma_f32_16x16x32_bf16 v[30:33], v[184:187], v[192:195], v[30:33]
	v_mfma_f32_16x16x32_bf16 v[22:25], v[176:179], v[200:203], v[22:25]
	v_mfma_f32_16x16x32_bf16 v[18:21], v[184:187], v[200:203], v[18:21]
	v_mfma_f32_16x16x32_bf16 v[14:17], v[176:179], v[208:211], v[14:17]
	v_mfma_f32_16x16x32_bf16 v[10:13], v[184:187], v[208:211], v[10:13]
	v_mfma_f32_16x16x32_bf16 v[6:9], v[176:179], v[224:227], v[6:9]
	v_mfma_f32_16x16x32_bf16 v[2:5], v[184:187], v[224:227], v[2:5]
	s_barrier
	s_setprio 0
	s_setprio 1
	s_setprio 0
	s_waitcnt lgkmcnt(0)
	s_add_i32 s44, 0, 0x18000
	s_add_i32 s45, 0, 0x1c000
	v_add_u32_e32 v168, s44, v0
	v_add_u32_e32 v184, s45, v0
	ds_read_b128 v[156:159], v168
	ds_read_b128 v[160:163], v168 offset:1024
	ds_read_b128 v[164:167], v168 offset:2048
	ds_read_b128 v[168:171], v168 offset:3072
	ds_read_b128 v[172:175], v184
	ds_read_b128 v[176:179], v184 offset:1024
	ds_read_b128 v[180:183], v184 offset:2048
	ds_read_b128 v[184:187], v184 offset:3072
	s_add_u32 s20, s26, 0x80000
	s_addc_u32 s21, s27, 0
	s_mov_b32 m0, s34
	v_lshl_add_u64 v[246:247], s[20:21], 0, v[66:67]
	ds_read_b128 v[188:191], v155 offset:32768
	ds_read_b128 v[192:195], v155 offset:33792
	ds_read_b128 v[196:199], v155 offset:34816
	ds_read_b128 v[200:203], v155 offset:35840
	ds_read_b128 v[204:207], v155 offset:36864
	ds_read_b128 v[208:211], v155 offset:37888
	ds_read_b128 v[220:223], v155 offset:38912
	ds_read_b128 v[224:227], v155 offset:39936
	global_load_lds_dwordx4 v[246:247], off
	v_lshl_add_u64 v[246:247], s[20:21], 0, v[132:133]
	s_mov_b32 m0, s35
	s_nop 0
	global_load_lds_dwordx4 v[246:247], off
	s_setprio 1
	s_nop 0
	s_waitcnt vmcnt(8) lgkmcnt(0)
	s_barrier
	v_mfma_f32_16x16x32_bf16 v[128:131], v[156:159], v[188:191], v[128:131]
	v_mfma_f32_16x16x32_bf16 v[124:127], v[164:167], v[188:191], v[124:127]
	v_mfma_f32_16x16x32_bf16 v[120:123], v[156:159], v[196:199], v[120:123]
	v_mfma_f32_16x16x32_bf16 v[116:119], v[164:167], v[196:199], v[116:119]
	v_mfma_f32_16x16x32_bf16 v[112:115], v[156:159], v[204:207], v[112:115]
	v_mfma_f32_16x16x32_bf16 v[108:111], v[164:167], v[204:207], v[108:111]
	v_mfma_f32_16x16x32_bf16 v[100:103], v[156:159], v[220:223], v[100:103]
	v_mfma_f32_16x16x32_bf16 v[92:95], v[164:167], v[220:223], v[92:95]
	v_mfma_f32_16x16x32_bf16 v[128:131], v[160:163], v[192:195], v[128:131]
	v_mfma_f32_16x16x32_bf16 v[124:127], v[168:171], v[192:195], v[124:127]
	v_mfma_f32_16x16x32_bf16 v[120:123], v[160:163], v[200:203], v[120:123]
	v_mfma_f32_16x16x32_bf16 v[116:119], v[168:171], v[200:203], v[116:119]
	v_mfma_f32_16x16x32_bf16 v[112:115], v[160:163], v[208:211], v[112:115]
	v_mfma_f32_16x16x32_bf16 v[108:111], v[168:171], v[208:211], v[108:111]
	v_mfma_f32_16x16x32_bf16 v[100:103], v[160:163], v[224:227], v[100:103]
	v_mfma_f32_16x16x32_bf16 v[92:95], v[168:171], v[224:227], v[92:95]
	v_mfma_f32_16x16x32_bf16 v[104:107], v[172:175], v[188:191], v[104:107]
	v_mfma_f32_16x16x32_bf16 v[96:99], v[180:183], v[188:191], v[96:99]
	v_mfma_f32_16x16x32_bf16 v[88:91], v[172:175], v[196:199], v[88:91]
	v_mfma_f32_16x16x32_bf16 v[84:87], v[180:183], v[196:199], v[84:87]
	v_mfma_f32_16x16x32_bf16 v[80:83], v[172:175], v[204:207], v[80:83]
	v_mfma_f32_16x16x32_bf16 v[76:79], v[180:183], v[204:207], v[76:79]
	v_mfma_f32_16x16x32_bf16 v[72:75], v[172:175], v[220:223], v[72:75]
	v_mfma_f32_16x16x32_bf16 v[68:71], v[180:183], v[220:223], v[68:71]
	v_mfma_f32_16x16x32_bf16 v[104:107], v[176:179], v[192:195], v[104:107]
	v_mfma_f32_16x16x32_bf16 v[96:99], v[184:187], v[192:195], v[96:99]
	v_mfma_f32_16x16x32_bf16 v[88:91], v[176:179], v[200:203], v[88:91]
	v_mfma_f32_16x16x32_bf16 v[84:87], v[184:187], v[200:203], v[84:87]
	v_mfma_f32_16x16x32_bf16 v[80:83], v[176:179], v[208:211], v[80:83]
	v_mfma_f32_16x16x32_bf16 v[76:79], v[184:187], v[208:211], v[76:79]
	v_mfma_f32_16x16x32_bf16 v[72:75], v[176:179], v[224:227], v[72:75]
	v_mfma_f32_16x16x32_bf16 v[68:71], v[184:187], v[224:227], v[68:71]
	s_barrier
; #define PG8_STAGE(bufoff, gbase, voff) do { _Pragma("unroll") for (int _i = 0; _i < 2; ++_i) \
;         __builtin_amdgcn_global_load_lds((const unsigned*)((const char*)(gbase) + (voff)[_i]), (PG8_LAS unsigned*)(lds + (bufoff) + ldsw + _i * 8192), 16, 0, 0); } while (0)
; #define PG8_LDA(dst, b, h) do { _Pragma("unroll") for (int m = 0; m < 4; ++m) _Pragma("unroll") for (int k = 0; k < 2; ++k) dst[m][k] = *(const PG8_LAS bf16x8*)(lds + PG8_SA(b, h) + aoff + m * 2048 + k * 1024); } while (0)
; #define PG8_MMA(ai, bj, At, Bt) do { __builtin_amdgcn_s_setprio(1); _Pragma("unroll") for (int m = 0; m < 4; ++m) _Pragma("unroll") for (int n = 0; n < 2; ++n) _Pragma("unroll") for (int k = 0; k < 2; ++k) \
;         acc[ai][bj][m][n] = __builtin_amdgcn_mfma_f32_16x16x32_bf16(Bt[n][k], At[m][k], acc[ai][bj][m][n], 0, 0, 0); __builtin_amdgcn_s_setprio(0); } while (0)
; #define PG8_WAIT_V(n) asm volatile("s_waitcnt vmcnt(" #n ")" ::: "memory")
; #define PG8_WAIT_L(n) asm volatile("s_waitcnt lgkmcnt(" #n ")" ::: "memory")
; #define PG8_BAR __builtin_amdgcn_s_barrier()
; #define PG8_SCHED __builtin_amdgcn_sched_barrier(0)
; template <class Epi, class Sched, bool ALIGN_EPI = false, bool SP2 = false>
; __device__ __forceinline__ void gemm_phase(PG8_LAS unsigned char* lds, const Gemm g, const Sched& S, const Epi& E) {
;     ...
;             PG8_LDA(At, 1, 1); PG8_STAGE(PG8_SB(1, 0), b3, voffB); PG8_STAGE(PG8_SB(1, 1), b3 + hstep, voffB); PG8_STAGE(PG8_SA(1, 0), a3, voffA);
;             PG8_WAIT_V(8); PG8_WAIT_L(0); PG8_BAR; PG8_MMA(1, 0, At, B0); PG8_MMA(1, 1, At, B1); PG8_BAR; PG8_SCHED;
;     ...
;         }
;         if constexpr (ALIGN_EPI) { if (wr == 0) PG8_BAR; }
	s_setprio 0
	s_setprio 1
	s_setprio 0
	s_waitcnt lgkmcnt(0)
	s_add_i32 s20, s44, s1
	v_lshl_add_u64 v[228:229], v[228:229], 0, s[88:89]
	s_mov_b32 m0, s20
	ds_read_b128 v[188:191], v155 offset:49152
	ds_read_b128 v[192:195], v155 offset:50176
	ds_read_b128 v[196:199], v155 offset:51200
	ds_read_b128 v[200:203], v155 offset:52224
	ds_read_b128 v[204:207], v155 offset:53248
	ds_read_b128 v[208:211], v155 offset:54272
	ds_read_b128 v[220:223], v155 offset:55296
	ds_read_b128 v[224:227], v155 offset:56320
	global_load_lds_dwordx4 v[228:229], off
	s_add_i32 m0, s20, 0x2000
	s_add_u32 s20, s24, 0x80080
	v_lshl_add_u64 v[228:229], v[230:231], 0, s[88:89]
	s_addc_u32 s21, s25, 0
	s_add_i32 s24, s45, s1
	global_load_lds_dwordx4 v[228:229], off
	v_lshl_add_u64 v[228:229], s[20:21], 0, v[66:67]
	s_mov_b32 m0, s24
	s_nop 0
	global_load_lds_dwordx4 v[228:229], off
	v_lshl_add_u64 v[228:229], s[20:21], 0, v[132:133]
	s_add_i32 m0, s24, 0x2000
	s_nop 0
	global_load_lds_dwordx4 v[228:229], off
	v_lshl_add_u64 v[228:229], v[232:233], 0, s[88:89]
	s_mov_b32 m0, s40
	s_nop 0
	global_load_lds_dwordx4 v[228:229], off
	v_lshl_add_u64 v[228:229], v[234:235], 0, s[88:89]
	s_mov_b32 m0, s41
	s_nop 0
	global_load_lds_dwordx4 v[228:229], off
	s_setprio 1
	s_nop 0
	s_waitcnt vmcnt(8) lgkmcnt(0)
	s_barrier
	v_mfma_f32_16x16x32_bf16 v[62:65], v[156:159], v[188:191], v[62:65]
	v_mfma_f32_16x16x32_bf16 v[58:61], v[164:167], v[188:191], v[58:61]
	v_mfma_f32_16x16x32_bf16 v[54:57], v[156:159], v[196:199], v[54:57]
	v_mfma_f32_16x16x32_bf16 v[50:53], v[164:167], v[196:199], v[50:53]
	v_mfma_f32_16x16x32_bf16 v[46:49], v[156:159], v[204:207], v[46:49]
	v_mfma_f32_16x16x32_bf16 v[42:45], v[164:167], v[204:207], v[42:45]
	v_mfma_f32_16x16x32_bf16 v[34:37], v[156:159], v[220:223], v[34:37]
	v_mfma_f32_16x16x32_bf16 v[26:29], v[164:167], v[220:223], v[26:29]
	v_mfma_f32_16x16x32_bf16 v[62:65], v[160:163], v[192:195], v[62:65]
	v_mfma_f32_16x16x32_bf16 v[58:61], v[168:171], v[192:195], v[58:61]
	v_mfma_f32_16x16x32_bf16 v[54:57], v[160:163], v[200:203], v[54:57]
	v_mfma_f32_16x16x32_bf16 v[50:53], v[168:171], v[200:203], v[50:53]
	v_mfma_f32_16x16x32_bf16 v[46:49], v[160:163], v[208:211], v[46:49]
	v_mfma_f32_16x16x32_bf16 v[42:45], v[168:171], v[208:211], v[42:45]
	v_mfma_f32_16x16x32_bf16 v[34:37], v[160:163], v[224:227], v[34:37]
	v_mfma_f32_16x16x32_bf16 v[26:29], v[168:171], v[224:227], v[26:29]
	v_mfma_f32_16x16x32_bf16 v[38:41], v[172:175], v[188:191], v[38:41]
	v_mfma_f32_16x16x32_bf16 v[30:33], v[180:183], v[188:191], v[30:33]
	v_mfma_f32_16x16x32_bf16 v[22:25], v[172:175], v[196:199], v[22:25]
	v_mfma_f32_16x16x32_bf16 v[18:21], v[180:183], v[196:199], v[18:21]
	v_mfma_f32_16x16x32_bf16 v[14:17], v[172:175], v[204:207], v[14:17]
	v_mfma_f32_16x16x32_bf16 v[10:13], v[180:183], v[204:207], v[10:13]
	v_mfma_f32_16x16x32_bf16 v[6:9], v[172:175], v[220:223], v[6:9]
	v_mfma_f32_16x16x32_bf16 v[2:5], v[180:183], v[220:223], v[2:5]
	v_mfma_f32_16x16x32_bf16 v[38:41], v[176:179], v[192:195], v[38:41]
	v_mfma_f32_16x16x32_bf16 v[30:33], v[184:187], v[192:195], v[30:33]
	v_mfma_f32_16x16x32_bf16 v[22:25], v[176:179], v[200:203], v[22:25]
	v_mfma_f32_16x16x32_bf16 v[18:21], v[184:187], v[200:203], v[18:21]
	v_mfma_f32_16x16x32_bf16 v[14:17], v[176:179], v[208:211], v[14:17]
	v_mfma_f32_16x16x32_bf16 v[10:13], v[184:187], v[208:211], v[10:13]
	v_mfma_f32_16x16x32_bf16 v[6:9], v[176:179], v[224:227], v[6:9]
	v_mfma_f32_16x16x32_bf16 v[2:5], v[184:187], v[224:227], v[2:5]
	s_barrier
	s_setprio 0
	s_setprio 1
	s_setprio 0
	s_waitcnt lgkmcnt(0)
	s_add_i32 s43, s43, 2
	s_add_u32 s13, s13, 0x100
	s_addc_u32 s15, s15, 0
	s_cmp_gt_u32 s43, 5
	s_mov_b64 s[20:21], s[22:23]
	s_cbranch_scc0 .LBB0_802
	s_and_b64 vcc, exec, s[8:9]
	s_cbranch_vccz .LBB0_805
	s_barrier

; #define PG8_STAGE(bufoff, gbase, voff) do { _Pragma("unroll") for (int _i = 0; _i < 2; ++_i) \
;         __builtin_amdgcn_global_load_lds((const unsigned*)((const char*)(gbase) + (voff)[_i]), (PG8_LAS unsigned*)(lds + (bufoff) + ldsw + _i * 8192), 16, 0, 0); } while (0)
; #define PG8_LDA(dst, b, h) do { _Pragma("unroll") for (int m = 0; m < 4; ++m) _Pragma("unroll") for (int k = 0; k < 2; ++k) dst[m][k] = *(const PG8_LAS bf16x8*)(lds + PG8_SA(b, h) + aoff + m * 2048 + k * 1024); } while (0)
; #define PG8_LDB(dst, b, h) do { _Pragma("unroll") for (int n = 0; n < 2; ++n) _Pragma("unroll") for (int k = 0; k < 2; ++k) dst[n][k] = *(const PG8_LAS bf16x8*)(lds + PG8_SB(b, h) + boff + n * 2048 + k * 1024); } while (0)
; #define PG8_MMA(ai, bj, At, Bt) do { __builtin_amdgcn_s_setprio(1); _Pragma("unroll") for (int m = 0; m < 4; ++m) _Pragma("unroll") for (int n = 0; n < 2; ++n) _Pragma("unroll") for (int k = 0; k < 2; ++k) \
;         acc[ai][bj][m][n] = __builtin_amdgcn_mfma_f32_16x16x32_bf16(Bt[n][k], At[m][k], acc[ai][bj][m][n], 0, 0, 0); __builtin_amdgcn_s_setprio(0); } while (0)
; #define PG8_WAIT_V(n) asm volatile("s_waitcnt vmcnt(" #n ")" ::: "memory")
; template <class Epi, class Sched, bool ALIGN_EPI = false, bool SP2 = false>
; __device__ __forceinline__ void gemm_phase(PG8_LAS unsigned char* lds, const Gemm g, const Sched& S, const Epi& E) {
;     ...
;             PG8_LDB(B0, 0, 0); PG8_LDB(B1, 0, 1); PG8_SCHED; PG8_LDA(At, 0, 0); PG8_STAGE(PG8_SA(1, 1), a1 + hstep, voffA);
;             PG8_WAIT_V(8); PG8_WAIT_L(0); PG8_BAR; PG8_MMA(0, 0, At, B0); PG8_MMA(0, 1, At, B1); PG8_BAR; PG8_SCHED;
;             PG8_LDA(At, 0, 1); PG8_STAGE(PG8_SB(0, 0), b2, voffB); PG8_STAGE(PG8_SB(0, 1), b2 + hstep, voffB); PG8_STAGE(PG8_SA(0, 0), a2, voffA);
;             PG8_WAIT_V(8); PG8_WAIT_L(0); PG8_BAR; PG8_MMA(1, 0, At, B0); PG8_MMA(1, 1, At, B1); PG8_BAR; PG8_SCHED;
;             PG8_LDB(B0, 1, 0); PG8_LDB(B1, 1, 1); PG8_SCHED; PG8_LDA(At, 1, 0); PG8_STAGE(PG8_SA(0, 1), a2 + hstep, voffA);
;             PG8_WAIT_V(8); PG8_WAIT_L(0); PG8_BAR; PG8_MMA(0, 0, At, B0); PG8_MMA(0, 1, At, B1); PG8_BAR; PG8_SCHED;
;             PG8_LDA(At, 1, 1); PG8_STAGE(PG8_SB(1, 0), b3, voffB); PG8_STAGE(PG8_SB(1, 1), b3 + hstep, voffB); PG8_STAGE(PG8_SA(1, 0), a3, voffA);
;             PG8_WAIT_V(8); PG8_WAIT_L(0); PG8_BAR; PG8_MMA(1, 0, At, B0); PG8_MMA(1, 1, At, B1); PG8_BAR; PG8_SCHED;
.LBB0_881:
	s_add_u32 s30, s28, 0x100
	s_addc_u32 s31, s29, 0
	s_add_i32 s59, 0, 0x10000
	s_cmp_eq_u32 s57, 28
	s_cselect_b32 s37, s2, s31
	s_cselect_b32 s36, s3, s30
	s_cselect_b32 s35, s21, s56
	s_cselect_b32 s34, s23, s55
	s_add_i32 s60, 0, 0x14000
	v_add_u32_e32 v144, s59, v156
	v_add_u32_e32 v154, s60, v156
	ds_read_b128 v[132:135], v144
	ds_read_b128 v[136:139], v144 offset:1024
	ds_read_b128 v[140:143], v144 offset:2048
	ds_read_b128 v[144:147], v144 offset:3072
	ds_read_b128 v[160:163], v154
	ds_read_b128 v[164:167], v154 offset:1024
	ds_read_b128 v[168:171], v154 offset:2048
	ds_read_b128 v[172:175], v154 offset:3072
	v_lshl_add_u64 v[154:155], s[28:29], 0, v[150:151]
	s_add_i32 m0, s39, 0xc000
	ds_read_b128 v[176:179], v158
	ds_read_b128 v[180:183], v158 offset:1024
	ds_read_b128 v[184:187], v158 offset:2048
	ds_read_b128 v[188:191], v158 offset:3072
	ds_read_b128 v[192:195], v158 offset:4096
	ds_read_b128 v[196:199], v158 offset:5120
	ds_read_b128 v[200:203], v158 offset:6144
	ds_read_b128 v[204:207], v158 offset:7168
	global_load_lds_dwordx4 v[154:155], off
	v_lshl_add_u64 v[154:155], s[28:29], 0, v[152:153]
	s_add_i32 m0, s39, 0xe000
	s_nop 0
	global_load_lds_dwordx4 v[154:155], off
	s_setprio 1
	s_nop 0
	s_waitcnt vmcnt(8) lgkmcnt(0)
	s_barrier
	v_mfma_f32_16x16x32_bf16 v[128:131], v[132:135], v[176:179], v[128:131]
	v_mfma_f32_16x16x32_bf16 v[124:127], v[140:143], v[176:179], v[124:127]
	v_mfma_f32_16x16x32_bf16 v[120:123], v[132:135], v[184:187], v[120:123]
	v_mfma_f32_16x16x32_bf16 v[112:115], v[140:143], v[184:187], v[112:115]
	v_mfma_f32_16x16x32_bf16 v[104:107], v[132:135], v[192:195], v[104:107]
	v_mfma_f32_16x16x32_bf16 v[96:99], v[140:143], v[192:195], v[96:99]
	v_mfma_f32_16x16x32_bf16 v[88:91], v[132:135], v[200:203], v[88:91]
	v_mfma_f32_16x16x32_bf16 v[76:79], v[140:143], v[200:203], v[76:79]
	v_mfma_f32_16x16x32_bf16 v[128:131], v[136:139], v[180:183], v[128:131]
	v_mfma_f32_16x16x32_bf16 v[124:127], v[144:147], v[180:183], v[124:127]
	v_mfma_f32_16x16x32_bf16 v[120:123], v[136:139], v[188:191], v[120:123]
	v_mfma_f32_16x16x32_bf16 v[112:115], v[144:147], v[188:191], v[112:115]
	v_mfma_f32_16x16x32_bf16 v[104:107], v[136:139], v[196:199], v[104:107]
	v_mfma_f32_16x16x32_bf16 v[96:99], v[144:147], v[196:199], v[96:99]
	v_mfma_f32_16x16x32_bf16 v[88:91], v[136:139], v[204:207], v[88:91]
	v_mfma_f32_16x16x32_bf16 v[76:79], v[144:147], v[204:207], v[76:79]
	v_mfma_f32_16x16x32_bf16 v[116:119], v[160:163], v[176:179], v[116:119]
	v_mfma_f32_16x16x32_bf16 v[108:111], v[168:171], v[176:179], v[108:111]
	v_mfma_f32_16x16x32_bf16 v[100:103], v[160:163], v[184:187], v[100:103]
	v_mfma_f32_16x16x32_bf16 v[92:95], v[168:171], v[184:187], v[92:95]
	v_mfma_f32_16x16x32_bf16 v[84:87], v[160:163], v[192:195], v[84:87]
	v_mfma_f32_16x16x32_bf16 v[80:83], v[168:171], v[192:195], v[80:83]
	v_mfma_f32_16x16x32_bf16 v[72:75], v[160:163], v[200:203], v[72:75]
	v_mfma_f32_16x16x32_bf16 v[68:71], v[168:171], v[200:203], v[68:71]
	v_mfma_f32_16x16x32_bf16 v[116:119], v[164:167], v[180:183], v[116:119]
	v_mfma_f32_16x16x32_bf16 v[108:111], v[172:175], v[180:183], v[108:111]
	v_mfma_f32_16x16x32_bf16 v[100:103], v[164:167], v[188:191], v[100:103]
	v_mfma_f32_16x16x32_bf16 v[92:95], v[172:175], v[188:191], v[92:95]
	v_mfma_f32_16x16x32_bf16 v[84:87], v[164:167], v[196:199], v[84:87]
	v_mfma_f32_16x16x32_bf16 v[80:83], v[172:175], v[196:199], v[80:83]
	v_mfma_f32_16x16x32_bf16 v[72:75], v[164:167], v[204:207], v[72:75]
	v_mfma_f32_16x16x32_bf16 v[68:71], v[172:175], v[204:207], v[68:71]
	s_barrier
	s_setprio 0
	s_setprio 1
	s_setprio 0
	s_waitcnt lgkmcnt(0)
	s_add_i32 s28, s59, s38
	v_lshl_add_u64 v[154:155], s[34:35], 0, v[66:67]
	s_mov_b32 m0, s28
	ds_read_b128 v[176:179], v158 offset:16384
	ds_read_b128 v[180:183], v158 offset:17408
	ds_read_b128 v[184:187], v158 offset:18432
	ds_read_b128 v[188:191], v158 offset:19456
	ds_read_b128 v[192:195], v158 offset:20480
	ds_read_b128 v[196:199], v158 offset:21504
	ds_read_b128 v[200:203], v158 offset:22528
	ds_read_b128 v[204:207], v158 offset:23552
	global_load_lds_dwordx4 v[154:155], off
	s_add_i32 m0, s28, 0x2000
	s_add_u32 s28, s34, 0x80000
	v_lshl_add_u64 v[208:209], s[34:35], 0, v[148:149]
	s_addc_u32 s29, s35, 0
	s_add_i32 s59, s60, s38
	global_load_lds_dwordx4 v[208:209], off
	v_lshl_add_u64 v[210:211], s[28:29], 0, v[66:67]
	s_mov_b32 m0, s59
	v_lshl_add_u64 v[220:221], s[36:37], 0, v[148:149]
	global_load_lds_dwordx4 v[210:211], off
	v_lshl_add_u64 v[210:211], s[28:29], 0, v[148:149]
	s_add_i32 m0, s59, 0x2000
	s_nop 0
	global_load_lds_dwordx4 v[210:211], off
	v_lshl_add_u64 v[210:211], s[36:37], 0, v[66:67]
	s_mov_b32 m0, s39
	s_nop 0
	global_load_lds_dwordx4 v[210:211], off
	s_mov_b32 m0, s40
	s_nop 0
	global_load_lds_dwordx4 v[220:221], off
	s_setprio 1
	s_nop 0
	s_waitcnt vmcnt(8) lgkmcnt(0)
	s_barrier
; #define PG8_STAGE(bufoff, gbase, voff) do { _Pragma("unroll") for (int _i = 0; _i < 2; ++_i) \
;         __builtin_amdgcn_global_load_lds((const unsigned*)((const char*)(gbase) + (voff)[_i]), (PG8_LAS unsigned*)(lds + (bufoff) + ldsw + _i * 8192), 16, 0, 0); } while (0)
; #define PG8_LDA(dst, b, h) do { _Pragma("unroll") for (int m = 0; m < 4; ++m) _Pragma("unroll") for (int k = 0; k < 2; ++k) dst[m][k] = *(const PG8_LAS bf16x8*)(lds + PG8_SA(b, h) + aoff + m * 2048 + k * 1024); } while (0)
; #define PG8_LDB(dst, b, h) do { _Pragma("unroll") for (int n = 0; n < 2; ++n) _Pragma("unroll") for (int k = 0; k < 2; ++k) dst[n][k] = *(const PG8_LAS bf16x8*)(lds + PG8_SB(b, h) + boff + n * 2048 + k * 1024); } while (0)
; #define PG8_MMA(ai, bj, At, Bt) do { __builtin_amdgcn_s_setprio(1); _Pragma("unroll") for (int m = 0; m < 4; ++m) _Pragma("unroll") for (int n = 0; n < 2; ++n) _Pragma("unroll") for (int k = 0; k < 2; ++k) \
;         acc[ai][bj][m][n] = __builtin_amdgcn_mfma_f32_16x16x32_bf16(Bt[n][k], At[m][k], acc[ai][bj][m][n], 0, 0, 0); __builtin_amdgcn_s_setprio(0); } while (0)
; #define PG8_WAIT_V(n) asm volatile("s_waitcnt vmcnt(" #n ")" ::: "memory")
; template <class Epi, class Sched, bool ALIGN_EPI = false, bool SP2 = false>
; __device__ __forceinline__ void gemm_phase(PG8_LAS unsigned char* lds, const Gemm g, const Sched& S, const Epi& E) {
;     ...
;             PG8_LDB(B0, 0, 0); PG8_LDB(B1, 0, 1); PG8_SCHED; PG8_LDA(At, 0, 0); PG8_STAGE(PG8_SA(1, 1), a1 + hstep, voffA);
;             PG8_WAIT_V(8); PG8_WAIT_L(0); PG8_BAR; PG8_MMA(0, 0, At, B0); PG8_MMA(0, 1, At, B1); PG8_BAR; PG8_SCHED;
;             PG8_LDA(At, 0, 1); PG8_STAGE(PG8_SB(0, 0), b2, voffB); PG8_STAGE(PG8_SB(0, 1), b2 + hstep, voffB); PG8_STAGE(PG8_SA(0, 0), a2, voffA);
;             PG8_WAIT_V(8); PG8_WAIT_L(0); PG8_BAR; PG8_MMA(1, 0, At, B0); PG8_MMA(1, 1, At, B1); PG8_BAR; PG8_SCHED;
;             PG8_LDB(B0, 1, 0); PG8_LDB(B1, 1, 1); PG8_SCHED; PG8_LDA(At, 1, 0); PG8_STAGE(PG8_SA(0, 1), a2 + hstep, voffA);
;             PG8_WAIT_V(8); PG8_WAIT_L(0); PG8_BAR; PG8_MMA(0, 0, At, B0); PG8_MMA(0, 1, At, B1); PG8_BAR; PG8_SCHED;
;             PG8_LDA(At, 1, 1); PG8_STAGE(PG8_SB(1, 0), b3, voffB); PG8_STAGE(PG8_SB(1, 1), b3 + hstep, voffB); PG8_STAGE(PG8_SA(1, 0), a3, voffA);
;             PG8_WAIT_V(8); PG8_WAIT_L(0); PG8_BAR; PG8_MMA(1, 0, At, B0); PG8_MMA(1, 1, At, B1); PG8_BAR; PG8_SCHED;
	v_mfma_f32_16x16x32_bf16 v[62:65], v[132:135], v[176:179], v[62:65]
	v_mfma_f32_16x16x32_bf16 v[58:61], v[140:143], v[176:179], v[58:61]
	v_mfma_f32_16x16x32_bf16 v[54:57], v[132:135], v[184:187], v[54:57]
	v_mfma_f32_16x16x32_bf16 v[46:49], v[140:143], v[184:187], v[46:49]
	v_mfma_f32_16x16x32_bf16 v[38:41], v[132:135], v[192:195], v[38:41]
	v_mfma_f32_16x16x32_bf16 v[30:33], v[140:143], v[192:195], v[30:33]
	v_mfma_f32_16x16x32_bf16 v[22:25], v[132:135], v[200:203], v[22:25]
	v_mfma_f32_16x16x32_bf16 v[10:13], v[140:143], v[200:203], v[10:13]
	v_mfma_f32_16x16x32_bf16 v[62:65], v[136:139], v[180:183], v[62:65]
	v_mfma_f32_16x16x32_bf16 v[58:61], v[144:147], v[180:183], v[58:61]
	v_mfma_f32_16x16x32_bf16 v[54:57], v[136:139], v[188:191], v[54:57]
	v_mfma_f32_16x16x32_bf16 v[46:49], v[144:147], v[188:191], v[46:49]
	v_mfma_f32_16x16x32_bf16 v[38:41], v[136:139], v[196:199], v[38:41]
	v_mfma_f32_16x16x32_bf16 v[30:33], v[144:147], v[196:199], v[30:33]
	v_mfma_f32_16x16x32_bf16 v[22:25], v[136:139], v[204:207], v[22:25]
	v_mfma_f32_16x16x32_bf16 v[10:13], v[144:147], v[204:207], v[10:13]
	v_mfma_f32_16x16x32_bf16 v[50:53], v[160:163], v[176:179], v[50:53]
	v_mfma_f32_16x16x32_bf16 v[42:45], v[168:171], v[176:179], v[42:45]
	v_mfma_f32_16x16x32_bf16 v[34:37], v[160:163], v[184:187], v[34:37]
	v_mfma_f32_16x16x32_bf16 v[26:29], v[168:171], v[184:187], v[26:29]
	v_mfma_f32_16x16x32_bf16 v[18:21], v[160:163], v[192:195], v[18:21]
	v_mfma_f32_16x16x32_bf16 v[14:17], v[168:171], v[192:195], v[14:17]
	v_mfma_f32_16x16x32_bf16 v[6:9], v[160:163], v[200:203], v[6:9]
	v_mfma_f32_16x16x32_bf16 v[2:5], v[168:171], v[200:203], v[2:5]
	v_mfma_f32_16x16x32_bf16 v[50:53], v[164:167], v[180:183], v[50:53]
	v_mfma_f32_16x16x32_bf16 v[42:45], v[172:175], v[180:183], v[42:45]
	v_mfma_f32_16x16x32_bf16 v[34:37], v[164:167], v[188:191], v[34:37]
	v_mfma_f32_16x16x32_bf16 v[26:29], v[172:175], v[188:191], v[26:29]
	v_mfma_f32_16x16x32_bf16 v[18:21], v[164:167], v[196:199], v[18:21]
	v_mfma_f32_16x16x32_bf16 v[14:17], v[172:175], v[196:199], v[14:17]
	v_mfma_f32_16x16x32_bf16 v[6:9], v[164:167], v[204:207], v[6:9]
	v_mfma_f32_16x16x32_bf16 v[2:5], v[172:175], v[204:207], v[2:5]
	s_barrier
	s_setprio 0
	s_setprio 1
	s_setprio 0
	s_waitcnt lgkmcnt(0)
	s_add_i32 s59, 0, 0x18000
	s_add_i32 s60, 0, 0x1c000
	v_add_u32_e32 v144, s59, v156
	v_add_u32_e32 v159, s60, v156
	ds_read_b128 v[132:135], v144
	ds_read_b128 v[136:139], v144 offset:1024
	ds_read_b128 v[140:143], v144 offset:2048
	ds_read_b128 v[144:147], v144 offset:3072
	ds_read_b128 v[160:163], v159
	ds_read_b128 v[164:167], v159 offset:1024
	ds_read_b128 v[168:171], v159 offset:2048
	ds_read_b128 v[172:175], v159 offset:3072
	s_add_u32 s28, s36, 0x80000
	s_addc_u32 s29, s37, 0
	s_mov_b32 m0, s41
	v_lshl_add_u64 v[222:223], s[28:29], 0, v[66:67]
	ds_read_b128 v[176:179], v158 offset:32768
	ds_read_b128 v[180:183], v158 offset:33792
	ds_read_b128 v[184:187], v158 offset:34816
	ds_read_b128 v[188:191], v158 offset:35840
	ds_read_b128 v[192:195], v158 offset:36864
	ds_read_b128 v[196:199], v158 offset:37888
	ds_read_b128 v[200:203], v158 offset:38912
	ds_read_b128 v[204:207], v158 offset:39936
	global_load_lds_dwordx4 v[222:223], off
	v_lshl_add_u64 v[222:223], s[28:29], 0, v[148:149]
	s_mov_b32 m0, s44
	s_nop 0
	global_load_lds_dwordx4 v[222:223], off
	s_setprio 1
	s_nop 0
	s_waitcnt vmcnt(8) lgkmcnt(0)
	s_barrier
	v_mfma_f32_16x16x32_bf16 v[128:131], v[132:135], v[176:179], v[128:131]
	v_mfma_f32_16x16x32_bf16 v[124:127], v[140:143], v[176:179], v[124:127]
	v_mfma_f32_16x16x32_bf16 v[120:123], v[132:135], v[184:187], v[120:123]
	v_mfma_f32_16x16x32_bf16 v[112:115], v[140:143], v[184:187], v[112:115]
	v_mfma_f32_16x16x32_bf16 v[104:107], v[132:135], v[192:195], v[104:107]
	v_mfma_f32_16x16x32_bf16 v[96:99], v[140:143], v[192:195], v[96:99]
	v_mfma_f32_16x16x32_bf16 v[88:91], v[132:135], v[200:203], v[88:91]
	v_mfma_f32_16x16x32_bf16 v[76:79], v[140:143], v[200:203], v[76:79]
	v_mfma_f32_16x16x32_bf16 v[128:131], v[136:139], v[180:183], v[128:131]
	v_mfma_f32_16x16x32_bf16 v[124:127], v[144:147], v[180:183], v[124:127]
	v_mfma_f32_16x16x32_bf16 v[120:123], v[136:139], v[188:191], v[120:123]
	v_mfma_f32_16x16x32_bf16 v[112:115], v[144:147], v[188:191], v[112:115]
	v_mfma_f32_16x16x32_bf16 v[104:107], v[136:139], v[196:199], v[104:107]
	v_mfma_f32_16x16x32_bf16 v[96:99], v[144:147], v[196:199], v[96:99]
	v_mfma_f32_16x16x32_bf16 v[88:91], v[136:139], v[204:207], v[88:91]
	v_mfma_f32_16x16x32_bf16 v[76:79], v[144:147], v[204:207], v[76:79]
	v_mfma_f32_16x16x32_bf16 v[116:119], v[160:163], v[176:179], v[116:119]
	v_mfma_f32_16x16x32_bf16 v[108:111], v[168:171], v[176:179], v[108:111]
	v_mfma_f32_16x16x32_bf16 v[100:103], v[160:163], v[184:187], v[100:103]
	v_mfma_f32_16x16x32_bf16 v[92:95], v[168:171], v[184:187], v[92:95]
	v_mfma_f32_16x16x32_bf16 v[84:87], v[160:163], v[192:195], v[84:87]
	v_mfma_f32_16x16x32_bf16 v[80:83], v[168:171], v[192:195], v[80:83]
	v_mfma_f32_16x16x32_bf16 v[72:75], v[160:163], v[200:203], v[72:75]
	v_mfma_f32_16x16x32_bf16 v[68:71], v[168:171], v[200:203], v[68:71]
	v_mfma_f32_16x16x32_bf16 v[116:119], v[164:167], v[180:183], v[116:119]
	v_mfma_f32_16x16x32_bf16 v[108:111], v[172:175], v[180:183], v[108:111]
	v_mfma_f32_16x16x32_bf16 v[100:103], v[164:167], v[188:191], v[100:103]
	v_mfma_f32_16x16x32_bf16 v[92:95], v[172:175], v[188:191], v[92:95]
	v_mfma_f32_16x16x32_bf16 v[84:87], v[164:167], v[196:199], v[84:87]
	v_mfma_f32_16x16x32_bf16 v[80:83], v[172:175], v[196:199], v[80:83]
	v_mfma_f32_16x16x32_bf16 v[72:75], v[164:167], v[204:207], v[72:75]
	v_mfma_f32_16x16x32_bf16 v[68:71], v[172:175], v[204:207], v[68:71]
	s_barrier
; #define PG8_STAGE(bufoff, gbase, voff) do { _Pragma("unroll") for (int _i = 0; _i < 2; ++_i) \
;         __builtin_amdgcn_global_load_lds((const unsigned*)((const char*)(gbase) + (voff)[_i]), (PG8_LAS unsigned*)(lds + (bufoff) + ldsw + _i * 8192), 16, 0, 0); } while (0)
; #define PG8_LDA(dst, b, h) do { _Pragma("unroll") for (int m = 0; m < 4; ++m) _Pragma("unroll") for (int k = 0; k < 2; ++k) dst[m][k] = *(const PG8_LAS bf16x8*)(lds + PG8_SA(b, h) + aoff + m * 2048 + k * 1024); } while (0)
; #define PG8_MMA(ai, bj, At, Bt) do { __builtin_amdgcn_s_setprio(1); _Pragma("unroll") for (int m = 0; m < 4; ++m) _Pragma("unroll") for (int n = 0; n < 2; ++n) _Pragma("unroll") for (int k = 0; k < 2; ++k) \
;         acc[ai][bj][m][n] = __builtin_amdgcn_mfma_f32_16x16x32_bf16(Bt[n][k], At[m][k], acc[ai][bj][m][n], 0, 0, 0); __builtin_amdgcn_s_setprio(0); } while (0)
; #define PG8_WAIT_V(n) asm volatile("s_waitcnt vmcnt(" #n ")" ::: "memory")
; #define PG8_WAIT_L(n) asm volatile("s_waitcnt lgkmcnt(" #n ")" ::: "memory")
; #define PG8_BAR __builtin_amdgcn_s_barrier()
; #define PG8_SCHED __builtin_amdgcn_sched_barrier(0)
; template <class Epi, class Sched, bool ALIGN_EPI = false, bool SP2 = false>
; __device__ __forceinline__ void gemm_phase(PG8_LAS unsigned char* lds, const Gemm g, const Sched& S, const Epi& E) {
;     ...
;             PG8_LDA(At, 1, 1); PG8_STAGE(PG8_SB(1, 0), b3, voffB); PG8_STAGE(PG8_SB(1, 1), b3 + hstep, voffB); PG8_STAGE(PG8_SA(1, 0), a3, voffA);
;             PG8_WAIT_V(8); PG8_WAIT_L(0); PG8_BAR; PG8_MMA(1, 0, At, B0); PG8_MMA(1, 1, At, B1); PG8_BAR; PG8_SCHED;
;     ...
;         }
;         if constexpr (ALIGN_EPI) { if (wr == 0) PG8_BAR; }
	s_setprio 0
	s_setprio 1
	s_setprio 0
	s_waitcnt lgkmcnt(0)
	s_add_i32 s28, s59, s38
	v_lshl_add_u64 v[154:155], v[154:155], 0, s[88:89]
	s_mov_b32 m0, s28
	ds_read_b128 v[176:179], v158 offset:49152
	ds_read_b128 v[180:183], v158 offset:50176
	ds_read_b128 v[184:187], v158 offset:51200
	ds_read_b128 v[188:191], v158 offset:52224
	ds_read_b128 v[192:195], v158 offset:53248
	ds_read_b128 v[196:199], v158 offset:54272
	ds_read_b128 v[200:203], v158 offset:55296
	ds_read_b128 v[204:207], v158 offset:56320
	global_load_lds_dwordx4 v[154:155], off
	s_add_i32 m0, s28, 0x2000
	s_add_u32 s28, s34, 0x80080
	v_lshl_add_u64 v[154:155], v[208:209], 0, s[88:89]
	s_addc_u32 s29, s35, 0
	s_add_i32 s34, s60, s38
	global_load_lds_dwordx4 v[154:155], off
	v_lshl_add_u64 v[154:155], s[28:29], 0, v[66:67]
	s_mov_b32 m0, s34
	s_nop 0
	global_load_lds_dwordx4 v[154:155], off
	v_lshl_add_u64 v[154:155], s[28:29], 0, v[148:149]
	s_add_i32 m0, s34, 0x2000
	s_nop 0
	global_load_lds_dwordx4 v[154:155], off
	v_lshl_add_u64 v[154:155], v[210:211], 0, s[88:89]
	s_mov_b32 m0, s47
	s_nop 0
	global_load_lds_dwordx4 v[154:155], off
	v_lshl_add_u64 v[154:155], v[220:221], 0, s[88:89]
	s_mov_b32 m0, s50
	s_nop 0
	global_load_lds_dwordx4 v[154:155], off
	s_setprio 1
	s_nop 0
	s_waitcnt vmcnt(8) lgkmcnt(0)
	s_barrier
	v_mfma_f32_16x16x32_bf16 v[62:65], v[132:135], v[176:179], v[62:65]
	v_mfma_f32_16x16x32_bf16 v[58:61], v[140:143], v[176:179], v[58:61]
	v_mfma_f32_16x16x32_bf16 v[54:57], v[132:135], v[184:187], v[54:57]
	v_mfma_f32_16x16x32_bf16 v[46:49], v[140:143], v[184:187], v[46:49]
	v_mfma_f32_16x16x32_bf16 v[38:41], v[132:135], v[192:195], v[38:41]
	v_mfma_f32_16x16x32_bf16 v[30:33], v[140:143], v[192:195], v[30:33]
	v_mfma_f32_16x16x32_bf16 v[22:25], v[132:135], v[200:203], v[22:25]
	v_mfma_f32_16x16x32_bf16 v[10:13], v[140:143], v[200:203], v[10:13]
	v_mfma_f32_16x16x32_bf16 v[62:65], v[136:139], v[180:183], v[62:65]
	v_mfma_f32_16x16x32_bf16 v[58:61], v[144:147], v[180:183], v[58:61]
	v_mfma_f32_16x16x32_bf16 v[54:57], v[136:139], v[188:191], v[54:57]
	v_mfma_f32_16x16x32_bf16 v[46:49], v[144:147], v[188:191], v[46:49]
	v_mfma_f32_16x16x32_bf16 v[38:41], v[136:139], v[196:199], v[38:41]
	v_mfma_f32_16x16x32_bf16 v[30:33], v[144:147], v[196:199], v[30:33]
	v_mfma_f32_16x16x32_bf16 v[22:25], v[136:139], v[204:207], v[22:25]
	v_mfma_f32_16x16x32_bf16 v[10:13], v[144:147], v[204:207], v[10:13]
	v_mfma_f32_16x16x32_bf16 v[50:53], v[160:163], v[176:179], v[50:53]
	v_mfma_f32_16x16x32_bf16 v[42:45], v[168:171], v[176:179], v[42:45]
	v_mfma_f32_16x16x32_bf16 v[34:37], v[160:163], v[184:187], v[34:37]
	v_mfma_f32_16x16x32_bf16 v[26:29], v[168:171], v[184:187], v[26:29]
	v_mfma_f32_16x16x32_bf16 v[18:21], v[160:163], v[192:195], v[18:21]
	v_mfma_f32_16x16x32_bf16 v[14:17], v[168:171], v[192:195], v[14:17]
	v_mfma_f32_16x16x32_bf16 v[6:9], v[160:163], v[200:203], v[6:9]
	v_mfma_f32_16x16x32_bf16 v[2:5], v[168:171], v[200:203], v[2:5]
	v_mfma_f32_16x16x32_bf16 v[50:53], v[164:167], v[180:183], v[50:53]
	v_mfma_f32_16x16x32_bf16 v[42:45], v[172:175], v[180:183], v[42:45]
	v_mfma_f32_16x16x32_bf16 v[34:37], v[164:167], v[188:191], v[34:37]
	v_mfma_f32_16x16x32_bf16 v[26:29], v[172:175], v[188:191], v[26:29]
	v_mfma_f32_16x16x32_bf16 v[18:21], v[164:167], v[196:199], v[18:21]
	v_mfma_f32_16x16x32_bf16 v[14:17], v[172:175], v[196:199], v[14:17]
	v_mfma_f32_16x16x32_bf16 v[6:9], v[164:167], v[204:207], v[6:9]
	v_mfma_f32_16x16x32_bf16 v[2:5], v[172:175], v[204:207], v[2:5]
	s_barrier
	s_setprio 0
	s_setprio 1
	s_setprio 0
	s_waitcnt lgkmcnt(0)
	s_add_i32 s57, s57, 2
	s_add_u32 s55, s55, 0x100
	s_addc_u32 s56, s56, 0
	s_cmp_gt_u32 s57, 29
	s_mov_b64 s[28:29], s[30:31]
	s_cbranch_scc0 .LBB0_881
	s_and_b64 vcc, exec, s[12:13]
	s_cbranch_vccz .LBB0_884
	s_barrier

; #define PG8_STAGE(bufoff, gbase, voff) do { _Pragma("unroll") for (int _i = 0; _i < 2; ++_i) \
;         __builtin_amdgcn_global_load_lds((const unsigned*)((const char*)(gbase) + (voff)[_i]), (PG8_LAS unsigned*)(lds + (bufoff) + ldsw + _i * 8192), 16, 0, 0); } while (0)
; #define PG8_LDA(dst, b, h) do { _Pragma("unroll") for (int m = 0; m < 4; ++m) _Pragma("unroll") for (int k = 0; k < 2; ++k) dst[m][k] = *(const PG8_LAS bf16x8*)(lds + PG8_SA(b, h) + aoff + m * 2048 + k * 1024); } while (0)
; #define PG8_LDB(dst, b, h) do { _Pragma("unroll") for (int n = 0; n < 2; ++n) _Pragma("unroll") for (int k = 0; k < 2; ++k) dst[n][k] = *(const PG8_LAS bf16x8*)(lds + PG8_SB(b, h) + boff + n * 2048 + k * 1024); } while (0)
; #define PG8_MMA(ai, bj, At, Bt) do { __builtin_amdgcn_s_setprio(1); _Pragma("unroll") for (int m = 0; m < 4; ++m) _Pragma("unroll") for (int n = 0; n < 2; ++n) _Pragma("unroll") for (int k = 0; k < 2; ++k) \
;         acc[ai][bj][m][n] = __builtin_amdgcn_mfma_f32_16x16x32_bf16(Bt[n][k], At[m][k], acc[ai][bj][m][n], 0, 0, 0); __builtin_amdgcn_s_setprio(0); } while (0)
; #define PG8_WAIT_V(n) asm volatile("s_waitcnt vmcnt(" #n ")" ::: "memory")
; template <class Epi, class Sched, bool ALIGN_EPI = false, bool SP2 = false>
; __device__ __forceinline__ void gemm_phase(PG8_LAS unsigned char* lds, const Gemm g, const Sched& S, const Epi& E) {
;     ...
;             PG8_LDB(B0, 0, 0); PG8_LDB(B1, 0, 1); PG8_SCHED; PG8_LDA(At, 0, 0); PG8_STAGE(PG8_SA(1, 1), a1 + hstep, voffA);
;             PG8_WAIT_V(8); PG8_WAIT_L(0); PG8_BAR; PG8_MMA(0, 0, At, B0); PG8_MMA(0, 1, At, B1); PG8_BAR; PG8_SCHED;
;             PG8_LDA(At, 0, 1); PG8_STAGE(PG8_SB(0, 0), b2, voffB); PG8_STAGE(PG8_SB(0, 1), b2 + hstep, voffB); PG8_STAGE(PG8_SA(0, 0), a2, voffA);
;             PG8_WAIT_V(8); PG8_WAIT_L(0); PG8_BAR; PG8_MMA(1, 0, At, B0); PG8_MMA(1, 1, At, B1); PG8_BAR; PG8_SCHED;
;             PG8_LDB(B0, 1, 0); PG8_LDB(B1, 1, 1); PG8_SCHED; PG8_LDA(At, 1, 0); PG8_STAGE(PG8_SA(0, 1), a2 + hstep, voffA);
;             PG8_WAIT_V(8); PG8_WAIT_L(0); PG8_BAR; PG8_MMA(0, 0, At, B0); PG8_MMA(0, 1, At, B1); PG8_BAR; PG8_SCHED;
;             PG8_LDA(At, 1, 1); PG8_STAGE(PG8_SB(1, 0), b3, voffB); PG8_STAGE(PG8_SB(1, 1), b3 + hstep, voffB); PG8_STAGE(PG8_SA(1, 0), a3, voffA);
;             PG8_WAIT_V(8); PG8_WAIT_L(0); PG8_BAR; PG8_MMA(1, 0, At, B0); PG8_MMA(1, 1, At, B1); PG8_BAR; PG8_SCHED;
.LBB0_905:
	s_add_u32 s38, s22, s36
	s_addc_u32 s39, s23, s37
	s_add_u32 s38, s38, 0x100
	s_addc_u32 s39, s39, 0
	s_add_u32 s63, s3, s36
	s_addc_u32 s64, s59, s37
	s_add_i32 s65, 0, 0x10000
	s_cmpk_eq_i32 s36, 0xf00
	s_cselect_b32 s41, s29, s39
	s_cselect_b32 s40, s60, s38
	s_cselect_b32 s39, s27, s64
	s_cselect_b32 s38, s61, s63
	s_add_i32 s63, 0, 0x14000
	v_add_u32_e32 v156, s65, v142
	v_add_u32_e32 v172, s63, v142
	ds_read_b128 v[144:147], v156
	ds_read_b128 v[148:151], v156 offset:1024
	ds_read_b128 v[152:155], v156 offset:2048
	ds_read_b128 v[156:159], v156 offset:3072
	ds_read_b128 v[160:163], v172
	ds_read_b128 v[164:167], v172 offset:1024
	ds_read_b128 v[168:171], v172 offset:2048
	ds_read_b128 v[172:175], v172 offset:3072
	v_lshl_add_u64 v[188:189], v[134:135], 0, s[36:37]
	s_add_i32 m0, s51, 0xc000
	ds_read_b128 v[176:179], v143
	ds_read_b128 v[180:183], v143 offset:1024
	ds_read_b128 v[184:187], v143 offset:2048
	ds_read_b128 v[192:195], v143 offset:3072
	ds_read_b128 v[196:199], v143 offset:4096
	ds_read_b128 v[200:203], v143 offset:5120
	ds_read_b128 v[204:207], v143 offset:6144
	ds_read_b128 v[208:211], v143 offset:7168
	global_load_lds_dwordx4 v[188:189], off
	v_lshl_add_u64 v[188:189], v[140:141], 0, s[36:37]
	s_add_i32 m0, s51, 0xe000
	s_nop 0
	global_load_lds_dwordx4 v[188:189], off
	s_setprio 1
	s_nop 0
	s_waitcnt vmcnt(8) lgkmcnt(0)
	s_barrier
	v_mfma_f32_16x16x32_bf16 v[68:71], v[144:147], v[176:179], v[68:71]
	v_mfma_f32_16x16x32_bf16 v[72:75], v[152:155], v[176:179], v[72:75]
	v_mfma_f32_16x16x32_bf16 v[92:95], v[144:147], v[184:187], v[92:95]
	v_mfma_f32_16x16x32_bf16 v[80:83], v[152:155], v[184:187], v[80:83]
	v_mfma_f32_16x16x32_bf16 v[128:131], v[144:147], v[196:199], v[128:131]
	v_mfma_f32_16x16x32_bf16 v[112:115], v[152:155], v[196:199], v[112:115]
	v_mfma_f32_16x16x32_bf16 v[136:139], v[144:147], v[204:207], v[136:139]
	v_mfma_f32_16x16x32_bf16 v[120:123], v[152:155], v[204:207], v[120:123]
	v_mfma_f32_16x16x32_bf16 v[68:71], v[148:151], v[180:183], v[68:71]
	v_mfma_f32_16x16x32_bf16 v[72:75], v[156:159], v[180:183], v[72:75]
	v_mfma_f32_16x16x32_bf16 v[92:95], v[148:151], v[192:195], v[92:95]
	v_mfma_f32_16x16x32_bf16 v[80:83], v[156:159], v[192:195], v[80:83]
	v_mfma_f32_16x16x32_bf16 v[128:131], v[148:151], v[200:203], v[128:131]
	v_mfma_f32_16x16x32_bf16 v[112:115], v[156:159], v[200:203], v[112:115]
	v_mfma_f32_16x16x32_bf16 v[136:139], v[148:151], v[208:211], v[136:139]
	v_mfma_f32_16x16x32_bf16 v[120:123], v[156:159], v[208:211], v[120:123]
	v_mfma_f32_16x16x32_bf16 v[58:61], v[160:163], v[176:179], v[58:61]
	v_mfma_f32_16x16x32_bf16 v[46:49], v[168:171], v[176:179], v[46:49]
	v_mfma_f32_16x16x32_bf16 v[76:79], v[160:163], v[184:187], v[76:79]
	v_mfma_f32_16x16x32_bf16 v[50:53], v[168:171], v[184:187], v[50:53]
	v_mfma_f32_16x16x32_bf16 v[124:127], v[160:163], v[196:199], v[124:127]
	v_mfma_f32_16x16x32_bf16 v[116:119], v[168:171], v[196:199], v[116:119]
	v_mfma_f32_16x16x32_bf16 v[108:111], v[160:163], v[204:207], v[108:111]
	v_mfma_f32_16x16x32_bf16 v[104:107], v[168:171], v[204:207], v[104:107]
	v_mfma_f32_16x16x32_bf16 v[58:61], v[164:167], v[180:183], v[58:61]
	v_mfma_f32_16x16x32_bf16 v[46:49], v[172:175], v[180:183], v[46:49]
	v_mfma_f32_16x16x32_bf16 v[76:79], v[164:167], v[192:195], v[76:79]
	v_mfma_f32_16x16x32_bf16 v[50:53], v[172:175], v[192:195], v[50:53]
	v_mfma_f32_16x16x32_bf16 v[124:127], v[164:167], v[200:203], v[124:127]
	v_mfma_f32_16x16x32_bf16 v[116:119], v[172:175], v[200:203], v[116:119]
	v_mfma_f32_16x16x32_bf16 v[108:111], v[164:167], v[208:211], v[108:111]
	v_mfma_f32_16x16x32_bf16 v[104:107], v[172:175], v[208:211], v[104:107]
	s_barrier
	s_setprio 0
	s_setprio 1
	s_setprio 0
	s_waitcnt lgkmcnt(0)
	s_add_i32 s64, s65, s50
	v_lshl_add_u64 v[188:189], s[38:39], 0, v[66:67]
	s_mov_b32 m0, s64
	ds_read_b128 v[176:179], v143 offset:16384
	ds_read_b128 v[180:183], v143 offset:17408
	ds_read_b128 v[184:187], v143 offset:18432
	ds_read_b128 v[192:195], v143 offset:19456
	ds_read_b128 v[196:199], v143 offset:20480
	ds_read_b128 v[200:203], v143 offset:21504
	ds_read_b128 v[204:207], v143 offset:22528
	ds_read_b128 v[208:211], v143 offset:23552
	global_load_lds_dwordx4 v[188:189], off
	s_add_i32 m0, s64, 0x2000
	s_add_u32 s64, s38, 0x80000
	v_lshl_add_u64 v[220:221], s[38:39], 0, v[84:85]
	s_addc_u32 s65, s39, 0
	s_add_i32 s63, s63, s50
	global_load_lds_dwordx4 v[220:221], off
	v_lshl_add_u64 v[222:223], s[64:65], 0, v[66:67]
	s_mov_b32 m0, s63
	v_lshl_add_u64 v[224:225], s[40:41], 0, v[84:85]
	global_load_lds_dwordx4 v[222:223], off
	v_lshl_add_u64 v[222:223], s[64:65], 0, v[84:85]
	s_add_i32 m0, s63, 0x2000
	s_nop 0
	global_load_lds_dwordx4 v[222:223], off
	v_lshl_add_u64 v[222:223], s[40:41], 0, v[66:67]
	s_mov_b32 m0, s51
	s_nop 0
	global_load_lds_dwordx4 v[222:223], off
	s_mov_b32 m0, s52
	s_nop 0
	global_load_lds_dwordx4 v[224:225], off
	s_setprio 1
	s_nop 0
	s_waitcnt vmcnt(8) lgkmcnt(0)
	s_barrier
; #define PG8_STAGE(bufoff, gbase, voff) do { _Pragma("unroll") for (int _i = 0; _i < 2; ++_i) \
;         __builtin_amdgcn_global_load_lds((const unsigned*)((const char*)(gbase) + (voff)[_i]), (PG8_LAS unsigned*)(lds + (bufoff) + ldsw + _i * 8192), 16, 0, 0); } while (0)
; #define PG8_LDA(dst, b, h) do { _Pragma("unroll") for (int m = 0; m < 4; ++m) _Pragma("unroll") for (int k = 0; k < 2; ++k) dst[m][k] = *(const PG8_LAS bf16x8*)(lds + PG8_SA(b, h) + aoff + m * 2048 + k * 1024); } while (0)
; #define PG8_LDB(dst, b, h) do { _Pragma("unroll") for (int n = 0; n < 2; ++n) _Pragma("unroll") for (int k = 0; k < 2; ++k) dst[n][k] = *(const PG8_LAS bf16x8*)(lds + PG8_SB(b, h) + boff + n * 2048 + k * 1024); } while (0)
; #define PG8_MMA(ai, bj, At, Bt) do { __builtin_amdgcn_s_setprio(1); _Pragma("unroll") for (int m = 0; m < 4; ++m) _Pragma("unroll") for (int n = 0; n < 2; ++n) _Pragma("unroll") for (int k = 0; k < 2; ++k) \
;         acc[ai][bj][m][n] = __builtin_amdgcn_mfma_f32_16x16x32_bf16(Bt[n][k], At[m][k], acc[ai][bj][m][n], 0, 0, 0); __builtin_amdgcn_s_setprio(0); } while (0)
; #define PG8_WAIT_V(n) asm volatile("s_waitcnt vmcnt(" #n ")" ::: "memory")
; template <class Epi, class Sched, bool ALIGN_EPI = false, bool SP2 = false>
; __device__ __forceinline__ void gemm_phase(PG8_LAS unsigned char* lds, const Gemm g, const Sched& S, const Epi& E) {
;     ...
;             PG8_LDB(B0, 0, 0); PG8_LDB(B1, 0, 1); PG8_SCHED; PG8_LDA(At, 0, 0); PG8_STAGE(PG8_SA(1, 1), a1 + hstep, voffA);
;             PG8_WAIT_V(8); PG8_WAIT_L(0); PG8_BAR; PG8_MMA(0, 0, At, B0); PG8_MMA(0, 1, At, B1); PG8_BAR; PG8_SCHED;
;             PG8_LDA(At, 0, 1); PG8_STAGE(PG8_SB(0, 0), b2, voffB); PG8_STAGE(PG8_SB(0, 1), b2 + hstep, voffB); PG8_STAGE(PG8_SA(0, 0), a2, voffA);
;             PG8_WAIT_V(8); PG8_WAIT_L(0); PG8_BAR; PG8_MMA(1, 0, At, B0); PG8_MMA(1, 1, At, B1); PG8_BAR; PG8_SCHED;
;             PG8_LDB(B0, 1, 0); PG8_LDB(B1, 1, 1); PG8_SCHED; PG8_LDA(At, 1, 0); PG8_STAGE(PG8_SA(0, 1), a2 + hstep, voffA);
;             PG8_WAIT_V(8); PG8_WAIT_L(0); PG8_BAR; PG8_MMA(0, 0, At, B0); PG8_MMA(0, 1, At, B1); PG8_BAR; PG8_SCHED;
;             PG8_LDA(At, 1, 1); PG8_STAGE(PG8_SB(1, 0), b3, voffB); PG8_STAGE(PG8_SB(1, 1), b3 + hstep, voffB); PG8_STAGE(PG8_SA(1, 0), a3, voffA);
;             PG8_WAIT_V(8); PG8_WAIT_L(0); PG8_BAR; PG8_MMA(1, 0, At, B0); PG8_MMA(1, 1, At, B1); PG8_BAR; PG8_SCHED;
	v_mfma_f32_16x16x32_bf16 v[100:103], v[144:147], v[176:179], v[100:103]
	v_mfma_f32_16x16x32_bf16 v[96:99], v[152:155], v[176:179], v[96:99]
	v_mfma_f32_16x16x32_bf16 v[88:91], v[144:147], v[184:187], v[88:91]
	v_mfma_f32_16x16x32_bf16 v[42:45], v[152:155], v[184:187], v[42:45]
	v_mfma_f32_16x16x32_bf16 v[38:41], v[144:147], v[196:199], v[38:41]
	v_mfma_f32_16x16x32_bf16 v[26:29], v[152:155], v[196:199], v[26:29]
	v_mfma_f32_16x16x32_bf16 v[22:25], v[144:147], v[204:207], v[22:25]
	v_mfma_f32_16x16x32_bf16 v[14:17], v[152:155], v[204:207], v[14:17]
	v_mfma_f32_16x16x32_bf16 v[100:103], v[148:151], v[180:183], v[100:103]
	v_mfma_f32_16x16x32_bf16 v[96:99], v[156:159], v[180:183], v[96:99]
	v_mfma_f32_16x16x32_bf16 v[88:91], v[148:151], v[192:195], v[88:91]
	v_mfma_f32_16x16x32_bf16 v[42:45], v[156:159], v[192:195], v[42:45]
	v_mfma_f32_16x16x32_bf16 v[38:41], v[148:151], v[200:203], v[38:41]
	v_mfma_f32_16x16x32_bf16 v[26:29], v[156:159], v[200:203], v[26:29]
	v_mfma_f32_16x16x32_bf16 v[22:25], v[148:151], v[208:211], v[22:25]
	v_mfma_f32_16x16x32_bf16 v[14:17], v[156:159], v[208:211], v[14:17]
	v_mfma_f32_16x16x32_bf16 v[62:65], v[160:163], v[176:179], v[62:65]
	v_mfma_f32_16x16x32_bf16 v[54:57], v[168:171], v[176:179], v[54:57]
	v_mfma_f32_16x16x32_bf16 v[34:37], v[160:163], v[184:187], v[34:37]
	v_mfma_f32_16x16x32_bf16 v[30:33], v[168:171], v[184:187], v[30:33]
	v_mfma_f32_16x16x32_bf16 v[18:21], v[160:163], v[196:199], v[18:21]
	v_mfma_f32_16x16x32_bf16 v[10:13], v[168:171], v[196:199], v[10:13]
	v_mfma_f32_16x16x32_bf16 v[6:9], v[160:163], v[204:207], v[6:9]
	v_mfma_f32_16x16x32_bf16 v[2:5], v[168:171], v[204:207], v[2:5]
	v_mfma_f32_16x16x32_bf16 v[62:65], v[164:167], v[180:183], v[62:65]
	v_mfma_f32_16x16x32_bf16 v[54:57], v[172:175], v[180:183], v[54:57]
	v_mfma_f32_16x16x32_bf16 v[34:37], v[164:167], v[192:195], v[34:37]
	v_mfma_f32_16x16x32_bf16 v[30:33], v[172:175], v[192:195], v[30:33]
	v_mfma_f32_16x16x32_bf16 v[18:21], v[164:167], v[200:203], v[18:21]
	v_mfma_f32_16x16x32_bf16 v[10:13], v[172:175], v[200:203], v[10:13]
	v_mfma_f32_16x16x32_bf16 v[6:9], v[164:167], v[208:211], v[6:9]
	v_mfma_f32_16x16x32_bf16 v[2:5], v[172:175], v[208:211], v[2:5]
	s_barrier
	s_setprio 0
	s_setprio 1
	s_setprio 0
	s_waitcnt lgkmcnt(0)
	s_add_i32 s63, 0, 0x18000
	s_add_i32 s64, 0, 0x1c000
	v_add_u32_e32 v156, s63, v142
	v_add_u32_e32 v172, s64, v142
	ds_read_b128 v[144:147], v156
	ds_read_b128 v[148:151], v156 offset:1024
	ds_read_b128 v[152:155], v156 offset:2048
	ds_read_b128 v[156:159], v156 offset:3072
	ds_read_b128 v[160:163], v172
	ds_read_b128 v[164:167], v172 offset:1024
	ds_read_b128 v[168:171], v172 offset:2048
	ds_read_b128 v[172:175], v172 offset:3072
	s_add_u32 s40, s40, 0x80000
	s_addc_u32 s41, s41, 0
	s_mov_b32 m0, s1
	v_lshl_add_u64 v[226:227], s[40:41], 0, v[66:67]
	ds_read_b128 v[176:179], v143 offset:32768
	ds_read_b128 v[180:183], v143 offset:33792
	ds_read_b128 v[184:187], v143 offset:34816
	ds_read_b128 v[192:195], v143 offset:35840
	ds_read_b128 v[196:199], v143 offset:36864
	ds_read_b128 v[200:203], v143 offset:37888
	ds_read_b128 v[204:207], v143 offset:38912
	ds_read_b128 v[208:211], v143 offset:39936
	global_load_lds_dwordx4 v[226:227], off
	v_lshl_add_u64 v[226:227], s[40:41], 0, v[84:85]
	s_mov_b32 m0, s54
	s_nop 0
	global_load_lds_dwordx4 v[226:227], off
	s_setprio 1
	s_nop 0
	s_waitcnt vmcnt(8) lgkmcnt(0)
	s_barrier
	v_mfma_f32_16x16x32_bf16 v[68:71], v[144:147], v[176:179], v[68:71]
	v_mfma_f32_16x16x32_bf16 v[72:75], v[152:155], v[176:179], v[72:75]
	v_mfma_f32_16x16x32_bf16 v[92:95], v[144:147], v[184:187], v[92:95]
	v_mfma_f32_16x16x32_bf16 v[80:83], v[152:155], v[184:187], v[80:83]
	v_mfma_f32_16x16x32_bf16 v[128:131], v[144:147], v[196:199], v[128:131]
	v_mfma_f32_16x16x32_bf16 v[112:115], v[152:155], v[196:199], v[112:115]
	v_mfma_f32_16x16x32_bf16 v[136:139], v[144:147], v[204:207], v[136:139]
	v_mfma_f32_16x16x32_bf16 v[120:123], v[152:155], v[204:207], v[120:123]
	v_mfma_f32_16x16x32_bf16 v[68:71], v[148:151], v[180:183], v[68:71]
	v_mfma_f32_16x16x32_bf16 v[72:75], v[156:159], v[180:183], v[72:75]
	v_mfma_f32_16x16x32_bf16 v[92:95], v[148:151], v[192:195], v[92:95]
	v_mfma_f32_16x16x32_bf16 v[80:83], v[156:159], v[192:195], v[80:83]
	v_mfma_f32_16x16x32_bf16 v[128:131], v[148:151], v[200:203], v[128:131]
	v_mfma_f32_16x16x32_bf16 v[112:115], v[156:159], v[200:203], v[112:115]
	v_mfma_f32_16x16x32_bf16 v[136:139], v[148:151], v[208:211], v[136:139]
	v_mfma_f32_16x16x32_bf16 v[120:123], v[156:159], v[208:211], v[120:123]
	v_mfma_f32_16x16x32_bf16 v[58:61], v[160:163], v[176:179], v[58:61]
	v_mfma_f32_16x16x32_bf16 v[46:49], v[168:171], v[176:179], v[46:49]
	v_mfma_f32_16x16x32_bf16 v[76:79], v[160:163], v[184:187], v[76:79]
	v_mfma_f32_16x16x32_bf16 v[50:53], v[168:171], v[184:187], v[50:53]
	v_mfma_f32_16x16x32_bf16 v[124:127], v[160:163], v[196:199], v[124:127]
	v_mfma_f32_16x16x32_bf16 v[116:119], v[168:171], v[196:199], v[116:119]
	v_mfma_f32_16x16x32_bf16 v[108:111], v[160:163], v[204:207], v[108:111]
	v_mfma_f32_16x16x32_bf16 v[104:107], v[168:171], v[204:207], v[104:107]
	v_mfma_f32_16x16x32_bf16 v[58:61], v[164:167], v[180:183], v[58:61]
	v_mfma_f32_16x16x32_bf16 v[46:49], v[172:175], v[180:183], v[46:49]
	v_mfma_f32_16x16x32_bf16 v[76:79], v[164:167], v[192:195], v[76:79]
	v_mfma_f32_16x16x32_bf16 v[50:53], v[172:175], v[192:195], v[50:53]
	v_mfma_f32_16x16x32_bf16 v[124:127], v[164:167], v[200:203], v[124:127]
	v_mfma_f32_16x16x32_bf16 v[116:119], v[172:175], v[200:203], v[116:119]
	v_mfma_f32_16x16x32_bf16 v[108:111], v[164:167], v[208:211], v[108:111]
	v_mfma_f32_16x16x32_bf16 v[104:107], v[172:175], v[208:211], v[104:107]
	s_barrier
; #define PG8_STAGE(bufoff, gbase, voff) do { _Pragma("unroll") for (int _i = 0; _i < 2; ++_i) \
;         __builtin_amdgcn_global_load_lds((const unsigned*)((const char*)(gbase) + (voff)[_i]), (PG8_LAS unsigned*)(lds + (bufoff) + ldsw + _i * 8192), 16, 0, 0); } while (0)
; #define PG8_LDA(dst, b, h) do { _Pragma("unroll") for (int m = 0; m < 4; ++m) _Pragma("unroll") for (int k = 0; k < 2; ++k) dst[m][k] = *(const PG8_LAS bf16x8*)(lds + PG8_SA(b, h) + aoff + m * 2048 + k * 1024); } while (0)
; #define PG8_MMA(ai, bj, At, Bt) do { __builtin_amdgcn_s_setprio(1); _Pragma("unroll") for (int m = 0; m < 4; ++m) _Pragma("unroll") for (int n = 0; n < 2; ++n) _Pragma("unroll") for (int k = 0; k < 2; ++k) \
;         acc[ai][bj][m][n] = __builtin_amdgcn_mfma_f32_16x16x32_bf16(Bt[n][k], At[m][k], acc[ai][bj][m][n], 0, 0, 0); __builtin_amdgcn_s_setprio(0); } while (0)
; #define PG8_WAIT_V(n) asm volatile("s_waitcnt vmcnt(" #n ")" ::: "memory")
; #define PG8_WAIT_L(n) asm volatile("s_waitcnt lgkmcnt(" #n ")" ::: "memory")
; #define PG8_BAR __builtin_amdgcn_s_barrier()
; #define PG8_SCHED __builtin_amdgcn_sched_barrier(0)
; template <class Epi, class Sched, bool ALIGN_EPI = false, bool SP2 = false>
; __device__ __forceinline__ void gemm_phase(PG8_LAS unsigned char* lds, const Gemm g, const Sched& S, const Epi& E) {
;     ...
;             PG8_LDA(At, 1, 1); PG8_STAGE(PG8_SB(1, 0), b3, voffB); PG8_STAGE(PG8_SB(1, 1), b3 + hstep, voffB); PG8_STAGE(PG8_SA(1, 0), a3, voffA);
;             PG8_WAIT_V(8); PG8_WAIT_L(0); PG8_BAR; PG8_MMA(1, 0, At, B0); PG8_MMA(1, 1, At, B1); PG8_BAR; PG8_SCHED;
;     ...
; #pragma unroll
;         for (int a = 0; a < 2; ++a)
; #pragma unroll
;             for (int b = 0; b < 2; ++b)
; #pragma unroll
;                 for (int m = 0; m < 4; ++m)
; #pragma unroll
;                     for (int n = 0; n < 2; ++n) acc[a][b][m][n] = (f32x4){0.f, 0.f, 0.f, 0.f};
;         cur = nxt; cA = nA; cB = nB; ++ui;
	s_setprio 0
	s_setprio 1
	s_setprio 0
	s_waitcnt lgkmcnt(0)
	s_add_i32 s40, s63, s50
	v_lshl_add_u64 v[188:189], v[188:189], 0, s[88:89]
	s_mov_b32 m0, s40
	ds_read_b128 v[176:179], v143 offset:49152
	ds_read_b128 v[180:183], v143 offset:50176
	ds_read_b128 v[184:187], v143 offset:51200
	ds_read_b128 v[192:195], v143 offset:52224
	ds_read_b128 v[196:199], v143 offset:53248
	ds_read_b128 v[200:203], v143 offset:54272
	ds_read_b128 v[204:207], v143 offset:55296
	ds_read_b128 v[208:211], v143 offset:56320
	global_load_lds_dwordx4 v[188:189], off
	s_add_i32 m0, s40, 0x2000
	s_add_u32 s38, s38, 0x80080
	v_lshl_add_u64 v[188:189], v[220:221], 0, s[88:89]
	s_addc_u32 s39, s39, 0
	s_add_i32 s40, s64, s50
	global_load_lds_dwordx4 v[188:189], off
	v_lshl_add_u64 v[188:189], s[38:39], 0, v[66:67]
	s_mov_b32 m0, s40
	s_nop 0
	global_load_lds_dwordx4 v[188:189], off
	v_lshl_add_u64 v[188:189], s[38:39], 0, v[84:85]
	s_add_i32 m0, s40, 0x2000
	s_nop 0
	global_load_lds_dwordx4 v[188:189], off
	v_lshl_add_u64 v[188:189], v[222:223], 0, s[88:89]
	s_mov_b32 m0, s55
	s_nop 0
	global_load_lds_dwordx4 v[188:189], off
	v_lshl_add_u64 v[188:189], v[224:225], 0, s[88:89]
	s_mov_b32 m0, s56
	s_nop 0
	global_load_lds_dwordx4 v[188:189], off
	s_setprio 1
	s_nop 0
	s_waitcnt vmcnt(8) lgkmcnt(0)
	s_barrier
	v_mfma_f32_16x16x32_bf16 v[100:103], v[144:147], v[176:179], v[100:103]
	v_mfma_f32_16x16x32_bf16 v[96:99], v[152:155], v[176:179], v[96:99]
	v_mfma_f32_16x16x32_bf16 v[88:91], v[144:147], v[184:187], v[88:91]
	v_mfma_f32_16x16x32_bf16 v[42:45], v[152:155], v[184:187], v[42:45]
	v_mfma_f32_16x16x32_bf16 v[38:41], v[144:147], v[196:199], v[38:41]
	v_mfma_f32_16x16x32_bf16 v[26:29], v[152:155], v[196:199], v[26:29]
	v_mfma_f32_16x16x32_bf16 v[22:25], v[144:147], v[204:207], v[22:25]
	v_mfma_f32_16x16x32_bf16 v[14:17], v[152:155], v[204:207], v[14:17]
	v_mfma_f32_16x16x32_bf16 v[100:103], v[148:151], v[180:183], v[100:103]
	v_mfma_f32_16x16x32_bf16 v[96:99], v[156:159], v[180:183], v[96:99]
	v_mfma_f32_16x16x32_bf16 v[88:91], v[148:151], v[192:195], v[88:91]
	v_mfma_f32_16x16x32_bf16 v[42:45], v[156:159], v[192:195], v[42:45]
	v_mfma_f32_16x16x32_bf16 v[38:41], v[148:151], v[200:203], v[38:41]
	v_mfma_f32_16x16x32_bf16 v[26:29], v[156:159], v[200:203], v[26:29]
	v_mfma_f32_16x16x32_bf16 v[22:25], v[148:151], v[208:211], v[22:25]
	v_mfma_f32_16x16x32_bf16 v[14:17], v[156:159], v[208:211], v[14:17]
	v_mfma_f32_16x16x32_bf16 v[62:65], v[160:163], v[176:179], v[62:65]
	v_mfma_f32_16x16x32_bf16 v[54:57], v[168:171], v[176:179], v[54:57]
	v_mfma_f32_16x16x32_bf16 v[34:37], v[160:163], v[184:187], v[34:37]
	v_mfma_f32_16x16x32_bf16 v[30:33], v[168:171], v[184:187], v[30:33]
	v_mfma_f32_16x16x32_bf16 v[18:21], v[160:163], v[196:199], v[18:21]
	v_mfma_f32_16x16x32_bf16 v[10:13], v[168:171], v[196:199], v[10:13]
	v_mfma_f32_16x16x32_bf16 v[6:9], v[160:163], v[204:207], v[6:9]
	v_mfma_f32_16x16x32_bf16 v[2:5], v[168:171], v[204:207], v[2:5]
	v_mfma_f32_16x16x32_bf16 v[62:65], v[164:167], v[180:183], v[62:65]
	v_mfma_f32_16x16x32_bf16 v[54:57], v[172:175], v[180:183], v[54:57]
	v_mfma_f32_16x16x32_bf16 v[34:37], v[164:167], v[192:195], v[34:37]
	v_mfma_f32_16x16x32_bf16 v[30:33], v[172:175], v[192:195], v[30:33]
	v_mfma_f32_16x16x32_bf16 v[18:21], v[164:167], v[200:203], v[18:21]
	v_mfma_f32_16x16x32_bf16 v[10:13], v[172:175], v[200:203], v[10:13]
	v_mfma_f32_16x16x32_bf16 v[6:9], v[164:167], v[208:211], v[6:9]
	v_mfma_f32_16x16x32_bf16 v[2:5], v[172:175], v[208:211], v[2:5]
	s_barrier
	s_setprio 0
	s_setprio 1
	s_setprio 0
	s_waitcnt lgkmcnt(0)
	s_add_i32 s62, s62, 2
	s_add_u32 s36, s36, 0x100
	s_addc_u32 s37, s37, 0
	s_cmp_gt_u32 s62, 29
	s_cbranch_scc0 .LBB0_905
	s_add_u32 s36, s3, 0xffffff00
	s_addc_u32 s37, s59, -1
	s_andn2_b64 vcc, exec, s[10:11]
	s_cbranch_vccnz .LBB0_896
	v_mov_b32_e32 v2, 0
	s_mov_b32 s12, s26
	s_mov_b32 s46, s28
	s_mov_b64 s[22:23], s[34:35]
	s_mov_b32 s57, s2
	v_mov_b32_e32 v3, v2
	v_mov_b32_e32 v4, v2
	v_mov_b32_e32 v5, v2
	v_mov_b32_e32 v6, v2
	v_mov_b32_e32 v7, v2
	v_mov_b32_e32 v8, v2
	v_mov_b32_e32 v9, v2
	v_mov_b32_e32 v10, v2
	v_mov_b32_e32 v11, v2
	v_mov_b32_e32 v12, v2
	v_mov_b32_e32 v13, v2
	v_mov_b32_e32 v18, v2
	v_mov_b32_e32 v19, v2
	v_mov_b32_e32 v20, v2
	v_mov_b32_e32 v21, v2
	v_mov_b32_e32 v30, v2
	v_mov_b32_e32 v31, v2
	v_mov_b32_e32 v32, v2
	v_mov_b32_e32 v33, v2
	v_mov_b32_e32 v34, v2
	v_mov_b32_e32 v35, v2
	v_mov_b32_e32 v36, v2
	v_mov_b32_e32 v37, v2
	v_mov_b32_e32 v54, v2
	v_mov_b32_e32 v55, v2
	v_mov_b32_e32 v56, v2
	v_mov_b32_e32 v57, v2
	v_mov_b32_e32 v62, v2
	v_mov_b32_e32 v63, v2
	v_mov_b32_e32 v64, v2
	v_mov_b32_e32 v65, v2
	v_mov_b32_e32 v14, v2
	v_mov_b32_e32 v15, v2
	v_mov_b32_e32 v16, v2
	v_mov_b32_e32 v17, v2
	v_mov_b32_e32 v22, v2
	v_mov_b32_e32 v23, v2
	v_mov_b32_e32 v24, v2
	v_mov_b32_e32 v25, v2
	v_mov_b32_e32 v26, v2
	v_mov_b32_e32 v27, v2
	v_mov_b32_e32 v28, v2
	v_mov_b32_e32 v29, v2
	v_mov_b32_e32 v38, v2
	v_mov_b32_e32 v39, v2
	v_mov_b32_e32 v40, v2
	v_mov_b32_e32 v41, v2
	v_mov_b32_e32 v42, v2
	v_mov_b32_e32 v43, v2
	v_mov_b32_e32 v44, v2
	v_mov_b32_e32 v45, v2
	v_mov_b32_e32 v88, v2
	v_mov_b32_e32 v89, v2
	v_mov_b32_e32 v90, v2
	v_mov_b32_e32 v91, v2
	v_mov_b32_e32 v96, v2
	v_mov_b32_e32 v97, v2
	v_mov_b32_e32 v98, v2
	v_mov_b32_e32 v99, v2
	v_mov_b32_e32 v100, v2
	v_mov_b32_e32 v101, v2
	v_mov_b32_e32 v102, v2
	v_mov_b32_e32 v103, v2
	v_mov_b32_e32 v104, v2
	v_mov_b32_e32 v105, v2
	v_mov_b32_e32 v106, v2
	v_mov_b32_e32 v107, v2
	v_mov_b32_e32 v108, v2
	v_mov_b32_e32 v109, v2
	v_mov_b32_e32 v110, v2
	v_mov_b32_e32 v111, v2
	v_mov_b32_e32 v116, v2
	v_mov_b32_e32 v117, v2
	v_mov_b32_e32 v118, v2
	v_mov_b32_e32 v119, v2
	v_mov_b32_e32 v124, v2
	v_mov_b32_e32 v125, v2
	v_mov_b32_e32 v126, v2
	v_mov_b32_e32 v127, v2
	v_mov_b32_e32 v50, v2
	v_mov_b32_e32 v51, v2
	v_mov_b32_e32 v52, v2
	v_mov_b32_e32 v53, v2
	v_mov_b32_e32 v76, v2
	v_mov_b32_e32 v77, v2
	v_mov_b32_e32 v78, v2
	v_mov_b32_e32 v79, v2
	v_mov_b32_e32 v46, v2
	v_mov_b32_e32 v47, v2
	v_mov_b32_e32 v48, v2
	v_mov_b32_e32 v49, v2
	v_mov_b32_e32 v58, v2
	v_mov_b32_e32 v59, v2
	v_mov_b32_e32 v60, v2
	v_mov_b32_e32 v61, v2
	v_mov_b32_e32 v120, v2
	v_mov_b32_e32 v121, v2
	v_mov_b32_e32 v122, v2
	v_mov_b32_e32 v123, v2
	v_mov_b32_e32 v136, v2
	v_mov_b32_e32 v137, v2
	v_mov_b32_e32 v138, v2
	v_mov_b32_e32 v139, v2
	v_mov_b32_e32 v112, v2
	v_mov_b32_e32 v113, v2
	v_mov_b32_e32 v114, v2
	v_mov_b32_e32 v115, v2
	v_mov_b32_e32 v128, v2
	v_mov_b32_e32 v129, v2
	v_mov_b32_e32 v130, v2
	v_mov_b32_e32 v131, v2
	v_mov_b32_e32 v80, v2
	v_mov_b32_e32 v81, v2
	v_mov_b32_e32 v82, v2
	v_mov_b32_e32 v83, v2
	v_mov_b32_e32 v92, v2
	v_mov_b32_e32 v93, v2
	v_mov_b32_e32 v94, v2
	v_mov_b32_e32 v95, v2
	v_mov_b32_e32 v72, v2
	v_mov_b32_e32 v73, v2
	v_mov_b32_e32 v74, v2
	v_mov_b32_e32 v75, v2
	v_mov_b32_e32 v68, v2
	v_mov_b32_e32 v69, v2
	v_mov_b32_e32 v70, v2
	v_mov_b32_e32 v71, v2
	s_mov_b64 s[64:65], s[72:73]
	s_andn2_b64 vcc, exec, s[8:9]
	s_mov_b32 s72, s67
	s_cbranch_vccnz .LBB0_897

; #define PG8_STAGE(bufoff, gbase, voff) do { _Pragma("unroll") for (int _i = 0; _i < 2; ++_i) \
;         __builtin_amdgcn_global_load_lds((const unsigned*)((const char*)(gbase) + (voff)[_i]), (PG8_LAS unsigned*)(lds + (bufoff) + ldsw + _i * 8192), 16, 0, 0); } while (0)
; #define PG8_LDA(dst, b, h) do { _Pragma("unroll") for (int m = 0; m < 4; ++m) _Pragma("unroll") for (int k = 0; k < 2; ++k) dst[m][k] = *(const PG8_LAS bf16x8*)(lds + PG8_SA(b, h) + aoff + m * 2048 + k * 1024); } while (0)
; #define PG8_LDB(dst, b, h) do { _Pragma("unroll") for (int n = 0; n < 2; ++n) _Pragma("unroll") for (int k = 0; k < 2; ++k) dst[n][k] = *(const PG8_LAS bf16x8*)(lds + PG8_SB(b, h) + boff + n * 2048 + k * 1024); } while (0)
; #define PG8_MMA(ai, bj, At, Bt) do { __builtin_amdgcn_s_setprio(1); _Pragma("unroll") for (int m = 0; m < 4; ++m) _Pragma("unroll") for (int n = 0; n < 2; ++n) _Pragma("unroll") for (int k = 0; k < 2; ++k) \
;         acc[ai][bj][m][n] = __builtin_amdgcn_mfma_f32_16x16x32_bf16(Bt[n][k], At[m][k], acc[ai][bj][m][n], 0, 0, 0); __builtin_amdgcn_s_setprio(0); } while (0)
; #define PG8_WAIT_V(n) asm volatile("s_waitcnt vmcnt(" #n ")" ::: "memory")
; template <class Epi, class Sched, bool ALIGN_EPI = false, bool SP2 = false>
; __device__ __forceinline__ void gemm_phase(PG8_LAS unsigned char* lds, const Gemm g, const Sched& S, const Epi& E) {
;     ...
;             PG8_LDB(B0, 0, 0); PG8_LDB(B1, 0, 1); PG8_SCHED; PG8_LDA(At, 0, 0); PG8_STAGE(PG8_SA(1, 1), a1 + hstep, voffA);
;             PG8_WAIT_V(8); PG8_WAIT_L(0); PG8_BAR; PG8_MMA(0, 0, At, B0); PG8_MMA(0, 1, At, B1); PG8_BAR; PG8_SCHED;
;             PG8_LDA(At, 0, 1); PG8_STAGE(PG8_SB(0, 0), b2, voffB); PG8_STAGE(PG8_SB(0, 1), b2 + hstep, voffB); PG8_STAGE(PG8_SA(0, 0), a2, voffA);
;             PG8_WAIT_V(8); PG8_WAIT_L(0); PG8_BAR; PG8_MMA(1, 0, At, B0); PG8_MMA(1, 1, At, B1); PG8_BAR; PG8_SCHED;
;             PG8_LDB(B0, 1, 0); PG8_LDB(B1, 1, 1); PG8_SCHED; PG8_LDA(At, 1, 0); PG8_STAGE(PG8_SA(0, 1), a2 + hstep, voffA);
;             PG8_WAIT_V(8); PG8_WAIT_L(0); PG8_BAR; PG8_MMA(0, 0, At, B0); PG8_MMA(0, 1, At, B1); PG8_BAR; PG8_SCHED;
;             PG8_LDA(At, 1, 1); PG8_STAGE(PG8_SB(1, 0), b3, voffB); PG8_STAGE(PG8_SB(1, 1), b3 + hstep, voffB); PG8_STAGE(PG8_SA(1, 0), a3, voffA);
;             PG8_WAIT_V(8); PG8_WAIT_L(0); PG8_BAR; PG8_MMA(1, 0, At, B0); PG8_MMA(1, 1, At, B1); PG8_BAR; PG8_SCHED;
.LBB0_979:
	s_xor_b64 s[40:41], s[38:39], -1
	s_add_u32 s27, s12, s2
	s_addc_u32 s29, s13, 0
	s_add_u32 s3, s27, 0x100
	s_addc_u32 s44, s29, 0
	s_and_b64 s[42:43], s[38:39], exec
	s_cselect_b32 s43, s44, s35
	s_cselect_b32 s42, s3, s34
	s_add_u32 s2, s20, s2
	s_addc_u32 s3, s21, 0
	s_add_u32 s44, s2, 0x100
	s_addc_u32 s45, s3, 0
	s_and_b64 s[2:3], s[38:39], exec
	s_cselect_b32 s39, s45, s31
	s_cselect_b32 s38, s44, s30
	s_add_i32 s44, 0, 0x10000
	s_add_i32 s45, 0, 0x14000
	v_add_u32_e32 v164, s44, v0
	v_add_u32_e32 v180, s45, v0
	ds_read_b128 v[152:155], v164
	ds_read_b128 v[156:159], v164 offset:1024
	ds_read_b128 v[160:163], v164 offset:2048
	ds_read_b128 v[164:167], v164 offset:3072
	ds_read_b128 v[168:171], v180
	ds_read_b128 v[172:175], v180 offset:1024
	ds_read_b128 v[176:179], v180 offset:2048
	ds_read_b128 v[180:183], v180 offset:3072
	s_add_u32 s2, s27, 0x80080
	s_addc_u32 s3, s29, 0
	v_lshl_add_u64 v[224:225], s[2:3], 0, v[66:67]
	s_add_i32 m0, s52, 0xc000
	ds_read_b128 v[184:187], v151
	ds_read_b128 v[188:191], v151 offset:1024
	ds_read_b128 v[192:195], v151 offset:2048
	ds_read_b128 v[196:199], v151 offset:3072
	ds_read_b128 v[200:203], v151 offset:4096
	ds_read_b128 v[204:207], v151 offset:5120
	ds_read_b128 v[208:211], v151 offset:6144
	ds_read_b128 v[220:223], v151 offset:7168
	global_load_lds_dwordx4 v[224:225], off
	v_lshl_add_u64 v[224:225], s[2:3], 0, v[132:133]
	s_add_i32 m0, s52, 0xe000
	s_nop 0
	global_load_lds_dwordx4 v[224:225], off
	s_setprio 1
	s_nop 0
	s_waitcnt vmcnt(8) lgkmcnt(0)
	s_barrier
	v_mfma_f32_16x16x32_bf16 v[128:131], v[152:155], v[184:187], v[128:131]
	v_mfma_f32_16x16x32_bf16 v[124:127], v[160:163], v[184:187], v[124:127]
	v_mfma_f32_16x16x32_bf16 v[120:123], v[152:155], v[192:195], v[120:123]
	v_mfma_f32_16x16x32_bf16 v[116:119], v[160:163], v[192:195], v[116:119]
	v_mfma_f32_16x16x32_bf16 v[112:115], v[152:155], v[200:203], v[112:115]
	v_mfma_f32_16x16x32_bf16 v[108:111], v[160:163], v[200:203], v[108:111]
	v_mfma_f32_16x16x32_bf16 v[100:103], v[152:155], v[208:211], v[100:103]
	v_mfma_f32_16x16x32_bf16 v[92:95], v[160:163], v[208:211], v[92:95]
	v_mfma_f32_16x16x32_bf16 v[128:131], v[156:159], v[188:191], v[128:131]
	v_mfma_f32_16x16x32_bf16 v[124:127], v[164:167], v[188:191], v[124:127]
	v_mfma_f32_16x16x32_bf16 v[120:123], v[156:159], v[196:199], v[120:123]
	v_mfma_f32_16x16x32_bf16 v[116:119], v[164:167], v[196:199], v[116:119]
	v_mfma_f32_16x16x32_bf16 v[112:115], v[156:159], v[204:207], v[112:115]
	v_mfma_f32_16x16x32_bf16 v[108:111], v[164:167], v[204:207], v[108:111]
	v_mfma_f32_16x16x32_bf16 v[100:103], v[156:159], v[220:223], v[100:103]
	v_mfma_f32_16x16x32_bf16 v[92:95], v[164:167], v[220:223], v[92:95]
	v_mfma_f32_16x16x32_bf16 v[104:107], v[168:171], v[184:187], v[104:107]
	v_mfma_f32_16x16x32_bf16 v[96:99], v[176:179], v[184:187], v[96:99]
	v_mfma_f32_16x16x32_bf16 v[88:91], v[168:171], v[192:195], v[88:91]
	v_mfma_f32_16x16x32_bf16 v[84:87], v[176:179], v[192:195], v[84:87]
	v_mfma_f32_16x16x32_bf16 v[80:83], v[168:171], v[200:203], v[80:83]
	v_mfma_f32_16x16x32_bf16 v[76:79], v[176:179], v[200:203], v[76:79]
	v_mfma_f32_16x16x32_bf16 v[72:75], v[168:171], v[208:211], v[72:75]
	v_mfma_f32_16x16x32_bf16 v[68:71], v[176:179], v[208:211], v[68:71]
	v_mfma_f32_16x16x32_bf16 v[104:107], v[172:175], v[188:191], v[104:107]
	v_mfma_f32_16x16x32_bf16 v[96:99], v[180:183], v[188:191], v[96:99]
	v_mfma_f32_16x16x32_bf16 v[88:91], v[172:175], v[196:199], v[88:91]
	v_mfma_f32_16x16x32_bf16 v[84:87], v[180:183], v[196:199], v[84:87]
	v_mfma_f32_16x16x32_bf16 v[80:83], v[172:175], v[204:207], v[80:83]
	v_mfma_f32_16x16x32_bf16 v[76:79], v[180:183], v[204:207], v[76:79]
	v_mfma_f32_16x16x32_bf16 v[72:75], v[172:175], v[220:223], v[72:75]
	v_mfma_f32_16x16x32_bf16 v[68:71], v[180:183], v[220:223], v[68:71]
	s_barrier
	s_setprio 0
	s_setprio 1
	s_setprio 0
	s_waitcnt lgkmcnt(0)
	s_add_i32 s2, s44, s51
	v_lshl_add_u64 v[224:225], s[38:39], 0, v[66:67]
	s_mov_b32 m0, s2
	ds_read_b128 v[184:187], v151 offset:16384
	ds_read_b128 v[188:191], v151 offset:17408
	ds_read_b128 v[192:195], v151 offset:18432
	ds_read_b128 v[196:199], v151 offset:19456
	ds_read_b128 v[200:203], v151 offset:20480
	ds_read_b128 v[204:207], v151 offset:21504
	ds_read_b128 v[208:211], v151 offset:22528
	ds_read_b128 v[220:223], v151 offset:23552
	global_load_lds_dwordx4 v[224:225], off
	s_add_i32 m0, s2, 0x2000
	s_add_u32 s2, s38, 0x80000
	v_lshl_add_u64 v[226:227], s[38:39], 0, v[132:133]
	s_addc_u32 s3, s39, 0
	s_add_i32 s27, s45, s51
	global_load_lds_dwordx4 v[226:227], off
	v_lshl_add_u64 v[228:229], s[2:3], 0, v[66:67]
	s_mov_b32 m0, s27
	v_lshl_add_u64 v[230:231], s[42:43], 0, v[132:133]
	global_load_lds_dwordx4 v[228:229], off
	v_lshl_add_u64 v[228:229], s[2:3], 0, v[132:133]
	s_add_i32 m0, s27, 0x2000
	s_nop 0
	global_load_lds_dwordx4 v[228:229], off
	v_lshl_add_u64 v[228:229], s[42:43], 0, v[66:67]
	s_mov_b32 m0, s52
	s_nop 0
	global_load_lds_dwordx4 v[228:229], off
	s_mov_b32 m0, s53
	s_nop 0
	global_load_lds_dwordx4 v[230:231], off
	s_setprio 1
	s_nop 0
	s_waitcnt vmcnt(8) lgkmcnt(0)
	s_barrier
; #define PG8_STAGE(bufoff, gbase, voff) do { _Pragma("unroll") for (int _i = 0; _i < 2; ++_i) \
;         __builtin_amdgcn_global_load_lds((const unsigned*)((const char*)(gbase) + (voff)[_i]), (PG8_LAS unsigned*)(lds + (bufoff) + ldsw + _i * 8192), 16, 0, 0); } while (0)
; #define PG8_LDA(dst, b, h) do { _Pragma("unroll") for (int m = 0; m < 4; ++m) _Pragma("unroll") for (int k = 0; k < 2; ++k) dst[m][k] = *(const PG8_LAS bf16x8*)(lds + PG8_SA(b, h) + aoff + m * 2048 + k * 1024); } while (0)
; #define PG8_LDB(dst, b, h) do { _Pragma("unroll") for (int n = 0; n < 2; ++n) _Pragma("unroll") for (int k = 0; k < 2; ++k) dst[n][k] = *(const PG8_LAS bf16x8*)(lds + PG8_SB(b, h) + boff + n * 2048 + k * 1024); } while (0)
; #define PG8_MMA(ai, bj, At, Bt) do { __builtin_amdgcn_s_setprio(1); _Pragma("unroll") for (int m = 0; m < 4; ++m) _Pragma("unroll") for (int n = 0; n < 2; ++n) _Pragma("unroll") for (int k = 0; k < 2; ++k) \
;         acc[ai][bj][m][n] = __builtin_amdgcn_mfma_f32_16x16x32_bf16(Bt[n][k], At[m][k], acc[ai][bj][m][n], 0, 0, 0); __builtin_amdgcn_s_setprio(0); } while (0)
; #define PG8_WAIT_V(n) asm volatile("s_waitcnt vmcnt(" #n ")" ::: "memory")
; template <class Epi, class Sched, bool ALIGN_EPI = false, bool SP2 = false>
; __device__ __forceinline__ void gemm_phase(PG8_LAS unsigned char* lds, const Gemm g, const Sched& S, const Epi& E) {
;     ...
;             PG8_LDB(B0, 0, 0); PG8_LDB(B1, 0, 1); PG8_SCHED; PG8_LDA(At, 0, 0); PG8_STAGE(PG8_SA(1, 1), a1 + hstep, voffA);
;             PG8_WAIT_V(8); PG8_WAIT_L(0); PG8_BAR; PG8_MMA(0, 0, At, B0); PG8_MMA(0, 1, At, B1); PG8_BAR; PG8_SCHED;
;             PG8_LDA(At, 0, 1); PG8_STAGE(PG8_SB(0, 0), b2, voffB); PG8_STAGE(PG8_SB(0, 1), b2 + hstep, voffB); PG8_STAGE(PG8_SA(0, 0), a2, voffA);
;             PG8_WAIT_V(8); PG8_WAIT_L(0); PG8_BAR; PG8_MMA(1, 0, At, B0); PG8_MMA(1, 1, At, B1); PG8_BAR; PG8_SCHED;
;             PG8_LDB(B0, 1, 0); PG8_LDB(B1, 1, 1); PG8_SCHED; PG8_LDA(At, 1, 0); PG8_STAGE(PG8_SA(0, 1), a2 + hstep, voffA);
;             PG8_WAIT_V(8); PG8_WAIT_L(0); PG8_BAR; PG8_MMA(0, 0, At, B0); PG8_MMA(0, 1, At, B1); PG8_BAR; PG8_SCHED;
;             PG8_LDA(At, 1, 1); PG8_STAGE(PG8_SB(1, 0), b3, voffB); PG8_STAGE(PG8_SB(1, 1), b3 + hstep, voffB); PG8_STAGE(PG8_SA(1, 0), a3, voffA);
;             PG8_WAIT_V(8); PG8_WAIT_L(0); PG8_BAR; PG8_MMA(1, 0, At, B0); PG8_MMA(1, 1, At, B1); PG8_BAR; PG8_SCHED;
	v_mfma_f32_16x16x32_bf16 v[62:65], v[152:155], v[184:187], v[62:65]
	v_mfma_f32_16x16x32_bf16 v[58:61], v[160:163], v[184:187], v[58:61]
	v_mfma_f32_16x16x32_bf16 v[54:57], v[152:155], v[192:195], v[54:57]
	v_mfma_f32_16x16x32_bf16 v[50:53], v[160:163], v[192:195], v[50:53]
	v_mfma_f32_16x16x32_bf16 v[46:49], v[152:155], v[200:203], v[46:49]
	v_mfma_f32_16x16x32_bf16 v[42:45], v[160:163], v[200:203], v[42:45]
	v_mfma_f32_16x16x32_bf16 v[34:37], v[152:155], v[208:211], v[34:37]
	v_mfma_f32_16x16x32_bf16 v[26:29], v[160:163], v[208:211], v[26:29]
	v_mfma_f32_16x16x32_bf16 v[62:65], v[156:159], v[188:191], v[62:65]
	v_mfma_f32_16x16x32_bf16 v[58:61], v[164:167], v[188:191], v[58:61]
	v_mfma_f32_16x16x32_bf16 v[54:57], v[156:159], v[196:199], v[54:57]
	v_mfma_f32_16x16x32_bf16 v[50:53], v[164:167], v[196:199], v[50:53]
	v_mfma_f32_16x16x32_bf16 v[46:49], v[156:159], v[204:207], v[46:49]
	v_mfma_f32_16x16x32_bf16 v[42:45], v[164:167], v[204:207], v[42:45]
	v_mfma_f32_16x16x32_bf16 v[34:37], v[156:159], v[220:223], v[34:37]
	v_mfma_f32_16x16x32_bf16 v[26:29], v[164:167], v[220:223], v[26:29]
	v_mfma_f32_16x16x32_bf16 v[38:41], v[168:171], v[184:187], v[38:41]
	v_mfma_f32_16x16x32_bf16 v[30:33], v[176:179], v[184:187], v[30:33]
	v_mfma_f32_16x16x32_bf16 v[22:25], v[168:171], v[192:195], v[22:25]
	v_mfma_f32_16x16x32_bf16 v[18:21], v[176:179], v[192:195], v[18:21]
	v_mfma_f32_16x16x32_bf16 v[14:17], v[168:171], v[200:203], v[14:17]
	v_mfma_f32_16x16x32_bf16 v[10:13], v[176:179], v[200:203], v[10:13]
	v_mfma_f32_16x16x32_bf16 v[6:9], v[168:171], v[208:211], v[6:9]
	v_mfma_f32_16x16x32_bf16 v[2:5], v[176:179], v[208:211], v[2:5]
	v_mfma_f32_16x16x32_bf16 v[38:41], v[172:175], v[188:191], v[38:41]
	v_mfma_f32_16x16x32_bf16 v[30:33], v[180:183], v[188:191], v[30:33]
	v_mfma_f32_16x16x32_bf16 v[22:25], v[172:175], v[196:199], v[22:25]
	v_mfma_f32_16x16x32_bf16 v[18:21], v[180:183], v[196:199], v[18:21]
	v_mfma_f32_16x16x32_bf16 v[14:17], v[172:175], v[204:207], v[14:17]
	v_mfma_f32_16x16x32_bf16 v[10:13], v[180:183], v[204:207], v[10:13]
	v_mfma_f32_16x16x32_bf16 v[6:9], v[172:175], v[220:223], v[6:9]
	v_mfma_f32_16x16x32_bf16 v[2:5], v[180:183], v[220:223], v[2:5]
	s_barrier
	s_setprio 0
	s_setprio 1
	s_setprio 0
	s_waitcnt lgkmcnt(0)
	s_add_i32 s27, 0, 0x18000
	s_add_i32 s29, 0, 0x1c000
	v_add_u32_e32 v164, s27, v0
	v_add_u32_e32 v180, s29, v0
	ds_read_b128 v[152:155], v164
	ds_read_b128 v[156:159], v164 offset:1024
	ds_read_b128 v[160:163], v164 offset:2048
	ds_read_b128 v[164:167], v164 offset:3072
	ds_read_b128 v[168:171], v180
	ds_read_b128 v[172:175], v180 offset:1024
	ds_read_b128 v[176:179], v180 offset:2048
	ds_read_b128 v[180:183], v180 offset:3072
	s_add_u32 s2, s42, 0x80000
	s_addc_u32 s3, s43, 0
	s_mov_b32 m0, s54
	v_lshl_add_u64 v[232:233], s[2:3], 0, v[66:67]
	ds_read_b128 v[184:187], v151 offset:32768
	ds_read_b128 v[188:191], v151 offset:33792
	ds_read_b128 v[192:195], v151 offset:34816
	ds_read_b128 v[196:199], v151 offset:35840
	ds_read_b128 v[200:203], v151 offset:36864
	ds_read_b128 v[204:207], v151 offset:37888
	ds_read_b128 v[208:211], v151 offset:38912
	ds_read_b128 v[220:223], v151 offset:39936
	global_load_lds_dwordx4 v[232:233], off
	v_lshl_add_u64 v[232:233], s[2:3], 0, v[132:133]
	s_mov_b32 m0, s55
	s_nop 0
	global_load_lds_dwordx4 v[232:233], off
	s_setprio 1
	s_nop 0
	s_waitcnt vmcnt(8) lgkmcnt(0)
	s_barrier
	v_mfma_f32_16x16x32_bf16 v[128:131], v[152:155], v[184:187], v[128:131]
	v_mfma_f32_16x16x32_bf16 v[124:127], v[160:163], v[184:187], v[124:127]
	v_mfma_f32_16x16x32_bf16 v[120:123], v[152:155], v[192:195], v[120:123]
	v_mfma_f32_16x16x32_bf16 v[116:119], v[160:163], v[192:195], v[116:119]
	v_mfma_f32_16x16x32_bf16 v[112:115], v[152:155], v[200:203], v[112:115]
	v_mfma_f32_16x16x32_bf16 v[108:111], v[160:163], v[200:203], v[108:111]
	v_mfma_f32_16x16x32_bf16 v[100:103], v[152:155], v[208:211], v[100:103]
	v_mfma_f32_16x16x32_bf16 v[92:95], v[160:163], v[208:211], v[92:95]
	v_mfma_f32_16x16x32_bf16 v[128:131], v[156:159], v[188:191], v[128:131]
	v_mfma_f32_16x16x32_bf16 v[124:127], v[164:167], v[188:191], v[124:127]
	v_mfma_f32_16x16x32_bf16 v[120:123], v[156:159], v[196:199], v[120:123]
	v_mfma_f32_16x16x32_bf16 v[116:119], v[164:167], v[196:199], v[116:119]
	v_mfma_f32_16x16x32_bf16 v[112:115], v[156:159], v[204:207], v[112:115]
	v_mfma_f32_16x16x32_bf16 v[108:111], v[164:167], v[204:207], v[108:111]
	v_mfma_f32_16x16x32_bf16 v[100:103], v[156:159], v[220:223], v[100:103]
	v_mfma_f32_16x16x32_bf16 v[92:95], v[164:167], v[220:223], v[92:95]
	v_mfma_f32_16x16x32_bf16 v[104:107], v[168:171], v[184:187], v[104:107]
	v_mfma_f32_16x16x32_bf16 v[96:99], v[176:179], v[184:187], v[96:99]
	v_mfma_f32_16x16x32_bf16 v[88:91], v[168:171], v[192:195], v[88:91]
	v_mfma_f32_16x16x32_bf16 v[84:87], v[176:179], v[192:195], v[84:87]
	v_mfma_f32_16x16x32_bf16 v[80:83], v[168:171], v[200:203], v[80:83]
	v_mfma_f32_16x16x32_bf16 v[76:79], v[176:179], v[200:203], v[76:79]
	v_mfma_f32_16x16x32_bf16 v[72:75], v[168:171], v[208:211], v[72:75]
	v_mfma_f32_16x16x32_bf16 v[68:71], v[176:179], v[208:211], v[68:71]
	v_mfma_f32_16x16x32_bf16 v[104:107], v[172:175], v[188:191], v[104:107]
	v_mfma_f32_16x16x32_bf16 v[96:99], v[180:183], v[188:191], v[96:99]
	v_mfma_f32_16x16x32_bf16 v[88:91], v[172:175], v[196:199], v[88:91]
	v_mfma_f32_16x16x32_bf16 v[84:87], v[180:183], v[196:199], v[84:87]
	v_mfma_f32_16x16x32_bf16 v[80:83], v[172:175], v[204:207], v[80:83]
	v_mfma_f32_16x16x32_bf16 v[76:79], v[180:183], v[204:207], v[76:79]
	v_mfma_f32_16x16x32_bf16 v[72:75], v[172:175], v[220:223], v[72:75]
	v_mfma_f32_16x16x32_bf16 v[68:71], v[180:183], v[220:223], v[68:71]
	s_barrier
; #define PG8_STAGE(bufoff, gbase, voff) do { _Pragma("unroll") for (int _i = 0; _i < 2; ++_i) \
;         __builtin_amdgcn_global_load_lds((const unsigned*)((const char*)(gbase) + (voff)[_i]), (PG8_LAS unsigned*)(lds + (bufoff) + ldsw + _i * 8192), 16, 0, 0); } while (0)
; #define PG8_LDA(dst, b, h) do { _Pragma("unroll") for (int m = 0; m < 4; ++m) _Pragma("unroll") for (int k = 0; k < 2; ++k) dst[m][k] = *(const PG8_LAS bf16x8*)(lds + PG8_SA(b, h) + aoff + m * 2048 + k * 1024); } while (0)
; #define PG8_MMA(ai, bj, At, Bt) do { __builtin_amdgcn_s_setprio(1); _Pragma("unroll") for (int m = 0; m < 4; ++m) _Pragma("unroll") for (int n = 0; n < 2; ++n) _Pragma("unroll") for (int k = 0; k < 2; ++k) \
;         acc[ai][bj][m][n] = __builtin_amdgcn_mfma_f32_16x16x32_bf16(Bt[n][k], At[m][k], acc[ai][bj][m][n], 0, 0, 0); __builtin_amdgcn_s_setprio(0); } while (0)
; #define PG8_WAIT_V(n) asm volatile("s_waitcnt vmcnt(" #n ")" ::: "memory")
; #define PG8_WAIT_L(n) asm volatile("s_waitcnt lgkmcnt(" #n ")" ::: "memory")
; #define PG8_BAR __builtin_amdgcn_s_barrier()
; #define PG8_SCHED __builtin_amdgcn_sched_barrier(0)
; template <class Epi, class Sched, bool ALIGN_EPI = false, bool SP2 = false>
; __device__ __forceinline__ void gemm_phase(PG8_LAS unsigned char* lds, const Gemm g, const Sched& S, const Epi& E) {
;     ...
;             PG8_LDA(At, 1, 1); PG8_STAGE(PG8_SB(1, 0), b3, voffB); PG8_STAGE(PG8_SB(1, 1), b3 + hstep, voffB); PG8_STAGE(PG8_SA(1, 0), a3, voffA);
;             PG8_WAIT_V(8); PG8_WAIT_L(0); PG8_BAR; PG8_MMA(1, 0, At, B0); PG8_MMA(1, 1, At, B1); PG8_BAR; PG8_SCHED;
	s_setprio 0
	s_setprio 1
	s_setprio 0
	s_waitcnt lgkmcnt(0)
	s_add_i32 s2, s27, s51
	v_lshl_add_u64 v[224:225], v[224:225], 0, s[88:89]
	s_mov_b32 m0, s2
	ds_read_b128 v[184:187], v151 offset:49152
	ds_read_b128 v[188:191], v151 offset:50176
	ds_read_b128 v[192:195], v151 offset:51200
	ds_read_b128 v[196:199], v151 offset:52224
	ds_read_b128 v[200:203], v151 offset:53248
	ds_read_b128 v[204:207], v151 offset:54272
	ds_read_b128 v[208:211], v151 offset:55296
	ds_read_b128 v[220:223], v151 offset:56320
	global_load_lds_dwordx4 v[224:225], off
	s_add_i32 m0, s2, 0x2000
	s_add_u32 s2, s38, 0x80080
	v_lshl_add_u64 v[224:225], v[226:227], 0, s[88:89]
	s_addc_u32 s3, s39, 0
	s_add_i32 s27, s29, s51
	global_load_lds_dwordx4 v[224:225], off
	v_lshl_add_u64 v[224:225], s[2:3], 0, v[66:67]
	s_mov_b32 m0, s27
	s_nop 0
	global_load_lds_dwordx4 v[224:225], off
	v_lshl_add_u64 v[224:225], s[2:3], 0, v[132:133]
	s_add_i32 m0, s27, 0x2000
	s_nop 0
	global_load_lds_dwordx4 v[224:225], off
	v_lshl_add_u64 v[224:225], v[228:229], 0, s[88:89]
	s_mov_b32 m0, s59
	s_nop 0
	global_load_lds_dwordx4 v[224:225], off
	v_lshl_add_u64 v[224:225], v[230:231], 0, s[88:89]
	s_mov_b32 m0, s60
	s_nop 0
	global_load_lds_dwordx4 v[224:225], off
	s_setprio 1
	s_nop 0
	s_waitcnt vmcnt(8) lgkmcnt(0)
	s_barrier
	v_mfma_f32_16x16x32_bf16 v[62:65], v[152:155], v[184:187], v[62:65]
	v_mfma_f32_16x16x32_bf16 v[58:61], v[160:163], v[184:187], v[58:61]
	v_mfma_f32_16x16x32_bf16 v[54:57], v[152:155], v[192:195], v[54:57]
	v_mfma_f32_16x16x32_bf16 v[50:53], v[160:163], v[192:195], v[50:53]
	v_mfma_f32_16x16x32_bf16 v[46:49], v[152:155], v[200:203], v[46:49]
	v_mfma_f32_16x16x32_bf16 v[42:45], v[160:163], v[200:203], v[42:45]
	v_mfma_f32_16x16x32_bf16 v[34:37], v[152:155], v[208:211], v[34:37]
	v_mfma_f32_16x16x32_bf16 v[26:29], v[160:163], v[208:211], v[26:29]
	v_mfma_f32_16x16x32_bf16 v[62:65], v[156:159], v[188:191], v[62:65]
	v_mfma_f32_16x16x32_bf16 v[58:61], v[164:167], v[188:191], v[58:61]
	v_mfma_f32_16x16x32_bf16 v[54:57], v[156:159], v[196:199], v[54:57]
	v_mfma_f32_16x16x32_bf16 v[50:53], v[164:167], v[196:199], v[50:53]
	v_mfma_f32_16x16x32_bf16 v[46:49], v[156:159], v[204:207], v[46:49]
	v_mfma_f32_16x16x32_bf16 v[42:45], v[164:167], v[204:207], v[42:45]
	v_mfma_f32_16x16x32_bf16 v[34:37], v[156:159], v[220:223], v[34:37]
	v_mfma_f32_16x16x32_bf16 v[26:29], v[164:167], v[220:223], v[26:29]
	v_mfma_f32_16x16x32_bf16 v[38:41], v[168:171], v[184:187], v[38:41]
	v_mfma_f32_16x16x32_bf16 v[30:33], v[176:179], v[184:187], v[30:33]
	v_mfma_f32_16x16x32_bf16 v[22:25], v[168:171], v[192:195], v[22:25]
	v_mfma_f32_16x16x32_bf16 v[18:21], v[176:179], v[192:195], v[18:21]
	v_mfma_f32_16x16x32_bf16 v[14:17], v[168:171], v[200:203], v[14:17]
	v_mfma_f32_16x16x32_bf16 v[10:13], v[176:179], v[200:203], v[10:13]
	v_mfma_f32_16x16x32_bf16 v[6:9], v[168:171], v[208:211], v[6:9]
	v_mfma_f32_16x16x32_bf16 v[2:5], v[176:179], v[208:211], v[2:5]
	v_mfma_f32_16x16x32_bf16 v[38:41], v[172:175], v[188:191], v[38:41]
	v_mfma_f32_16x16x32_bf16 v[30:33], v[180:183], v[188:191], v[30:33]
	v_mfma_f32_16x16x32_bf16 v[22:25], v[172:175], v[196:199], v[22:25]
	v_mfma_f32_16x16x32_bf16 v[18:21], v[180:183], v[196:199], v[18:21]
	v_mfma_f32_16x16x32_bf16 v[14:17], v[172:175], v[204:207], v[14:17]
	v_mfma_f32_16x16x32_bf16 v[10:13], v[180:183], v[204:207], v[10:13]
	v_mfma_f32_16x16x32_bf16 v[6:9], v[172:175], v[220:223], v[6:9]
	v_mfma_f32_16x16x32_bf16 v[2:5], v[180:183], v[220:223], v[2:5]
	s_barrier
	s_setprio 0
	s_setprio 1
	s_setprio 0
	s_waitcnt lgkmcnt(0)
	s_movk_i32 s2, 0x100
	s_mov_b64 s[38:39], 0
	s_and_b64 vcc, exec, s[40:41]
	s_cbranch_vccnz .LBB0_991

; #define PG8_STAGE(bufoff, gbase, voff) do { _Pragma("unroll") for (int _i = 0; _i < 2; ++_i) \
;         __builtin_amdgcn_global_load_lds((const unsigned*)((const char*)(gbase) + (voff)[_i]), (PG8_LAS unsigned*)(lds + (bufoff) + ldsw + _i * 8192), 16, 0, 0); } while (0)
; #define PG8_LDA(dst, b, h) do { _Pragma("unroll") for (int m = 0; m < 4; ++m) _Pragma("unroll") for (int k = 0; k < 2; ++k) dst[m][k] = *(const PG8_LAS bf16x8*)(lds + PG8_SA(b, h) + aoff + m * 2048 + k * 1024); } while (0)
; #define PG8_LDB(dst, b, h) do { _Pragma("unroll") for (int n = 0; n < 2; ++n) _Pragma("unroll") for (int k = 0; k < 2; ++k) dst[n][k] = *(const PG8_LAS bf16x8*)(lds + PG8_SB(b, h) + boff + n * 2048 + k * 1024); } while (0)
; #define PG8_MMA(ai, bj, At, Bt) do { __builtin_amdgcn_s_setprio(1); _Pragma("unroll") for (int m = 0; m < 4; ++m) _Pragma("unroll") for (int n = 0; n < 2; ++n) _Pragma("unroll") for (int k = 0; k < 2; ++k) \
;         acc[ai][bj][m][n] = __builtin_amdgcn_mfma_f32_16x16x32_bf16(Bt[n][k], At[m][k], acc[ai][bj][m][n], 0, 0, 0); __builtin_amdgcn_s_setprio(0); } while (0)
; #define PG8_WAIT_V(n) asm volatile("s_waitcnt vmcnt(" #n ")" ::: "memory")
; template <class Epi, class Sched, bool ALIGN_EPI = false, bool SP2 = false>
; __device__ __forceinline__ void gemm_phase(PG8_LAS unsigned char* lds, const Gemm g, const Sched& S, const Epi& E) {
;     ...
;             PG8_LDB(B0, 0, 0); PG8_LDB(B1, 0, 1); PG8_SCHED; PG8_LDA(At, 0, 0); PG8_STAGE(PG8_SA(1, 1), a1 + hstep, voffA);
;             PG8_WAIT_V(8); PG8_WAIT_L(0); PG8_BAR; PG8_MMA(0, 0, At, B0); PG8_MMA(0, 1, At, B1); PG8_BAR; PG8_SCHED;
;             PG8_LDA(At, 0, 1); PG8_STAGE(PG8_SB(0, 0), b2, voffB); PG8_STAGE(PG8_SB(0, 1), b2 + hstep, voffB); PG8_STAGE(PG8_SA(0, 0), a2, voffA);
;             PG8_WAIT_V(8); PG8_WAIT_L(0); PG8_BAR; PG8_MMA(1, 0, At, B0); PG8_MMA(1, 1, At, B1); PG8_BAR; PG8_SCHED;
;             PG8_LDB(B0, 1, 0); PG8_LDB(B1, 1, 1); PG8_SCHED; PG8_LDA(At, 1, 0); PG8_STAGE(PG8_SA(0, 1), a2 + hstep, voffA);
;             PG8_WAIT_V(8); PG8_WAIT_L(0); PG8_BAR; PG8_MMA(0, 0, At, B0); PG8_MMA(0, 1, At, B1); PG8_BAR; PG8_SCHED;
;             PG8_LDA(At, 1, 1); PG8_STAGE(PG8_SB(1, 0), b3, voffB); PG8_STAGE(PG8_SB(1, 1), b3 + hstep, voffB); PG8_STAGE(PG8_SA(1, 0), a3, voffA);
;             PG8_WAIT_V(8); PG8_WAIT_L(0); PG8_BAR; PG8_MMA(1, 0, At, B0); PG8_MMA(1, 1, At, B1); PG8_BAR; PG8_SCHED;
.LBB0_1205:
	s_lshl_b32 s52, s31, 7
	s_add_u32 s53, s42, s52
	s_addc_u32 s54, s43, 0
	s_add_u32 s55, s53, 0x100
	s_addc_u32 s56, s54, 0
	s_and_b64 s[50:51], s[48:49], exec
	s_cselect_b32 s51, s56, s1
	s_cselect_b32 s50, s55, s2
	s_add_u32 s52, s44, s52
	s_addc_u32 s55, s45, 0
	s_add_u32 s52, s52, 0x100
	s_addc_u32 s55, s55, 0
	s_and_b64 s[48:49], s[48:49], exec
	s_cselect_b32 s49, s55, s3
	s_cselect_b32 s48, s52, s29
	s_add_i32 s55, 0, 0x10000
	v_add_u32_e32 v138, s55, v140
	s_add_i32 s56, 0, 0x14000
	ds_read_b128 v[144:147], v138
	ds_read_b128 v[148:151], v138 offset:1024
	ds_read_b128 v[152:155], v138 offset:2048
	ds_read_b128 v[156:159], v138 offset:3072
	v_add_u32_e32 v138, s56, v140
	ds_read_b128 v[160:163], v138
	ds_read_b128 v[164:167], v138 offset:1024
	ds_read_b128 v[168:171], v138 offset:2048
	ds_read_b128 v[172:175], v138 offset:3072
	s_add_u32 s52, s53, 0x80080
	s_addc_u32 s53, s54, 0
	v_lshl_add_u64 v[138:139], s[52:53], 0, v[132:133]
	s_add_i32 m0, s41, 0xc000
	ds_read_b128 v[176:179], v142
	ds_read_b128 v[180:183], v142 offset:1024
	ds_read_b128 v[184:187], v142 offset:2048
	ds_read_b128 v[188:191], v142 offset:3072
	ds_read_b128 v[192:195], v142 offset:4096
	ds_read_b128 v[196:199], v142 offset:5120
	ds_read_b128 v[200:203], v142 offset:6144
	ds_read_b128 v[204:207], v142 offset:7168
	global_load_lds_dwordx4 v[138:139], off
	v_lshl_add_u64 v[138:139], s[52:53], 0, v[134:135]
	s_add_i32 m0, s41, 0xe000
	s_nop 0
	global_load_lds_dwordx4 v[138:139], off
	s_setprio 1
	s_nop 0
	s_waitcnt vmcnt(8) lgkmcnt(0)
	s_barrier
	v_mfma_f32_16x16x32_bf16 v[128:131], v[144:147], v[176:179], v[128:131]
	v_mfma_f32_16x16x32_bf16 v[124:127], v[152:155], v[176:179], v[124:127]
	v_mfma_f32_16x16x32_bf16 v[112:115], v[144:147], v[184:187], v[112:115]
	v_mfma_f32_16x16x32_bf16 v[108:111], v[152:155], v[184:187], v[108:111]
	v_mfma_f32_16x16x32_bf16 v[96:99], v[144:147], v[192:195], v[96:99]
	v_mfma_f32_16x16x32_bf16 v[92:95], v[152:155], v[192:195], v[92:95]
	v_mfma_f32_16x16x32_bf16 v[80:83], v[144:147], v[200:203], v[80:83]
	v_mfma_f32_16x16x32_bf16 v[76:79], v[152:155], v[200:203], v[76:79]
	v_mfma_f32_16x16x32_bf16 v[128:131], v[148:151], v[180:183], v[128:131]
	v_mfma_f32_16x16x32_bf16 v[124:127], v[156:159], v[180:183], v[124:127]
	v_mfma_f32_16x16x32_bf16 v[112:115], v[148:151], v[188:191], v[112:115]
	v_mfma_f32_16x16x32_bf16 v[108:111], v[156:159], v[188:191], v[108:111]
	v_mfma_f32_16x16x32_bf16 v[96:99], v[148:151], v[196:199], v[96:99]
	v_mfma_f32_16x16x32_bf16 v[92:95], v[156:159], v[196:199], v[92:95]
	v_mfma_f32_16x16x32_bf16 v[80:83], v[148:151], v[204:207], v[80:83]
	v_mfma_f32_16x16x32_bf16 v[76:79], v[156:159], v[204:207], v[76:79]
	v_mfma_f32_16x16x32_bf16 v[120:123], v[160:163], v[176:179], v[120:123]
	v_mfma_f32_16x16x32_bf16 v[116:119], v[168:171], v[176:179], v[116:119]
	v_mfma_f32_16x16x32_bf16 v[104:107], v[160:163], v[184:187], v[104:107]
	v_mfma_f32_16x16x32_bf16 v[100:103], v[168:171], v[184:187], v[100:103]
	v_mfma_f32_16x16x32_bf16 v[88:91], v[160:163], v[192:195], v[88:91]
	v_mfma_f32_16x16x32_bf16 v[84:87], v[168:171], v[192:195], v[84:87]
	v_mfma_f32_16x16x32_bf16 v[72:75], v[160:163], v[200:203], v[72:75]
	v_mfma_f32_16x16x32_bf16 v[68:71], v[168:171], v[200:203], v[68:71]
	v_mfma_f32_16x16x32_bf16 v[120:123], v[164:167], v[180:183], v[120:123]
	v_mfma_f32_16x16x32_bf16 v[116:119], v[172:175], v[180:183], v[116:119]
	v_mfma_f32_16x16x32_bf16 v[104:107], v[164:167], v[188:191], v[104:107]
	v_mfma_f32_16x16x32_bf16 v[100:103], v[172:175], v[188:191], v[100:103]
	v_mfma_f32_16x16x32_bf16 v[88:91], v[164:167], v[196:199], v[88:91]
	v_mfma_f32_16x16x32_bf16 v[84:87], v[172:175], v[196:199], v[84:87]
	v_mfma_f32_16x16x32_bf16 v[72:75], v[164:167], v[204:207], v[72:75]
	v_mfma_f32_16x16x32_bf16 v[68:71], v[172:175], v[204:207], v[68:71]
	s_barrier
	s_setprio 0
	s_setprio 1
	s_setprio 0
	s_waitcnt lgkmcnt(0)
	s_add_i32 s52, s55, s39
	v_lshl_add_u64 v[138:139], s[48:49], 0, v[66:67]
	s_mov_b32 m0, s52
	ds_read_b128 v[176:179], v142 offset:16384
	ds_read_b128 v[180:183], v142 offset:17408
	ds_read_b128 v[184:187], v142 offset:18432
	ds_read_b128 v[188:191], v142 offset:19456
	ds_read_b128 v[192:195], v142 offset:20480
	ds_read_b128 v[196:199], v142 offset:21504
	ds_read_b128 v[200:203], v142 offset:22528
	ds_read_b128 v[204:207], v142 offset:23552
	global_load_lds_dwordx4 v[138:139], off
	s_add_i32 m0, s52, 0x2000
	s_add_u32 s52, s48, 0x80000
	v_lshl_add_u64 v[208:209], s[48:49], 0, v[136:137]
	s_addc_u32 s53, s49, 0
	s_add_i32 s54, s56, s39
	global_load_lds_dwordx4 v[208:209], off
	v_lshl_add_u64 v[210:211], s[52:53], 0, v[66:67]
	s_mov_b32 m0, s54
	v_lshl_add_u64 v[220:221], s[50:51], 0, v[134:135]
	global_load_lds_dwordx4 v[210:211], off
	v_lshl_add_u64 v[210:211], s[52:53], 0, v[136:137]
	s_add_i32 m0, s54, 0x2000
	s_nop 0
	global_load_lds_dwordx4 v[210:211], off
	v_lshl_add_u64 v[210:211], s[50:51], 0, v[132:133]
	s_mov_b32 m0, s41
	s_nop 0
	global_load_lds_dwordx4 v[210:211], off
	s_mov_b32 m0, s68
	s_nop 0
	global_load_lds_dwordx4 v[220:221], off
	s_setprio 1
	s_nop 0
	s_waitcnt vmcnt(8) lgkmcnt(0)
	s_barrier
; #define PG8_STAGE(bufoff, gbase, voff) do { _Pragma("unroll") for (int _i = 0; _i < 2; ++_i) \
;         __builtin_amdgcn_global_load_lds((const unsigned*)((const char*)(gbase) + (voff)[_i]), (PG8_LAS unsigned*)(lds + (bufoff) + ldsw + _i * 8192), 16, 0, 0); } while (0)
; #define PG8_LDA(dst, b, h) do { _Pragma("unroll") for (int m = 0; m < 4; ++m) _Pragma("unroll") for (int k = 0; k < 2; ++k) dst[m][k] = *(const PG8_LAS bf16x8*)(lds + PG8_SA(b, h) + aoff + m * 2048 + k * 1024); } while (0)
; #define PG8_LDB(dst, b, h) do { _Pragma("unroll") for (int n = 0; n < 2; ++n) _Pragma("unroll") for (int k = 0; k < 2; ++k) dst[n][k] = *(const PG8_LAS bf16x8*)(lds + PG8_SB(b, h) + boff + n * 2048 + k * 1024); } while (0)
; #define PG8_MMA(ai, bj, At, Bt) do { __builtin_amdgcn_s_setprio(1); _Pragma("unroll") for (int m = 0; m < 4; ++m) _Pragma("unroll") for (int n = 0; n < 2; ++n) _Pragma("unroll") for (int k = 0; k < 2; ++k) \
;         acc[ai][bj][m][n] = __builtin_amdgcn_mfma_f32_16x16x32_bf16(Bt[n][k], At[m][k], acc[ai][bj][m][n], 0, 0, 0); __builtin_amdgcn_s_setprio(0); } while (0)
; #define PG8_WAIT_V(n) asm volatile("s_waitcnt vmcnt(" #n ")" ::: "memory")
; template <class Epi, class Sched, bool ALIGN_EPI = false, bool SP2 = false>
; __device__ __forceinline__ void gemm_phase(PG8_LAS unsigned char* lds, const Gemm g, const Sched& S, const Epi& E) {
;     ...
;             PG8_LDB(B0, 0, 0); PG8_LDB(B1, 0, 1); PG8_SCHED; PG8_LDA(At, 0, 0); PG8_STAGE(PG8_SA(1, 1), a1 + hstep, voffA);
;             PG8_WAIT_V(8); PG8_WAIT_L(0); PG8_BAR; PG8_MMA(0, 0, At, B0); PG8_MMA(0, 1, At, B1); PG8_BAR; PG8_SCHED;
;             PG8_LDA(At, 0, 1); PG8_STAGE(PG8_SB(0, 0), b2, voffB); PG8_STAGE(PG8_SB(0, 1), b2 + hstep, voffB); PG8_STAGE(PG8_SA(0, 0), a2, voffA);
;             PG8_WAIT_V(8); PG8_WAIT_L(0); PG8_BAR; PG8_MMA(1, 0, At, B0); PG8_MMA(1, 1, At, B1); PG8_BAR; PG8_SCHED;
;             PG8_LDB(B0, 1, 0); PG8_LDB(B1, 1, 1); PG8_SCHED; PG8_LDA(At, 1, 0); PG8_STAGE(PG8_SA(0, 1), a2 + hstep, voffA);
;             PG8_WAIT_V(8); PG8_WAIT_L(0); PG8_BAR; PG8_MMA(0, 0, At, B0); PG8_MMA(0, 1, At, B1); PG8_BAR; PG8_SCHED;
;             PG8_LDA(At, 1, 1); PG8_STAGE(PG8_SB(1, 0), b3, voffB); PG8_STAGE(PG8_SB(1, 1), b3 + hstep, voffB); PG8_STAGE(PG8_SA(1, 0), a3, voffA);
;             PG8_WAIT_V(8); PG8_WAIT_L(0); PG8_BAR; PG8_MMA(1, 0, At, B0); PG8_MMA(1, 1, At, B1); PG8_BAR; PG8_SCHED;
	v_mfma_f32_16x16x32_bf16 v[62:65], v[144:147], v[176:179], v[62:65]
	v_mfma_f32_16x16x32_bf16 v[58:61], v[152:155], v[176:179], v[58:61]
	v_mfma_f32_16x16x32_bf16 v[46:49], v[144:147], v[184:187], v[46:49]
	v_mfma_f32_16x16x32_bf16 v[42:45], v[152:155], v[184:187], v[42:45]
	v_mfma_f32_16x16x32_bf16 v[30:33], v[144:147], v[192:195], v[30:33]
	v_mfma_f32_16x16x32_bf16 v[26:29], v[152:155], v[192:195], v[26:29]
	v_mfma_f32_16x16x32_bf16 v[14:17], v[144:147], v[200:203], v[14:17]
	v_mfma_f32_16x16x32_bf16 v[10:13], v[152:155], v[200:203], v[10:13]
	v_mfma_f32_16x16x32_bf16 v[62:65], v[148:151], v[180:183], v[62:65]
	v_mfma_f32_16x16x32_bf16 v[58:61], v[156:159], v[180:183], v[58:61]
	v_mfma_f32_16x16x32_bf16 v[46:49], v[148:151], v[188:191], v[46:49]
	v_mfma_f32_16x16x32_bf16 v[42:45], v[156:159], v[188:191], v[42:45]
	v_mfma_f32_16x16x32_bf16 v[30:33], v[148:151], v[196:199], v[30:33]
	v_mfma_f32_16x16x32_bf16 v[26:29], v[156:159], v[196:199], v[26:29]
	v_mfma_f32_16x16x32_bf16 v[14:17], v[148:151], v[204:207], v[14:17]
	v_mfma_f32_16x16x32_bf16 v[10:13], v[156:159], v[204:207], v[10:13]
	v_mfma_f32_16x16x32_bf16 v[54:57], v[160:163], v[176:179], v[54:57]
	v_mfma_f32_16x16x32_bf16 v[50:53], v[168:171], v[176:179], v[50:53]
	v_mfma_f32_16x16x32_bf16 v[38:41], v[160:163], v[184:187], v[38:41]
	v_mfma_f32_16x16x32_bf16 v[34:37], v[168:171], v[184:187], v[34:37]
	v_mfma_f32_16x16x32_bf16 v[22:25], v[160:163], v[192:195], v[22:25]
	v_mfma_f32_16x16x32_bf16 v[18:21], v[168:171], v[192:195], v[18:21]
	v_mfma_f32_16x16x32_bf16 v[6:9], v[160:163], v[200:203], v[6:9]
	v_mfma_f32_16x16x32_bf16 v[2:5], v[168:171], v[200:203], v[2:5]
	v_mfma_f32_16x16x32_bf16 v[54:57], v[164:167], v[180:183], v[54:57]
	v_mfma_f32_16x16x32_bf16 v[50:53], v[172:175], v[180:183], v[50:53]
	v_mfma_f32_16x16x32_bf16 v[38:41], v[164:167], v[188:191], v[38:41]
	v_mfma_f32_16x16x32_bf16 v[34:37], v[172:175], v[188:191], v[34:37]
	v_mfma_f32_16x16x32_bf16 v[22:25], v[164:167], v[196:199], v[22:25]
	v_mfma_f32_16x16x32_bf16 v[18:21], v[172:175], v[196:199], v[18:21]
	v_mfma_f32_16x16x32_bf16 v[6:9], v[164:167], v[204:207], v[6:9]
	v_mfma_f32_16x16x32_bf16 v[2:5], v[172:175], v[204:207], v[2:5]
	s_barrier
	s_setprio 0
	s_setprio 1
	s_setprio 0
	s_waitcnt lgkmcnt(0)
	s_add_i32 s52, 0, 0x18000
	v_add_u32_e32 v143, s52, v140
	s_add_i32 s53, 0, 0x1c000
	ds_read_b128 v[144:147], v143
	ds_read_b128 v[148:151], v143 offset:1024
	ds_read_b128 v[152:155], v143 offset:2048
	ds_read_b128 v[156:159], v143 offset:3072
	v_add_u32_e32 v143, s53, v140
	ds_read_b128 v[160:163], v143
	ds_read_b128 v[164:167], v143 offset:1024
	ds_read_b128 v[168:171], v143 offset:2048
	ds_read_b128 v[172:175], v143 offset:3072
	s_add_u32 s50, s50, 0x80000
	s_addc_u32 s51, s51, 0
	s_mov_b32 m0, s69
	v_lshl_add_u64 v[222:223], s[50:51], 0, v[132:133]
	ds_read_b128 v[176:179], v142 offset:32768
	ds_read_b128 v[180:183], v142 offset:33792
	ds_read_b128 v[184:187], v142 offset:34816
	ds_read_b128 v[188:191], v142 offset:35840
	ds_read_b128 v[192:195], v142 offset:36864
	ds_read_b128 v[196:199], v142 offset:37888
	ds_read_b128 v[200:203], v142 offset:38912
	ds_read_b128 v[204:207], v142 offset:39936
	global_load_lds_dwordx4 v[222:223], off
	v_lshl_add_u64 v[222:223], s[50:51], 0, v[134:135]
	s_mov_b32 m0, s70
	s_nop 0
	global_load_lds_dwordx4 v[222:223], off
	s_setprio 1
	s_nop 0
	s_waitcnt vmcnt(8) lgkmcnt(0)
	s_barrier
	v_mfma_f32_16x16x32_bf16 v[128:131], v[144:147], v[176:179], v[128:131]
	v_mfma_f32_16x16x32_bf16 v[124:127], v[152:155], v[176:179], v[124:127]
	v_mfma_f32_16x16x32_bf16 v[112:115], v[144:147], v[184:187], v[112:115]
	v_mfma_f32_16x16x32_bf16 v[108:111], v[152:155], v[184:187], v[108:111]
	v_mfma_f32_16x16x32_bf16 v[96:99], v[144:147], v[192:195], v[96:99]
	v_mfma_f32_16x16x32_bf16 v[92:95], v[152:155], v[192:195], v[92:95]
	v_mfma_f32_16x16x32_bf16 v[80:83], v[144:147], v[200:203], v[80:83]
	v_mfma_f32_16x16x32_bf16 v[76:79], v[152:155], v[200:203], v[76:79]
	v_mfma_f32_16x16x32_bf16 v[128:131], v[148:151], v[180:183], v[128:131]
	v_mfma_f32_16x16x32_bf16 v[124:127], v[156:159], v[180:183], v[124:127]
	v_mfma_f32_16x16x32_bf16 v[112:115], v[148:151], v[188:191], v[112:115]
	v_mfma_f32_16x16x32_bf16 v[108:111], v[156:159], v[188:191], v[108:111]
	v_mfma_f32_16x16x32_bf16 v[96:99], v[148:151], v[196:199], v[96:99]
	v_mfma_f32_16x16x32_bf16 v[92:95], v[156:159], v[196:199], v[92:95]
	v_mfma_f32_16x16x32_bf16 v[80:83], v[148:151], v[204:207], v[80:83]
	v_mfma_f32_16x16x32_bf16 v[76:79], v[156:159], v[204:207], v[76:79]
	v_mfma_f32_16x16x32_bf16 v[120:123], v[160:163], v[176:179], v[120:123]
	v_mfma_f32_16x16x32_bf16 v[116:119], v[168:171], v[176:179], v[116:119]
	v_mfma_f32_16x16x32_bf16 v[104:107], v[160:163], v[184:187], v[104:107]
	v_mfma_f32_16x16x32_bf16 v[100:103], v[168:171], v[184:187], v[100:103]
	v_mfma_f32_16x16x32_bf16 v[88:91], v[160:163], v[192:195], v[88:91]
	v_mfma_f32_16x16x32_bf16 v[84:87], v[168:171], v[192:195], v[84:87]
	v_mfma_f32_16x16x32_bf16 v[72:75], v[160:163], v[200:203], v[72:75]
	v_mfma_f32_16x16x32_bf16 v[68:71], v[168:171], v[200:203], v[68:71]
	v_mfma_f32_16x16x32_bf16 v[120:123], v[164:167], v[180:183], v[120:123]
	v_mfma_f32_16x16x32_bf16 v[116:119], v[172:175], v[180:183], v[116:119]
	v_mfma_f32_16x16x32_bf16 v[104:107], v[164:167], v[188:191], v[104:107]
	v_mfma_f32_16x16x32_bf16 v[100:103], v[172:175], v[188:191], v[100:103]
	v_mfma_f32_16x16x32_bf16 v[88:91], v[164:167], v[196:199], v[88:91]
	v_mfma_f32_16x16x32_bf16 v[84:87], v[172:175], v[196:199], v[84:87]
	v_mfma_f32_16x16x32_bf16 v[72:75], v[164:167], v[204:207], v[72:75]
	v_mfma_f32_16x16x32_bf16 v[68:71], v[172:175], v[204:207], v[68:71]
	s_barrier
; #define PG8_STAGE(bufoff, gbase, voff) do { _Pragma("unroll") for (int _i = 0; _i < 2; ++_i) \
;         __builtin_amdgcn_global_load_lds((const unsigned*)((const char*)(gbase) + (voff)[_i]), (PG8_LAS unsigned*)(lds + (bufoff) + ldsw + _i * 8192), 16, 0, 0); } while (0)
; #define PG8_LDA(dst, b, h) do { _Pragma("unroll") for (int m = 0; m < 4; ++m) _Pragma("unroll") for (int k = 0; k < 2; ++k) dst[m][k] = *(const PG8_LAS bf16x8*)(lds + PG8_SA(b, h) + aoff + m * 2048 + k * 1024); } while (0)
; #define PG8_MMA(ai, bj, At, Bt) do { __builtin_amdgcn_s_setprio(1); _Pragma("unroll") for (int m = 0; m < 4; ++m) _Pragma("unroll") for (int n = 0; n < 2; ++n) _Pragma("unroll") for (int k = 0; k < 2; ++k) \
;         acc[ai][bj][m][n] = __builtin_amdgcn_mfma_f32_16x16x32_bf16(Bt[n][k], At[m][k], acc[ai][bj][m][n], 0, 0, 0); __builtin_amdgcn_s_setprio(0); } while (0)
; #define PG8_WAIT_V(n) asm volatile("s_waitcnt vmcnt(" #n ")" ::: "memory")
; #define PG8_WAIT_L(n) asm volatile("s_waitcnt lgkmcnt(" #n ")" ::: "memory")
; #define PG8_BAR __builtin_amdgcn_s_barrier()
; #define PG8_SCHED __builtin_amdgcn_sched_barrier(0)
; template <class Epi, class Sched, bool ALIGN_EPI = false, bool SP2 = false>
; __device__ __forceinline__ void gemm_phase(PG8_LAS unsigned char* lds, const Gemm g, const Sched& S, const Epi& E) {
;     ...
;             PG8_LDA(At, 1, 1); PG8_STAGE(PG8_SB(1, 0), b3, voffB); PG8_STAGE(PG8_SB(1, 1), b3 + hstep, voffB); PG8_STAGE(PG8_SA(1, 0), a3, voffA);
;             PG8_WAIT_V(8); PG8_WAIT_L(0); PG8_BAR; PG8_MMA(1, 0, At, B0); PG8_MMA(1, 1, At, B1); PG8_BAR; PG8_SCHED;
	s_setprio 0
	s_setprio 1
	s_setprio 0
	s_waitcnt lgkmcnt(0)
	s_add_i32 s50, s52, s39
	v_lshl_add_u64 v[138:139], v[138:139], 0, s[88:89]
	s_mov_b32 m0, s50
	ds_read_b128 v[176:179], v142 offset:49152
	ds_read_b128 v[180:183], v142 offset:50176
	ds_read_b128 v[184:187], v142 offset:51200
	ds_read_b128 v[188:191], v142 offset:52224
	ds_read_b128 v[192:195], v142 offset:53248
	ds_read_b128 v[196:199], v142 offset:54272
	ds_read_b128 v[200:203], v142 offset:55296
	ds_read_b128 v[204:207], v142 offset:56320
	global_load_lds_dwordx4 v[138:139], off
	s_add_i32 m0, s50, 0x2000
	s_add_u32 s48, s48, 0x80080
	v_lshl_add_u64 v[138:139], v[208:209], 0, s[88:89]
	s_addc_u32 s49, s49, 0
	s_add_i32 s50, s53, s39
	global_load_lds_dwordx4 v[138:139], off
	v_lshl_add_u64 v[138:139], s[48:49], 0, v[66:67]
	s_mov_b32 m0, s50
	s_nop 0
	global_load_lds_dwordx4 v[138:139], off
	v_lshl_add_u64 v[138:139], s[48:49], 0, v[136:137]
	s_add_i32 m0, s50, 0x2000
	s_nop 0
	global_load_lds_dwordx4 v[138:139], off
	v_lshl_add_u64 v[138:139], v[210:211], 0, s[88:89]
	s_mov_b32 m0, s71
	s_nop 0
	global_load_lds_dwordx4 v[138:139], off
	v_lshl_add_u64 v[138:139], v[220:221], 0, s[88:89]
	s_mov_b32 m0, s72
	s_nop 0
	global_load_lds_dwordx4 v[138:139], off
	s_setprio 1
	s_nop 0
	s_waitcnt vmcnt(8) lgkmcnt(0)
	s_barrier
	v_mfma_f32_16x16x32_bf16 v[62:65], v[144:147], v[176:179], v[62:65]
	v_mfma_f32_16x16x32_bf16 v[58:61], v[152:155], v[176:179], v[58:61]
	v_mfma_f32_16x16x32_bf16 v[46:49], v[144:147], v[184:187], v[46:49]
	v_mfma_f32_16x16x32_bf16 v[42:45], v[152:155], v[184:187], v[42:45]
	v_mfma_f32_16x16x32_bf16 v[30:33], v[144:147], v[192:195], v[30:33]
	v_mfma_f32_16x16x32_bf16 v[26:29], v[152:155], v[192:195], v[26:29]
	v_mfma_f32_16x16x32_bf16 v[14:17], v[144:147], v[200:203], v[14:17]
	v_mfma_f32_16x16x32_bf16 v[10:13], v[152:155], v[200:203], v[10:13]
	v_mfma_f32_16x16x32_bf16 v[62:65], v[148:151], v[180:183], v[62:65]
	v_mfma_f32_16x16x32_bf16 v[58:61], v[156:159], v[180:183], v[58:61]
	v_mfma_f32_16x16x32_bf16 v[46:49], v[148:151], v[188:191], v[46:49]
	v_mfma_f32_16x16x32_bf16 v[42:45], v[156:159], v[188:191], v[42:45]
	v_mfma_f32_16x16x32_bf16 v[30:33], v[148:151], v[196:199], v[30:33]
	v_mfma_f32_16x16x32_bf16 v[26:29], v[156:159], v[196:199], v[26:29]
	v_mfma_f32_16x16x32_bf16 v[14:17], v[148:151], v[204:207], v[14:17]
	v_mfma_f32_16x16x32_bf16 v[10:13], v[156:159], v[204:207], v[10:13]
	v_mfma_f32_16x16x32_bf16 v[54:57], v[160:163], v[176:179], v[54:57]
	v_mfma_f32_16x16x32_bf16 v[50:53], v[168:171], v[176:179], v[50:53]
	v_mfma_f32_16x16x32_bf16 v[38:41], v[160:163], v[184:187], v[38:41]
	v_mfma_f32_16x16x32_bf16 v[34:37], v[168:171], v[184:187], v[34:37]
	v_mfma_f32_16x16x32_bf16 v[22:25], v[160:163], v[192:195], v[22:25]
	v_mfma_f32_16x16x32_bf16 v[18:21], v[168:171], v[192:195], v[18:21]
	v_mfma_f32_16x16x32_bf16 v[6:9], v[160:163], v[200:203], v[6:9]
	v_mfma_f32_16x16x32_bf16 v[2:5], v[168:171], v[200:203], v[2:5]
	v_mfma_f32_16x16x32_bf16 v[54:57], v[164:167], v[180:183], v[54:57]
	v_mfma_f32_16x16x32_bf16 v[50:53], v[172:175], v[180:183], v[50:53]
	v_mfma_f32_16x16x32_bf16 v[38:41], v[164:167], v[188:191], v[38:41]
	v_mfma_f32_16x16x32_bf16 v[34:37], v[172:175], v[188:191], v[34:37]
	v_mfma_f32_16x16x32_bf16 v[22:25], v[164:167], v[196:199], v[22:25]
	v_mfma_f32_16x16x32_bf16 v[18:21], v[172:175], v[196:199], v[18:21]
	v_mfma_f32_16x16x32_bf16 v[6:9], v[164:167], v[204:207], v[6:9]
	v_mfma_f32_16x16x32_bf16 v[2:5], v[172:175], v[204:207], v[2:5]
	s_barrier
	s_setprio 0
	s_setprio 1
	s_setprio 0
	s_waitcnt lgkmcnt(0)
	s_add_i32 s48, s31, 2
	s_cmp_gt_u32 s31, 29
	s_mov_b32 s31, s48
	s_cbranch_scc1 .LBB0_1217

;     __host__ __device__ bool next(int i, Unit& u) const { if (i != 0 || r < 0 || r >= 148) return false; if (r < 116) { u.pm = r % 29; u.pn = 47 + r / 29; } else { u.pm = 32; u.pn = 19 + (r - 116); } u.ko = 0; return true; }
;     __host__ __device__ bool next(int i, Unit& u) const { const int L = i * G + (G - 1 - c); if (L >= nN * S) return false; u.pm = pm; u.pn = L % nN; u.ko = (L / nN) * ksub; return true; }
; #define PG8_STAGE(bufoff, gbase, voff) do { _Pragma("unroll") for (int _i = 0; _i < 2; ++_i) \
;         __builtin_amdgcn_global_load_lds((const unsigned*)((const char*)(gbase) + (voff)[_i]), (PG8_LAS unsigned*)(lds + (bufoff) + ldsw + _i * 8192), 16, 0, 0); } while (0)
; #define PG8_LDA(dst, b, h) do { _Pragma("unroll") for (int m = 0; m < 4; ++m) _Pragma("unroll") for (int k = 0; k < 2; ++k) dst[m][k] = *(const PG8_LAS bf16x8*)(lds + PG8_SA(b, h) + aoff + m * 2048 + k * 1024); } while (0)
; #define PG8_BAR __builtin_amdgcn_s_barrier()
; template <class Epi, class Sched, bool ALIGN_EPI = false, bool SP2 = false>
; __device__ __forceinline__ void gemm_phase(PG8_LAS unsigned char* lds, const Gemm g, const Sched& S, const Epi& E) {
;     ...
;         const bool has_next = S.next(ui + 1, nxt);
;         const char* nA = has_next ? (const char*)g.A + (size_t)nxt.pm * tstep + (size_t)nxt.ko * 2 : cA; const char* nB = has_next ? (const char*)g.Bt + (size_t)nxt.pn * tstep + (size_t)nxt.ko * 2 : cB;
;         for (int t = 0; t < nt; t += 2) {
;             const bool last = (t == nt - 2);
;             const char* a1 = cA + (size_t)(t + 1) * kstep;
;             const char* a2 = last ? nA : cA + (size_t)(t + 2) * kstep; const char* b2 = last ? nB : cB + (size_t)(t + 2) * kstep;
;             const char* a3 = a2 + kstep; const char* b3 = b2 + kstep;
;             if (last && has_next) S.a_ready(nxt);
;             if constexpr (SP2) {
;             PG8_LDB(B0, 0, 0); PG8_LDB(B1, 0, 1); PG8_SCHED; PG8_LDA(At, 0, 0); PG8_STAGE(PG8_SA(1, 1), a1 + hstep, voffA);
;             PG8_WAIT_V(8); PG8_WAIT_L(0); PG8_BAR; PG8_MMA(0, 0, At, B0); PG8_MMA(0, 1, At, B1); PG8_BAR; PG8_SCHED;
;             PG8_LDA(At, 0, 1); PG8_STAGE(PG8_SB(0, 0), b2, voffB); PG8_STAGE(PG8_SB(0, 1), b2 + hstep, voffB); PG8_STAGE(PG8_SA(0, 0), a2, voffA);
;             PG8_WAIT_V(8); PG8_WAIT_L(0); PG8_BAR; PG8_MMA(1, 0, At, B0); PG8_MMA(1, 1, At, B1); PG8_BAR; PG8_SCHED;
.LBB0_1294:
	s_add_u32 s26, s24, 0x100
	s_addc_u32 s27, s25, 0
	s_add_i32 s54, 0, 0x10000
	s_cmpk_eq_i32 s53, 0x54
	s_cselect_b32 s31, s13, s27
	s_cselect_b32 s30, s12, s26
	s_cselect_b32 s29, s23, s3
	s_cselect_b32 s28, s22, s2
	s_add_i32 s55, 0, 0x14000
	v_add_u32_e32 v144, s54, v156
	v_add_u32_e32 v154, s55, v156
	ds_read_b128 v[132:135], v144
	ds_read_b128 v[136:139], v144 offset:1024
	ds_read_b128 v[140:143], v144 offset:2048
	ds_read_b128 v[144:147], v144 offset:3072
	ds_read_b128 v[160:163], v154
	ds_read_b128 v[164:167], v154 offset:1024
	ds_read_b128 v[168:171], v154 offset:2048
	ds_read_b128 v[172:175], v154 offset:3072
	v_lshl_add_u64 v[154:155], s[24:25], 0, v[150:151]
	s_add_i32 m0, s39, 0xc000
	ds_read_b128 v[176:179], v158
	ds_read_b128 v[180:183], v158 offset:1024
	ds_read_b128 v[184:187], v158 offset:2048
	ds_read_b128 v[188:191], v158 offset:3072
	ds_read_b128 v[192:195], v158 offset:4096
	ds_read_b128 v[196:199], v158 offset:5120
	ds_read_b128 v[200:203], v158 offset:6144
	ds_read_b128 v[204:207], v158 offset:7168
	global_load_lds_dwordx4 v[154:155], off
	v_lshl_add_u64 v[154:155], s[24:25], 0, v[152:153]
	s_add_i32 m0, s39, 0xe000
	s_nop 0
	global_load_lds_dwordx4 v[154:155], off
	s_setprio 1
	s_nop 0
	s_waitcnt vmcnt(8) lgkmcnt(0)
	s_barrier
	v_mfma_f32_16x16x32_bf16 v[128:131], v[132:135], v[176:179], v[128:131]
	v_mfma_f32_16x16x32_bf16 v[124:127], v[140:143], v[176:179], v[124:127]
	v_mfma_f32_16x16x32_bf16 v[120:123], v[132:135], v[184:187], v[120:123]
	v_mfma_f32_16x16x32_bf16 v[112:115], v[140:143], v[184:187], v[112:115]
	v_mfma_f32_16x16x32_bf16 v[104:107], v[132:135], v[192:195], v[104:107]
	v_mfma_f32_16x16x32_bf16 v[96:99], v[140:143], v[192:195], v[96:99]
	v_mfma_f32_16x16x32_bf16 v[88:91], v[132:135], v[200:203], v[88:91]
	v_mfma_f32_16x16x32_bf16 v[76:79], v[140:143], v[200:203], v[76:79]
	v_mfma_f32_16x16x32_bf16 v[128:131], v[136:139], v[180:183], v[128:131]
	v_mfma_f32_16x16x32_bf16 v[124:127], v[144:147], v[180:183], v[124:127]
	v_mfma_f32_16x16x32_bf16 v[120:123], v[136:139], v[188:191], v[120:123]
	v_mfma_f32_16x16x32_bf16 v[112:115], v[144:147], v[188:191], v[112:115]
	v_mfma_f32_16x16x32_bf16 v[104:107], v[136:139], v[196:199], v[104:107]
	v_mfma_f32_16x16x32_bf16 v[96:99], v[144:147], v[196:199], v[96:99]
	v_mfma_f32_16x16x32_bf16 v[88:91], v[136:139], v[204:207], v[88:91]
	v_mfma_f32_16x16x32_bf16 v[76:79], v[144:147], v[204:207], v[76:79]
	v_mfma_f32_16x16x32_bf16 v[116:119], v[160:163], v[176:179], v[116:119]
	v_mfma_f32_16x16x32_bf16 v[108:111], v[168:171], v[176:179], v[108:111]
	v_mfma_f32_16x16x32_bf16 v[100:103], v[160:163], v[184:187], v[100:103]
	v_mfma_f32_16x16x32_bf16 v[92:95], v[168:171], v[184:187], v[92:95]
	v_mfma_f32_16x16x32_bf16 v[84:87], v[160:163], v[192:195], v[84:87]
	v_mfma_f32_16x16x32_bf16 v[80:83], v[168:171], v[192:195], v[80:83]
	v_mfma_f32_16x16x32_bf16 v[72:75], v[160:163], v[200:203], v[72:75]
	v_mfma_f32_16x16x32_bf16 v[68:71], v[168:171], v[200:203], v[68:71]
	v_mfma_f32_16x16x32_bf16 v[116:119], v[164:167], v[180:183], v[116:119]
	v_mfma_f32_16x16x32_bf16 v[108:111], v[172:175], v[180:183], v[108:111]
	v_mfma_f32_16x16x32_bf16 v[100:103], v[164:167], v[188:191], v[100:103]
	v_mfma_f32_16x16x32_bf16 v[92:95], v[172:175], v[188:191], v[92:95]
	v_mfma_f32_16x16x32_bf16 v[84:87], v[164:167], v[196:199], v[84:87]
	v_mfma_f32_16x16x32_bf16 v[80:83], v[172:175], v[196:199], v[80:83]
	v_mfma_f32_16x16x32_bf16 v[72:75], v[164:167], v[204:207], v[72:75]
	v_mfma_f32_16x16x32_bf16 v[68:71], v[172:175], v[204:207], v[68:71]
	s_barrier
	s_setprio 0
	s_setprio 1
	s_setprio 0
	s_waitcnt lgkmcnt(0)
	s_add_i32 s24, s54, s38
	v_lshl_add_u64 v[154:155], s[28:29], 0, v[66:67]
	s_mov_b32 m0, s24
	ds_read_b128 v[176:179], v158 offset:16384
	ds_read_b128 v[180:183], v158 offset:17408
	ds_read_b128 v[184:187], v158 offset:18432
	ds_read_b128 v[188:191], v158 offset:19456
	ds_read_b128 v[192:195], v158 offset:20480
	ds_read_b128 v[196:199], v158 offset:21504
	ds_read_b128 v[200:203], v158 offset:22528
	ds_read_b128 v[204:207], v158 offset:23552
	global_load_lds_dwordx4 v[154:155], off
	s_add_i32 m0, s24, 0x2000
	s_add_u32 s24, s28, 0x160000
	v_lshl_add_u64 v[208:209], s[28:29], 0, v[148:149]
	s_addc_u32 s25, s29, 0
	s_add_i32 s54, s55, s38
	global_load_lds_dwordx4 v[208:209], off
	v_lshl_add_u64 v[210:211], s[24:25], 0, v[66:67]
	s_mov_b32 m0, s54
	v_lshl_add_u64 v[220:221], s[30:31], 0, v[148:149]
	global_load_lds_dwordx4 v[210:211], off
	v_lshl_add_u64 v[210:211], s[24:25], 0, v[148:149]
	s_add_i32 m0, s54, 0x2000
	s_nop 0
	global_load_lds_dwordx4 v[210:211], off
	v_lshl_add_u64 v[210:211], s[30:31], 0, v[66:67]
	s_mov_b32 m0, s39
	s_nop 0
	global_load_lds_dwordx4 v[210:211], off
	s_mov_b32 m0, s40
	s_nop 0
	global_load_lds_dwordx4 v[220:221], off
	s_setprio 1
	s_nop 0
	s_waitcnt vmcnt(8) lgkmcnt(0)
	s_barrier
; #define PG8_STAGE(bufoff, gbase, voff) do { _Pragma("unroll") for (int _i = 0; _i < 2; ++_i) \
;         __builtin_amdgcn_global_load_lds((const unsigned*)((const char*)(gbase) + (voff)[_i]), (PG8_LAS unsigned*)(lds + (bufoff) + ldsw + _i * 8192), 16, 0, 0); } while (0)
; #define PG8_LDA(dst, b, h) do { _Pragma("unroll") for (int m = 0; m < 4; ++m) _Pragma("unroll") for (int k = 0; k < 2; ++k) dst[m][k] = *(const PG8_LAS bf16x8*)(lds + PG8_SA(b, h) + aoff + m * 2048 + k * 1024); } while (0)
; #define PG8_LDB(dst, b, h) do { _Pragma("unroll") for (int n = 0; n < 2; ++n) _Pragma("unroll") for (int k = 0; k < 2; ++k) dst[n][k] = *(const PG8_LAS bf16x8*)(lds + PG8_SB(b, h) + boff + n * 2048 + k * 1024); } while (0)
; #define PG8_MMA(ai, bj, At, Bt) do { __builtin_amdgcn_s_setprio(1); _Pragma("unroll") for (int m = 0; m < 4; ++m) _Pragma("unroll") for (int n = 0; n < 2; ++n) _Pragma("unroll") for (int k = 0; k < 2; ++k) \
;         acc[ai][bj][m][n] = __builtin_amdgcn_mfma_f32_16x16x32_bf16(Bt[n][k], At[m][k], acc[ai][bj][m][n], 0, 0, 0); __builtin_amdgcn_s_setprio(0); } while (0)
; #define PG8_WAIT_V(n) asm volatile("s_waitcnt vmcnt(" #n ")" ::: "memory")
; #define PG8_WAIT_L(n) asm volatile("s_waitcnt lgkmcnt(" #n ")" ::: "memory")
; #define PG8_BAR __builtin_amdgcn_s_barrier()
; #define PG8_SCHED __builtin_amdgcn_sched_barrier(0)
; template <class Epi, class Sched, bool ALIGN_EPI = false, bool SP2 = false>
; __device__ __forceinline__ void gemm_phase(PG8_LAS unsigned char* lds, const Gemm g, const Sched& S, const Epi& E) {
;     ...
;             PG8_WAIT_V(8); PG8_WAIT_L(0); PG8_BAR; PG8_MMA(1, 0, At, B0); PG8_MMA(1, 1, At, B1); PG8_BAR; PG8_SCHED;
;             PG8_LDB(B0, 1, 0); PG8_LDB(B1, 1, 1); PG8_SCHED; PG8_LDA(At, 1, 0); PG8_STAGE(PG8_SA(0, 1), a2 + hstep, voffA);
;             PG8_WAIT_V(8); PG8_WAIT_L(0); PG8_BAR; PG8_MMA(0, 0, At, B0); PG8_MMA(0, 1, At, B1); PG8_BAR; PG8_SCHED;
	v_mfma_f32_16x16x32_bf16 v[62:65], v[132:135], v[176:179], v[62:65]
	v_mfma_f32_16x16x32_bf16 v[58:61], v[140:143], v[176:179], v[58:61]
	v_mfma_f32_16x16x32_bf16 v[54:57], v[132:135], v[184:187], v[54:57]
	v_mfma_f32_16x16x32_bf16 v[46:49], v[140:143], v[184:187], v[46:49]
	v_mfma_f32_16x16x32_bf16 v[38:41], v[132:135], v[192:195], v[38:41]
	v_mfma_f32_16x16x32_bf16 v[30:33], v[140:143], v[192:195], v[30:33]
	v_mfma_f32_16x16x32_bf16 v[22:25], v[132:135], v[200:203], v[22:25]
	v_mfma_f32_16x16x32_bf16 v[10:13], v[140:143], v[200:203], v[10:13]
	v_mfma_f32_16x16x32_bf16 v[62:65], v[136:139], v[180:183], v[62:65]
	v_mfma_f32_16x16x32_bf16 v[58:61], v[144:147], v[180:183], v[58:61]
	v_mfma_f32_16x16x32_bf16 v[54:57], v[136:139], v[188:191], v[54:57]
	v_mfma_f32_16x16x32_bf16 v[46:49], v[144:147], v[188:191], v[46:49]
	v_mfma_f32_16x16x32_bf16 v[38:41], v[136:139], v[196:199], v[38:41]
	v_mfma_f32_16x16x32_bf16 v[30:33], v[144:147], v[196:199], v[30:33]
	v_mfma_f32_16x16x32_bf16 v[22:25], v[136:139], v[204:207], v[22:25]
	v_mfma_f32_16x16x32_bf16 v[10:13], v[144:147], v[204:207], v[10:13]
	v_mfma_f32_16x16x32_bf16 v[50:53], v[160:163], v[176:179], v[50:53]
	v_mfma_f32_16x16x32_bf16 v[42:45], v[168:171], v[176:179], v[42:45]
	v_mfma_f32_16x16x32_bf16 v[34:37], v[160:163], v[184:187], v[34:37]
	v_mfma_f32_16x16x32_bf16 v[26:29], v[168:171], v[184:187], v[26:29]
	v_mfma_f32_16x16x32_bf16 v[18:21], v[160:163], v[192:195], v[18:21]
	v_mfma_f32_16x16x32_bf16 v[14:17], v[168:171], v[192:195], v[14:17]
	v_mfma_f32_16x16x32_bf16 v[6:9], v[160:163], v[200:203], v[6:9]
	v_mfma_f32_16x16x32_bf16 v[2:5], v[168:171], v[200:203], v[2:5]
	v_mfma_f32_16x16x32_bf16 v[50:53], v[164:167], v[180:183], v[50:53]
	v_mfma_f32_16x16x32_bf16 v[42:45], v[172:175], v[180:183], v[42:45]
	v_mfma_f32_16x16x32_bf16 v[34:37], v[164:167], v[188:191], v[34:37]
	v_mfma_f32_16x16x32_bf16 v[26:29], v[172:175], v[188:191], v[26:29]
	v_mfma_f32_16x16x32_bf16 v[18:21], v[164:167], v[196:199], v[18:21]
	v_mfma_f32_16x16x32_bf16 v[14:17], v[172:175], v[196:199], v[14:17]
	v_mfma_f32_16x16x32_bf16 v[6:9], v[164:167], v[204:207], v[6:9]
	v_mfma_f32_16x16x32_bf16 v[2:5], v[172:175], v[204:207], v[2:5]
	s_barrier
	s_setprio 0
	s_setprio 1
	s_setprio 0
	s_waitcnt lgkmcnt(0)
	s_add_i32 s54, 0, 0x18000
	s_add_i32 s55, 0, 0x1c000
	v_add_u32_e32 v144, s54, v156
	v_add_u32_e32 v159, s55, v156
	ds_read_b128 v[132:135], v144
	ds_read_b128 v[136:139], v144 offset:1024
	ds_read_b128 v[140:143], v144 offset:2048
	ds_read_b128 v[144:147], v144 offset:3072
	ds_read_b128 v[160:163], v159
	ds_read_b128 v[164:167], v159 offset:1024
	ds_read_b128 v[168:171], v159 offset:2048
	ds_read_b128 v[172:175], v159 offset:3072
	s_add_u32 s24, s30, 0x160000
	s_addc_u32 s25, s31, 0
	s_mov_b32 m0, s41
	v_lshl_add_u64 v[222:223], s[24:25], 0, v[66:67]
	ds_read_b128 v[176:179], v158 offset:32768
	ds_read_b128 v[180:183], v158 offset:33792
	ds_read_b128 v[184:187], v158 offset:34816
	ds_read_b128 v[188:191], v158 offset:35840
	ds_read_b128 v[192:195], v158 offset:36864
	ds_read_b128 v[196:199], v158 offset:37888
	ds_read_b128 v[200:203], v158 offset:38912
	ds_read_b128 v[204:207], v158 offset:39936
	global_load_lds_dwordx4 v[222:223], off
	v_lshl_add_u64 v[222:223], s[24:25], 0, v[148:149]
	s_mov_b32 m0, s42
	s_nop 0
	global_load_lds_dwordx4 v[222:223], off
	s_setprio 1
	s_nop 0
	s_waitcnt vmcnt(8) lgkmcnt(0)
	s_barrier
	v_mfma_f32_16x16x32_bf16 v[128:131], v[132:135], v[176:179], v[128:131]
	v_mfma_f32_16x16x32_bf16 v[124:127], v[140:143], v[176:179], v[124:127]
	v_mfma_f32_16x16x32_bf16 v[120:123], v[132:135], v[184:187], v[120:123]
	v_mfma_f32_16x16x32_bf16 v[112:115], v[140:143], v[184:187], v[112:115]
	v_mfma_f32_16x16x32_bf16 v[104:107], v[132:135], v[192:195], v[104:107]
	v_mfma_f32_16x16x32_bf16 v[96:99], v[140:143], v[192:195], v[96:99]
	v_mfma_f32_16x16x32_bf16 v[88:91], v[132:135], v[200:203], v[88:91]
	v_mfma_f32_16x16x32_bf16 v[76:79], v[140:143], v[200:203], v[76:79]
	v_mfma_f32_16x16x32_bf16 v[128:131], v[136:139], v[180:183], v[128:131]
	v_mfma_f32_16x16x32_bf16 v[124:127], v[144:147], v[180:183], v[124:127]
	v_mfma_f32_16x16x32_bf16 v[120:123], v[136:139], v[188:191], v[120:123]
	v_mfma_f32_16x16x32_bf16 v[112:115], v[144:147], v[188:191], v[112:115]
	v_mfma_f32_16x16x32_bf16 v[104:107], v[136:139], v[196:199], v[104:107]
	v_mfma_f32_16x16x32_bf16 v[96:99], v[144:147], v[196:199], v[96:99]
	v_mfma_f32_16x16x32_bf16 v[88:91], v[136:139], v[204:207], v[88:91]
	v_mfma_f32_16x16x32_bf16 v[76:79], v[144:147], v[204:207], v[76:79]
	v_mfma_f32_16x16x32_bf16 v[116:119], v[160:163], v[176:179], v[116:119]
	v_mfma_f32_16x16x32_bf16 v[108:111], v[168:171], v[176:179], v[108:111]
	v_mfma_f32_16x16x32_bf16 v[100:103], v[160:163], v[184:187], v[100:103]
	v_mfma_f32_16x16x32_bf16 v[92:95], v[168:171], v[184:187], v[92:95]
	v_mfma_f32_16x16x32_bf16 v[84:87], v[160:163], v[192:195], v[84:87]
	v_mfma_f32_16x16x32_bf16 v[80:83], v[168:171], v[192:195], v[80:83]
	v_mfma_f32_16x16x32_bf16 v[72:75], v[160:163], v[200:203], v[72:75]
	v_mfma_f32_16x16x32_bf16 v[68:71], v[168:171], v[200:203], v[68:71]
	v_mfma_f32_16x16x32_bf16 v[116:119], v[164:167], v[180:183], v[116:119]
	v_mfma_f32_16x16x32_bf16 v[108:111], v[172:175], v[180:183], v[108:111]
	v_mfma_f32_16x16x32_bf16 v[100:103], v[164:167], v[188:191], v[100:103]
	v_mfma_f32_16x16x32_bf16 v[92:95], v[172:175], v[188:191], v[92:95]
	v_mfma_f32_16x16x32_bf16 v[84:87], v[164:167], v[196:199], v[84:87]
	v_mfma_f32_16x16x32_bf16 v[80:83], v[172:175], v[196:199], v[80:83]
	v_mfma_f32_16x16x32_bf16 v[72:75], v[164:167], v[204:207], v[72:75]
	v_mfma_f32_16x16x32_bf16 v[68:71], v[172:175], v[204:207], v[68:71]
	s_barrier
; #define PG8_STAGE(bufoff, gbase, voff) do { _Pragma("unroll") for (int _i = 0; _i < 2; ++_i) \
;         __builtin_amdgcn_global_load_lds((const unsigned*)((const char*)(gbase) + (voff)[_i]), (PG8_LAS unsigned*)(lds + (bufoff) + ldsw + _i * 8192), 16, 0, 0); } while (0)
; #define PG8_LDA(dst, b, h) do { _Pragma("unroll") for (int m = 0; m < 4; ++m) _Pragma("unroll") for (int k = 0; k < 2; ++k) dst[m][k] = *(const PG8_LAS bf16x8*)(lds + PG8_SA(b, h) + aoff + m * 2048 + k * 1024); } while (0)
; #define PG8_MMA(ai, bj, At, Bt) do { __builtin_amdgcn_s_setprio(1); _Pragma("unroll") for (int m = 0; m < 4; ++m) _Pragma("unroll") for (int n = 0; n < 2; ++n) _Pragma("unroll") for (int k = 0; k < 2; ++k) \
;         acc[ai][bj][m][n] = __builtin_amdgcn_mfma_f32_16x16x32_bf16(Bt[n][k], At[m][k], acc[ai][bj][m][n], 0, 0, 0); __builtin_amdgcn_s_setprio(0); } while (0)
; #define PG8_WAIT_V(n) asm volatile("s_waitcnt vmcnt(" #n ")" ::: "memory")
; #define PG8_WAIT_L(n) asm volatile("s_waitcnt lgkmcnt(" #n ")" ::: "memory")
; #define PG8_BAR __builtin_amdgcn_s_barrier()
; #define PG8_SCHED __builtin_amdgcn_sched_barrier(0)
; template <class Epi, class Sched, bool ALIGN_EPI = false, bool SP2 = false>
; __device__ __forceinline__ void gemm_phase(PG8_LAS unsigned char* lds, const Gemm g, const Sched& S, const Epi& E) {
;     ...
;             PG8_LDA(At, 1, 1); PG8_STAGE(PG8_SB(1, 0), b3, voffB); PG8_STAGE(PG8_SB(1, 1), b3 + hstep, voffB); PG8_STAGE(PG8_SA(1, 0), a3, voffA);
;             PG8_WAIT_V(8); PG8_WAIT_L(0); PG8_BAR; PG8_MMA(1, 0, At, B0); PG8_MMA(1, 1, At, B1); PG8_BAR; PG8_SCHED;
;     ...
;         if constexpr (ALIGN_EPI) { if (wr == 0) PG8_BAR; }
	s_setprio 0
	s_setprio 1
	s_setprio 0
	s_waitcnt lgkmcnt(0)
	s_add_i32 s24, s54, s38
	v_lshl_add_u64 v[154:155], v[154:155], 0, s[88:89]
	s_mov_b32 m0, s24
	ds_read_b128 v[176:179], v158 offset:49152
	ds_read_b128 v[180:183], v158 offset:50176
	ds_read_b128 v[184:187], v158 offset:51200
	ds_read_b128 v[188:191], v158 offset:52224
	ds_read_b128 v[192:195], v158 offset:53248
	ds_read_b128 v[196:199], v158 offset:54272
	ds_read_b128 v[200:203], v158 offset:55296
	ds_read_b128 v[204:207], v158 offset:56320
	global_load_lds_dwordx4 v[154:155], off
	s_add_i32 m0, s24, 0x2000
	s_add_u32 s24, s28, 0x160080
	v_lshl_add_u64 v[154:155], v[208:209], 0, s[88:89]
	s_addc_u32 s25, s29, 0
	s_add_i32 s28, s55, s38
	global_load_lds_dwordx4 v[154:155], off
	v_lshl_add_u64 v[154:155], s[24:25], 0, v[66:67]
	s_mov_b32 m0, s28
	s_nop 0
	global_load_lds_dwordx4 v[154:155], off
	v_lshl_add_u64 v[154:155], s[24:25], 0, v[148:149]
	s_add_i32 m0, s28, 0x2000
	s_nop 0
	global_load_lds_dwordx4 v[154:155], off
	v_lshl_add_u64 v[154:155], v[210:211], 0, s[88:89]
	s_mov_b32 m0, s45
	s_nop 0
	global_load_lds_dwordx4 v[154:155], off
	v_lshl_add_u64 v[154:155], v[220:221], 0, s[88:89]
	s_mov_b32 m0, s46
	s_nop 0
	global_load_lds_dwordx4 v[154:155], off
	s_setprio 1
	s_nop 0
	s_waitcnt vmcnt(8) lgkmcnt(0)
	s_barrier
	v_mfma_f32_16x16x32_bf16 v[62:65], v[132:135], v[176:179], v[62:65]
	v_mfma_f32_16x16x32_bf16 v[58:61], v[140:143], v[176:179], v[58:61]
	v_mfma_f32_16x16x32_bf16 v[54:57], v[132:135], v[184:187], v[54:57]
	v_mfma_f32_16x16x32_bf16 v[46:49], v[140:143], v[184:187], v[46:49]
	v_mfma_f32_16x16x32_bf16 v[38:41], v[132:135], v[192:195], v[38:41]
	v_mfma_f32_16x16x32_bf16 v[30:33], v[140:143], v[192:195], v[30:33]
	v_mfma_f32_16x16x32_bf16 v[22:25], v[132:135], v[200:203], v[22:25]
	v_mfma_f32_16x16x32_bf16 v[10:13], v[140:143], v[200:203], v[10:13]
	v_mfma_f32_16x16x32_bf16 v[62:65], v[136:139], v[180:183], v[62:65]
	v_mfma_f32_16x16x32_bf16 v[58:61], v[144:147], v[180:183], v[58:61]
	v_mfma_f32_16x16x32_bf16 v[54:57], v[136:139], v[188:191], v[54:57]
	v_mfma_f32_16x16x32_bf16 v[46:49], v[144:147], v[188:191], v[46:49]
	v_mfma_f32_16x16x32_bf16 v[38:41], v[136:139], v[196:199], v[38:41]
	v_mfma_f32_16x16x32_bf16 v[30:33], v[144:147], v[196:199], v[30:33]
	v_mfma_f32_16x16x32_bf16 v[22:25], v[136:139], v[204:207], v[22:25]
	v_mfma_f32_16x16x32_bf16 v[10:13], v[144:147], v[204:207], v[10:13]
	v_mfma_f32_16x16x32_bf16 v[50:53], v[160:163], v[176:179], v[50:53]
	v_mfma_f32_16x16x32_bf16 v[42:45], v[168:171], v[176:179], v[42:45]
	v_mfma_f32_16x16x32_bf16 v[34:37], v[160:163], v[184:187], v[34:37]
	v_mfma_f32_16x16x32_bf16 v[26:29], v[168:171], v[184:187], v[26:29]
	v_mfma_f32_16x16x32_bf16 v[18:21], v[160:163], v[192:195], v[18:21]
	v_mfma_f32_16x16x32_bf16 v[14:17], v[168:171], v[192:195], v[14:17]
	v_mfma_f32_16x16x32_bf16 v[6:9], v[160:163], v[200:203], v[6:9]
	v_mfma_f32_16x16x32_bf16 v[2:5], v[168:171], v[200:203], v[2:5]
	v_mfma_f32_16x16x32_bf16 v[50:53], v[164:167], v[180:183], v[50:53]
	v_mfma_f32_16x16x32_bf16 v[42:45], v[172:175], v[180:183], v[42:45]
	v_mfma_f32_16x16x32_bf16 v[34:37], v[164:167], v[188:191], v[34:37]
	v_mfma_f32_16x16x32_bf16 v[26:29], v[172:175], v[188:191], v[26:29]
	v_mfma_f32_16x16x32_bf16 v[18:21], v[164:167], v[196:199], v[18:21]
	v_mfma_f32_16x16x32_bf16 v[14:17], v[172:175], v[196:199], v[14:17]
	v_mfma_f32_16x16x32_bf16 v[6:9], v[164:167], v[204:207], v[6:9]
	v_mfma_f32_16x16x32_bf16 v[2:5], v[172:175], v[204:207], v[2:5]
	s_barrier
	s_setprio 0
	s_setprio 1
	s_setprio 0
	s_waitcnt lgkmcnt(0)
	s_add_i32 s53, s53, 2
	s_add_u32 s2, s2, 0x100
	s_addc_u32 s3, s3, 0
	s_cmpk_gt_u32 s53, 0x55
	s_mov_b64 s[24:25], s[26:27]
	s_cbranch_scc0 .LBB0_1294
	s_and_b64 vcc, exec, s[20:21]
	s_cbranch_vccz .LBB0_1297
	s_barrier

;     __host__ __device__ bool next(int i, Unit& u) const { if (i != 0 || r < 0 || r >= 148) return false; if (r < 116) { u.pm = r % 29; u.pn = 47 + r / 29; } else { u.pm = 32; u.pn = 19 + (r - 116); } u.ko = 0; return true; }
;     __host__ __device__ bool next(int i, Unit& u) const { const int L = i * G + (G - 1 - c); if (L >= nN * S) return false; u.pm = pm; u.pn = L % nN; u.ko = (L / nN) * ksub; return true; }
; #define PG8_STAGE(bufoff, gbase, voff) do { _Pragma("unroll") for (int _i = 0; _i < 2; ++_i) \
;         __builtin_amdgcn_global_load_lds((const unsigned*)((const char*)(gbase) + (voff)[_i]), (PG8_LAS unsigned*)(lds + (bufoff) + ldsw + _i * 8192), 16, 0, 0); } while (0)
; #define PG8_LDA(dst, b, h) do { _Pragma("unroll") for (int m = 0; m < 4; ++m) _Pragma("unroll") for (int k = 0; k < 2; ++k) dst[m][k] = *(const PG8_LAS bf16x8*)(lds + PG8_SA(b, h) + aoff + m * 2048 + k * 1024); } while (0)
; #define PG8_BAR __builtin_amdgcn_s_barrier()
; template <class Epi, class Sched, bool ALIGN_EPI = false, bool SP2 = false>
; __device__ __forceinline__ void gemm_phase(PG8_LAS unsigned char* lds, const Gemm g, const Sched& S, const Epi& E) {
;     ...
;         const bool has_next = S.next(ui + 1, nxt);
;         const char* nA = has_next ? (const char*)g.A + (size_t)nxt.pm * tstep + (size_t)nxt.ko * 2 : cA; const char* nB = has_next ? (const char*)g.Bt + (size_t)nxt.pn * tstep + (size_t)nxt.ko * 2 : cB;
;         for (int t = 0; t < nt; t += 2) {
;             const bool last = (t == nt - 2);
;             const char* a1 = cA + (size_t)(t + 1) * kstep;
;             const char* a2 = last ? nA : cA + (size_t)(t + 2) * kstep; const char* b2 = last ? nB : cB + (size_t)(t + 2) * kstep;
;             const char* a3 = a2 + kstep; const char* b3 = b2 + kstep;
;             if (last && has_next) S.a_ready(nxt);
;             if constexpr (SP2) {
;             PG8_LDB(B0, 0, 0); PG8_LDB(B1, 0, 1); PG8_SCHED; PG8_LDA(At, 0, 0); PG8_STAGE(PG8_SA(1, 1), a1 + hstep, voffA);
;             PG8_WAIT_V(8); PG8_WAIT_L(0); PG8_BAR; PG8_MMA(0, 0, At, B0); PG8_MMA(0, 1, At, B1); PG8_BAR; PG8_SCHED;
;             PG8_LDA(At, 0, 1); PG8_STAGE(PG8_SB(0, 0), b2, voffB); PG8_STAGE(PG8_SB(0, 1), b2 + hstep, voffB); PG8_STAGE(PG8_SA(0, 0), a2, voffA);
;             PG8_WAIT_V(8); PG8_WAIT_L(0); PG8_BAR; PG8_MMA(1, 0, At, B0); PG8_MMA(1, 1, At, B1); PG8_BAR; PG8_SCHED;
.LBB0_1324:
	s_add_u32 s28, s22, s26
	s_addc_u32 s29, s23, s27
	s_add_u32 s28, s28, 0x100
	s_addc_u32 s29, s29, 0
	s_add_u32 s54, s3, s26
	s_addc_u32 s55, s52, s27
	s_add_i32 s56, 0, 0x10000
	s_cmpk_eq_i32 s26, 0x2b00
	s_cselect_b32 s31, s25, s29
	s_cselect_b32 s30, s24, s28
	s_cselect_b32 s29, s13, s55
	s_cselect_b32 s28, s12, s54
	s_add_i32 s57, 0, 0x14000
	v_add_u32_e32 v156, s56, v142
	v_add_u32_e32 v172, s57, v142
	ds_read_b128 v[144:147], v156
	ds_read_b128 v[148:151], v156 offset:1024
	ds_read_b128 v[152:155], v156 offset:2048
	ds_read_b128 v[156:159], v156 offset:3072
	ds_read_b128 v[160:163], v172
	ds_read_b128 v[164:167], v172 offset:1024
	ds_read_b128 v[168:171], v172 offset:2048
	ds_read_b128 v[172:175], v172 offset:3072
	v_lshl_add_u64 v[208:209], v[138:139], 0, s[26:27]
	s_add_i32 m0, s43, 0xc000
	ds_read_b128 v[176:179], v143
	ds_read_b128 v[180:183], v143 offset:1024
	ds_read_b128 v[184:187], v143 offset:2048
	ds_read_b128 v[188:191], v143 offset:3072
	ds_read_b128 v[192:195], v143 offset:4096
	ds_read_b128 v[196:199], v143 offset:5120
	ds_read_b128 v[200:203], v143 offset:6144
	ds_read_b128 v[204:207], v143 offset:7168
	global_load_lds_dwordx4 v[208:209], off
	v_lshl_add_u64 v[208:209], v[140:141], 0, s[26:27]
	s_add_i32 m0, s43, 0xe000
	s_nop 0
	global_load_lds_dwordx4 v[208:209], off
	s_setprio 1
	s_nop 0
	s_waitcnt vmcnt(8) lgkmcnt(0)
	s_barrier
	v_mfma_f32_16x16x32_bf16 v[128:131], v[144:147], v[176:179], v[128:131]
	v_mfma_f32_16x16x32_bf16 v[124:127], v[152:155], v[176:179], v[124:127]
	v_mfma_f32_16x16x32_bf16 v[112:115], v[144:147], v[184:187], v[112:115]
	v_mfma_f32_16x16x32_bf16 v[104:107], v[152:155], v[184:187], v[104:107]
	v_mfma_f32_16x16x32_bf16 v[96:99], v[144:147], v[192:195], v[96:99]
	v_mfma_f32_16x16x32_bf16 v[88:91], v[152:155], v[192:195], v[88:91]
	v_mfma_f32_16x16x32_bf16 v[80:83], v[144:147], v[200:203], v[80:83]
	v_mfma_f32_16x16x32_bf16 v[72:75], v[152:155], v[200:203], v[72:75]
	v_mfma_f32_16x16x32_bf16 v[128:131], v[148:151], v[180:183], v[128:131]
	v_mfma_f32_16x16x32_bf16 v[124:127], v[156:159], v[180:183], v[124:127]
	v_mfma_f32_16x16x32_bf16 v[112:115], v[148:151], v[188:191], v[112:115]
	v_mfma_f32_16x16x32_bf16 v[104:107], v[156:159], v[188:191], v[104:107]
	v_mfma_f32_16x16x32_bf16 v[96:99], v[148:151], v[196:199], v[96:99]
	v_mfma_f32_16x16x32_bf16 v[88:91], v[156:159], v[196:199], v[88:91]
	v_mfma_f32_16x16x32_bf16 v[80:83], v[148:151], v[204:207], v[80:83]
	v_mfma_f32_16x16x32_bf16 v[72:75], v[156:159], v[204:207], v[72:75]
	v_mfma_f32_16x16x32_bf16 v[116:119], v[160:163], v[176:179], v[116:119]
	v_mfma_f32_16x16x32_bf16 v[108:111], v[168:171], v[176:179], v[108:111]
	v_mfma_f32_16x16x32_bf16 v[100:103], v[160:163], v[184:187], v[100:103]
	v_mfma_f32_16x16x32_bf16 v[92:95], v[168:171], v[184:187], v[92:95]
	v_mfma_f32_16x16x32_bf16 v[84:87], v[160:163], v[192:195], v[84:87]
	v_mfma_f32_16x16x32_bf16 v[76:79], v[168:171], v[192:195], v[76:79]
	v_mfma_f32_16x16x32_bf16 v[68:71], v[160:163], v[200:203], v[68:71]
	v_mfma_f32_16x16x32_bf16 v[62:65], v[168:171], v[200:203], v[62:65]
	v_mfma_f32_16x16x32_bf16 v[116:119], v[164:167], v[180:183], v[116:119]
	v_mfma_f32_16x16x32_bf16 v[108:111], v[172:175], v[180:183], v[108:111]
	v_mfma_f32_16x16x32_bf16 v[100:103], v[164:167], v[188:191], v[100:103]
	v_mfma_f32_16x16x32_bf16 v[92:95], v[172:175], v[188:191], v[92:95]
	v_mfma_f32_16x16x32_bf16 v[84:87], v[164:167], v[196:199], v[84:87]
	v_mfma_f32_16x16x32_bf16 v[76:79], v[172:175], v[196:199], v[76:79]
	v_mfma_f32_16x16x32_bf16 v[68:71], v[164:167], v[204:207], v[68:71]
	v_mfma_f32_16x16x32_bf16 v[62:65], v[172:175], v[204:207], v[62:65]
	s_barrier
	s_setprio 0
	s_setprio 1
	s_setprio 0
	s_waitcnt lgkmcnt(0)
	s_add_i32 s54, s56, s42
	v_lshl_add_u64 v[208:209], s[28:29], 0, v[66:67]
	s_mov_b32 m0, s54
	ds_read_b128 v[176:179], v143 offset:16384
	ds_read_b128 v[180:183], v143 offset:17408
	ds_read_b128 v[184:187], v143 offset:18432
	ds_read_b128 v[188:191], v143 offset:19456
	ds_read_b128 v[192:195], v143 offset:20480
	ds_read_b128 v[196:199], v143 offset:21504
	ds_read_b128 v[200:203], v143 offset:22528
	ds_read_b128 v[204:207], v143 offset:23552
	global_load_lds_dwordx4 v[208:209], off
	s_add_i32 m0, s54, 0x2000
	s_add_u32 s54, s28, 0x160000
	v_lshl_add_u64 v[210:211], s[28:29], 0, v[132:133]
	s_addc_u32 s55, s29, 0
	s_add_i32 s56, s57, s42
	global_load_lds_dwordx4 v[210:211], off
	v_lshl_add_u64 v[220:221], s[54:55], 0, v[66:67]
	s_mov_b32 m0, s56
	v_lshl_add_u64 v[222:223], s[30:31], 0, v[132:133]
	global_load_lds_dwordx4 v[220:221], off
	v_lshl_add_u64 v[220:221], s[54:55], 0, v[132:133]
	s_add_i32 m0, s56, 0x2000
	s_nop 0
	global_load_lds_dwordx4 v[220:221], off
	v_lshl_add_u64 v[220:221], s[30:31], 0, v[66:67]
	s_mov_b32 m0, s43
	s_nop 0
	global_load_lds_dwordx4 v[220:221], off
	s_mov_b32 m0, s44
	s_nop 0
	global_load_lds_dwordx4 v[222:223], off
	s_setprio 1
	s_nop 0
	s_waitcnt vmcnt(8) lgkmcnt(0)
	s_barrier
; #define PG8_STAGE(bufoff, gbase, voff) do { _Pragma("unroll") for (int _i = 0; _i < 2; ++_i) \
;         __builtin_amdgcn_global_load_lds((const unsigned*)((const char*)(gbase) + (voff)[_i]), (PG8_LAS unsigned*)(lds + (bufoff) + ldsw + _i * 8192), 16, 0, 0); } while (0)
; #define PG8_LDA(dst, b, h) do { _Pragma("unroll") for (int m = 0; m < 4; ++m) _Pragma("unroll") for (int k = 0; k < 2; ++k) dst[m][k] = *(const PG8_LAS bf16x8*)(lds + PG8_SA(b, h) + aoff + m * 2048 + k * 1024); } while (0)
; #define PG8_LDB(dst, b, h) do { _Pragma("unroll") for (int n = 0; n < 2; ++n) _Pragma("unroll") for (int k = 0; k < 2; ++k) dst[n][k] = *(const PG8_LAS bf16x8*)(lds + PG8_SB(b, h) + boff + n * 2048 + k * 1024); } while (0)
; #define PG8_MMA(ai, bj, At, Bt) do { __builtin_amdgcn_s_setprio(1); _Pragma("unroll") for (int m = 0; m < 4; ++m) _Pragma("unroll") for (int n = 0; n < 2; ++n) _Pragma("unroll") for (int k = 0; k < 2; ++k) \
;         acc[ai][bj][m][n] = __builtin_amdgcn_mfma_f32_16x16x32_bf16(Bt[n][k], At[m][k], acc[ai][bj][m][n], 0, 0, 0); __builtin_amdgcn_s_setprio(0); } while (0)
; #define PG8_WAIT_V(n) asm volatile("s_waitcnt vmcnt(" #n ")" ::: "memory")
; #define PG8_WAIT_L(n) asm volatile("s_waitcnt lgkmcnt(" #n ")" ::: "memory")
; #define PG8_BAR __builtin_amdgcn_s_barrier()
; #define PG8_SCHED __builtin_amdgcn_sched_barrier(0)
; template <class Epi, class Sched, bool ALIGN_EPI = false, bool SP2 = false>
; __device__ __forceinline__ void gemm_phase(PG8_LAS unsigned char* lds, const Gemm g, const Sched& S, const Epi& E) {
;     ...
;             PG8_WAIT_V(8); PG8_WAIT_L(0); PG8_BAR; PG8_MMA(1, 0, At, B0); PG8_MMA(1, 1, At, B1); PG8_BAR; PG8_SCHED;
;             PG8_LDB(B0, 1, 0); PG8_LDB(B1, 1, 1); PG8_SCHED; PG8_LDA(At, 1, 0); PG8_STAGE(PG8_SA(0, 1), a2 + hstep, voffA);
;             PG8_WAIT_V(8); PG8_WAIT_L(0); PG8_BAR; PG8_MMA(0, 0, At, B0); PG8_MMA(0, 1, At, B1); PG8_BAR; PG8_SCHED;
	v_mfma_f32_16x16x32_bf16 v[58:61], v[144:147], v[176:179], v[58:61]
	v_mfma_f32_16x16x32_bf16 v[54:57], v[152:155], v[176:179], v[54:57]
	v_mfma_f32_16x16x32_bf16 v[46:49], v[144:147], v[184:187], v[46:49]
	v_mfma_f32_16x16x32_bf16 v[38:41], v[152:155], v[184:187], v[38:41]
	v_mfma_f32_16x16x32_bf16 v[30:33], v[144:147], v[192:195], v[30:33]
	v_mfma_f32_16x16x32_bf16 v[22:25], v[152:155], v[192:195], v[22:25]
	v_mfma_f32_16x16x32_bf16 v[120:123], v[144:147], v[200:203], v[120:123]
	v_mfma_f32_16x16x32_bf16 v[10:13], v[152:155], v[200:203], v[10:13]
	v_mfma_f32_16x16x32_bf16 v[58:61], v[148:151], v[180:183], v[58:61]
	v_mfma_f32_16x16x32_bf16 v[54:57], v[156:159], v[180:183], v[54:57]
	v_mfma_f32_16x16x32_bf16 v[46:49], v[148:151], v[188:191], v[46:49]
	v_mfma_f32_16x16x32_bf16 v[38:41], v[156:159], v[188:191], v[38:41]
	v_mfma_f32_16x16x32_bf16 v[30:33], v[148:151], v[196:199], v[30:33]
	v_mfma_f32_16x16x32_bf16 v[22:25], v[156:159], v[196:199], v[22:25]
	v_mfma_f32_16x16x32_bf16 v[120:123], v[148:151], v[204:207], v[120:123]
	v_mfma_f32_16x16x32_bf16 v[10:13], v[156:159], v[204:207], v[10:13]
	v_mfma_f32_16x16x32_bf16 v[50:53], v[160:163], v[176:179], v[50:53]
	v_mfma_f32_16x16x32_bf16 v[42:45], v[168:171], v[176:179], v[42:45]
	v_mfma_f32_16x16x32_bf16 v[34:37], v[160:163], v[184:187], v[34:37]
	v_mfma_f32_16x16x32_bf16 v[26:29], v[168:171], v[184:187], v[26:29]
	v_mfma_f32_16x16x32_bf16 v[18:21], v[160:163], v[192:195], v[18:21]
	v_mfma_f32_16x16x32_bf16 v[14:17], v[168:171], v[192:195], v[14:17]
	v_mfma_f32_16x16x32_bf16 v[6:9], v[160:163], v[200:203], v[6:9]
	v_mfma_f32_16x16x32_bf16 v[2:5], v[168:171], v[200:203], v[2:5]
	v_mfma_f32_16x16x32_bf16 v[50:53], v[164:167], v[180:183], v[50:53]
	v_mfma_f32_16x16x32_bf16 v[42:45], v[172:175], v[180:183], v[42:45]
	v_mfma_f32_16x16x32_bf16 v[34:37], v[164:167], v[188:191], v[34:37]
	v_mfma_f32_16x16x32_bf16 v[26:29], v[172:175], v[188:191], v[26:29]
	v_mfma_f32_16x16x32_bf16 v[18:21], v[164:167], v[196:199], v[18:21]
	v_mfma_f32_16x16x32_bf16 v[14:17], v[172:175], v[196:199], v[14:17]
	v_mfma_f32_16x16x32_bf16 v[6:9], v[164:167], v[204:207], v[6:9]
	v_mfma_f32_16x16x32_bf16 v[2:5], v[172:175], v[204:207], v[2:5]
	s_barrier
	s_setprio 0
	s_setprio 1
	s_setprio 0
	s_waitcnt lgkmcnt(0)
	s_add_i32 s54, 0, 0x18000
	s_add_i32 s55, 0, 0x1c000
	v_add_u32_e32 v156, s54, v142
	v_add_u32_e32 v172, s55, v142
	ds_read_b128 v[144:147], v156
	ds_read_b128 v[148:151], v156 offset:1024
	ds_read_b128 v[152:155], v156 offset:2048
	ds_read_b128 v[156:159], v156 offset:3072
	ds_read_b128 v[160:163], v172
	ds_read_b128 v[164:167], v172 offset:1024
	ds_read_b128 v[168:171], v172 offset:2048
	ds_read_b128 v[172:175], v172 offset:3072
	s_add_u32 s30, s30, 0x160000
	s_addc_u32 s31, s31, 0
	s_mov_b32 m0, s45
	v_lshl_add_u64 v[224:225], s[30:31], 0, v[66:67]
	ds_read_b128 v[176:179], v143 offset:32768
	ds_read_b128 v[180:183], v143 offset:33792
	ds_read_b128 v[184:187], v143 offset:34816
	ds_read_b128 v[188:191], v143 offset:35840
	ds_read_b128 v[192:195], v143 offset:36864
	ds_read_b128 v[196:199], v143 offset:37888
	ds_read_b128 v[200:203], v143 offset:38912
	ds_read_b128 v[204:207], v143 offset:39936
	global_load_lds_dwordx4 v[224:225], off
	v_lshl_add_u64 v[224:225], s[30:31], 0, v[132:133]
	s_mov_b32 m0, s1
	s_nop 0
	global_load_lds_dwordx4 v[224:225], off
	s_setprio 1
	s_nop 0
	s_waitcnt vmcnt(8) lgkmcnt(0)
	s_barrier
	v_mfma_f32_16x16x32_bf16 v[128:131], v[144:147], v[176:179], v[128:131]
	v_mfma_f32_16x16x32_bf16 v[124:127], v[152:155], v[176:179], v[124:127]
	v_mfma_f32_16x16x32_bf16 v[112:115], v[144:147], v[184:187], v[112:115]
	v_mfma_f32_16x16x32_bf16 v[104:107], v[152:155], v[184:187], v[104:107]
	v_mfma_f32_16x16x32_bf16 v[96:99], v[144:147], v[192:195], v[96:99]
	v_mfma_f32_16x16x32_bf16 v[88:91], v[152:155], v[192:195], v[88:91]
	v_mfma_f32_16x16x32_bf16 v[80:83], v[144:147], v[200:203], v[80:83]
	v_mfma_f32_16x16x32_bf16 v[72:75], v[152:155], v[200:203], v[72:75]
	v_mfma_f32_16x16x32_bf16 v[128:131], v[148:151], v[180:183], v[128:131]
	v_mfma_f32_16x16x32_bf16 v[124:127], v[156:159], v[180:183], v[124:127]
	v_mfma_f32_16x16x32_bf16 v[112:115], v[148:151], v[188:191], v[112:115]
	v_mfma_f32_16x16x32_bf16 v[104:107], v[156:159], v[188:191], v[104:107]
	v_mfma_f32_16x16x32_bf16 v[96:99], v[148:151], v[196:199], v[96:99]
	v_mfma_f32_16x16x32_bf16 v[88:91], v[156:159], v[196:199], v[88:91]
	v_mfma_f32_16x16x32_bf16 v[80:83], v[148:151], v[204:207], v[80:83]
	v_mfma_f32_16x16x32_bf16 v[72:75], v[156:159], v[204:207], v[72:75]
	v_mfma_f32_16x16x32_bf16 v[116:119], v[160:163], v[176:179], v[116:119]
	v_mfma_f32_16x16x32_bf16 v[108:111], v[168:171], v[176:179], v[108:111]
	v_mfma_f32_16x16x32_bf16 v[100:103], v[160:163], v[184:187], v[100:103]
	v_mfma_f32_16x16x32_bf16 v[92:95], v[168:171], v[184:187], v[92:95]
	v_mfma_f32_16x16x32_bf16 v[84:87], v[160:163], v[192:195], v[84:87]
	v_mfma_f32_16x16x32_bf16 v[76:79], v[168:171], v[192:195], v[76:79]
	v_mfma_f32_16x16x32_bf16 v[68:71], v[160:163], v[200:203], v[68:71]
	v_mfma_f32_16x16x32_bf16 v[62:65], v[168:171], v[200:203], v[62:65]
	v_mfma_f32_16x16x32_bf16 v[116:119], v[164:167], v[180:183], v[116:119]
	v_mfma_f32_16x16x32_bf16 v[108:111], v[172:175], v[180:183], v[108:111]
	v_mfma_f32_16x16x32_bf16 v[100:103], v[164:167], v[188:191], v[100:103]
	v_mfma_f32_16x16x32_bf16 v[92:95], v[172:175], v[188:191], v[92:95]
	v_mfma_f32_16x16x32_bf16 v[84:87], v[164:167], v[196:199], v[84:87]
	v_mfma_f32_16x16x32_bf16 v[76:79], v[172:175], v[196:199], v[76:79]
	v_mfma_f32_16x16x32_bf16 v[68:71], v[164:167], v[204:207], v[68:71]
	v_mfma_f32_16x16x32_bf16 v[62:65], v[172:175], v[204:207], v[62:65]
	s_barrier
; #define PG8_STAGE(bufoff, gbase, voff) do { _Pragma("unroll") for (int _i = 0; _i < 2; ++_i) \
;         __builtin_amdgcn_global_load_lds((const unsigned*)((const char*)(gbase) + (voff)[_i]), (PG8_LAS unsigned*)(lds + (bufoff) + ldsw + _i * 8192), 16, 0, 0); } while (0)
; #define PG8_LDA(dst, b, h) do { _Pragma("unroll") for (int m = 0; m < 4; ++m) _Pragma("unroll") for (int k = 0; k < 2; ++k) dst[m][k] = *(const PG8_LAS bf16x8*)(lds + PG8_SA(b, h) + aoff + m * 2048 + k * 1024); } while (0)
; #define PG8_MMA(ai, bj, At, Bt) do { __builtin_amdgcn_s_setprio(1); _Pragma("unroll") for (int m = 0; m < 4; ++m) _Pragma("unroll") for (int n = 0; n < 2; ++n) _Pragma("unroll") for (int k = 0; k < 2; ++k) \
;         acc[ai][bj][m][n] = __builtin_amdgcn_mfma_f32_16x16x32_bf16(Bt[n][k], At[m][k], acc[ai][bj][m][n], 0, 0, 0); __builtin_amdgcn_s_setprio(0); } while (0)
; #define PG8_WAIT_V(n) asm volatile("s_waitcnt vmcnt(" #n ")" ::: "memory")
; #define PG8_WAIT_L(n) asm volatile("s_waitcnt lgkmcnt(" #n ")" ::: "memory")
; #define PG8_BAR __builtin_amdgcn_s_barrier()
; #define PG8_SCHED __builtin_amdgcn_sched_barrier(0)
; template <class Epi, class Sched, bool ALIGN_EPI = false, bool SP2 = false>
; __device__ __forceinline__ void gemm_phase(PG8_LAS unsigned char* lds, const Gemm g, const Sched& S, const Epi& E) {
;     ...
;             PG8_LDA(At, 1, 1); PG8_STAGE(PG8_SB(1, 0), b3, voffB); PG8_STAGE(PG8_SB(1, 1), b3 + hstep, voffB); PG8_STAGE(PG8_SA(1, 0), a3, voffA);
;             PG8_WAIT_V(8); PG8_WAIT_L(0); PG8_BAR; PG8_MMA(1, 0, At, B0); PG8_MMA(1, 1, At, B1); PG8_BAR; PG8_SCHED;
;     ...
;         if (!has_next) break;
; #pragma unroll
;         for (int a = 0; a < 2; ++a)
; #pragma unroll
;             for (int b = 0; b < 2; ++b)
; #pragma unroll
;                 for (int m = 0; m < 4; ++m)
; #pragma unroll
;                     for (int n = 0; n < 2; ++n) acc[a][b][m][n] = (f32x4){0.f, 0.f, 0.f, 0.f};
;         cur = nxt; cA = nA; cB = nB; ++ui;
	s_setprio 0
	s_setprio 1
	s_setprio 0
	s_waitcnt lgkmcnt(0)
	s_add_i32 s30, s54, s42
	v_lshl_add_u64 v[208:209], v[208:209], 0, s[88:89]
	s_mov_b32 m0, s30
	ds_read_b128 v[176:179], v143 offset:49152
	ds_read_b128 v[180:183], v143 offset:50176
	ds_read_b128 v[184:187], v143 offset:51200
	ds_read_b128 v[188:191], v143 offset:52224
	ds_read_b128 v[192:195], v143 offset:53248
	ds_read_b128 v[196:199], v143 offset:54272
	ds_read_b128 v[200:203], v143 offset:55296
	ds_read_b128 v[204:207], v143 offset:56320
	global_load_lds_dwordx4 v[208:209], off
	s_add_i32 m0, s30, 0x2000
	s_add_u32 s28, s28, 0x160080
	v_lshl_add_u64 v[208:209], v[210:211], 0, s[88:89]
	s_addc_u32 s29, s29, 0
	s_add_i32 s30, s55, s42
	global_load_lds_dwordx4 v[208:209], off
	v_lshl_add_u64 v[208:209], s[28:29], 0, v[66:67]
	s_mov_b32 m0, s30
	s_nop 0
	global_load_lds_dwordx4 v[208:209], off
	v_lshl_add_u64 v[208:209], s[28:29], 0, v[132:133]
	s_add_i32 m0, s30, 0x2000
	s_nop 0
	global_load_lds_dwordx4 v[208:209], off
	v_lshl_add_u64 v[208:209], v[220:221], 0, s[88:89]
	s_mov_b32 m0, s47
	s_nop 0
	global_load_lds_dwordx4 v[208:209], off
	v_lshl_add_u64 v[208:209], v[222:223], 0, s[88:89]
	s_mov_b32 m0, s48
	s_nop 0
	global_load_lds_dwordx4 v[208:209], off
	s_setprio 1
	s_nop 0
	s_waitcnt vmcnt(8) lgkmcnt(0)
	s_barrier
	v_mfma_f32_16x16x32_bf16 v[58:61], v[144:147], v[176:179], v[58:61]
	v_mfma_f32_16x16x32_bf16 v[54:57], v[152:155], v[176:179], v[54:57]
	v_mfma_f32_16x16x32_bf16 v[46:49], v[144:147], v[184:187], v[46:49]
	v_mfma_f32_16x16x32_bf16 v[38:41], v[152:155], v[184:187], v[38:41]
	v_mfma_f32_16x16x32_bf16 v[30:33], v[144:147], v[192:195], v[30:33]
	v_mfma_f32_16x16x32_bf16 v[22:25], v[152:155], v[192:195], v[22:25]
	v_mfma_f32_16x16x32_bf16 v[120:123], v[144:147], v[200:203], v[120:123]
	v_mfma_f32_16x16x32_bf16 v[10:13], v[152:155], v[200:203], v[10:13]
	v_mfma_f32_16x16x32_bf16 v[58:61], v[148:151], v[180:183], v[58:61]
	v_mfma_f32_16x16x32_bf16 v[54:57], v[156:159], v[180:183], v[54:57]
	v_mfma_f32_16x16x32_bf16 v[46:49], v[148:151], v[188:191], v[46:49]
	v_mfma_f32_16x16x32_bf16 v[38:41], v[156:159], v[188:191], v[38:41]
	v_mfma_f32_16x16x32_bf16 v[30:33], v[148:151], v[196:199], v[30:33]
	v_mfma_f32_16x16x32_bf16 v[22:25], v[156:159], v[196:199], v[22:25]
	v_mfma_f32_16x16x32_bf16 v[120:123], v[148:151], v[204:207], v[120:123]
	v_mfma_f32_16x16x32_bf16 v[10:13], v[156:159], v[204:207], v[10:13]
	v_mfma_f32_16x16x32_bf16 v[50:53], v[160:163], v[176:179], v[50:53]
	v_mfma_f32_16x16x32_bf16 v[42:45], v[168:171], v[176:179], v[42:45]
	v_mfma_f32_16x16x32_bf16 v[34:37], v[160:163], v[184:187], v[34:37]
	v_mfma_f32_16x16x32_bf16 v[26:29], v[168:171], v[184:187], v[26:29]
	v_mfma_f32_16x16x32_bf16 v[18:21], v[160:163], v[192:195], v[18:21]
	v_mfma_f32_16x16x32_bf16 v[14:17], v[168:171], v[192:195], v[14:17]
	v_mfma_f32_16x16x32_bf16 v[6:9], v[160:163], v[200:203], v[6:9]
	v_mfma_f32_16x16x32_bf16 v[2:5], v[168:171], v[200:203], v[2:5]
	v_mfma_f32_16x16x32_bf16 v[50:53], v[164:167], v[180:183], v[50:53]
	v_mfma_f32_16x16x32_bf16 v[42:45], v[172:175], v[180:183], v[42:45]
	v_mfma_f32_16x16x32_bf16 v[34:37], v[164:167], v[188:191], v[34:37]
	v_mfma_f32_16x16x32_bf16 v[26:29], v[172:175], v[188:191], v[26:29]
	v_mfma_f32_16x16x32_bf16 v[18:21], v[164:167], v[196:199], v[18:21]
	v_mfma_f32_16x16x32_bf16 v[14:17], v[172:175], v[196:199], v[14:17]
	v_mfma_f32_16x16x32_bf16 v[6:9], v[164:167], v[204:207], v[6:9]
	v_mfma_f32_16x16x32_bf16 v[2:5], v[172:175], v[204:207], v[2:5]
	s_barrier
	s_setprio 0
	s_setprio 1
	s_setprio 0
	s_waitcnt lgkmcnt(0)
	s_add_i32 s53, s53, 2
	s_add_u32 s26, s26, 0x100
	s_addc_u32 s27, s27, 0
	s_cmpk_gt_u32 s53, 0x55
	s_cbranch_scc0 .LBB0_1324
	s_add_u32 s26, s3, 0xffffff00
	s_addc_u32 s27, s52, -1
	s_and_b64 vcc, exec, s[10:11]
	s_cbranch_vccnz .LBB0_1311
	v_mov_b32_e32 v2, 0
	s_mov_b32 s20, s50
	s_mov_b32 s40, s51
	s_mov_b64 s[22:23], s[24:25]
	s_mov_b32 s49, s2
	v_mov_b32_e32 v3, v2
	v_mov_b32_e32 v4, v2
	v_mov_b32_e32 v5, v2
	v_mov_b32_e32 v6, v2
	v_mov_b32_e32 v7, v2
	v_mov_b32_e32 v8, v2
	v_mov_b32_e32 v9, v2
	v_mov_b32_e32 v14, v2
	v_mov_b32_e32 v15, v2
	v_mov_b32_e32 v16, v2
	v_mov_b32_e32 v17, v2
	v_mov_b32_e32 v18, v2
	v_mov_b32_e32 v19, v2
	v_mov_b32_e32 v20, v2
	v_mov_b32_e32 v21, v2
	v_mov_b32_e32 v26, v2
	v_mov_b32_e32 v27, v2
	v_mov_b32_e32 v28, v2
	v_mov_b32_e32 v29, v2
	v_mov_b32_e32 v34, v2
	v_mov_b32_e32 v35, v2
	v_mov_b32_e32 v36, v2
	v_mov_b32_e32 v37, v2
	v_mov_b32_e32 v42, v2
	v_mov_b32_e32 v43, v2
	v_mov_b32_e32 v44, v2
	v_mov_b32_e32 v45, v2
	v_mov_b32_e32 v50, v2
	v_mov_b32_e32 v51, v2
	v_mov_b32_e32 v52, v2
	v_mov_b32_e32 v53, v2
	v_mov_b32_e32 v10, v2
	v_mov_b32_e32 v11, v2
	v_mov_b32_e32 v12, v2
	v_mov_b32_e32 v13, v2
	v_mov_b32_e32 v120, v2
	v_mov_b32_e32 v121, v2
	v_mov_b32_e32 v122, v2
	v_mov_b32_e32 v123, v2
	v_mov_b32_e32 v22, v2
	v_mov_b32_e32 v23, v2
	v_mov_b32_e32 v24, v2
	v_mov_b32_e32 v25, v2
	v_mov_b32_e32 v30, v2
	v_mov_b32_e32 v31, v2
	v_mov_b32_e32 v32, v2
	v_mov_b32_e32 v33, v2
	v_mov_b32_e32 v38, v2
	v_mov_b32_e32 v39, v2
	v_mov_b32_e32 v40, v2
	v_mov_b32_e32 v41, v2
	v_mov_b32_e32 v46, v2
	v_mov_b32_e32 v47, v2
	v_mov_b32_e32 v48, v2
	v_mov_b32_e32 v49, v2
	v_mov_b32_e32 v54, v2
	v_mov_b32_e32 v55, v2
	v_mov_b32_e32 v56, v2
	v_mov_b32_e32 v57, v2
	v_mov_b32_e32 v58, v2
	v_mov_b32_e32 v59, v2
	v_mov_b32_e32 v60, v2
	v_mov_b32_e32 v61, v2
	v_mov_b32_e32 v62, v2
	v_mov_b32_e32 v63, v2
	v_mov_b32_e32 v64, v2
	v_mov_b32_e32 v65, v2
	v_mov_b32_e32 v68, v2
	v_mov_b32_e32 v69, v2
	v_mov_b32_e32 v70, v2
	v_mov_b32_e32 v71, v2
	v_mov_b32_e32 v76, v2
	v_mov_b32_e32 v77, v2
	v_mov_b32_e32 v78, v2
	v_mov_b32_e32 v79, v2
	v_mov_b32_e32 v84, v2
	v_mov_b32_e32 v85, v2
	v_mov_b32_e32 v86, v2
	v_mov_b32_e32 v87, v2
	v_mov_b32_e32 v92, v2
	v_mov_b32_e32 v93, v2
	v_mov_b32_e32 v94, v2
	v_mov_b32_e32 v95, v2
	v_mov_b32_e32 v100, v2
	v_mov_b32_e32 v101, v2
	v_mov_b32_e32 v102, v2
	v_mov_b32_e32 v103, v2
	v_mov_b32_e32 v108, v2
	v_mov_b32_e32 v109, v2
	v_mov_b32_e32 v110, v2
	v_mov_b32_e32 v111, v2
	v_mov_b32_e32 v116, v2
	v_mov_b32_e32 v117, v2
	v_mov_b32_e32 v118, v2
	v_mov_b32_e32 v119, v2
	v_mov_b32_e32 v72, v2
	v_mov_b32_e32 v73, v2
	v_mov_b32_e32 v74, v2
	v_mov_b32_e32 v75, v2
	v_mov_b32_e32 v80, v2
	v_mov_b32_e32 v81, v2
	v_mov_b32_e32 v82, v2
	v_mov_b32_e32 v83, v2
	v_mov_b32_e32 v88, v2
	v_mov_b32_e32 v89, v2
	v_mov_b32_e32 v90, v2
	v_mov_b32_e32 v91, v2
	v_mov_b32_e32 v96, v2
	v_mov_b32_e32 v97, v2
	v_mov_b32_e32 v98, v2
	v_mov_b32_e32 v99, v2
	v_mov_b32_e32 v104, v2
	v_mov_b32_e32 v105, v2
	v_mov_b32_e32 v106, v2
	v_mov_b32_e32 v107, v2
	v_mov_b32_e32 v112, v2
	v_mov_b32_e32 v113, v2
	v_mov_b32_e32 v114, v2
	v_mov_b32_e32 v115, v2
	v_mov_b32_e32 v124, v2
	v_mov_b32_e32 v125, v2
	v_mov_b32_e32 v126, v2
	v_mov_b32_e32 v127, v2
	v_mov_b32_e32 v128, v2
	v_mov_b32_e32 v129, v2
	v_mov_b32_e32 v130, v2
	v_mov_b32_e32 v131, v2
	s_andn2_b64 vcc, exec, s[6:7]
	s_cbranch_vccnz .LBB0_1312

;     __host__ __device__ bool next(int i, Unit& u) const { if (i != 0 || r < 0 || r >= 148) return false; if (r < 116) { u.pm = r % 29; u.pn = 47 + r / 29; } else { u.pm = 32; u.pn = 19 + (r - 116); } u.ko = 0; return true; }
;     __host__ __device__ bool next(int i, Unit& u) const { const int L = i * G + (G - 1 - c); if (L >= nN * S) return false; u.pm = pm; u.pn = L % nN; u.ko = (L / nN) * ksub; return true; }
; #define PG8_STAGE(bufoff, gbase, voff) do { _Pragma("unroll") for (int _i = 0; _i < 2; ++_i) \
;         __builtin_amdgcn_global_load_lds((const unsigned*)((const char*)(gbase) + (voff)[_i]), (PG8_LAS unsigned*)(lds + (bufoff) + ldsw + _i * 8192), 16, 0, 0); } while (0)
; #define PG8_LDA(dst, b, h) do { _Pragma("unroll") for (int m = 0; m < 4; ++m) _Pragma("unroll") for (int k = 0; k < 2; ++k) dst[m][k] = *(const PG8_LAS bf16x8*)(lds + PG8_SA(b, h) + aoff + m * 2048 + k * 1024); } while (0)
; #define PG8_BAR __builtin_amdgcn_s_barrier()
; template <class Epi, class Sched, bool ALIGN_EPI = false, bool SP2 = false>
; __device__ __forceinline__ void gemm_phase(PG8_LAS unsigned char* lds, const Gemm g, const Sched& S, const Epi& E) {
;     ...
;         const bool has_next = S.next(ui + 1, nxt);
;         const char* nA = has_next ? (const char*)g.A + (size_t)nxt.pm * tstep + (size_t)nxt.ko * 2 : cA; const char* nB = has_next ? (const char*)g.Bt + (size_t)nxt.pn * tstep + (size_t)nxt.ko * 2 : cB;
;         for (int t = 0; t < nt; t += 2) {
;             const bool last = (t == nt - 2);
;             const char* a1 = cA + (size_t)(t + 1) * kstep;
;             const char* a2 = last ? nA : cA + (size_t)(t + 2) * kstep; const char* b2 = last ? nB : cB + (size_t)(t + 2) * kstep;
;             const char* a3 = a2 + kstep; const char* b3 = b2 + kstep;
;             if (last && has_next) S.a_ready(nxt);
;             if constexpr (SP2) {
;             PG8_LDB(B0, 0, 0); PG8_LDB(B1, 0, 1); PG8_SCHED; PG8_LDA(At, 0, 0); PG8_STAGE(PG8_SA(1, 1), a1 + hstep, voffA);
;             PG8_WAIT_V(8); PG8_WAIT_L(0); PG8_BAR; PG8_MMA(0, 0, At, B0); PG8_MMA(0, 1, At, B1); PG8_BAR; PG8_SCHED;
;             PG8_LDA(At, 0, 1); PG8_STAGE(PG8_SB(0, 0), b2, voffB); PG8_STAGE(PG8_SB(0, 1), b2 + hstep, voffB); PG8_STAGE(PG8_SA(0, 0), a2, voffA);
;             PG8_WAIT_V(8); PG8_WAIT_L(0); PG8_BAR; PG8_MMA(1, 0, At, B0); PG8_MMA(1, 1, At, B1); PG8_BAR; PG8_SCHED;
.LBB0_1583:
	s_add_u32 s20, s18, 0x100
	s_addc_u32 s21, s19, 0
	s_cmp_eq_u32 s43, 4
	s_cselect_b32 s25, s17, s21
	s_cselect_b32 s24, s16, s20
	s_cselect_b32 s23, s15, s42
	s_cselect_b32 s22, s14, s13
	s_add_i32 s44, 0, 0x10000
	s_add_i32 s45, 0, 0x14000
	v_add_u32_e32 v168, s44, v0
	v_add_u32_e32 v184, s45, v0
	ds_read_b128 v[156:159], v168
	ds_read_b128 v[160:163], v168 offset:1024
	ds_read_b128 v[164:167], v168 offset:2048
	ds_read_b128 v[168:171], v168 offset:3072
	ds_read_b128 v[172:175], v184
	ds_read_b128 v[176:179], v184 offset:1024
	ds_read_b128 v[180:183], v184 offset:2048
	ds_read_b128 v[184:187], v184 offset:3072
	v_lshl_add_u64 v[228:229], s[18:19], 0, v[150:151]
	s_add_i32 m0, s28, 0xc000
	ds_read_b128 v[188:191], v155
	ds_read_b128 v[192:195], v155 offset:1024
	ds_read_b128 v[196:199], v155 offset:2048
	ds_read_b128 v[200:203], v155 offset:3072
	ds_read_b128 v[204:207], v155 offset:4096
	ds_read_b128 v[208:211], v155 offset:5120
	ds_read_b128 v[220:223], v155 offset:6144
	ds_read_b128 v[224:227], v155 offset:7168
	global_load_lds_dwordx4 v[228:229], off
	v_lshl_add_u64 v[228:229], s[18:19], 0, v[152:153]
	s_add_i32 m0, s28, 0xe000
	s_nop 0
	global_load_lds_dwordx4 v[228:229], off
	s_setprio 1
	s_nop 0
	s_waitcnt vmcnt(8) lgkmcnt(0)
	s_barrier
	v_mfma_f32_16x16x32_bf16 v[128:131], v[156:159], v[188:191], v[128:131]
	v_mfma_f32_16x16x32_bf16 v[124:127], v[164:167], v[188:191], v[124:127]
	v_mfma_f32_16x16x32_bf16 v[120:123], v[156:159], v[196:199], v[120:123]
	v_mfma_f32_16x16x32_bf16 v[116:119], v[164:167], v[196:199], v[116:119]
	v_mfma_f32_16x16x32_bf16 v[112:115], v[156:159], v[204:207], v[112:115]
	v_mfma_f32_16x16x32_bf16 v[108:111], v[164:167], v[204:207], v[108:111]
	v_mfma_f32_16x16x32_bf16 v[100:103], v[156:159], v[220:223], v[100:103]
	v_mfma_f32_16x16x32_bf16 v[92:95], v[164:167], v[220:223], v[92:95]
	v_mfma_f32_16x16x32_bf16 v[128:131], v[160:163], v[192:195], v[128:131]
	v_mfma_f32_16x16x32_bf16 v[124:127], v[168:171], v[192:195], v[124:127]
	v_mfma_f32_16x16x32_bf16 v[120:123], v[160:163], v[200:203], v[120:123]
	v_mfma_f32_16x16x32_bf16 v[116:119], v[168:171], v[200:203], v[116:119]
	v_mfma_f32_16x16x32_bf16 v[112:115], v[160:163], v[208:211], v[112:115]
	v_mfma_f32_16x16x32_bf16 v[108:111], v[168:171], v[208:211], v[108:111]
	v_mfma_f32_16x16x32_bf16 v[100:103], v[160:163], v[224:227], v[100:103]
	v_mfma_f32_16x16x32_bf16 v[92:95], v[168:171], v[224:227], v[92:95]
	v_mfma_f32_16x16x32_bf16 v[104:107], v[172:175], v[188:191], v[104:107]
	v_mfma_f32_16x16x32_bf16 v[96:99], v[180:183], v[188:191], v[96:99]
	v_mfma_f32_16x16x32_bf16 v[88:91], v[172:175], v[196:199], v[88:91]
	v_mfma_f32_16x16x32_bf16 v[84:87], v[180:183], v[196:199], v[84:87]
	v_mfma_f32_16x16x32_bf16 v[80:83], v[172:175], v[204:207], v[80:83]
	v_mfma_f32_16x16x32_bf16 v[76:79], v[180:183], v[204:207], v[76:79]
	v_mfma_f32_16x16x32_bf16 v[72:75], v[172:175], v[220:223], v[72:75]
	v_mfma_f32_16x16x32_bf16 v[68:71], v[180:183], v[220:223], v[68:71]
	v_mfma_f32_16x16x32_bf16 v[104:107], v[176:179], v[192:195], v[104:107]
	v_mfma_f32_16x16x32_bf16 v[96:99], v[184:187], v[192:195], v[96:99]
	v_mfma_f32_16x16x32_bf16 v[88:91], v[176:179], v[200:203], v[88:91]
	v_mfma_f32_16x16x32_bf16 v[84:87], v[184:187], v[200:203], v[84:87]
	v_mfma_f32_16x16x32_bf16 v[80:83], v[176:179], v[208:211], v[80:83]
	v_mfma_f32_16x16x32_bf16 v[76:79], v[184:187], v[208:211], v[76:79]
	v_mfma_f32_16x16x32_bf16 v[72:75], v[176:179], v[224:227], v[72:75]
	v_mfma_f32_16x16x32_bf16 v[68:71], v[184:187], v[224:227], v[68:71]
	s_barrier
	s_setprio 0
	s_setprio 1
	s_setprio 0
	s_waitcnt lgkmcnt(0)
	s_add_i32 s18, s44, s1
	v_lshl_add_u64 v[228:229], s[22:23], 0, v[66:67]
	s_mov_b32 m0, s18
	ds_read_b128 v[188:191], v155 offset:16384
	ds_read_b128 v[192:195], v155 offset:17408
	ds_read_b128 v[196:199], v155 offset:18432
	ds_read_b128 v[200:203], v155 offset:19456
	ds_read_b128 v[204:207], v155 offset:20480
	ds_read_b128 v[208:211], v155 offset:21504
	ds_read_b128 v[220:223], v155 offset:22528
	ds_read_b128 v[224:227], v155 offset:23552
	global_load_lds_dwordx4 v[228:229], off
	s_add_i32 m0, s18, 0x2000
	s_add_u32 s18, s22, 0x160000
	v_lshl_add_u64 v[230:231], s[22:23], 0, v[132:133]
	s_addc_u32 s19, s23, 0
	s_add_i32 s44, s45, s1
	global_load_lds_dwordx4 v[230:231], off
	v_lshl_add_u64 v[232:233], s[18:19], 0, v[66:67]
	s_mov_b32 m0, s44
	v_lshl_add_u64 v[234:235], s[24:25], 0, v[132:133]
	global_load_lds_dwordx4 v[232:233], off
	v_lshl_add_u64 v[232:233], s[18:19], 0, v[132:133]
	s_add_i32 m0, s44, 0x2000
	s_nop 0
	global_load_lds_dwordx4 v[232:233], off
	v_lshl_add_u64 v[232:233], s[24:25], 0, v[66:67]
	s_mov_b32 m0, s28
	s_nop 0
	global_load_lds_dwordx4 v[232:233], off
	s_mov_b32 m0, s29
	s_nop 0
	global_load_lds_dwordx4 v[234:235], off
	s_setprio 1
	s_nop 0
	s_waitcnt vmcnt(8) lgkmcnt(0)
	s_barrier
; #define PG8_STAGE(bufoff, gbase, voff) do { _Pragma("unroll") for (int _i = 0; _i < 2; ++_i) \
;         __builtin_amdgcn_global_load_lds((const unsigned*)((const char*)(gbase) + (voff)[_i]), (PG8_LAS unsigned*)(lds + (bufoff) + ldsw + _i * 8192), 16, 0, 0); } while (0)
; #define PG8_LDA(dst, b, h) do { _Pragma("unroll") for (int m = 0; m < 4; ++m) _Pragma("unroll") for (int k = 0; k < 2; ++k) dst[m][k] = *(const PG8_LAS bf16x8*)(lds + PG8_SA(b, h) + aoff + m * 2048 + k * 1024); } while (0)
; #define PG8_LDB(dst, b, h) do { _Pragma("unroll") for (int n = 0; n < 2; ++n) _Pragma("unroll") for (int k = 0; k < 2; ++k) dst[n][k] = *(const PG8_LAS bf16x8*)(lds + PG8_SB(b, h) + boff + n * 2048 + k * 1024); } while (0)
; #define PG8_MMA(ai, bj, At, Bt) do { __builtin_amdgcn_s_setprio(1); _Pragma("unroll") for (int m = 0; m < 4; ++m) _Pragma("unroll") for (int n = 0; n < 2; ++n) _Pragma("unroll") for (int k = 0; k < 2; ++k) \
;         acc[ai][bj][m][n] = __builtin_amdgcn_mfma_f32_16x16x32_bf16(Bt[n][k], At[m][k], acc[ai][bj][m][n], 0, 0, 0); __builtin_amdgcn_s_setprio(0); } while (0)
; #define PG8_WAIT_V(n) asm volatile("s_waitcnt vmcnt(" #n ")" ::: "memory")
; #define PG8_WAIT_L(n) asm volatile("s_waitcnt lgkmcnt(" #n ")" ::: "memory")
; #define PG8_BAR __builtin_amdgcn_s_barrier()
; #define PG8_SCHED __builtin_amdgcn_sched_barrier(0)
; template <class Epi, class Sched, bool ALIGN_EPI = false, bool SP2 = false>
; __device__ __forceinline__ void gemm_phase(PG8_LAS unsigned char* lds, const Gemm g, const Sched& S, const Epi& E) {
;     ...
;             PG8_WAIT_V(8); PG8_WAIT_L(0); PG8_BAR; PG8_MMA(1, 0, At, B0); PG8_MMA(1, 1, At, B1); PG8_BAR; PG8_SCHED;
;             PG8_LDB(B0, 1, 0); PG8_LDB(B1, 1, 1); PG8_SCHED; PG8_LDA(At, 1, 0); PG8_STAGE(PG8_SA(0, 1), a2 + hstep, voffA);
;             PG8_WAIT_V(8); PG8_WAIT_L(0); PG8_BAR; PG8_MMA(0, 0, At, B0); PG8_MMA(0, 1, At, B1); PG8_BAR; PG8_SCHED;
	v_mfma_f32_16x16x32_bf16 v[62:65], v[156:159], v[188:191], v[62:65]
	v_mfma_f32_16x16x32_bf16 v[58:61], v[164:167], v[188:191], v[58:61]
	v_mfma_f32_16x16x32_bf16 v[54:57], v[156:159], v[196:199], v[54:57]
	v_mfma_f32_16x16x32_bf16 v[50:53], v[164:167], v[196:199], v[50:53]
	v_mfma_f32_16x16x32_bf16 v[46:49], v[156:159], v[204:207], v[46:49]
	v_mfma_f32_16x16x32_bf16 v[42:45], v[164:167], v[204:207], v[42:45]
	v_mfma_f32_16x16x32_bf16 v[34:37], v[156:159], v[220:223], v[34:37]
	v_mfma_f32_16x16x32_bf16 v[26:29], v[164:167], v[220:223], v[26:29]
	v_mfma_f32_16x16x32_bf16 v[62:65], v[160:163], v[192:195], v[62:65]
	v_mfma_f32_16x16x32_bf16 v[58:61], v[168:171], v[192:195], v[58:61]
	v_mfma_f32_16x16x32_bf16 v[54:57], v[160:163], v[200:203], v[54:57]
	v_mfma_f32_16x16x32_bf16 v[50:53], v[168:171], v[200:203], v[50:53]
	v_mfma_f32_16x16x32_bf16 v[46:49], v[160:163], v[208:211], v[46:49]
	v_mfma_f32_16x16x32_bf16 v[42:45], v[168:171], v[208:211], v[42:45]
	v_mfma_f32_16x16x32_bf16 v[34:37], v[160:163], v[224:227], v[34:37]
	v_mfma_f32_16x16x32_bf16 v[26:29], v[168:171], v[224:227], v[26:29]
	v_mfma_f32_16x16x32_bf16 v[38:41], v[172:175], v[188:191], v[38:41]
	v_mfma_f32_16x16x32_bf16 v[30:33], v[180:183], v[188:191], v[30:33]
	v_mfma_f32_16x16x32_bf16 v[22:25], v[172:175], v[196:199], v[22:25]
	v_mfma_f32_16x16x32_bf16 v[18:21], v[180:183], v[196:199], v[18:21]
	v_mfma_f32_16x16x32_bf16 v[14:17], v[172:175], v[204:207], v[14:17]
	v_mfma_f32_16x16x32_bf16 v[10:13], v[180:183], v[204:207], v[10:13]
	v_mfma_f32_16x16x32_bf16 v[6:9], v[172:175], v[220:223], v[6:9]
	v_mfma_f32_16x16x32_bf16 v[2:5], v[180:183], v[220:223], v[2:5]
	v_mfma_f32_16x16x32_bf16 v[38:41], v[176:179], v[192:195], v[38:41]
	v_mfma_f32_16x16x32_bf16 v[30:33], v[184:187], v[192:195], v[30:33]
	v_mfma_f32_16x16x32_bf16 v[22:25], v[176:179], v[200:203], v[22:25]
	v_mfma_f32_16x16x32_bf16 v[18:21], v[184:187], v[200:203], v[18:21]
	v_mfma_f32_16x16x32_bf16 v[14:17], v[176:179], v[208:211], v[14:17]
	v_mfma_f32_16x16x32_bf16 v[10:13], v[184:187], v[208:211], v[10:13]
	v_mfma_f32_16x16x32_bf16 v[6:9], v[176:179], v[224:227], v[6:9]
	v_mfma_f32_16x16x32_bf16 v[2:5], v[184:187], v[224:227], v[2:5]
	s_barrier
	s_setprio 0
	s_setprio 1
	s_setprio 0
	s_waitcnt lgkmcnt(0)
	s_add_i32 s44, 0, 0x18000
	s_add_i32 s45, 0, 0x1c000
	v_add_u32_e32 v168, s44, v0
	v_add_u32_e32 v184, s45, v0
	ds_read_b128 v[156:159], v168
	ds_read_b128 v[160:163], v168 offset:1024
	ds_read_b128 v[164:167], v168 offset:2048
	ds_read_b128 v[168:171], v168 offset:3072
	ds_read_b128 v[172:175], v184
	ds_read_b128 v[176:179], v184 offset:1024
	ds_read_b128 v[180:183], v184 offset:2048
	ds_read_b128 v[184:187], v184 offset:3072
	s_add_u32 s18, s24, 0x160000
	s_addc_u32 s19, s25, 0
	s_mov_b32 m0, s30
	v_lshl_add_u64 v[246:247], s[18:19], 0, v[66:67]
	ds_read_b128 v[188:191], v155 offset:32768
	ds_read_b128 v[192:195], v155 offset:33792
	ds_read_b128 v[196:199], v155 offset:34816
	ds_read_b128 v[200:203], v155 offset:35840
	ds_read_b128 v[204:207], v155 offset:36864
	ds_read_b128 v[208:211], v155 offset:37888
	ds_read_b128 v[220:223], v155 offset:38912
	ds_read_b128 v[224:227], v155 offset:39936
	global_load_lds_dwordx4 v[246:247], off
	v_lshl_add_u64 v[246:247], s[18:19], 0, v[132:133]
	s_mov_b32 m0, s31
	s_nop 0
	global_load_lds_dwordx4 v[246:247], off
	s_setprio 1
	s_nop 0
	s_waitcnt vmcnt(8) lgkmcnt(0)
	s_barrier
	v_mfma_f32_16x16x32_bf16 v[128:131], v[156:159], v[188:191], v[128:131]
	v_mfma_f32_16x16x32_bf16 v[124:127], v[164:167], v[188:191], v[124:127]
	v_mfma_f32_16x16x32_bf16 v[120:123], v[156:159], v[196:199], v[120:123]
	v_mfma_f32_16x16x32_bf16 v[116:119], v[164:167], v[196:199], v[116:119]
	v_mfma_f32_16x16x32_bf16 v[112:115], v[156:159], v[204:207], v[112:115]
	v_mfma_f32_16x16x32_bf16 v[108:111], v[164:167], v[204:207], v[108:111]
	v_mfma_f32_16x16x32_bf16 v[100:103], v[156:159], v[220:223], v[100:103]
	v_mfma_f32_16x16x32_bf16 v[92:95], v[164:167], v[220:223], v[92:95]
	v_mfma_f32_16x16x32_bf16 v[128:131], v[160:163], v[192:195], v[128:131]
	v_mfma_f32_16x16x32_bf16 v[124:127], v[168:171], v[192:195], v[124:127]
	v_mfma_f32_16x16x32_bf16 v[120:123], v[160:163], v[200:203], v[120:123]
	v_mfma_f32_16x16x32_bf16 v[116:119], v[168:171], v[200:203], v[116:119]
	v_mfma_f32_16x16x32_bf16 v[112:115], v[160:163], v[208:211], v[112:115]
	v_mfma_f32_16x16x32_bf16 v[108:111], v[168:171], v[208:211], v[108:111]
	v_mfma_f32_16x16x32_bf16 v[100:103], v[160:163], v[224:227], v[100:103]
	v_mfma_f32_16x16x32_bf16 v[92:95], v[168:171], v[224:227], v[92:95]
	v_mfma_f32_16x16x32_bf16 v[104:107], v[172:175], v[188:191], v[104:107]
	v_mfma_f32_16x16x32_bf16 v[96:99], v[180:183], v[188:191], v[96:99]
	v_mfma_f32_16x16x32_bf16 v[88:91], v[172:175], v[196:199], v[88:91]
	v_mfma_f32_16x16x32_bf16 v[84:87], v[180:183], v[196:199], v[84:87]
	v_mfma_f32_16x16x32_bf16 v[80:83], v[172:175], v[204:207], v[80:83]
	v_mfma_f32_16x16x32_bf16 v[76:79], v[180:183], v[204:207], v[76:79]
	v_mfma_f32_16x16x32_bf16 v[72:75], v[172:175], v[220:223], v[72:75]
	v_mfma_f32_16x16x32_bf16 v[68:71], v[180:183], v[220:223], v[68:71]
	v_mfma_f32_16x16x32_bf16 v[104:107], v[176:179], v[192:195], v[104:107]
	v_mfma_f32_16x16x32_bf16 v[96:99], v[184:187], v[192:195], v[96:99]
	v_mfma_f32_16x16x32_bf16 v[88:91], v[176:179], v[200:203], v[88:91]
	v_mfma_f32_16x16x32_bf16 v[84:87], v[184:187], v[200:203], v[84:87]
	v_mfma_f32_16x16x32_bf16 v[80:83], v[176:179], v[208:211], v[80:83]
	v_mfma_f32_16x16x32_bf16 v[76:79], v[184:187], v[208:211], v[76:79]
	v_mfma_f32_16x16x32_bf16 v[72:75], v[176:179], v[224:227], v[72:75]
	v_mfma_f32_16x16x32_bf16 v[68:71], v[184:187], v[224:227], v[68:71]
	s_barrier
; #define PG8_STAGE(bufoff, gbase, voff) do { _Pragma("unroll") for (int _i = 0; _i < 2; ++_i) \
;         __builtin_amdgcn_global_load_lds((const unsigned*)((const char*)(gbase) + (voff)[_i]), (PG8_LAS unsigned*)(lds + (bufoff) + ldsw + _i * 8192), 16, 0, 0); } while (0)
; #define PG8_LDA(dst, b, h) do { _Pragma("unroll") for (int m = 0; m < 4; ++m) _Pragma("unroll") for (int k = 0; k < 2; ++k) dst[m][k] = *(const PG8_LAS bf16x8*)(lds + PG8_SA(b, h) + aoff + m * 2048 + k * 1024); } while (0)
; #define PG8_MMA(ai, bj, At, Bt) do { __builtin_amdgcn_s_setprio(1); _Pragma("unroll") for (int m = 0; m < 4; ++m) _Pragma("unroll") for (int n = 0; n < 2; ++n) _Pragma("unroll") for (int k = 0; k < 2; ++k) \
;         acc[ai][bj][m][n] = __builtin_amdgcn_mfma_f32_16x16x32_bf16(Bt[n][k], At[m][k], acc[ai][bj][m][n], 0, 0, 0); __builtin_amdgcn_s_setprio(0); } while (0)
; #define PG8_WAIT_V(n) asm volatile("s_waitcnt vmcnt(" #n ")" ::: "memory")
; #define PG8_WAIT_L(n) asm volatile("s_waitcnt lgkmcnt(" #n ")" ::: "memory")
; #define PG8_BAR __builtin_amdgcn_s_barrier()
; #define PG8_SCHED __builtin_amdgcn_sched_barrier(0)
; template <class Epi, class Sched, bool ALIGN_EPI = false, bool SP2 = false>
; __device__ __forceinline__ void gemm_phase(PG8_LAS unsigned char* lds, const Gemm g, const Sched& S, const Epi& E) {
;     ...
;             PG8_LDA(At, 1, 1); PG8_STAGE(PG8_SB(1, 0), b3, voffB); PG8_STAGE(PG8_SB(1, 1), b3 + hstep, voffB); PG8_STAGE(PG8_SA(1, 0), a3, voffA);
;             PG8_WAIT_V(8); PG8_WAIT_L(0); PG8_BAR; PG8_MMA(1, 0, At, B0); PG8_MMA(1, 1, At, B1); PG8_BAR; PG8_SCHED;
;     ...
;         if constexpr (ALIGN_EPI) { if (wr == 0) PG8_BAR; }
	s_setprio 0
	s_setprio 1
	s_setprio 0
	s_waitcnt lgkmcnt(0)
	s_add_i32 s18, s44, s1
	v_lshl_add_u64 v[228:229], v[228:229], 0, s[88:89]
	s_mov_b32 m0, s18
	ds_read_b128 v[188:191], v155 offset:49152
	ds_read_b128 v[192:195], v155 offset:50176
	ds_read_b128 v[196:199], v155 offset:51200
	ds_read_b128 v[200:203], v155 offset:52224
	ds_read_b128 v[204:207], v155 offset:53248
	ds_read_b128 v[208:211], v155 offset:54272
	ds_read_b128 v[220:223], v155 offset:55296
	ds_read_b128 v[224:227], v155 offset:56320
	global_load_lds_dwordx4 v[228:229], off
	s_add_i32 m0, s18, 0x2000
	s_add_u32 s18, s22, 0x160080
	v_lshl_add_u64 v[228:229], v[230:231], 0, s[88:89]
	s_addc_u32 s19, s23, 0
	s_add_i32 s22, s45, s1
	global_load_lds_dwordx4 v[228:229], off
	v_lshl_add_u64 v[228:229], s[18:19], 0, v[66:67]
	s_mov_b32 m0, s22
	s_nop 0
	global_load_lds_dwordx4 v[228:229], off
	v_lshl_add_u64 v[228:229], s[18:19], 0, v[132:133]
	s_add_i32 m0, s22, 0x2000
	s_nop 0
	global_load_lds_dwordx4 v[228:229], off
	v_lshl_add_u64 v[228:229], v[232:233], 0, s[88:89]
	s_mov_b32 m0, s38
	s_nop 0
	global_load_lds_dwordx4 v[228:229], off
	v_lshl_add_u64 v[228:229], v[234:235], 0, s[88:89]
	s_mov_b32 m0, s39
	s_nop 0
	global_load_lds_dwordx4 v[228:229], off
	s_setprio 1
	s_nop 0
	s_waitcnt vmcnt(8) lgkmcnt(0)
	s_barrier
	v_mfma_f32_16x16x32_bf16 v[62:65], v[156:159], v[188:191], v[62:65]
	v_mfma_f32_16x16x32_bf16 v[58:61], v[164:167], v[188:191], v[58:61]
	v_mfma_f32_16x16x32_bf16 v[54:57], v[156:159], v[196:199], v[54:57]
	v_mfma_f32_16x16x32_bf16 v[50:53], v[164:167], v[196:199], v[50:53]
	v_mfma_f32_16x16x32_bf16 v[46:49], v[156:159], v[204:207], v[46:49]
	v_mfma_f32_16x16x32_bf16 v[42:45], v[164:167], v[204:207], v[42:45]
	v_mfma_f32_16x16x32_bf16 v[34:37], v[156:159], v[220:223], v[34:37]
	v_mfma_f32_16x16x32_bf16 v[26:29], v[164:167], v[220:223], v[26:29]
	v_mfma_f32_16x16x32_bf16 v[62:65], v[160:163], v[192:195], v[62:65]
	v_mfma_f32_16x16x32_bf16 v[58:61], v[168:171], v[192:195], v[58:61]
	v_mfma_f32_16x16x32_bf16 v[54:57], v[160:163], v[200:203], v[54:57]
	v_mfma_f32_16x16x32_bf16 v[50:53], v[168:171], v[200:203], v[50:53]
	v_mfma_f32_16x16x32_bf16 v[46:49], v[160:163], v[208:211], v[46:49]
	v_mfma_f32_16x16x32_bf16 v[42:45], v[168:171], v[208:211], v[42:45]
	v_mfma_f32_16x16x32_bf16 v[34:37], v[160:163], v[224:227], v[34:37]
	v_mfma_f32_16x16x32_bf16 v[26:29], v[168:171], v[224:227], v[26:29]
	v_mfma_f32_16x16x32_bf16 v[38:41], v[172:175], v[188:191], v[38:41]
	v_mfma_f32_16x16x32_bf16 v[30:33], v[180:183], v[188:191], v[30:33]
	v_mfma_f32_16x16x32_bf16 v[22:25], v[172:175], v[196:199], v[22:25]
	v_mfma_f32_16x16x32_bf16 v[18:21], v[180:183], v[196:199], v[18:21]
	v_mfma_f32_16x16x32_bf16 v[14:17], v[172:175], v[204:207], v[14:17]
	v_mfma_f32_16x16x32_bf16 v[10:13], v[180:183], v[204:207], v[10:13]
	v_mfma_f32_16x16x32_bf16 v[6:9], v[172:175], v[220:223], v[6:9]
	v_mfma_f32_16x16x32_bf16 v[2:5], v[180:183], v[220:223], v[2:5]
	v_mfma_f32_16x16x32_bf16 v[38:41], v[176:179], v[192:195], v[38:41]
	v_mfma_f32_16x16x32_bf16 v[30:33], v[184:187], v[192:195], v[30:33]
	v_mfma_f32_16x16x32_bf16 v[22:25], v[176:179], v[200:203], v[22:25]
	v_mfma_f32_16x16x32_bf16 v[18:21], v[184:187], v[200:203], v[18:21]
	v_mfma_f32_16x16x32_bf16 v[14:17], v[176:179], v[208:211], v[14:17]
	v_mfma_f32_16x16x32_bf16 v[10:13], v[184:187], v[208:211], v[10:13]
	v_mfma_f32_16x16x32_bf16 v[6:9], v[176:179], v[224:227], v[6:9]
	v_mfma_f32_16x16x32_bf16 v[2:5], v[184:187], v[224:227], v[2:5]
	s_barrier
	s_setprio 0
	s_setprio 1
	s_setprio 0
	s_waitcnt lgkmcnt(0)
	s_add_i32 s43, s43, 2
	s_add_u32 s13, s13, 0x100
	s_addc_u32 s42, s42, 0
	s_cmp_gt_u32 s43, 5
	s_mov_b64 s[18:19], s[20:21]
	s_cbranch_scc0 .LBB0_1583
	s_and_b64 vcc, exec, s[10:11]
	s_cbranch_vccz .LBB0_1586
	s_barrier
